# GEMM k-loops: ks=1 fragment ds_reads issued before the ks=0 MFMAs into fresh registers (all 7 loops); scan loop with three input register sets
# speedup vs baseline: 1.1162x; 1.0094x over previous
.LBB0_86:
	s_add_i32 s35, s11, 1
	s_bitcmp1_b32 s35, 0
	s_cselect_b32 s37, 0x9000, 0
	v_add_u32_e32 v110, s37, v81
	v_lshl_add_u64 v[106:107], v[94:95], 0, s[12:13]
	s_mov_b64 s[38:39], 0x6181080
	v_readfirstlane_b32 s37, v110
	v_add_u32_e32 v111, 0x1000, v110
	v_lshl_add_u64 v[108:109], v[106:107], 0, s[38:39]
	s_mov_b32 m0, s37
	s_mov_b64 s[38:39], 0x61e5080
	v_readfirstlane_b32 s37, v111
	v_add_u32_e32 v111, 0x2000, v110
	global_load_lds_dwordx4 v[108:109], off
	v_lshl_add_u64 v[108:109], v[106:107], 0, s[38:39]
	s_mov_b32 m0, s37
	s_mov_b64 s[38:39], 0x6249080
	v_readfirstlane_b32 s37, v111
	v_add_u32_e32 v111, 0x3000, v110
	global_load_lds_dwordx4 v[108:109], off
	v_lshl_add_u64 v[108:109], v[106:107], 0, s[38:39]
	s_mov_b32 m0, s37
	s_mov_b64 s[38:39], 0x62ad080
	v_readfirstlane_b32 s37, v111
	global_load_lds_dwordx4 v[108:109], off
	v_lshl_add_u64 v[108:109], v[106:107], 0, s[38:39]
	s_mov_b32 m0, s37
	s_mov_b64 s[38:39], 0x6311080
	global_load_lds_dwordx4 v[108:109], off
	v_add_u32_e32 v108, 0x4000, v110
	v_lshl_add_u64 v[106:107], v[106:107], 0, s[38:39]
	v_readfirstlane_b32 s37, v108
	s_mov_b32 m0, s37
	v_add_u32_e32 v111, 0x5000, v110
	global_load_lds_dwordx4 v[106:107], off
	v_lshl_add_u64 v[106:107], v[100:101], 0, s[12:13]
	s_mov_b64 s[38:39], 0x14531080
	v_readfirstlane_b32 s37, v111
	v_add_u32_e32 v111, 0x6000, v110
	v_lshl_add_u64 v[108:109], v[106:107], 0, s[38:39]
	s_mov_b32 m0, s37
	s_mov_b64 s[38:39], 0x14541080
	v_readfirstlane_b32 s37, v111
	v_add_u32_e32 v111, 0x7000, v110
	global_load_lds_dwordx4 v[108:109], off
	v_lshl_add_u64 v[108:109], v[106:107], 0, s[38:39]
	s_mov_b32 m0, s37
	s_mov_b64 s[38:39], 0x14551080
	v_readfirstlane_b32 s37, v111
	global_load_lds_dwordx4 v[108:109], off
	v_lshl_add_u64 v[108:109], v[106:107], 0, s[38:39]
	s_mov_b32 m0, s37
	s_mov_b64 s[38:39], 0x14561080
	global_load_lds_dwordx4 v[108:109], off
	v_add_u32_e32 v108, 0x8000, v110
	v_lshl_add_u64 v[106:107], v[106:107], 0, s[38:39]
	v_readfirstlane_b32 s37, v108
	s_mov_b32 m0, s37
	s_bitcmp1_b32 s11, 0
	global_load_lds_dwordx4 v[106:107], off
	s_cselect_b32 s11, 0x9000, 0
	s_add_i32 s11, s11, 0
	v_add_u32_e32 v114, s11, v116
	v_add_u32_e32 v115, v114, v117
	ds_read_b128 v[106:109], v115
	ds_read_b128 v[110:113], v115 offset:2048
	ds_read_b128 v[122:125], v115 offset:4096
	ds_read_b128 v[156:159], v115 offset:6144
	v_add_u32_e32 v114, v114, v118
	ds_read_b128 v[166:169], v115 offset:8192
	ds_read_b128 v[178:181], v114 offset:20480
	ds_read_b128 v[182:185], v114 offset:22528
	ds_read_b128 v[186:189], v114 offset:24576
	ds_read_b128 v[190:193], v114 offset:26624
	v_add_u32_e32 v210, s11, v119
	v_add_u32_e32 v211, v210, v117
	ds_read_b128 v[212:215], v211
	ds_read_b128 v[216:219], v211 offset:2048
	ds_read_b128 v[220:223], v211 offset:4096
	ds_read_b128 v[224:227], v211 offset:6144
	v_add_u32_e32 v228, v210, v118
	ds_read_b128 v[230:233], v211 offset:8192
	ds_read_b128 v[234:237], v228 offset:20480
	ds_read_b128 v[238:241], v228 offset:22528
	ds_read_b128 v[242:245], v228 offset:24576
	ds_read_b128 v[246:249], v228 offset:26624
	s_setprio 1
	s_waitcnt lgkmcnt(9)
	v_mfma_f32_16x16x32_bf16 v[76:79], v[178:181], v[106:109], v[76:79]
	v_mfma_f32_16x16x32_bf16 v[72:75], v[182:185], v[106:109], v[72:75]
	v_mfma_f32_16x16x32_bf16 v[68:71], v[186:189], v[106:109], v[68:71]
	v_mfma_f32_16x16x32_bf16 v[64:67], v[190:193], v[106:109], v[64:67]
	v_mfma_f32_16x16x32_bf16 v[60:63], v[178:181], v[110:113], v[60:63]
	v_mfma_f32_16x16x32_bf16 v[56:59], v[182:185], v[110:113], v[56:59]
	v_mfma_f32_16x16x32_bf16 v[52:55], v[186:189], v[110:113], v[52:55]
	v_mfma_f32_16x16x32_bf16 v[48:51], v[190:193], v[110:113], v[48:51]
	v_mfma_f32_16x16x32_bf16 v[44:47], v[178:181], v[122:125], v[44:47]
	v_mfma_f32_16x16x32_bf16 v[40:43], v[182:185], v[122:125], v[40:43]
	v_mfma_f32_16x16x32_bf16 v[36:39], v[186:189], v[122:125], v[36:39]
	v_mfma_f32_16x16x32_bf16 v[32:35], v[190:193], v[122:125], v[32:35]
	v_mfma_f32_16x16x32_bf16 v[28:31], v[178:181], v[156:159], v[28:31]
	v_mfma_f32_16x16x32_bf16 v[24:27], v[182:185], v[156:159], v[24:27]
	v_mfma_f32_16x16x32_bf16 v[20:23], v[186:189], v[156:159], v[20:23]
	v_mfma_f32_16x16x32_bf16 v[16:19], v[190:193], v[156:159], v[16:19]
	v_mfma_f32_16x16x32_bf16 v[12:15], v[178:181], v[166:169], v[12:15]
	v_mfma_f32_16x16x32_bf16 v[8:11], v[182:185], v[166:169], v[8:11]
	v_mfma_f32_16x16x32_bf16 v[4:7], v[186:189], v[166:169], v[4:7]
	v_mfma_f32_16x16x32_bf16 v[0:3], v[190:193], v[166:169], v[0:3]
	s_setprio 0
	s_setprio 1
	s_waitcnt lgkmcnt(0)
	v_mfma_f32_16x16x32_bf16 v[76:79], v[234:237], v[212:215], v[76:79]
	v_mfma_f32_16x16x32_bf16 v[72:75], v[238:241], v[212:215], v[72:75]
	v_mfma_f32_16x16x32_bf16 v[68:71], v[242:245], v[212:215], v[68:71]
	v_mfma_f32_16x16x32_bf16 v[64:67], v[246:249], v[212:215], v[64:67]
	v_mfma_f32_16x16x32_bf16 v[60:63], v[234:237], v[216:219], v[60:63]
	v_mfma_f32_16x16x32_bf16 v[56:59], v[238:241], v[216:219], v[56:59]
	v_mfma_f32_16x16x32_bf16 v[52:55], v[242:245], v[216:219], v[52:55]
	v_mfma_f32_16x16x32_bf16 v[48:51], v[246:249], v[216:219], v[48:51]
	v_mfma_f32_16x16x32_bf16 v[44:47], v[234:237], v[220:223], v[44:47]
	v_mfma_f32_16x16x32_bf16 v[40:43], v[238:241], v[220:223], v[40:43]
	v_mfma_f32_16x16x32_bf16 v[36:39], v[242:245], v[220:223], v[36:39]
	v_mfma_f32_16x16x32_bf16 v[32:35], v[246:249], v[220:223], v[32:35]
	v_mfma_f32_16x16x32_bf16 v[28:31], v[234:237], v[224:227], v[28:31]
	v_mfma_f32_16x16x32_bf16 v[24:27], v[238:241], v[224:227], v[24:27]
	v_mfma_f32_16x16x32_bf16 v[20:23], v[242:245], v[224:227], v[20:23]
	v_mfma_f32_16x16x32_bf16 v[16:19], v[246:249], v[224:227], v[16:19]
	v_mfma_f32_16x16x32_bf16 v[12:15], v[234:237], v[230:233], v[12:15]
	v_mfma_f32_16x16x32_bf16 v[8:11], v[238:241], v[230:233], v[8:11]
	v_mfma_f32_16x16x32_bf16 v[4:7], v[242:245], v[230:233], v[4:7]
	v_mfma_f32_16x16x32_bf16 v[0:3], v[246:249], v[230:233], v[0:3]
	s_setprio 0
	s_waitcnt vmcnt(0)
	s_add_u32 s12, s12, 0x80
	s_addc_u32 s13, s13, 0
	s_cmpk_lg_i32 s12, 0x780
	s_mov_b32 s11, s35
	s_waitcnt vmcnt(0)
	s_barrier
	s_cbranch_scc1 .LBB0_86
	v_add_u32_e32 v122, v120, v118
	v_add_u32_e32 v123, v120, v117
	ds_read_b128 v[106:109], v122 offset:63488
	ds_read_b128 v[110:113], v122 offset:61440
	ds_read_b128 v[156:159], v122 offset:59392
	ds_read_b128 v[166:169], v122 offset:57344
	ds_read_b128 v[178:181], v123 offset:45056
	ds_read_b128 v[182:185], v123 offset:43008
	ds_read_b128 v[186:189], v123 offset:40960
	ds_read_b128 v[190:193], v123 offset:38912
	ds_read_b128 v[194:197], v123 offset:36864
	s_setprio 1
	s_waitcnt lgkmcnt(0)
	v_mfma_f32_16x16x32_bf16 v[76:79], v[166:169], v[194:197], v[76:79]
	v_mfma_f32_16x16x32_bf16 v[72:75], v[156:159], v[194:197], v[72:75]
	v_mfma_f32_16x16x32_bf16 v[68:71], v[110:113], v[194:197], v[68:71]
	v_mfma_f32_16x16x32_bf16 v[64:67], v[106:109], v[194:197], v[64:67]
	v_mfma_f32_16x16x32_bf16 v[60:63], v[166:169], v[190:193], v[60:63]
	v_mfma_f32_16x16x32_bf16 v[56:59], v[156:159], v[190:193], v[56:59]
	v_mfma_f32_16x16x32_bf16 v[52:55], v[110:113], v[190:193], v[52:55]
	v_mfma_f32_16x16x32_bf16 v[48:51], v[106:109], v[190:193], v[48:51]
	v_mfma_f32_16x16x32_bf16 v[44:47], v[166:169], v[186:189], v[44:47]
	v_mfma_f32_16x16x32_bf16 v[40:43], v[156:159], v[186:189], v[40:43]
	v_mfma_f32_16x16x32_bf16 v[36:39], v[110:113], v[186:189], v[36:39]
	v_mfma_f32_16x16x32_bf16 v[32:35], v[106:109], v[186:189], v[32:35]
	v_mfma_f32_16x16x32_bf16 v[28:31], v[166:169], v[182:185], v[28:31]
	v_mfma_f32_16x16x32_bf16 v[24:27], v[156:159], v[182:185], v[24:27]
	v_mfma_f32_16x16x32_bf16 v[20:23], v[110:113], v[182:185], v[20:23]
	v_mfma_f32_16x16x32_bf16 v[16:19], v[106:109], v[182:185], v[16:19]
	v_mfma_f32_16x16x32_bf16 v[12:15], v[166:169], v[178:181], v[12:15]
	v_mfma_f32_16x16x32_bf16 v[8:11], v[156:159], v[178:181], v[8:11]
	v_mfma_f32_16x16x32_bf16 v[4:7], v[110:113], v[178:181], v[4:7]
	v_mfma_f32_16x16x32_bf16 v[0:3], v[106:109], v[178:181], v[0:3]
	s_setprio 0
	v_add_u32_e32 v124, v121, v117
	ds_read_b128 v[106:109], v124 offset:36864
	ds_read_b128 v[110:113], v124 offset:38912
	ds_read_b128 v[156:159], v124 offset:40960
	ds_read_b128 v[166:169], v124 offset:43008
	v_add_u32_e32 v125, v121, v118
	ds_read_b128 v[178:181], v124 offset:45056
	ds_read_b128 v[182:185], v125 offset:57344
	ds_read_b128 v[186:189], v125 offset:59392
	ds_read_b128 v[190:193], v125 offset:61440
	ds_read_b128 v[194:197], v125 offset:63488
	s_setprio 1
	s_waitcnt lgkmcnt(1)
	v_mfma_f32_16x16x32_bf16 v[68:71], v[190:193], v[106:109], v[68:71]
	s_waitcnt lgkmcnt(0)
	v_mfma_f32_16x16x32_bf16 v[64:67], v[194:197], v[106:109], v[64:67]
	v_mfma_f32_16x16x32_bf16 v[60:63], v[182:185], v[110:113], v[60:63]
	v_mfma_f32_16x16x32_bf16 v[56:59], v[186:189], v[110:113], v[56:59]
	v_mfma_f32_16x16x32_bf16 v[52:55], v[190:193], v[110:113], v[52:55]
	v_mfma_f32_16x16x32_bf16 v[48:51], v[194:197], v[110:113], v[48:51]
	v_mfma_f32_16x16x32_bf16 v[44:47], v[182:185], v[156:159], v[44:47]
	v_mfma_f32_16x16x32_bf16 v[40:43], v[186:189], v[156:159], v[40:43]
	v_mfma_f32_16x16x32_bf16 v[36:39], v[190:193], v[156:159], v[36:39]
	v_mfma_f32_16x16x32_bf16 v[32:35], v[194:197], v[156:159], v[32:35]
	v_mfma_f32_16x16x32_bf16 v[28:31], v[182:185], v[166:169], v[28:31]
	v_mfma_f32_16x16x32_bf16 v[24:27], v[186:189], v[166:169], v[24:27]
	v_mfma_f32_16x16x32_bf16 v[20:23], v[190:193], v[166:169], v[20:23]
	v_mfma_f32_16x16x32_bf16 v[16:19], v[194:197], v[166:169], v[16:19]
	v_mfma_f32_16x16x32_bf16 v[12:15], v[182:185], v[178:181], v[12:15]
	v_mfma_f32_16x16x32_bf16 v[8:11], v[186:189], v[178:181], v[8:11]
	v_mfma_f32_16x16x32_bf16 v[4:7], v[190:193], v[178:181], v[4:7]
	v_mfma_f32_16x16x32_bf16 v[0:3], v[194:197], v[178:181], v[0:3]
	v_mfma_f32_16x16x32_bf16 v[198:201], v[182:185], v[106:109], v[76:79]
	v_mfma_f32_16x16x32_bf16 v[206:209], v[186:189], v[106:109], v[72:75]
	s_setprio 0
	s_nop 1
	v_mov_b32_e32 v72, v97
	s_waitcnt vmcnt(0)
	s_barrier
	s_mul_i32 s12, s36, 0xa0
	v_add_u32_e32 v72, v72, v176
	v_ashrrev_i32_e32 v73, 7, v72
	v_and_b32_e32 v74, 64, v72
	v_lshrrev_b32_e32 v75, 2, v72
	v_and_or_b32 v72, v72, 15, s12
	s_movk_i32 s11, 0x50
	s_mov_b32 s35, 0
	v_and_b32_e32 v75, 12, v75
	v_mad_u64_u32 v[72:73], s[36:37], v73, s11, v[72:73]
	s_lshl_b32 s13, s10, 7
	v_or3_b32 v112, v74, v75, s13
	v_mov_b64_e32 v[74:75], s[0:1]
	s_movk_i32 s36, 0x3200
	v_ashrrev_i32_e32 v73, 31, v72
	v_mad_i64_i32 v[76:77], s[10:11], v72, s36, v[74:75]
	s_mov_b64 s[38:39], 0x1800
	v_lshl_add_u64 v[114:115], v[76:77], 0, s[38:39]
	v_lshlrev_b64 v[76:77], 12, v[72:73]
	v_ashrrev_i32_e32 v113, 31, v112
	v_lshl_add_u64 v[106:107], s[4:5], 0, v[76:77]
	v_lshlrev_b64 v[76:77], 1, v[112:113]
	v_lshl_add_u64 v[108:109], v[114:115], 0, v[76:77]
	global_load_dwordx2 v[108:109], v[108:109], off
	v_lshlrev_b64 v[78:79], 2, v[112:113]
	v_lshl_add_u64 v[110:111], v[106:107], 0, v[78:79]
	s_waitcnt vmcnt(0)
	v_and_b32_e32 v107, 0xffff0000, v108
	v_lshlrev_b32_e32 v106, 16, v108
	v_and_b32_e32 v157, 0xffff0000, v109
	v_lshlrev_b32_e32 v156, 16, v109
	v_pk_mul_f32 v[106:107], v[198:199], v[106:107]
	v_pk_mul_f32 v[108:109], v[200:201], v[156:157]
	global_store_dwordx4 v[110:111], v[106:109], off
	s_nop 1
	v_or_b32_e32 v106, 16, v112
	v_ashrrev_i32_e32 v107, 31, v106
	v_lshlrev_b64 v[106:107], 1, v[106:107]
	v_lshl_add_u64 v[108:109], v[114:115], 0, v[106:107]
	global_load_dwordx2 v[108:109], v[108:109], off
	s_waitcnt vmcnt(0)
	v_and_b32_e32 v157, 0xffff0000, v108
	v_lshlrev_b32_e32 v156, 16, v108
	v_or_b32_e32 v108, 32, v112
	v_and_b32_e32 v159, 0xffff0000, v109
	v_lshlrev_b32_e32 v158, 16, v109
	v_ashrrev_i32_e32 v109, 31, v108
	v_pk_mul_f32 v[156:157], v[206:207], v[156:157]
	v_pk_mul_f32 v[158:159], v[208:209], v[158:159]
	v_lshlrev_b64 v[108:109], 1, v[108:109]
	global_store_dwordx4 v[110:111], v[156:159], off offset:64
	s_nop 1
	v_lshl_add_u64 v[156:157], v[114:115], 0, v[108:109]
	global_load_dwordx2 v[156:157], v[156:157], off
	s_waitcnt vmcnt(0)
	v_and_b32_e32 v159, 0xffff0000, v156
	v_lshlrev_b32_e32 v158, 16, v156
	v_pk_mul_f32 v[68:69], v[68:69], v[158:159]
	v_and_b32_e32 v159, 0xffff0000, v157
	v_lshlrev_b32_e32 v158, 16, v157
	v_pk_mul_f32 v[70:71], v[70:71], v[158:159]
	global_store_dwordx4 v[110:111], v[68:71], off offset:128
	s_nop 1
	v_or_b32_e32 v68, 48, v112
	v_ashrrev_i32_e32 v69, 31, v68
	v_lshlrev_b64 v[68:69], 1, v[68:69]
	v_lshl_add_u64 v[70:71], v[114:115], 0, v[68:69]
	global_load_dwordx2 v[70:71], v[70:71], off
	s_waitcnt vmcnt(0)
	v_and_b32_e32 v113, 0xffff0000, v70
	v_lshlrev_b32_e32 v112, 16, v70
	v_pk_mul_f32 v[64:65], v[64:65], v[112:113]
	v_and_b32_e32 v113, 0xffff0000, v71
	v_lshlrev_b32_e32 v112, 16, v71
	v_pk_mul_f32 v[66:67], v[66:67], v[112:113]
	global_store_dwordx4 v[110:111], v[64:67], off offset:192
	s_nop 1
	v_add_u32_e32 v64, 16, v72
	v_mad_i64_i32 v[66:67], s[10:11], v64, s36, v[74:75]
	v_lshl_add_u64 v[66:67], v[66:67], 0, s[38:39]
	v_lshl_add_u64 v[70:71], v[66:67], 0, v[76:77]
	global_load_dwordx2 v[70:71], v[70:71], off
	v_ashrrev_i32_e32 v65, 31, v64
	v_lshlrev_b64 v[64:65], 12, v[64:65]
	v_lshl_add_u64 v[64:65], s[4:5], 0, v[64:65]
	v_lshl_add_u64 v[64:65], v[64:65], 0, v[78:79]
	s_waitcnt vmcnt(0)
	v_and_b32_e32 v111, 0xffff0000, v70
	v_lshlrev_b32_e32 v110, 16, v70
	v_pk_mul_f32 v[60:61], v[60:61], v[110:111]
	v_and_b32_e32 v111, 0xffff0000, v71
	v_lshlrev_b32_e32 v110, 16, v71
	v_pk_mul_f32 v[62:63], v[62:63], v[110:111]
	global_store_dwordx4 v[64:65], v[60:63], off
	s_nop 1
	v_lshl_add_u64 v[60:61], v[66:67], 0, v[106:107]
	global_load_dwordx2 v[60:61], v[60:61], off
	s_waitcnt vmcnt(0)
	v_and_b32_e32 v63, 0xffff0000, v60
	v_lshlrev_b32_e32 v62, 16, v60
	v_pk_mul_f32 v[56:57], v[56:57], v[62:63]
	v_and_b32_e32 v63, 0xffff0000, v61
	v_lshlrev_b32_e32 v62, 16, v61
	v_pk_mul_f32 v[58:59], v[58:59], v[62:63]
	global_store_dwordx4 v[64:65], v[56:59], off offset:64
	s_nop 1
	v_lshl_add_u64 v[56:57], v[66:67], 0, v[108:109]
	global_load_dwordx2 v[56:57], v[56:57], off
	s_waitcnt vmcnt(0)
	v_and_b32_e32 v59, 0xffff0000, v56
	v_lshlrev_b32_e32 v58, 16, v56
	v_pk_mul_f32 v[52:53], v[52:53], v[58:59]
	v_and_b32_e32 v59, 0xffff0000, v57
	v_lshlrev_b32_e32 v58, 16, v57
	v_pk_mul_f32 v[54:55], v[54:55], v[58:59]
	global_store_dwordx4 v[64:65], v[52:55], off offset:128
	s_nop 1
	v_lshl_add_u64 v[52:53], v[66:67], 0, v[68:69]
	global_load_dwordx2 v[52:53], v[52:53], off
	s_waitcnt vmcnt(0)
	v_and_b32_e32 v55, 0xffff0000, v52
	v_lshlrev_b32_e32 v54, 16, v52
	v_pk_mul_f32 v[48:49], v[48:49], v[54:55]
	v_and_b32_e32 v55, 0xffff0000, v53
	v_lshlrev_b32_e32 v54, 16, v53
	v_pk_mul_f32 v[50:51], v[50:51], v[54:55]
	global_store_dwordx4 v[64:65], v[48:51], off offset:192
	s_nop 1
	v_add_u32_e32 v48, 32, v72
	v_mad_i64_i32 v[50:51], s[10:11], v48, s36, v[74:75]
	v_lshl_add_u64 v[50:51], v[50:51], 0, s[38:39]
	v_lshl_add_u64 v[52:53], v[50:51], 0, v[76:77]
	global_load_dwordx2 v[52:53], v[52:53], off
	v_ashrrev_i32_e32 v49, 31, v48
	v_lshlrev_b64 v[48:49], 12, v[48:49]
	v_lshl_add_u64 v[48:49], s[4:5], 0, v[48:49]
	v_lshl_add_u64 v[48:49], v[48:49], 0, v[78:79]
	s_waitcnt vmcnt(0)
	v_and_b32_e32 v55, 0xffff0000, v52
	v_lshlrev_b32_e32 v54, 16, v52
	v_pk_mul_f32 v[44:45], v[44:45], v[54:55]
	v_and_b32_e32 v55, 0xffff0000, v53
	v_lshlrev_b32_e32 v54, 16, v53
	v_pk_mul_f32 v[46:47], v[46:47], v[54:55]
	global_store_dwordx4 v[48:49], v[44:47], off
	s_nop 1
	v_lshl_add_u64 v[44:45], v[50:51], 0, v[106:107]
	global_load_dwordx2 v[44:45], v[44:45], off
	s_waitcnt vmcnt(0)
	v_and_b32_e32 v47, 0xffff0000, v44
	v_lshlrev_b32_e32 v46, 16, v44
	v_pk_mul_f32 v[40:41], v[40:41], v[46:47]
	v_and_b32_e32 v47, 0xffff0000, v45
	v_lshlrev_b32_e32 v46, 16, v45
	v_pk_mul_f32 v[42:43], v[42:43], v[46:47]
	global_store_dwordx4 v[48:49], v[40:43], off offset:64
	s_nop 1
	v_lshl_add_u64 v[40:41], v[50:51], 0, v[108:109]
	global_load_dwordx2 v[40:41], v[40:41], off
	s_waitcnt vmcnt(0)
	v_and_b32_e32 v43, 0xffff0000, v40
	v_lshlrev_b32_e32 v42, 16, v40
	v_pk_mul_f32 v[36:37], v[36:37], v[42:43]
	v_and_b32_e32 v43, 0xffff0000, v41
	v_lshlrev_b32_e32 v42, 16, v41
	v_pk_mul_f32 v[38:39], v[38:39], v[42:43]
	global_store_dwordx4 v[48:49], v[36:39], off offset:128
	s_nop 1
	v_lshl_add_u64 v[36:37], v[50:51], 0, v[68:69]
	global_load_dwordx2 v[36:37], v[36:37], off
	s_waitcnt vmcnt(0)
	v_and_b32_e32 v39, 0xffff0000, v36
	v_lshlrev_b32_e32 v38, 16, v36
	v_pk_mul_f32 v[32:33], v[32:33], v[38:39]
	v_and_b32_e32 v39, 0xffff0000, v37
	v_lshlrev_b32_e32 v38, 16, v37
	v_pk_mul_f32 v[34:35], v[34:35], v[38:39]
	global_store_dwordx4 v[48:49], v[32:35], off offset:192
	s_nop 1
	v_add_u32_e32 v32, 48, v72
	v_mad_i64_i32 v[34:35], s[10:11], v32, s36, v[74:75]
	v_lshl_add_u64 v[34:35], v[34:35], 0, s[38:39]
	v_lshl_add_u64 v[36:37], v[34:35], 0, v[76:77]
	global_load_dwordx2 v[36:37], v[36:37], off
	v_ashrrev_i32_e32 v33, 31, v32
	v_lshlrev_b64 v[32:33], 12, v[32:33]
	v_lshl_add_u64 v[32:33], s[4:5], 0, v[32:33]
	v_lshl_add_u64 v[32:33], v[32:33], 0, v[78:79]
	s_waitcnt vmcnt(0)
	v_and_b32_e32 v39, 0xffff0000, v36
	v_lshlrev_b32_e32 v38, 16, v36
	v_pk_mul_f32 v[28:29], v[28:29], v[38:39]
	v_and_b32_e32 v39, 0xffff0000, v37
	v_lshlrev_b32_e32 v38, 16, v37
	v_pk_mul_f32 v[30:31], v[30:31], v[38:39]
	global_store_dwordx4 v[32:33], v[28:31], off
	s_nop 1
	v_lshl_add_u64 v[28:29], v[34:35], 0, v[106:107]
	global_load_dwordx2 v[28:29], v[28:29], off
	s_waitcnt vmcnt(0)
	v_and_b32_e32 v31, 0xffff0000, v28
	v_lshlrev_b32_e32 v30, 16, v28
	v_pk_mul_f32 v[24:25], v[24:25], v[30:31]
	v_and_b32_e32 v31, 0xffff0000, v29
	v_lshlrev_b32_e32 v30, 16, v29
	v_pk_mul_f32 v[26:27], v[26:27], v[30:31]
	global_store_dwordx4 v[32:33], v[24:27], off offset:64
	s_nop 1
	v_lshl_add_u64 v[24:25], v[34:35], 0, v[108:109]
	global_load_dwordx2 v[24:25], v[24:25], off
	s_waitcnt vmcnt(0)
	v_and_b32_e32 v27, 0xffff0000, v24
	v_lshlrev_b32_e32 v26, 16, v24
	v_pk_mul_f32 v[20:21], v[20:21], v[26:27]
	v_and_b32_e32 v27, 0xffff0000, v25
	v_lshlrev_b32_e32 v26, 16, v25
	v_pk_mul_f32 v[22:23], v[22:23], v[26:27]
	global_store_dwordx4 v[32:33], v[20:23], off offset:128
	s_nop 1
	v_lshl_add_u64 v[20:21], v[34:35], 0, v[68:69]
	global_load_dwordx2 v[20:21], v[20:21], off
	s_waitcnt vmcnt(0)
	v_and_b32_e32 v23, 0xffff0000, v20
	v_lshlrev_b32_e32 v22, 16, v20
	v_pk_mul_f32 v[16:17], v[16:17], v[22:23]
	v_and_b32_e32 v23, 0xffff0000, v21
	v_lshlrev_b32_e32 v22, 16, v21
	v_pk_mul_f32 v[18:19], v[18:19], v[22:23]
	global_store_dwordx4 v[32:33], v[16:19], off offset:192
	s_nop 1
	v_add_u32_e32 v16, 64, v72
	v_mad_i64_i32 v[18:19], s[10:11], v16, s36, v[74:75]
	v_lshl_add_u64 v[18:19], v[18:19], 0, s[38:39]
	v_lshl_add_u64 v[20:21], v[18:19], 0, v[76:77]
	global_load_dwordx2 v[20:21], v[20:21], off
	v_ashrrev_i32_e32 v17, 31, v16
	v_lshlrev_b64 v[16:17], 12, v[16:17]
	v_lshl_add_u64 v[16:17], s[4:5], 0, v[16:17]
	v_lshl_add_u64 v[16:17], v[16:17], 0, v[78:79]
	s_mov_b64 s[10:11], 0x800
	s_waitcnt vmcnt(0)
	v_and_b32_e32 v23, 0xffff0000, v20
	v_lshlrev_b32_e32 v22, 16, v20
	v_pk_mul_f32 v[12:13], v[12:13], v[22:23]
	v_and_b32_e32 v23, 0xffff0000, v21
	v_lshlrev_b32_e32 v22, 16, v21
	v_pk_mul_f32 v[14:15], v[14:15], v[22:23]
	global_store_dwordx4 v[16:17], v[12:15], off
	s_nop 1
	v_lshl_add_u64 v[12:13], v[18:19], 0, v[106:107]
	global_load_dwordx2 v[12:13], v[12:13], off
	s_waitcnt vmcnt(0)
	v_and_b32_e32 v15, 0xffff0000, v12
	v_lshlrev_b32_e32 v14, 16, v12
	v_pk_mul_f32 v[8:9], v[8:9], v[14:15]
	v_and_b32_e32 v15, 0xffff0000, v13
	v_lshlrev_b32_e32 v14, 16, v13
	v_pk_mul_f32 v[10:11], v[10:11], v[14:15]
	global_store_dwordx4 v[16:17], v[8:11], off offset:64
	s_nop 1
	v_lshl_add_u64 v[8:9], v[18:19], 0, v[108:109]
	global_load_dwordx2 v[8:9], v[8:9], off
	s_waitcnt vmcnt(0)
	v_and_b32_e32 v11, 0xffff0000, v8
	v_lshlrev_b32_e32 v10, 16, v8
	v_pk_mul_f32 v[4:5], v[4:5], v[10:11]
	v_and_b32_e32 v11, 0xffff0000, v9
	v_lshlrev_b32_e32 v10, 16, v9
	v_pk_mul_f32 v[6:7], v[6:7], v[10:11]
	global_store_dwordx4 v[16:17], v[4:7], off offset:128
	s_nop 1
	v_lshl_add_u64 v[4:5], v[18:19], 0, v[68:69]
	global_load_dwordx2 v[4:5], v[4:5], off
	s_waitcnt vmcnt(0)
	v_and_b32_e32 v7, 0xffff0000, v4
	v_lshlrev_b32_e32 v6, 16, v4
	v_pk_mul_f32 v[0:1], v[0:1], v[6:7]
	v_and_b32_e32 v7, 0xffff0000, v5
	v_lshlrev_b32_e32 v6, 16, v5
	v_pk_mul_f32 v[2:3], v[2:3], v[6:7]
	global_store_dwordx4 v[16:17], v[0:3], off offset:192
	s_nop 1
	v_lshl_add_u64 v[0:1], v[104:105], 0, s[10:11]
	v_readfirstlane_b32 s10, v81
	s_mov_b32 m0, s10
	s_mov_b64 s[10:11], 0x64800
	global_load_lds_dwordx4 v[0:1], off
	v_lshl_add_u64 v[0:1], v[104:105], 0, s[10:11]
	v_readfirstlane_b32 s10, v133
	s_mov_b32 m0, s10
	s_mov_b64 s[10:11], 0xc8800
	global_load_lds_dwordx4 v[0:1], off
	v_lshl_add_u64 v[0:1], v[104:105], 0, s[10:11]
	v_readfirstlane_b32 s10, v132
	s_mov_b32 m0, s10
	s_mov_b64 s[10:11], 0x12c800
	global_load_lds_dwordx4 v[0:1], off
	v_lshl_add_u64 v[0:1], v[104:105], 0, s[10:11]
	v_readfirstlane_b32 s10, v131
	s_mov_b32 m0, s10
	s_mov_b64 s[10:11], 0x190800
	global_load_lds_dwordx4 v[0:1], off
	v_lshl_add_u64 v[0:1], v[104:105], 0, s[10:11]
	v_readfirstlane_b32 s10, v130
	s_mov_b32 m0, s10
	v_readfirstlane_b32 s10, v129
	global_load_lds_dwordx4 v[0:1], off
	v_lshl_add_u64 v[0:1], v[86:87], 0, s[8:9]
	s_mov_b32 m0, s10
	v_readfirstlane_b32 s10, v128
	global_load_lds_dwordx4 v[0:1], off
	v_lshl_add_u64 v[2:3], v[0:1], 0, s[40:41]
	s_mov_b32 m0, s10
	s_mov_b64 s[10:11], 0x20000
	global_load_lds_dwordx4 v[2:3], off
	v_lshl_add_u64 v[2:3], v[0:1], 0, s[10:11]
	v_readfirstlane_b32 s10, v127
	s_mov_b32 m0, s10
	s_mov_b64 s[10:11], 0x30000
	v_lshl_add_u64 v[0:1], v[0:1], 0, s[10:11]
	v_readfirstlane_b32 s10, v126
	global_load_lds_dwordx4 v[2:3], off
	s_mov_b32 m0, s10
	s_mov_b64 s[10:11], 0
	global_load_lds_dwordx4 v[0:1], off
	s_waitcnt vmcnt(0)
	v_mov_b32_e32 v0, 0
	v_mov_b32_e32 v1, v0
	v_mov_b32_e32 v2, v0
	v_mov_b32_e32 v3, v0
	v_mov_b32_e32 v4, v0
	v_mov_b32_e32 v5, v0
	v_mov_b32_e32 v6, v0
	v_mov_b32_e32 v7, v0
	v_mov_b32_e32 v8, v0
	v_mov_b32_e32 v9, v0
	v_mov_b32_e32 v10, v0
	v_mov_b32_e32 v11, v0
	v_mov_b32_e32 v12, v0
	v_mov_b32_e32 v13, v0
	v_mov_b32_e32 v14, v0
	v_mov_b32_e32 v15, v0
	v_mov_b32_e32 v16, v0
	v_mov_b32_e32 v17, v0
	v_mov_b32_e32 v18, v0
	v_mov_b32_e32 v19, v0
	v_mov_b32_e32 v20, v0
	v_mov_b32_e32 v21, v0
	v_mov_b32_e32 v22, v0
	v_mov_b32_e32 v23, v0
	v_mov_b32_e32 v24, v0
	v_mov_b32_e32 v25, v0
	v_mov_b32_e32 v26, v0
	v_mov_b32_e32 v27, v0
	v_mov_b32_e32 v28, v0
	v_mov_b32_e32 v29, v0
	v_mov_b32_e32 v30, v0
	v_mov_b32_e32 v31, v0
	v_mov_b32_e32 v32, v0
	v_mov_b32_e32 v33, v0
	v_mov_b32_e32 v34, v0
	v_mov_b32_e32 v35, v0
	v_mov_b32_e32 v36, v0
	v_mov_b32_e32 v37, v0
	v_mov_b32_e32 v38, v0
	v_mov_b32_e32 v39, v0
	v_mov_b32_e32 v40, v0
	v_mov_b32_e32 v41, v0
	v_mov_b32_e32 v42, v0
	v_mov_b32_e32 v43, v0
	v_mov_b32_e32 v44, v0
	v_mov_b32_e32 v45, v0
	v_mov_b32_e32 v46, v0
	v_mov_b32_e32 v47, v0
	v_mov_b32_e32 v48, v0
	v_mov_b32_e32 v49, v0
	v_mov_b32_e32 v50, v0
	v_mov_b32_e32 v51, v0
	v_mov_b32_e32 v52, v0
	v_mov_b32_e32 v53, v0
	v_mov_b32_e32 v54, v0
	v_mov_b32_e32 v55, v0
	v_mov_b32_e32 v56, v0
	v_mov_b32_e32 v57, v0
	v_mov_b32_e32 v58, v0
	v_mov_b32_e32 v59, v0
	v_mov_b32_e32 v60, v0
	v_mov_b32_e32 v61, v0
	v_mov_b32_e32 v62, v0
	v_mov_b32_e32 v63, v0
	v_mov_b32_e32 v64, v0
	v_mov_b32_e32 v65, v0
	v_mov_b32_e32 v66, v0
	v_mov_b32_e32 v67, v0
	v_mov_b32_e32 v68, v0
	v_mov_b32_e32 v69, v0
	v_mov_b32_e32 v70, v0
	v_mov_b32_e32 v71, v0
	v_mov_b32_e32 v72, v0
	v_mov_b32_e32 v73, v0
	v_mov_b32_e32 v74, v0
	v_mov_b32_e32 v75, v0
	v_mov_b32_e32 v76, v0
	v_mov_b32_e32 v77, v0
	v_mov_b32_e32 v78, v0
	v_mov_b32_e32 v79, v0
	s_waitcnt vmcnt(0) lgkmcnt(0)
	s_barrier
.LBB0_88:
	s_add_i32 s36, s35, 1
	s_bitcmp1_b32 s36, 0
	s_cselect_b32 s37, 0x9000, 0
	v_add_u32_e32 v108, s37, v81
	v_lshl_add_u64 v[104:105], v[94:95], 0, s[10:11]
	s_mov_b64 s[38:39], 0x6181880
	v_readfirstlane_b32 s37, v108
	v_add_u32_e32 v109, 0x1000, v108
	v_lshl_add_u64 v[106:107], v[104:105], 0, s[38:39]
	s_mov_b32 m0, s37
	s_mov_b64 s[38:39], 0x61e5880
	v_readfirstlane_b32 s37, v109
	v_add_u32_e32 v109, 0x2000, v108
	global_load_lds_dwordx4 v[106:107], off
	v_lshl_add_u64 v[106:107], v[104:105], 0, s[38:39]
	s_mov_b32 m0, s37
	s_mov_b64 s[38:39], 0x6249880
	v_readfirstlane_b32 s37, v109
	v_add_u32_e32 v109, 0x3000, v108
	global_load_lds_dwordx4 v[106:107], off
	v_lshl_add_u64 v[106:107], v[104:105], 0, s[38:39]
	s_mov_b32 m0, s37
	s_mov_b64 s[38:39], 0x62ad880
	v_readfirstlane_b32 s37, v109
	global_load_lds_dwordx4 v[106:107], off
	v_lshl_add_u64 v[106:107], v[104:105], 0, s[38:39]
	s_mov_b32 m0, s37
	s_mov_b64 s[38:39], 0x6311880
	global_load_lds_dwordx4 v[106:107], off
	v_add_u32_e32 v106, 0x4000, v108
	v_lshl_add_u64 v[104:105], v[104:105], 0, s[38:39]
	v_readfirstlane_b32 s37, v106
	s_mov_b32 m0, s37
	v_add_u32_e32 v109, 0x5000, v108
	global_load_lds_dwordx4 v[104:105], off
	v_lshl_add_u64 v[104:105], v[100:101], 0, s[10:11]
	s_mov_b64 s[38:39], 0x14731080
	v_readfirstlane_b32 s37, v109
	v_add_u32_e32 v109, 0x6000, v108
	v_lshl_add_u64 v[106:107], v[104:105], 0, s[38:39]
	s_mov_b32 m0, s37
	s_mov_b64 s[38:39], 0x14741080
	v_readfirstlane_b32 s37, v109
	v_add_u32_e32 v109, 0x7000, v108
	global_load_lds_dwordx4 v[106:107], off
	v_lshl_add_u64 v[106:107], v[104:105], 0, s[38:39]
	s_mov_b32 m0, s37
	s_mov_b64 s[38:39], 0x14751080
	v_readfirstlane_b32 s37, v109
	global_load_lds_dwordx4 v[106:107], off
	v_lshl_add_u64 v[106:107], v[104:105], 0, s[38:39]
	s_mov_b32 m0, s37
	s_mov_b64 s[38:39], 0x14761080
	global_load_lds_dwordx4 v[106:107], off
	v_add_u32_e32 v106, 0x8000, v108
	v_lshl_add_u64 v[104:105], v[104:105], 0, s[38:39]
	v_readfirstlane_b32 s37, v106
	s_mov_b32 m0, s37
	s_bitcmp1_b32 s35, 0
	global_load_lds_dwordx4 v[104:105], off
	s_cselect_b32 s35, 0x9000, 0
	s_add_i32 s35, s35, 0
	v_add_u32_e32 v166, s35, v116
	v_add_u32_e32 v167, v166, v117
	ds_read_b128 v[104:107], v167
	ds_read_b128 v[108:111], v167 offset:2048
	ds_read_b128 v[112:115], v167 offset:4096
	ds_read_b128 v[156:159], v167 offset:6144
	v_add_u32_e32 v177, v166, v118
	ds_read_b128 v[166:169], v167 offset:8192
	ds_read_b128 v[178:181], v177 offset:20480
	ds_read_b128 v[182:185], v177 offset:22528
	ds_read_b128 v[186:189], v177 offset:24576
	ds_read_b128 v[190:193], v177 offset:26624
	v_add_u32_e32 v210, s35, v119
	v_add_u32_e32 v211, v210, v117
	ds_read_b128 v[212:215], v211
	ds_read_b128 v[216:219], v211 offset:2048
	ds_read_b128 v[220:223], v211 offset:4096
	ds_read_b128 v[224:227], v211 offset:6144
	v_add_u32_e32 v228, v210, v118
	ds_read_b128 v[230:233], v211 offset:8192
	ds_read_b128 v[234:237], v228 offset:20480
	ds_read_b128 v[238:241], v228 offset:22528
	ds_read_b128 v[242:245], v228 offset:24576
	ds_read_b128 v[246:249], v228 offset:26624
	s_setprio 1
	s_waitcnt lgkmcnt(9)
	v_mfma_f32_16x16x32_bf16 v[76:79], v[178:181], v[104:107], v[76:79]
	v_mfma_f32_16x16x32_bf16 v[72:75], v[182:185], v[104:107], v[72:75]
	v_mfma_f32_16x16x32_bf16 v[68:71], v[186:189], v[104:107], v[68:71]
	v_mfma_f32_16x16x32_bf16 v[64:67], v[190:193], v[104:107], v[64:67]
	v_mfma_f32_16x16x32_bf16 v[60:63], v[178:181], v[108:111], v[60:63]
	v_mfma_f32_16x16x32_bf16 v[56:59], v[182:185], v[108:111], v[56:59]
	v_mfma_f32_16x16x32_bf16 v[52:55], v[186:189], v[108:111], v[52:55]
	v_mfma_f32_16x16x32_bf16 v[48:51], v[190:193], v[108:111], v[48:51]
	v_mfma_f32_16x16x32_bf16 v[44:47], v[178:181], v[112:115], v[44:47]
	v_mfma_f32_16x16x32_bf16 v[40:43], v[182:185], v[112:115], v[40:43]
	v_mfma_f32_16x16x32_bf16 v[36:39], v[186:189], v[112:115], v[36:39]
	v_mfma_f32_16x16x32_bf16 v[32:35], v[190:193], v[112:115], v[32:35]
	v_mfma_f32_16x16x32_bf16 v[28:31], v[178:181], v[156:159], v[28:31]
	v_mfma_f32_16x16x32_bf16 v[24:27], v[182:185], v[156:159], v[24:27]
	v_mfma_f32_16x16x32_bf16 v[20:23], v[186:189], v[156:159], v[20:23]
	v_mfma_f32_16x16x32_bf16 v[16:19], v[190:193], v[156:159], v[16:19]
	v_mfma_f32_16x16x32_bf16 v[12:15], v[178:181], v[166:169], v[12:15]
	v_mfma_f32_16x16x32_bf16 v[8:11], v[182:185], v[166:169], v[8:11]
	v_mfma_f32_16x16x32_bf16 v[4:7], v[186:189], v[166:169], v[4:7]
	v_mfma_f32_16x16x32_bf16 v[0:3], v[190:193], v[166:169], v[0:3]
	s_setprio 0
	s_setprio 1
	s_waitcnt lgkmcnt(0)
	v_mfma_f32_16x16x32_bf16 v[76:79], v[234:237], v[212:215], v[76:79]
	v_mfma_f32_16x16x32_bf16 v[72:75], v[238:241], v[212:215], v[72:75]
	v_mfma_f32_16x16x32_bf16 v[68:71], v[242:245], v[212:215], v[68:71]
	v_mfma_f32_16x16x32_bf16 v[64:67], v[246:249], v[212:215], v[64:67]
	v_mfma_f32_16x16x32_bf16 v[60:63], v[234:237], v[216:219], v[60:63]
	v_mfma_f32_16x16x32_bf16 v[56:59], v[238:241], v[216:219], v[56:59]
	v_mfma_f32_16x16x32_bf16 v[52:55], v[242:245], v[216:219], v[52:55]
	v_mfma_f32_16x16x32_bf16 v[48:51], v[246:249], v[216:219], v[48:51]
	v_mfma_f32_16x16x32_bf16 v[44:47], v[234:237], v[220:223], v[44:47]
	v_mfma_f32_16x16x32_bf16 v[40:43], v[238:241], v[220:223], v[40:43]
	v_mfma_f32_16x16x32_bf16 v[36:39], v[242:245], v[220:223], v[36:39]
	v_mfma_f32_16x16x32_bf16 v[32:35], v[246:249], v[220:223], v[32:35]
	v_mfma_f32_16x16x32_bf16 v[28:31], v[234:237], v[224:227], v[28:31]
	v_mfma_f32_16x16x32_bf16 v[24:27], v[238:241], v[224:227], v[24:27]
	v_mfma_f32_16x16x32_bf16 v[20:23], v[242:245], v[224:227], v[20:23]
	v_mfma_f32_16x16x32_bf16 v[16:19], v[246:249], v[224:227], v[16:19]
	v_mfma_f32_16x16x32_bf16 v[12:15], v[234:237], v[230:233], v[12:15]
	v_mfma_f32_16x16x32_bf16 v[8:11], v[238:241], v[230:233], v[8:11]
	v_mfma_f32_16x16x32_bf16 v[4:7], v[242:245], v[230:233], v[4:7]
	v_mfma_f32_16x16x32_bf16 v[0:3], v[246:249], v[230:233], v[0:3]
	s_setprio 0
	s_waitcnt vmcnt(0)
	s_add_u32 s10, s10, 0x80
	s_addc_u32 s11, s11, 0
	s_cmpk_lg_i32 s10, 0x780
	s_mov_b32 s35, s36
	s_waitcnt vmcnt(0)
	s_barrier
	s_cbranch_scc1 .LBB0_88
	ds_read_b128 v[104:107], v122 offset:63488
	ds_read_b128 v[108:111], v122 offset:61440
	ds_read_b128 v[112:115], v122 offset:59392
	ds_read_b128 v[156:159], v122 offset:57344
	ds_read_b128 v[166:169], v123 offset:45056
	ds_read_b128 v[178:181], v123 offset:43008
	ds_read_b128 v[182:185], v123 offset:40960
	ds_read_b128 v[186:189], v123 offset:38912
	ds_read_b128 v[190:193], v123 offset:36864
	s_setprio 1
	s_waitcnt lgkmcnt(0)
	v_mfma_f32_16x16x32_bf16 v[76:79], v[156:159], v[190:193], v[76:79]
	v_mfma_f32_16x16x32_bf16 v[72:75], v[112:115], v[190:193], v[72:75]
	v_mfma_f32_16x16x32_bf16 v[68:71], v[108:111], v[190:193], v[68:71]
	v_mfma_f32_16x16x32_bf16 v[64:67], v[104:107], v[190:193], v[64:67]
	v_mfma_f32_16x16x32_bf16 v[60:63], v[156:159], v[186:189], v[60:63]
	v_mfma_f32_16x16x32_bf16 v[56:59], v[112:115], v[186:189], v[56:59]
	v_mfma_f32_16x16x32_bf16 v[52:55], v[108:111], v[186:189], v[52:55]
	v_mfma_f32_16x16x32_bf16 v[48:51], v[104:107], v[186:189], v[48:51]
	v_mfma_f32_16x16x32_bf16 v[44:47], v[156:159], v[182:185], v[44:47]
	v_mfma_f32_16x16x32_bf16 v[40:43], v[112:115], v[182:185], v[40:43]
	v_mfma_f32_16x16x32_bf16 v[36:39], v[108:111], v[182:185], v[36:39]
	v_mfma_f32_16x16x32_bf16 v[32:35], v[104:107], v[182:185], v[32:35]
	v_mfma_f32_16x16x32_bf16 v[28:31], v[156:159], v[178:181], v[28:31]
	v_mfma_f32_16x16x32_bf16 v[24:27], v[112:115], v[178:181], v[24:27]
	v_mfma_f32_16x16x32_bf16 v[20:23], v[108:111], v[178:181], v[20:23]
	v_mfma_f32_16x16x32_bf16 v[16:19], v[104:107], v[178:181], v[16:19]
	v_mfma_f32_16x16x32_bf16 v[12:15], v[156:159], v[166:169], v[12:15]
	v_mfma_f32_16x16x32_bf16 v[8:11], v[112:115], v[166:169], v[8:11]
	v_mfma_f32_16x16x32_bf16 v[4:7], v[108:111], v[166:169], v[4:7]
	v_mfma_f32_16x16x32_bf16 v[0:3], v[104:107], v[166:169], v[0:3]
	s_setprio 0
	ds_read_b128 v[104:107], v124 offset:36864
	ds_read_b128 v[108:111], v124 offset:38912
	ds_read_b128 v[112:115], v124 offset:40960
	ds_read_b128 v[156:159], v124 offset:43008
	ds_read_b128 v[166:169], v124 offset:45056
	ds_read_b128 v[178:181], v125 offset:57344
	ds_read_b128 v[182:185], v125 offset:59392
	ds_read_b128 v[186:189], v125 offset:61440
	ds_read_b128 v[190:193], v125 offset:63488
	s_setprio 1
	s_waitcnt lgkmcnt(3)
	v_mfma_f32_16x16x32_bf16 v[76:79], v[178:181], v[104:107], v[76:79]
	s_waitcnt lgkmcnt(0)
	v_mfma_f32_16x16x32_bf16 v[64:67], v[190:193], v[104:107], v[64:67]
	v_mfma_f32_16x16x32_bf16 v[60:63], v[178:181], v[108:111], v[60:63]
	v_mfma_f32_16x16x32_bf16 v[56:59], v[182:185], v[108:111], v[56:59]
	v_mfma_f32_16x16x32_bf16 v[52:55], v[186:189], v[108:111], v[52:55]
	v_mfma_f32_16x16x32_bf16 v[48:51], v[190:193], v[108:111], v[48:51]
	v_mfma_f32_16x16x32_bf16 v[44:47], v[178:181], v[112:115], v[44:47]
	v_mfma_f32_16x16x32_bf16 v[40:43], v[182:185], v[112:115], v[40:43]
	v_mfma_f32_16x16x32_bf16 v[36:39], v[186:189], v[112:115], v[36:39]
	v_mfma_f32_16x16x32_bf16 v[32:35], v[190:193], v[112:115], v[32:35]
	v_mfma_f32_16x16x32_bf16 v[28:31], v[178:181], v[156:159], v[28:31]
	v_mfma_f32_16x16x32_bf16 v[24:27], v[182:185], v[156:159], v[24:27]
	v_mfma_f32_16x16x32_bf16 v[20:23], v[186:189], v[156:159], v[20:23]
	v_mfma_f32_16x16x32_bf16 v[16:19], v[190:193], v[156:159], v[16:19]
	v_mfma_f32_16x16x32_bf16 v[12:15], v[178:181], v[166:169], v[12:15]
	v_mfma_f32_16x16x32_bf16 v[8:11], v[182:185], v[166:169], v[8:11]
	v_mfma_f32_16x16x32_bf16 v[4:7], v[186:189], v[166:169], v[4:7]
	v_mfma_f32_16x16x32_bf16 v[0:3], v[190:193], v[166:169], v[0:3]
	v_mfma_f32_16x16x32_bf16 v[194:197], v[182:185], v[104:107], v[72:75]
	v_mfma_f32_16x16x32_bf16 v[198:201], v[186:189], v[104:107], v[68:71]
	s_setprio 0
	s_nop 1
	v_mov_b32_e32 v68, v97
	s_waitcnt vmcnt(0)
	s_barrier
	s_movk_i32 s11, 0x50
	v_add_u32_e32 v68, v68, v176
	v_ashrrev_i32_e32 v69, 7, v68
	v_and_b32_e32 v70, 64, v68
	v_lshrrev_b32_e32 v71, 2, v68
	v_and_or_b32 v68, v68, 15, s12
	s_mov_b32 s10, 0
	v_and_b32_e32 v71, 12, v71
	v_mad_u64_u32 v[68:69], s[36:37], v69, s11, v[68:69]
	v_or3_b32 v104, v70, v71, s13
	v_mov_b64_e32 v[70:71], s[0:1]
	s_movk_i32 s11, 0x3200
	v_ashrrev_i32_e32 v69, 31, v68
	v_mad_i64_i32 v[72:73], s[36:37], v68, s11, v[70:71]
	s_mov_b64 s[38:39], 0x2000
	v_lshl_add_u64 v[112:113], v[72:73], 0, s[38:39]
	v_lshlrev_b64 v[72:73], 12, v[68:69]
	v_ashrrev_i32_e32 v105, 31, v104
	v_lshl_add_u64 v[106:107], s[4:5], 0, v[72:73]
	v_lshlrev_b64 v[72:73], 1, v[104:105]
	v_lshl_add_u64 v[108:109], v[112:113], 0, v[72:73]
	v_lshlrev_b64 v[74:75], 2, v[104:105]
	v_lshl_add_u64 v[106:107], v[106:107], 0, v[74:75]
	global_load_dwordx2 v[114:115], v[108:109], off
	s_waitcnt vmcnt(0)
	v_and_b32_e32 v157, 0xffff0000, v114
	global_load_dwordx4 v[108:111], v[106:107], off
	v_lshlrev_b32_e32 v156, 16, v114
	s_waitcnt vmcnt(0)
	v_pk_fma_f32 v[76:77], v[76:77], v[156:157], v[108:109]
	v_and_b32_e32 v109, 0xffff0000, v115
	v_lshlrev_b32_e32 v108, 16, v115
	v_pk_fma_f32 v[78:79], v[78:79], v[108:109], v[110:111]
	global_store_dwordx4 v[106:107], v[76:79], off
	global_load_dwordx4 v[108:111], v[106:107], off offset:64
	s_nop 0
	v_or_b32_e32 v76, 16, v104
	v_ashrrev_i32_e32 v77, 31, v76
	v_lshlrev_b64 v[76:77], 1, v[76:77]
	v_lshl_add_u64 v[78:79], v[112:113], 0, v[76:77]
	global_load_dwordx2 v[78:79], v[78:79], off
	s_waitcnt vmcnt(0)
	v_and_b32_e32 v115, 0xffff0000, v78
	v_lshlrev_b32_e32 v114, 16, v78
	v_or_b32_e32 v78, 32, v104
	v_pk_fma_f32 v[108:109], v[194:195], v[114:115], v[108:109]
	v_and_b32_e32 v115, 0xffff0000, v79
	v_lshlrev_b32_e32 v114, 16, v79
	v_ashrrev_i32_e32 v79, 31, v78
	v_pk_fma_f32 v[110:111], v[196:197], v[114:115], v[110:111]
	v_lshlrev_b64 v[78:79], 1, v[78:79]
	global_store_dwordx4 v[106:107], v[108:111], off offset:64
	v_or_b32_e32 v104, 48, v104
	v_ashrrev_i32_e32 v105, 31, v104
	v_lshl_add_u64 v[108:109], v[112:113], 0, v[78:79]
	global_load_dwordx2 v[114:115], v[108:109], off
	v_lshlrev_b64 v[104:105], 1, v[104:105]
	global_load_dwordx4 v[108:111], v[106:107], off offset:128
	s_waitcnt vmcnt(1)
	v_and_b32_e32 v157, 0xffff0000, v114
	v_lshlrev_b32_e32 v156, 16, v114
	s_waitcnt vmcnt(0)
	v_pk_fma_f32 v[108:109], v[198:199], v[156:157], v[108:109]
	v_and_b32_e32 v157, 0xffff0000, v115
	v_lshlrev_b32_e32 v156, 16, v115
	v_pk_fma_f32 v[110:111], v[200:201], v[156:157], v[110:111]
	global_store_dwordx4 v[106:107], v[108:111], off offset:128
	s_nop 1
	v_lshl_add_u64 v[108:109], v[112:113], 0, v[104:105]
	global_load_dwordx2 v[112:113], v[108:109], off
	s_waitcnt vmcnt(0)
	v_and_b32_e32 v115, 0xffff0000, v112
	global_load_dwordx4 v[108:111], v[106:107], off offset:192
	v_lshlrev_b32_e32 v114, 16, v112
	s_waitcnt vmcnt(0)
	v_pk_fma_f32 v[64:65], v[64:65], v[114:115], v[108:109]
	v_and_b32_e32 v109, 0xffff0000, v113
	v_lshlrev_b32_e32 v108, 16, v113
	v_pk_fma_f32 v[66:67], v[66:67], v[108:109], v[110:111]
	global_store_dwordx4 v[106:107], v[64:67], off offset:192
	s_nop 1
	v_add_u32_e32 v64, 16, v68
	v_ashrrev_i32_e32 v65, 31, v64
	v_mad_i64_i32 v[66:67], s[36:37], v64, s11, v[70:71]
	v_lshl_add_u64 v[66:67], v[66:67], 0, s[38:39]
	v_lshlrev_b64 v[64:65], 12, v[64:65]
	v_lshl_add_u64 v[64:65], s[4:5], 0, v[64:65]
	v_lshl_add_u64 v[106:107], v[66:67], 0, v[72:73]
	v_lshl_add_u64 v[64:65], v[64:65], 0, v[74:75]
	global_load_dwordx2 v[110:111], v[106:107], off
	s_waitcnt vmcnt(0)
	v_and_b32_e32 v113, 0xffff0000, v110
	global_load_dwordx4 v[106:109], v[64:65], off
	v_lshlrev_b32_e32 v112, 16, v110
	s_waitcnt vmcnt(0)
	v_pk_fma_f32 v[60:61], v[60:61], v[112:113], v[106:107]
	v_and_b32_e32 v107, 0xffff0000, v111
	v_lshlrev_b32_e32 v106, 16, v111
	v_pk_fma_f32 v[62:63], v[62:63], v[106:107], v[108:109]
	global_store_dwordx4 v[64:65], v[60:63], off
	s_nop 1
	v_lshl_add_u64 v[60:61], v[66:67], 0, v[76:77]
	global_load_dwordx2 v[106:107], v[60:61], off
	s_waitcnt vmcnt(0)
	v_and_b32_e32 v109, 0xffff0000, v106
	global_load_dwordx4 v[60:63], v[64:65], off offset:64
	v_lshlrev_b32_e32 v108, 16, v106
	s_waitcnt vmcnt(0)
	v_pk_fma_f32 v[56:57], v[56:57], v[108:109], v[60:61]
	v_and_b32_e32 v61, 0xffff0000, v107
	v_lshlrev_b32_e32 v60, 16, v107
	v_pk_fma_f32 v[58:59], v[58:59], v[60:61], v[62:63]
	global_store_dwordx4 v[64:65], v[56:59], off offset:64
	s_nop 1
	v_lshl_add_u64 v[56:57], v[66:67], 0, v[78:79]
	global_load_dwordx2 v[60:61], v[56:57], off
	s_waitcnt vmcnt(0)
	v_and_b32_e32 v63, 0xffff0000, v60
	global_load_dwordx4 v[56:59], v[64:65], off offset:128
	v_lshlrev_b32_e32 v62, 16, v60
	s_waitcnt vmcnt(0)
	v_pk_fma_f32 v[52:53], v[52:53], v[62:63], v[56:57]
	v_and_b32_e32 v57, 0xffff0000, v61
	v_lshlrev_b32_e32 v56, 16, v61
	v_pk_fma_f32 v[54:55], v[54:55], v[56:57], v[58:59]
	global_store_dwordx4 v[64:65], v[52:55], off offset:128
	s_nop 1
	v_lshl_add_u64 v[52:53], v[66:67], 0, v[104:105]
	global_load_dwordx2 v[56:57], v[52:53], off
	s_waitcnt vmcnt(0)
	v_and_b32_e32 v59, 0xffff0000, v56
	global_load_dwordx4 v[52:55], v[64:65], off offset:192
	v_lshlrev_b32_e32 v58, 16, v56
	s_waitcnt vmcnt(0)
	v_pk_fma_f32 v[48:49], v[48:49], v[58:59], v[52:53]
	v_and_b32_e32 v53, 0xffff0000, v57
	v_lshlrev_b32_e32 v52, 16, v57
	v_pk_fma_f32 v[50:51], v[50:51], v[52:53], v[54:55]
	global_store_dwordx4 v[64:65], v[48:51], off offset:192
	s_nop 1
	v_add_u32_e32 v48, 32, v68
	v_ashrrev_i32_e32 v49, 31, v48
	v_mad_i64_i32 v[50:51], s[36:37], v48, s11, v[70:71]
	v_lshl_add_u64 v[54:55], v[50:51], 0, s[38:39]
	v_lshlrev_b64 v[48:49], 12, v[48:49]
	v_lshl_add_u64 v[48:49], s[4:5], 0, v[48:49]
	v_lshl_add_u64 v[50:51], v[54:55], 0, v[72:73]
	v_lshl_add_u64 v[48:49], v[48:49], 0, v[74:75]
	global_load_dwordx2 v[56:57], v[50:51], off
	s_waitcnt vmcnt(0)
	v_and_b32_e32 v59, 0xffff0000, v56
	global_load_dwordx4 v[50:53], v[48:49], off
	v_lshlrev_b32_e32 v58, 16, v56
	s_waitcnt vmcnt(0)
	v_pk_fma_f32 v[44:45], v[44:45], v[58:59], v[50:51]
	v_and_b32_e32 v51, 0xffff0000, v57
	v_lshlrev_b32_e32 v50, 16, v57
	v_pk_fma_f32 v[46:47], v[46:47], v[50:51], v[52:53]
	global_store_dwordx4 v[48:49], v[44:47], off
	s_nop 1
	v_lshl_add_u64 v[44:45], v[54:55], 0, v[76:77]
	global_load_dwordx2 v[50:51], v[44:45], off
	s_waitcnt vmcnt(0)
	v_and_b32_e32 v53, 0xffff0000, v50
	global_load_dwordx4 v[44:47], v[48:49], off offset:64
	v_lshlrev_b32_e32 v52, 16, v50
	s_waitcnt vmcnt(0)
	v_pk_fma_f32 v[40:41], v[40:41], v[52:53], v[44:45]
	v_and_b32_e32 v45, 0xffff0000, v51
	v_lshlrev_b32_e32 v44, 16, v51
	v_pk_fma_f32 v[42:43], v[42:43], v[44:45], v[46:47]
	global_store_dwordx4 v[48:49], v[40:43], off offset:64
	s_nop 1
	v_lshl_add_u64 v[40:41], v[54:55], 0, v[78:79]
	global_load_dwordx2 v[44:45], v[40:41], off
	s_waitcnt vmcnt(0)
	v_and_b32_e32 v47, 0xffff0000, v44
	global_load_dwordx4 v[40:43], v[48:49], off offset:128
	v_lshlrev_b32_e32 v46, 16, v44
	s_waitcnt vmcnt(0)
	v_pk_fma_f32 v[36:37], v[36:37], v[46:47], v[40:41]
	v_and_b32_e32 v41, 0xffff0000, v45
	v_lshlrev_b32_e32 v40, 16, v45
	v_pk_fma_f32 v[38:39], v[38:39], v[40:41], v[42:43]
	global_store_dwordx4 v[48:49], v[36:39], off offset:128
	s_nop 1
	v_lshl_add_u64 v[36:37], v[54:55], 0, v[104:105]
	global_load_dwordx2 v[40:41], v[36:37], off
	s_waitcnt vmcnt(0)
	v_and_b32_e32 v43, 0xffff0000, v40
	global_load_dwordx4 v[36:39], v[48:49], off offset:192
	v_lshlrev_b32_e32 v42, 16, v40
	s_waitcnt vmcnt(0)
	v_pk_fma_f32 v[32:33], v[32:33], v[42:43], v[36:37]
	v_and_b32_e32 v37, 0xffff0000, v41
	v_lshlrev_b32_e32 v36, 16, v41
	v_pk_fma_f32 v[34:35], v[34:35], v[36:37], v[38:39]
	global_store_dwordx4 v[48:49], v[32:35], off offset:192
	s_nop 1
	v_add_u32_e32 v32, 48, v68
	v_ashrrev_i32_e32 v33, 31, v32
	v_mad_i64_i32 v[34:35], s[36:37], v32, s11, v[70:71]
	v_lshl_add_u64 v[38:39], v[34:35], 0, s[38:39]
	v_lshlrev_b64 v[32:33], 12, v[32:33]
	v_lshl_add_u64 v[32:33], s[4:5], 0, v[32:33]
	v_lshl_add_u64 v[34:35], v[38:39], 0, v[72:73]
	v_lshl_add_u64 v[32:33], v[32:33], 0, v[74:75]
	global_load_dwordx2 v[40:41], v[34:35], off
	s_waitcnt vmcnt(0)
	v_and_b32_e32 v43, 0xffff0000, v40
	global_load_dwordx4 v[34:37], v[32:33], off
	v_lshlrev_b32_e32 v42, 16, v40
	s_waitcnt vmcnt(0)
	v_pk_fma_f32 v[28:29], v[28:29], v[42:43], v[34:35]
	v_and_b32_e32 v35, 0xffff0000, v41
	v_lshlrev_b32_e32 v34, 16, v41
	v_pk_fma_f32 v[30:31], v[30:31], v[34:35], v[36:37]
	global_store_dwordx4 v[32:33], v[28:31], off
	s_nop 1
	v_lshl_add_u64 v[28:29], v[38:39], 0, v[76:77]
	global_load_dwordx2 v[34:35], v[28:29], off
	s_waitcnt vmcnt(0)
	v_and_b32_e32 v37, 0xffff0000, v34
	global_load_dwordx4 v[28:31], v[32:33], off offset:64
	v_lshlrev_b32_e32 v36, 16, v34
	s_waitcnt vmcnt(0)
	v_pk_fma_f32 v[24:25], v[24:25], v[36:37], v[28:29]
	v_and_b32_e32 v29, 0xffff0000, v35
	v_lshlrev_b32_e32 v28, 16, v35
	v_pk_fma_f32 v[26:27], v[26:27], v[28:29], v[30:31]
	global_store_dwordx4 v[32:33], v[24:27], off offset:64
	s_nop 1
	v_lshl_add_u64 v[24:25], v[38:39], 0, v[78:79]
	global_load_dwordx2 v[28:29], v[24:25], off
	s_waitcnt vmcnt(0)
	v_and_b32_e32 v31, 0xffff0000, v28
	global_load_dwordx4 v[24:27], v[32:33], off offset:128
	v_lshlrev_b32_e32 v30, 16, v28
	s_waitcnt vmcnt(0)
	v_pk_fma_f32 v[20:21], v[20:21], v[30:31], v[24:25]
	v_and_b32_e32 v25, 0xffff0000, v29
	v_lshlrev_b32_e32 v24, 16, v29
	v_pk_fma_f32 v[22:23], v[22:23], v[24:25], v[26:27]
	global_store_dwordx4 v[32:33], v[20:23], off offset:128
	s_nop 1
	v_lshl_add_u64 v[20:21], v[38:39], 0, v[104:105]
	global_load_dwordx2 v[24:25], v[20:21], off
	s_waitcnt vmcnt(0)
	v_and_b32_e32 v27, 0xffff0000, v24
	global_load_dwordx4 v[20:23], v[32:33], off offset:192
	v_lshlrev_b32_e32 v26, 16, v24
	s_waitcnt vmcnt(0)
	v_pk_fma_f32 v[16:17], v[16:17], v[26:27], v[20:21]
	v_and_b32_e32 v21, 0xffff0000, v25
	v_lshlrev_b32_e32 v20, 16, v25
	v_pk_fma_f32 v[18:19], v[18:19], v[20:21], v[22:23]
	global_store_dwordx4 v[32:33], v[16:19], off offset:192
	s_nop 1
	v_add_u32_e32 v16, 64, v68
	v_ashrrev_i32_e32 v17, 31, v16
	v_mad_i64_i32 v[18:19], s[36:37], v16, s11, v[70:71]
	v_lshl_add_u64 v[20:21], v[18:19], 0, s[38:39]
	v_lshlrev_b64 v[16:17], 12, v[16:17]
	v_lshl_add_u64 v[16:17], s[4:5], 0, v[16:17]
	v_lshl_add_u64 v[18:19], v[20:21], 0, v[72:73]
	v_lshl_add_u64 v[22:23], v[16:17], 0, v[74:75]
	global_load_dwordx2 v[24:25], v[18:19], off
	s_mov_b64 s[36:37], 0x1000
	global_load_dwordx4 v[16:19], v[22:23], off
	v_readfirstlane_b32 s11, v81
	s_mov_b32 m0, s11
	v_readfirstlane_b32 s11, v133
	s_waitcnt vmcnt(1)
	v_and_b32_e32 v27, 0xffff0000, v24
	v_lshlrev_b32_e32 v26, 16, v24
	s_waitcnt vmcnt(0)
	v_pk_fma_f32 v[12:13], v[12:13], v[26:27], v[16:17]
	v_and_b32_e32 v17, 0xffff0000, v25
	v_lshlrev_b32_e32 v16, 16, v25
	v_pk_fma_f32 v[14:15], v[14:15], v[16:17], v[18:19]
	global_store_dwordx4 v[22:23], v[12:15], off
	s_nop 1
	v_lshl_add_u64 v[12:13], v[20:21], 0, v[76:77]
	global_load_dwordx2 v[16:17], v[12:13], off
	s_waitcnt vmcnt(0)
	v_and_b32_e32 v19, 0xffff0000, v16
	global_load_dwordx4 v[12:15], v[22:23], off offset:64
	v_lshlrev_b32_e32 v18, 16, v16
	s_waitcnt vmcnt(0)
	v_pk_fma_f32 v[8:9], v[8:9], v[18:19], v[12:13]
	v_and_b32_e32 v13, 0xffff0000, v17
	v_lshlrev_b32_e32 v12, 16, v17
	v_pk_fma_f32 v[10:11], v[10:11], v[12:13], v[14:15]
	global_store_dwordx4 v[22:23], v[8:11], off offset:64
	s_nop 1
	v_lshl_add_u64 v[8:9], v[20:21], 0, v[78:79]
	global_load_dwordx2 v[12:13], v[8:9], off
	s_waitcnt vmcnt(0)
	v_and_b32_e32 v15, 0xffff0000, v12
	global_load_dwordx4 v[8:11], v[22:23], off offset:128
	v_lshlrev_b32_e32 v14, 16, v12
	s_waitcnt vmcnt(0)
	v_pk_fma_f32 v[4:5], v[4:5], v[14:15], v[8:9]
	v_and_b32_e32 v9, 0xffff0000, v13
	v_lshlrev_b32_e32 v8, 16, v13
	v_pk_fma_f32 v[6:7], v[6:7], v[8:9], v[10:11]
	global_store_dwordx4 v[22:23], v[4:7], off offset:128
	s_nop 1
	v_lshl_add_u64 v[4:5], v[20:21], 0, v[104:105]
	global_load_dwordx2 v[8:9], v[4:5], off
	s_waitcnt vmcnt(0)
	v_and_b32_e32 v11, 0xffff0000, v8
	global_load_dwordx4 v[4:7], v[22:23], off offset:192
	v_lshlrev_b32_e32 v10, 16, v8
	s_waitcnt vmcnt(0)
	v_pk_fma_f32 v[0:1], v[0:1], v[10:11], v[4:5]
	v_and_b32_e32 v5, 0xffff0000, v9
	v_lshlrev_b32_e32 v4, 16, v9
	v_pk_fma_f32 v[2:3], v[2:3], v[4:5], v[6:7]
	global_store_dwordx4 v[22:23], v[0:3], off offset:192
	s_nop 1
	v_lshl_add_u64 v[0:1], v[102:103], 0, v[96:97]
	v_lshl_add_u64 v[2:3], v[0:1], 0, s[36:37]
	s_mov_b64 s[36:37], 0x65000
	global_load_lds_dwordx4 v[2:3], off
	v_lshl_add_u64 v[2:3], v[0:1], 0, s[36:37]
	s_mov_b32 m0, s11
	s_mov_b64 s[36:37], 0xc9000
	v_readfirstlane_b32 s11, v132
	global_load_lds_dwordx4 v[2:3], off
	v_lshl_add_u64 v[2:3], v[0:1], 0, s[36:37]
	s_mov_b32 m0, s11
	s_mov_b64 s[36:37], 0x12d000
	v_readfirstlane_b32 s11, v131
	global_load_lds_dwordx4 v[2:3], off
	v_lshl_add_u64 v[2:3], v[0:1], 0, s[36:37]
	s_mov_b32 m0, s11
	s_mov_b64 s[36:37], 0x191000
	v_readfirstlane_b32 s11, v130
	global_load_lds_dwordx4 v[2:3], off
	v_lshl_add_u64 v[0:1], v[0:1], 0, s[36:37]
	s_mov_b32 m0, s11
	s_nop 0
	global_load_lds_dwordx4 v[0:1], off
	v_lshl_add_u64 v[0:1], v[88:89], 0, s[8:9]
	v_readfirstlane_b32 s8, v129
	s_mov_b32 m0, s8
	v_readfirstlane_b32 s8, v128
	global_load_lds_dwordx4 v[0:1], off
	v_lshl_add_u64 v[2:3], v[0:1], 0, s[40:41]
	s_mov_b32 m0, s8
	s_mov_b64 s[8:9], 0x20000
	global_load_lds_dwordx4 v[2:3], off
	v_lshl_add_u64 v[2:3], v[0:1], 0, s[8:9]
	v_readfirstlane_b32 s8, v127
	s_mov_b32 m0, s8
	s_mov_b64 s[8:9], 0x30000
	v_lshl_add_u64 v[0:1], v[0:1], 0, s[8:9]
	v_readfirstlane_b32 s8, v126
	global_load_lds_dwordx4 v[2:3], off
	s_mov_b32 m0, s8
	s_mov_b64 s[8:9], 0
	global_load_lds_dwordx4 v[0:1], off
	s_waitcnt vmcnt(0)
	v_mov_b32_e32 v0, 0
	v_mov_b32_e32 v1, v0
	v_mov_b32_e32 v2, v0
	v_mov_b32_e32 v3, v0
	v_mov_b32_e32 v4, v0
	v_mov_b32_e32 v5, v0
	v_mov_b32_e32 v6, v0
	v_mov_b32_e32 v7, v0
	v_mov_b32_e32 v8, v0
	v_mov_b32_e32 v9, v0
	v_mov_b32_e32 v10, v0
	v_mov_b32_e32 v11, v0
	v_mov_b32_e32 v12, v0
	v_mov_b32_e32 v13, v0
	v_mov_b32_e32 v14, v0
	v_mov_b32_e32 v15, v0
	v_mov_b32_e32 v16, v0
	v_mov_b32_e32 v17, v0
	v_mov_b32_e32 v18, v0
	v_mov_b32_e32 v19, v0
	v_mov_b32_e32 v20, v0
	v_mov_b32_e32 v21, v0
	v_mov_b32_e32 v22, v0
	v_mov_b32_e32 v23, v0
	v_mov_b32_e32 v24, v0
	v_mov_b32_e32 v25, v0
	v_mov_b32_e32 v26, v0
	v_mov_b32_e32 v27, v0
	v_mov_b32_e32 v28, v0
	v_mov_b32_e32 v29, v0
	v_mov_b32_e32 v30, v0
	v_mov_b32_e32 v31, v0
	v_mov_b32_e32 v32, v0
	v_mov_b32_e32 v33, v0
	v_mov_b32_e32 v34, v0
	v_mov_b32_e32 v35, v0
	v_mov_b32_e32 v36, v0
	v_mov_b32_e32 v37, v0
	v_mov_b32_e32 v38, v0
	v_mov_b32_e32 v39, v0
	v_mov_b32_e32 v40, v0
	v_mov_b32_e32 v41, v0
	v_mov_b32_e32 v42, v0
	v_mov_b32_e32 v43, v0
	v_mov_b32_e32 v44, v0
	v_mov_b32_e32 v45, v0
	v_mov_b32_e32 v46, v0
	v_mov_b32_e32 v47, v0
	v_mov_b32_e32 v48, v0
	v_mov_b32_e32 v49, v0
	v_mov_b32_e32 v50, v0
	v_mov_b32_e32 v51, v0
	v_mov_b32_e32 v52, v0
	v_mov_b32_e32 v53, v0
	v_mov_b32_e32 v54, v0
	v_mov_b32_e32 v55, v0
	v_mov_b32_e32 v56, v0
	v_mov_b32_e32 v57, v0
	v_mov_b32_e32 v58, v0
	v_mov_b32_e32 v59, v0
	v_mov_b32_e32 v60, v0
	v_mov_b32_e32 v61, v0
	v_mov_b32_e32 v62, v0
	v_mov_b32_e32 v63, v0
	v_mov_b32_e32 v64, v0
	v_mov_b32_e32 v65, v0
	v_mov_b32_e32 v66, v0
	v_mov_b32_e32 v67, v0
	v_mov_b32_e32 v68, v0
	v_mov_b32_e32 v69, v0
	v_mov_b32_e32 v70, v0
	v_mov_b32_e32 v71, v0
	v_mov_b32_e32 v72, v0
	v_mov_b32_e32 v73, v0
	v_mov_b32_e32 v74, v0
	v_mov_b32_e32 v75, v0
	v_mov_b32_e32 v76, v0
	v_mov_b32_e32 v77, v0
	v_mov_b32_e32 v78, v0
	v_mov_b32_e32 v79, v0
	s_waitcnt vmcnt(0) lgkmcnt(0)
	s_barrier
.LBB0_90:
	s_add_i32 s11, s10, 1
	s_bitcmp1_b32 s11, 0
	s_cselect_b32 s35, 0x9000, 0
	v_add_u32_e32 v96, s35, v81
	v_lshl_add_u64 v[102:103], v[94:95], 0, s[8:9]
	s_mov_b64 s[36:37], 0x6182080
	v_readfirstlane_b32 s35, v96
	v_add_u32_e32 v106, 0x1000, v96
	v_lshl_add_u64 v[104:105], v[102:103], 0, s[36:37]
	s_mov_b32 m0, s35
	s_mov_b64 s[36:37], 0x61e6080
	v_readfirstlane_b32 s35, v106
	v_add_u32_e32 v106, 0x2000, v96
	global_load_lds_dwordx4 v[104:105], off
	v_lshl_add_u64 v[104:105], v[102:103], 0, s[36:37]
	s_mov_b32 m0, s35
	s_mov_b64 s[36:37], 0x624a080
	v_readfirstlane_b32 s35, v106
	v_add_u32_e32 v106, 0x3000, v96
	global_load_lds_dwordx4 v[104:105], off
	v_lshl_add_u64 v[104:105], v[102:103], 0, s[36:37]
	s_mov_b32 m0, s35
	s_mov_b64 s[36:37], 0x62ae080
	v_readfirstlane_b32 s35, v106
	global_load_lds_dwordx4 v[104:105], off
	v_lshl_add_u64 v[104:105], v[102:103], 0, s[36:37]
	s_mov_b32 m0, s35
	s_mov_b64 s[36:37], 0x6312080
	global_load_lds_dwordx4 v[104:105], off
	v_add_u32_e32 v104, 0x4000, v96
	v_lshl_add_u64 v[102:103], v[102:103], 0, s[36:37]
	v_readfirstlane_b32 s35, v104
	s_mov_b32 m0, s35
	v_add_u32_e32 v106, 0x5000, v96
	global_load_lds_dwordx4 v[102:103], off
	v_lshl_add_u64 v[102:103], v[100:101], 0, s[8:9]
	s_mov_b64 s[36:37], 0x14931080
	v_readfirstlane_b32 s35, v106
	v_add_u32_e32 v106, 0x6000, v96
	v_lshl_add_u64 v[104:105], v[102:103], 0, s[36:37]
	s_mov_b32 m0, s35
	s_mov_b64 s[36:37], 0x14941080
	v_readfirstlane_b32 s35, v106
	v_add_u32_e32 v106, 0x7000, v96
	global_load_lds_dwordx4 v[104:105], off
	v_lshl_add_u64 v[104:105], v[102:103], 0, s[36:37]
	s_mov_b32 m0, s35
	s_mov_b64 s[36:37], 0x14951080
	v_readfirstlane_b32 s35, v106
	v_add_u32_e32 v96, 0x8000, v96
	global_load_lds_dwordx4 v[104:105], off
	v_lshl_add_u64 v[104:105], v[102:103], 0, s[36:37]
	s_mov_b32 m0, s35
	s_mov_b64 s[36:37], 0x14961080
	v_readfirstlane_b32 s35, v96
	global_load_lds_dwordx4 v[104:105], off
	v_lshl_add_u64 v[102:103], v[102:103], 0, s[36:37]
	s_mov_b32 m0, s35
	s_bitcmp1_b32 s10, 0
	global_load_lds_dwordx4 v[102:103], off
	s_cselect_b32 s10, 0x9000, 0
	s_add_i32 s10, s10, 0
	v_add_u32_e32 v96, s10, v116
	v_add_u32_e32 v114, v96, v117
	ds_read_b128 v[102:105], v114
	ds_read_b128 v[106:109], v114 offset:2048
	ds_read_b128 v[110:113], v114 offset:4096
	ds_read_b128 v[126:129], v114 offset:6144
	v_add_u32_e32 v96, v96, v118
	ds_read_b128 v[130:133], v114 offset:8192
	ds_read_b128 v[156:159], v96 offset:20480
	ds_read_b128 v[166:169], v96 offset:22528
	ds_read_b128 v[178:181], v96 offset:24576
	ds_read_b128 v[182:185], v96 offset:26624
	v_add_u32_e32 v210, s10, v119
	v_add_u32_e32 v211, v210, v117
	ds_read_b128 v[212:215], v211
	ds_read_b128 v[216:219], v211 offset:2048
	ds_read_b128 v[220:223], v211 offset:4096
	ds_read_b128 v[224:227], v211 offset:6144
	v_add_u32_e32 v228, v210, v118
	ds_read_b128 v[230:233], v211 offset:8192
	ds_read_b128 v[234:237], v228 offset:20480
	ds_read_b128 v[238:241], v228 offset:22528
	ds_read_b128 v[242:245], v228 offset:24576
	ds_read_b128 v[246:249], v228 offset:26624
	s_setprio 1
	s_waitcnt lgkmcnt(9)
	v_mfma_f32_16x16x32_bf16 v[76:79], v[156:159], v[102:105], v[76:79]
	v_mfma_f32_16x16x32_bf16 v[72:75], v[166:169], v[102:105], v[72:75]
	v_mfma_f32_16x16x32_bf16 v[68:71], v[178:181], v[102:105], v[68:71]
	v_mfma_f32_16x16x32_bf16 v[64:67], v[182:185], v[102:105], v[64:67]
	v_mfma_f32_16x16x32_bf16 v[60:63], v[156:159], v[106:109], v[60:63]
	v_mfma_f32_16x16x32_bf16 v[56:59], v[166:169], v[106:109], v[56:59]
	v_mfma_f32_16x16x32_bf16 v[52:55], v[178:181], v[106:109], v[52:55]
	v_mfma_f32_16x16x32_bf16 v[48:51], v[182:185], v[106:109], v[48:51]
	v_mfma_f32_16x16x32_bf16 v[44:47], v[156:159], v[110:113], v[44:47]
	v_mfma_f32_16x16x32_bf16 v[40:43], v[166:169], v[110:113], v[40:43]
	v_mfma_f32_16x16x32_bf16 v[36:39], v[178:181], v[110:113], v[36:39]
	v_mfma_f32_16x16x32_bf16 v[32:35], v[182:185], v[110:113], v[32:35]
	v_mfma_f32_16x16x32_bf16 v[28:31], v[156:159], v[126:129], v[28:31]
	v_mfma_f32_16x16x32_bf16 v[24:27], v[166:169], v[126:129], v[24:27]
	v_mfma_f32_16x16x32_bf16 v[20:23], v[178:181], v[126:129], v[20:23]
	v_mfma_f32_16x16x32_bf16 v[16:19], v[182:185], v[126:129], v[16:19]
	v_mfma_f32_16x16x32_bf16 v[12:15], v[156:159], v[130:133], v[12:15]
	v_mfma_f32_16x16x32_bf16 v[8:11], v[166:169], v[130:133], v[8:11]
	v_mfma_f32_16x16x32_bf16 v[4:7], v[178:181], v[130:133], v[4:7]
	v_mfma_f32_16x16x32_bf16 v[0:3], v[182:185], v[130:133], v[0:3]
	s_setprio 0
	s_setprio 1
	s_waitcnt lgkmcnt(0)
	v_mfma_f32_16x16x32_bf16 v[76:79], v[234:237], v[212:215], v[76:79]
	v_mfma_f32_16x16x32_bf16 v[72:75], v[238:241], v[212:215], v[72:75]
	v_mfma_f32_16x16x32_bf16 v[68:71], v[242:245], v[212:215], v[68:71]
	v_mfma_f32_16x16x32_bf16 v[64:67], v[246:249], v[212:215], v[64:67]
	v_mfma_f32_16x16x32_bf16 v[60:63], v[234:237], v[216:219], v[60:63]
	v_mfma_f32_16x16x32_bf16 v[56:59], v[238:241], v[216:219], v[56:59]
	v_mfma_f32_16x16x32_bf16 v[52:55], v[242:245], v[216:219], v[52:55]
	v_mfma_f32_16x16x32_bf16 v[48:51], v[246:249], v[216:219], v[48:51]
	v_mfma_f32_16x16x32_bf16 v[44:47], v[234:237], v[220:223], v[44:47]
	v_mfma_f32_16x16x32_bf16 v[40:43], v[238:241], v[220:223], v[40:43]
	v_mfma_f32_16x16x32_bf16 v[36:39], v[242:245], v[220:223], v[36:39]
	v_mfma_f32_16x16x32_bf16 v[32:35], v[246:249], v[220:223], v[32:35]
	v_mfma_f32_16x16x32_bf16 v[28:31], v[234:237], v[224:227], v[28:31]
	v_mfma_f32_16x16x32_bf16 v[24:27], v[238:241], v[224:227], v[24:27]
	v_mfma_f32_16x16x32_bf16 v[20:23], v[242:245], v[224:227], v[20:23]
	v_mfma_f32_16x16x32_bf16 v[16:19], v[246:249], v[224:227], v[16:19]
	v_mfma_f32_16x16x32_bf16 v[12:15], v[234:237], v[230:233], v[12:15]
	v_mfma_f32_16x16x32_bf16 v[8:11], v[238:241], v[230:233], v[8:11]
	v_mfma_f32_16x16x32_bf16 v[4:7], v[242:245], v[230:233], v[4:7]
	v_mfma_f32_16x16x32_bf16 v[0:3], v[246:249], v[230:233], v[0:3]
	s_setprio 0
	s_waitcnt vmcnt(0)
	s_add_u32 s8, s8, 0x80
	s_addc_u32 s9, s9, 0
	s_cmpk_lg_i32 s8, 0x780
	s_mov_b32 s10, s11
	s_waitcnt vmcnt(0)
	s_barrier
	s_cbranch_scc1 .LBB0_90
	ds_read_b128 v[100:103], v122 offset:63488
	ds_read_b128 v[104:107], v122 offset:61440
	ds_read_b128 v[108:111], v122 offset:59392
	ds_read_b128 v[112:115], v122 offset:57344
	ds_read_b128 v[126:129], v123 offset:45056
	ds_read_b128 v[130:133], v123 offset:43008
	ds_read_b128 v[156:159], v123 offset:40960
	ds_read_b128 v[166:169], v123 offset:38912
	ds_read_b128 v[178:181], v123 offset:36864
	s_setprio 1
	s_waitcnt lgkmcnt(0)
	v_mfma_f32_16x16x32_bf16 v[76:79], v[112:115], v[178:181], v[76:79]
	v_mfma_f32_16x16x32_bf16 v[72:75], v[108:111], v[178:181], v[72:75]
	v_mfma_f32_16x16x32_bf16 v[68:71], v[104:107], v[178:181], v[68:71]
	v_mfma_f32_16x16x32_bf16 v[64:67], v[100:103], v[178:181], v[64:67]
	v_mfma_f32_16x16x32_bf16 v[60:63], v[112:115], v[166:169], v[60:63]
	v_mfma_f32_16x16x32_bf16 v[56:59], v[108:111], v[166:169], v[56:59]
	v_mfma_f32_16x16x32_bf16 v[52:55], v[104:107], v[166:169], v[52:55]
	v_mfma_f32_16x16x32_bf16 v[48:51], v[100:103], v[166:169], v[48:51]
	v_mfma_f32_16x16x32_bf16 v[44:47], v[112:115], v[156:159], v[44:47]
	v_mfma_f32_16x16x32_bf16 v[40:43], v[108:111], v[156:159], v[40:43]
	v_mfma_f32_16x16x32_bf16 v[36:39], v[104:107], v[156:159], v[36:39]
	v_mfma_f32_16x16x32_bf16 v[32:35], v[100:103], v[156:159], v[32:35]
	v_mfma_f32_16x16x32_bf16 v[28:31], v[112:115], v[130:133], v[28:31]
	v_mfma_f32_16x16x32_bf16 v[24:27], v[108:111], v[130:133], v[24:27]
	v_mfma_f32_16x16x32_bf16 v[20:23], v[104:107], v[130:133], v[20:23]
	v_mfma_f32_16x16x32_bf16 v[16:19], v[100:103], v[130:133], v[16:19]
	v_mfma_f32_16x16x32_bf16 v[12:15], v[112:115], v[126:129], v[12:15]
	v_mfma_f32_16x16x32_bf16 v[8:11], v[108:111], v[126:129], v[8:11]
	v_mfma_f32_16x16x32_bf16 v[4:7], v[104:107], v[126:129], v[4:7]
	v_mfma_f32_16x16x32_bf16 v[0:3], v[100:103], v[126:129], v[0:3]
	s_setprio 0
	ds_read_b128 v[100:103], v124 offset:36864
	ds_read_b128 v[104:107], v124 offset:38912
	ds_read_b128 v[108:111], v124 offset:40960
	ds_read_b128 v[112:115], v124 offset:43008
	ds_read_b128 v[126:129], v124 offset:45056
	ds_read_b128 v[130:133], v125 offset:57344
	ds_read_b128 v[156:159], v125 offset:59392
	ds_read_b128 v[166:169], v125 offset:61440
	ds_read_b128 v[122:125], v125 offset:63488
	s_setprio 1
	s_waitcnt lgkmcnt(3)
	v_mfma_f32_16x16x32_bf16 v[178:181], v[130:133], v[100:103], v[76:79]
	s_waitcnt lgkmcnt(2)
	v_mfma_f32_16x16x32_bf16 v[72:75], v[156:159], v[100:103], v[72:75]
	s_waitcnt lgkmcnt(1)
	v_mfma_f32_16x16x32_bf16 v[68:71], v[166:169], v[100:103], v[68:71]
	s_waitcnt lgkmcnt(0)
	v_mfma_f32_16x16x32_bf16 v[64:67], v[122:125], v[100:103], v[64:67]
	v_mfma_f32_16x16x32_bf16 v[60:63], v[130:133], v[104:107], v[60:63]
	v_mfma_f32_16x16x32_bf16 v[56:59], v[156:159], v[104:107], v[56:59]
	v_mfma_f32_16x16x32_bf16 v[52:55], v[166:169], v[104:107], v[52:55]
	v_mfma_f32_16x16x32_bf16 v[48:51], v[122:125], v[104:107], v[48:51]
	v_mfma_f32_16x16x32_bf16 v[44:47], v[130:133], v[108:111], v[44:47]
	v_mfma_f32_16x16x32_bf16 v[40:43], v[156:159], v[108:111], v[40:43]
	v_mfma_f32_16x16x32_bf16 v[36:39], v[166:169], v[108:111], v[36:39]
	v_mfma_f32_16x16x32_bf16 v[32:35], v[122:125], v[108:111], v[32:35]
	v_mfma_f32_16x16x32_bf16 v[28:31], v[130:133], v[112:115], v[28:31]
	v_mfma_f32_16x16x32_bf16 v[24:27], v[156:159], v[112:115], v[24:27]
	v_mfma_f32_16x16x32_bf16 v[20:23], v[166:169], v[112:115], v[20:23]
	v_mfma_f32_16x16x32_bf16 v[16:19], v[122:125], v[112:115], v[16:19]
	v_mfma_f32_16x16x32_bf16 v[12:15], v[130:133], v[126:129], v[12:15]
	v_mfma_f32_16x16x32_bf16 v[8:11], v[156:159], v[126:129], v[8:11]
	v_mfma_f32_16x16x32_bf16 v[4:7], v[166:169], v[126:129], v[4:7]
	v_mfma_f32_16x16x32_bf16 v[0:3], v[122:125], v[126:129], v[0:3]
	s_setprio 0
	v_mov_b32_e32 v76, v97
	s_waitcnt vmcnt(0)
	s_barrier
	s_mov_b32 s35, 0
	v_add_u32_e32 v76, v76, v176
	v_lshrrev_b32_e32 v78, 2, v76
	v_ashrrev_i32_e32 v77, 7, v76
	v_and_b32_e32 v94, 64, v76
	v_and_b32_e32 v95, 12, v78
	v_and_or_b32 v76, v76, 15, s12
	s_movk_i32 s8, 0x50
	v_mad_u64_u32 v[78:79], s[8:9], v77, s8, v[76:77]
	v_or3_b32 v108, v94, v95, s13
	v_mov_b64_e32 v[94:95], s[0:1]
	s_movk_i32 s10, 0x3200
	v_ashrrev_i32_e32 v79, 31, v78
	v_mad_i64_i32 v[76:77], s[8:9], v78, s10, v[94:95]
	s_mov_b64 s[12:13], 0x2800
	v_lshl_add_u64 v[110:111], v[76:77], 0, s[12:13]
	v_lshlrev_b64 v[76:77], 12, v[78:79]
	v_lshl_add_u64 v[102:103], s[4:5], 0, v[76:77]
	v_lshlrev_b64 v[76:77], 11, v[78:79]
	v_ashrrev_i32_e32 v109, 31, v108
	v_lshl_add_u64 v[104:105], s[6:7], 0, v[76:77]
	v_lshlrev_b64 v[76:77], 1, v[108:109]
	v_lshlrev_b64 v[100:101], 2, v[108:109]
	v_lshl_add_u64 v[112:113], v[110:111], 0, v[76:77]
	v_lshl_add_u64 v[106:107], v[102:103], 0, v[100:101]
	global_load_dwordx2 v[102:103], v[112:113], off
	v_mov_b32_e32 v125, v180
	global_load_dwordx4 v[112:115], v[106:107], off
	v_mov_b32_e32 v180, v179
	v_mov_b32_e32 v124, v178
	v_lshl_add_u64 v[104:105], v[104:105], 0, v[76:77]
	s_waitcnt vmcnt(1)
	v_lshlrev_b32_e32 v123, 16, v103
	v_lshlrev_b32_e32 v122, 16, v102
	v_and_b32_e32 v103, 0xffff0000, v103
	v_and_b32_e32 v102, 0xffff0000, v102
	s_waitcnt vmcnt(0)
	v_mov_b32_e32 v127, v114
	v_mov_b32_e32 v114, v113
	v_mov_b32_e32 v126, v112
	v_pk_fma_f32 v[102:103], v[180:181], v[102:103], v[114:115]
	v_pk_fma_f32 v[122:123], v[124:125], v[122:123], v[126:127]
	v_and_b32_sdwa v109, v103, v154 dst_sel:DWORD dst_unused:UNUSED_PAD src0_sel:WORD_1 src1_sel:DWORD
	v_and_b32_sdwa v112, v102, v154 dst_sel:DWORD dst_unused:UNUSED_PAD src0_sel:WORD_1 src1_sel:DWORD
	v_and_b32_sdwa v79, v123, v154 dst_sel:DWORD dst_unused:UNUSED_PAD src0_sel:WORD_1 src1_sel:DWORD
	v_and_b32_sdwa v96, v122, v154 dst_sel:DWORD dst_unused:UNUSED_PAD src0_sel:WORD_1 src1_sel:DWORD
	v_add3_u32 v103, v103, v109, s33
	v_add3_u32 v102, v102, v112, s33
	v_add3_u32 v96, v122, v96, s33
	v_add3_u32 v79, v123, v79, s33
	v_and_b32_e32 v103, 0xffff0000, v103
	v_and_b32_e32 v102, 0xffff0000, v102
	v_or_b32_sdwa v103, v103, v79 dst_sel:DWORD dst_unused:UNUSED_PAD src0_sel:DWORD src1_sel:WORD_1
	v_or_b32_sdwa v102, v102, v96 dst_sel:DWORD dst_unused:UNUSED_PAD src0_sel:DWORD src1_sel:WORD_1
	global_store_dwordx2 v[104:105], v[102:103], off
	v_or_b32_e32 v102, 16, v108
	v_ashrrev_i32_e32 v103, 31, v102
	v_lshlrev_b64 v[102:103], 1, v[102:103]
	v_lshl_add_u64 v[112:113], v[110:111], 0, v[102:103]
	global_load_dwordx2 v[112:113], v[112:113], off
	v_mov_b32_e32 v124, v72
	v_mov_b32_e32 v125, v74
	v_mov_b32_e32 v74, v73
	s_waitcnt vmcnt(0)
	v_lshlrev_b32_e32 v123, 16, v113
	v_lshlrev_b32_e32 v122, 16, v112
	v_and_b32_e32 v127, 0xffff0000, v113
	v_and_b32_e32 v126, 0xffff0000, v112
	global_load_dwordx4 v[112:115], v[106:107], off offset:64
	s_waitcnt vmcnt(0)
	v_mov_b32_e32 v72, v112
	v_mov_b32_e32 v73, v114
	v_pk_fma_f32 v[72:73], v[124:125], v[122:123], v[72:73]
	v_mov_b32_e32 v114, v113
	v_pk_fma_f32 v[74:75], v[74:75], v[126:127], v[114:115]
	v_and_b32_sdwa v79, v73, v154 dst_sel:DWORD dst_unused:UNUSED_PAD src0_sel:WORD_1 src1_sel:DWORD
	v_and_b32_sdwa v96, v72, v154 dst_sel:DWORD dst_unused:UNUSED_PAD src0_sel:WORD_1 src1_sel:DWORD
	v_add3_u32 v72, v72, v96, s33
	v_add3_u32 v73, v73, v79, s33
	v_and_b32_sdwa v79, v75, v154 dst_sel:DWORD dst_unused:UNUSED_PAD src0_sel:WORD_1 src1_sel:DWORD
	v_and_b32_sdwa v96, v74, v154 dst_sel:DWORD dst_unused:UNUSED_PAD src0_sel:WORD_1 src1_sel:DWORD
	v_add3_u32 v75, v75, v79, s33
	v_add3_u32 v74, v74, v96, s33
	v_and_b32_e32 v75, 0xffff0000, v75
	v_and_b32_e32 v74, 0xffff0000, v74
	v_or_b32_sdwa v73, v75, v73 dst_sel:DWORD dst_unused:UNUSED_PAD src0_sel:DWORD src1_sel:WORD_1
	v_or_b32_sdwa v72, v74, v72 dst_sel:DWORD dst_unused:UNUSED_PAD src0_sel:DWORD src1_sel:WORD_1
	global_store_dwordx2 v[104:105], v[72:73], off offset:32
	v_or_b32_e32 v72, 32, v108
	v_ashrrev_i32_e32 v73, 31, v72
	v_lshlrev_b64 v[72:73], 1, v[72:73]
	v_lshl_add_u64 v[74:75], v[110:111], 0, v[72:73]
	global_load_dwordx2 v[74:75], v[74:75], off
	v_mov_b32_e32 v124, v68
	global_load_dwordx4 v[112:115], v[106:107], off offset:128
	v_mov_b32_e32 v125, v70
	v_mov_b32_e32 v70, v69
	s_waitcnt vmcnt(1)
	v_lshlrev_b32_e32 v123, 16, v75
	v_lshlrev_b32_e32 v122, 16, v74
	s_waitcnt vmcnt(0)
	v_mov_b32_e32 v68, v112
	v_mov_b32_e32 v69, v114
	v_and_b32_e32 v75, 0xffff0000, v75
	v_and_b32_e32 v74, 0xffff0000, v74
	v_pk_fma_f32 v[68:69], v[124:125], v[122:123], v[68:69]
	v_mov_b32_e32 v114, v113
	v_pk_fma_f32 v[70:71], v[70:71], v[74:75], v[114:115]
	v_and_b32_sdwa v74, v69, v154 dst_sel:DWORD dst_unused:UNUSED_PAD src0_sel:WORD_1 src1_sel:DWORD
	v_and_b32_sdwa v75, v68, v154 dst_sel:DWORD dst_unused:UNUSED_PAD src0_sel:WORD_1 src1_sel:DWORD
	v_add3_u32 v68, v68, v75, s33
	v_add3_u32 v69, v69, v74, s33
	v_and_b32_sdwa v74, v71, v154 dst_sel:DWORD dst_unused:UNUSED_PAD src0_sel:WORD_1 src1_sel:DWORD
	v_and_b32_sdwa v75, v70, v154 dst_sel:DWORD dst_unused:UNUSED_PAD src0_sel:WORD_1 src1_sel:DWORD
	v_add3_u32 v71, v71, v74, s33
	v_add3_u32 v70, v70, v75, s33
	v_and_b32_e32 v71, 0xffff0000, v71
	v_and_b32_e32 v70, 0xffff0000, v70
	v_or_b32_sdwa v69, v71, v69 dst_sel:DWORD dst_unused:UNUSED_PAD src0_sel:DWORD src1_sel:WORD_1
	v_or_b32_sdwa v68, v70, v68 dst_sel:DWORD dst_unused:UNUSED_PAD src0_sel:DWORD src1_sel:WORD_1
	global_store_dwordx2 v[104:105], v[68:69], off offset:64
	v_or_b32_e32 v68, 48, v108
	v_ashrrev_i32_e32 v69, 31, v68
	v_lshlrev_b64 v[68:69], 1, v[68:69]
	v_lshl_add_u64 v[70:71], v[110:111], 0, v[68:69]
	global_load_dwordx2 v[70:71], v[70:71], off
	v_mov_b32_e32 v110, v64
	global_load_dwordx4 v[106:109], v[106:107], off offset:192
	v_mov_b32_e32 v111, v66
	v_mov_b32_e32 v66, v65
	s_waitcnt vmcnt(1)
	v_lshlrev_b32_e32 v75, 16, v71
	v_lshlrev_b32_e32 v74, 16, v70
	s_waitcnt vmcnt(0)
	v_mov_b32_e32 v64, v106
	v_mov_b32_e32 v65, v108
	v_and_b32_e32 v71, 0xffff0000, v71
	v_and_b32_e32 v70, 0xffff0000, v70
	v_pk_fma_f32 v[64:65], v[110:111], v[74:75], v[64:65]
	v_mov_b32_e32 v108, v107
	v_pk_fma_f32 v[66:67], v[66:67], v[70:71], v[108:109]
	v_and_b32_sdwa v70, v65, v154 dst_sel:DWORD dst_unused:UNUSED_PAD src0_sel:WORD_1 src1_sel:DWORD
	v_and_b32_sdwa v71, v64, v154 dst_sel:DWORD dst_unused:UNUSED_PAD src0_sel:WORD_1 src1_sel:DWORD
	v_add3_u32 v64, v64, v71, s33
	v_add3_u32 v65, v65, v70, s33
	v_and_b32_sdwa v70, v67, v154 dst_sel:DWORD dst_unused:UNUSED_PAD src0_sel:WORD_1 src1_sel:DWORD
	v_and_b32_sdwa v71, v66, v154 dst_sel:DWORD dst_unused:UNUSED_PAD src0_sel:WORD_1 src1_sel:DWORD
	v_add3_u32 v67, v67, v70, s33
	v_add3_u32 v66, v66, v71, s33
	v_and_b32_e32 v67, 0xffff0000, v67
	v_and_b32_e32 v66, 0xffff0000, v66
	v_or_b32_sdwa v65, v67, v65 dst_sel:DWORD dst_unused:UNUSED_PAD src0_sel:DWORD src1_sel:WORD_1
	v_or_b32_sdwa v64, v66, v64 dst_sel:DWORD dst_unused:UNUSED_PAD src0_sel:DWORD src1_sel:WORD_1
	global_store_dwordx2 v[104:105], v[64:65], off offset:96
	v_add_u32_e32 v64, 16, v78
	v_ashrrev_i32_e32 v65, 31, v64
	v_mad_i64_i32 v[66:67], s[8:9], v64, s10, v[94:95]
	v_lshl_add_u64 v[70:71], v[66:67], 0, s[12:13]
	v_lshlrev_b64 v[66:67], 12, v[64:65]
	v_lshl_add_u64 v[66:67], s[4:5], 0, v[66:67]
	v_lshl_add_u64 v[74:75], v[70:71], 0, v[76:77]
	v_lshl_add_u64 v[66:67], v[66:67], 0, v[100:101]
	global_load_dwordx2 v[74:75], v[74:75], off
	v_mov_b32_e32 v110, v60
	global_load_dwordx4 v[104:107], v[66:67], off
	v_mov_b32_e32 v111, v62
	v_mov_b32_e32 v62, v61
	v_lshlrev_b64 v[64:65], 11, v[64:65]
	v_lshl_add_u64 v[64:65], s[6:7], 0, v[64:65]
	v_lshl_add_u64 v[64:65], v[64:65], 0, v[76:77]
	s_waitcnt vmcnt(1)
	v_lshlrev_b32_e32 v109, 16, v75
	v_lshlrev_b32_e32 v108, 16, v74
	s_waitcnt vmcnt(0)
	v_mov_b32_e32 v60, v104
	v_mov_b32_e32 v61, v106
	v_and_b32_e32 v75, 0xffff0000, v75
	v_and_b32_e32 v74, 0xffff0000, v74
	v_pk_fma_f32 v[60:61], v[110:111], v[108:109], v[60:61]
	v_mov_b32_e32 v106, v105
	v_pk_fma_f32 v[62:63], v[62:63], v[74:75], v[106:107]
	v_and_b32_sdwa v74, v61, v154 dst_sel:DWORD dst_unused:UNUSED_PAD src0_sel:WORD_1 src1_sel:DWORD
	v_and_b32_sdwa v75, v60, v154 dst_sel:DWORD dst_unused:UNUSED_PAD src0_sel:WORD_1 src1_sel:DWORD
	v_add3_u32 v60, v60, v75, s33
	v_add3_u32 v61, v61, v74, s33
	v_and_b32_sdwa v74, v63, v154 dst_sel:DWORD dst_unused:UNUSED_PAD src0_sel:WORD_1 src1_sel:DWORD
	v_and_b32_sdwa v75, v62, v154 dst_sel:DWORD dst_unused:UNUSED_PAD src0_sel:WORD_1 src1_sel:DWORD
	v_add3_u32 v63, v63, v74, s33
	v_add3_u32 v62, v62, v75, s33
	v_and_b32_e32 v63, 0xffff0000, v63
	v_and_b32_e32 v62, 0xffff0000, v62
	v_or_b32_sdwa v61, v63, v61 dst_sel:DWORD dst_unused:UNUSED_PAD src0_sel:DWORD src1_sel:WORD_1
	v_or_b32_sdwa v60, v62, v60 dst_sel:DWORD dst_unused:UNUSED_PAD src0_sel:DWORD src1_sel:WORD_1
	global_store_dwordx2 v[64:65], v[60:61], off
	v_lshl_add_u64 v[60:61], v[70:71], 0, v[102:103]
	global_load_dwordx2 v[60:61], v[60:61], off
	v_mov_b32_e32 v104, v56
	v_mov_b32_e32 v105, v58
	v_mov_b32_e32 v58, v57
	s_waitcnt vmcnt(0)
	v_lshlrev_b32_e32 v75, 16, v61
	v_lshlrev_b32_e32 v74, 16, v60
	v_and_b32_e32 v107, 0xffff0000, v61
	v_and_b32_e32 v106, 0xffff0000, v60
	global_load_dwordx4 v[60:63], v[66:67], off offset:64
	s_waitcnt vmcnt(0)
	v_mov_b32_e32 v56, v60
	v_mov_b32_e32 v57, v62
	v_pk_fma_f32 v[56:57], v[104:105], v[74:75], v[56:57]
	v_mov_b32_e32 v62, v61
	v_pk_fma_f32 v[58:59], v[58:59], v[106:107], v[62:63]
	v_and_b32_sdwa v60, v57, v154 dst_sel:DWORD dst_unused:UNUSED_PAD src0_sel:WORD_1 src1_sel:DWORD
	v_and_b32_sdwa v61, v56, v154 dst_sel:DWORD dst_unused:UNUSED_PAD src0_sel:WORD_1 src1_sel:DWORD
	v_add3_u32 v56, v56, v61, s33
	v_add3_u32 v57, v57, v60, s33
	v_and_b32_sdwa v60, v59, v154 dst_sel:DWORD dst_unused:UNUSED_PAD src0_sel:WORD_1 src1_sel:DWORD
	v_and_b32_sdwa v61, v58, v154 dst_sel:DWORD dst_unused:UNUSED_PAD src0_sel:WORD_1 src1_sel:DWORD
	v_add3_u32 v59, v59, v60, s33
	v_add3_u32 v58, v58, v61, s33
	v_and_b32_e32 v59, 0xffff0000, v59
	v_and_b32_e32 v58, 0xffff0000, v58
	v_or_b32_sdwa v57, v59, v57 dst_sel:DWORD dst_unused:UNUSED_PAD src0_sel:DWORD src1_sel:WORD_1
	v_or_b32_sdwa v56, v58, v56 dst_sel:DWORD dst_unused:UNUSED_PAD src0_sel:DWORD src1_sel:WORD_1
	global_store_dwordx2 v[64:65], v[56:57], off offset:32
	v_lshl_add_u64 v[56:57], v[70:71], 0, v[72:73]
	global_load_dwordx2 v[56:57], v[56:57], off
	v_mov_b32_e32 v62, v52
	v_mov_b32_e32 v63, v54
	v_mov_b32_e32 v54, v53
	s_waitcnt vmcnt(0)
	v_lshlrev_b32_e32 v61, 16, v57
	v_lshlrev_b32_e32 v60, 16, v56
	v_and_b32_e32 v75, 0xffff0000, v57
	v_and_b32_e32 v74, 0xffff0000, v56
	global_load_dwordx4 v[56:59], v[66:67], off offset:128
	s_waitcnt vmcnt(0)
	v_mov_b32_e32 v52, v56
	v_mov_b32_e32 v53, v58
	v_pk_fma_f32 v[52:53], v[62:63], v[60:61], v[52:53]
	v_mov_b32_e32 v58, v57
	v_pk_fma_f32 v[54:55], v[54:55], v[74:75], v[58:59]
	v_and_b32_sdwa v56, v53, v154 dst_sel:DWORD dst_unused:UNUSED_PAD src0_sel:WORD_1 src1_sel:DWORD
	v_and_b32_sdwa v57, v52, v154 dst_sel:DWORD dst_unused:UNUSED_PAD src0_sel:WORD_1 src1_sel:DWORD
	v_add3_u32 v52, v52, v57, s33
	v_add3_u32 v53, v53, v56, s33
	v_and_b32_sdwa v56, v55, v154 dst_sel:DWORD dst_unused:UNUSED_PAD src0_sel:WORD_1 src1_sel:DWORD
	v_and_b32_sdwa v57, v54, v154 dst_sel:DWORD dst_unused:UNUSED_PAD src0_sel:WORD_1 src1_sel:DWORD
	v_add3_u32 v55, v55, v56, s33
	v_add3_u32 v54, v54, v57, s33
	v_and_b32_e32 v55, 0xffff0000, v55
	v_and_b32_e32 v54, 0xffff0000, v54
	v_or_b32_sdwa v53, v55, v53 dst_sel:DWORD dst_unused:UNUSED_PAD src0_sel:DWORD src1_sel:WORD_1
	v_or_b32_sdwa v52, v54, v52 dst_sel:DWORD dst_unused:UNUSED_PAD src0_sel:DWORD src1_sel:WORD_1
	global_store_dwordx2 v[64:65], v[52:53], off offset:64
	v_lshl_add_u64 v[52:53], v[70:71], 0, v[68:69]
	global_load_dwordx2 v[52:53], v[52:53], off
	v_mov_b32_e32 v58, v48
	v_mov_b32_e32 v59, v50
	v_mov_b32_e32 v50, v49
	s_waitcnt vmcnt(0)
	v_lshlrev_b32_e32 v57, 16, v53
	v_lshlrev_b32_e32 v56, 16, v52
	v_and_b32_e32 v61, 0xffff0000, v53
	v_and_b32_e32 v60, 0xffff0000, v52
	global_load_dwordx4 v[52:55], v[66:67], off offset:192
	s_waitcnt vmcnt(0)
	v_mov_b32_e32 v48, v52
	v_mov_b32_e32 v49, v54
	v_pk_fma_f32 v[48:49], v[58:59], v[56:57], v[48:49]
	v_mov_b32_e32 v54, v53
	v_pk_fma_f32 v[50:51], v[50:51], v[60:61], v[54:55]
	v_and_b32_sdwa v52, v49, v154 dst_sel:DWORD dst_unused:UNUSED_PAD src0_sel:WORD_1 src1_sel:DWORD
	v_and_b32_sdwa v53, v48, v154 dst_sel:DWORD dst_unused:UNUSED_PAD src0_sel:WORD_1 src1_sel:DWORD
	v_add3_u32 v48, v48, v53, s33
	v_add3_u32 v49, v49, v52, s33
	v_and_b32_sdwa v52, v51, v154 dst_sel:DWORD dst_unused:UNUSED_PAD src0_sel:WORD_1 src1_sel:DWORD
	v_and_b32_sdwa v53, v50, v154 dst_sel:DWORD dst_unused:UNUSED_PAD src0_sel:WORD_1 src1_sel:DWORD
	v_add3_u32 v51, v51, v52, s33
	v_add3_u32 v50, v50, v53, s33
	v_and_b32_e32 v51, 0xffff0000, v51
	v_and_b32_e32 v50, 0xffff0000, v50
	v_or_b32_sdwa v49, v51, v49 dst_sel:DWORD dst_unused:UNUSED_PAD src0_sel:DWORD src1_sel:WORD_1
	v_or_b32_sdwa v48, v50, v48 dst_sel:DWORD dst_unused:UNUSED_PAD src0_sel:DWORD src1_sel:WORD_1
	global_store_dwordx2 v[64:65], v[48:49], off offset:96
	v_add_u32_e32 v48, 32, v78
	v_mad_i64_i32 v[50:51], s[8:9], v48, s10, v[94:95]
	v_lshl_add_u64 v[52:53], v[50:51], 0, s[12:13]
	v_lshl_add_u64 v[54:55], v[52:53], 0, v[76:77]
	global_load_dwordx2 v[54:55], v[54:55], off
	v_ashrrev_i32_e32 v49, 31, v48
	v_lshlrev_b64 v[50:51], 12, v[48:49]
	v_lshl_add_u64 v[50:51], s[4:5], 0, v[50:51]
	v_lshl_add_u64 v[50:51], v[50:51], 0, v[100:101]
	v_mov_b32_e32 v60, v44
	v_mov_b32_e32 v61, v46
	v_mov_b32_e32 v46, v45
	v_lshlrev_b64 v[48:49], 11, v[48:49]
	v_lshl_add_u64 v[48:49], s[6:7], 0, v[48:49]
	v_lshl_add_u64 v[48:49], v[48:49], 0, v[76:77]
	s_waitcnt vmcnt(0)
	v_lshlrev_b32_e32 v59, 16, v55
	v_lshlrev_b32_e32 v58, 16, v54
	v_and_b32_e32 v63, 0xffff0000, v55
	v_and_b32_e32 v62, 0xffff0000, v54
	global_load_dwordx4 v[54:57], v[50:51], off
	s_waitcnt vmcnt(0)
	v_mov_b32_e32 v44, v54
	v_mov_b32_e32 v45, v56
	v_pk_fma_f32 v[44:45], v[60:61], v[58:59], v[44:45]
	v_mov_b32_e32 v56, v55
	v_pk_fma_f32 v[46:47], v[46:47], v[62:63], v[56:57]
	v_and_b32_sdwa v54, v45, v154 dst_sel:DWORD dst_unused:UNUSED_PAD src0_sel:WORD_1 src1_sel:DWORD
	v_and_b32_sdwa v55, v44, v154 dst_sel:DWORD dst_unused:UNUSED_PAD src0_sel:WORD_1 src1_sel:DWORD
	v_add3_u32 v44, v44, v55, s33
	v_add3_u32 v45, v45, v54, s33
	v_and_b32_sdwa v54, v47, v154 dst_sel:DWORD dst_unused:UNUSED_PAD src0_sel:WORD_1 src1_sel:DWORD
	v_and_b32_sdwa v55, v46, v154 dst_sel:DWORD dst_unused:UNUSED_PAD src0_sel:WORD_1 src1_sel:DWORD
	v_add3_u32 v47, v47, v54, s33
	v_add3_u32 v46, v46, v55, s33
	v_and_b32_e32 v47, 0xffff0000, v47
	v_and_b32_e32 v46, 0xffff0000, v46
	v_or_b32_sdwa v45, v47, v45 dst_sel:DWORD dst_unused:UNUSED_PAD src0_sel:DWORD src1_sel:WORD_1
	v_or_b32_sdwa v44, v46, v44 dst_sel:DWORD dst_unused:UNUSED_PAD src0_sel:DWORD src1_sel:WORD_1
	global_store_dwordx2 v[48:49], v[44:45], off
	v_lshl_add_u64 v[44:45], v[52:53], 0, v[102:103]
	global_load_dwordx2 v[44:45], v[44:45], off
	v_mov_b32_e32 v56, v40
	v_mov_b32_e32 v57, v42
	v_mov_b32_e32 v42, v41
	s_waitcnt vmcnt(0)
	v_lshlrev_b32_e32 v55, 16, v45
	v_lshlrev_b32_e32 v54, 16, v44
	v_and_b32_e32 v59, 0xffff0000, v45
	v_and_b32_e32 v58, 0xffff0000, v44
	global_load_dwordx4 v[44:47], v[50:51], off offset:64
	s_waitcnt vmcnt(0)
	v_mov_b32_e32 v40, v44
	v_mov_b32_e32 v41, v46
	v_pk_fma_f32 v[40:41], v[56:57], v[54:55], v[40:41]
	v_mov_b32_e32 v46, v45
	v_pk_fma_f32 v[42:43], v[42:43], v[58:59], v[46:47]
	v_and_b32_sdwa v44, v41, v154 dst_sel:DWORD dst_unused:UNUSED_PAD src0_sel:WORD_1 src1_sel:DWORD
	v_and_b32_sdwa v45, v40, v154 dst_sel:DWORD dst_unused:UNUSED_PAD src0_sel:WORD_1 src1_sel:DWORD
	v_add3_u32 v40, v40, v45, s33
	v_add3_u32 v41, v41, v44, s33
	v_and_b32_sdwa v44, v43, v154 dst_sel:DWORD dst_unused:UNUSED_PAD src0_sel:WORD_1 src1_sel:DWORD
	v_and_b32_sdwa v45, v42, v154 dst_sel:DWORD dst_unused:UNUSED_PAD src0_sel:WORD_1 src1_sel:DWORD
	v_add3_u32 v43, v43, v44, s33
	v_add3_u32 v42, v42, v45, s33
	v_and_b32_e32 v43, 0xffff0000, v43
	v_and_b32_e32 v42, 0xffff0000, v42
	v_or_b32_sdwa v41, v43, v41 dst_sel:DWORD dst_unused:UNUSED_PAD src0_sel:DWORD src1_sel:WORD_1
	v_or_b32_sdwa v40, v42, v40 dst_sel:DWORD dst_unused:UNUSED_PAD src0_sel:DWORD src1_sel:WORD_1
	global_store_dwordx2 v[48:49], v[40:41], off offset:32
	v_lshl_add_u64 v[40:41], v[52:53], 0, v[72:73]
	global_load_dwordx2 v[40:41], v[40:41], off
	v_mov_b32_e32 v46, v36
	v_mov_b32_e32 v47, v38
	v_mov_b32_e32 v38, v37
	s_waitcnt vmcnt(0)
	v_lshlrev_b32_e32 v45, 16, v41
	v_lshlrev_b32_e32 v44, 16, v40
	v_and_b32_e32 v55, 0xffff0000, v41
	v_and_b32_e32 v54, 0xffff0000, v40
	global_load_dwordx4 v[40:43], v[50:51], off offset:128
	s_waitcnt vmcnt(0)
	v_mov_b32_e32 v36, v40
	v_mov_b32_e32 v37, v42
	v_pk_fma_f32 v[36:37], v[46:47], v[44:45], v[36:37]
	v_mov_b32_e32 v42, v41
	v_pk_fma_f32 v[38:39], v[38:39], v[54:55], v[42:43]
	v_and_b32_sdwa v40, v37, v154 dst_sel:DWORD dst_unused:UNUSED_PAD src0_sel:WORD_1 src1_sel:DWORD
	v_and_b32_sdwa v41, v36, v154 dst_sel:DWORD dst_unused:UNUSED_PAD src0_sel:WORD_1 src1_sel:DWORD
	v_add3_u32 v36, v36, v41, s33
	v_add3_u32 v37, v37, v40, s33
	v_and_b32_sdwa v40, v39, v154 dst_sel:DWORD dst_unused:UNUSED_PAD src0_sel:WORD_1 src1_sel:DWORD
	v_and_b32_sdwa v41, v38, v154 dst_sel:DWORD dst_unused:UNUSED_PAD src0_sel:WORD_1 src1_sel:DWORD
	v_add3_u32 v39, v39, v40, s33
	v_add3_u32 v38, v38, v41, s33
	v_and_b32_e32 v39, 0xffff0000, v39
	v_and_b32_e32 v38, 0xffff0000, v38
	v_or_b32_sdwa v37, v39, v37 dst_sel:DWORD dst_unused:UNUSED_PAD src0_sel:DWORD src1_sel:WORD_1
	v_or_b32_sdwa v36, v38, v36 dst_sel:DWORD dst_unused:UNUSED_PAD src0_sel:DWORD src1_sel:WORD_1
	global_store_dwordx2 v[48:49], v[36:37], off offset:64
	v_lshl_add_u64 v[36:37], v[52:53], 0, v[68:69]
	global_load_dwordx2 v[36:37], v[36:37], off
	v_mov_b32_e32 v42, v32
	v_mov_b32_e32 v43, v34
	v_mov_b32_e32 v34, v33
	s_waitcnt vmcnt(0)
	v_lshlrev_b32_e32 v41, 16, v37
	v_lshlrev_b32_e32 v40, 16, v36
	v_and_b32_e32 v45, 0xffff0000, v37
	v_and_b32_e32 v44, 0xffff0000, v36
	global_load_dwordx4 v[36:39], v[50:51], off offset:192
	s_waitcnt vmcnt(0)
	v_mov_b32_e32 v32, v36
	v_mov_b32_e32 v33, v38
	v_pk_fma_f32 v[32:33], v[42:43], v[40:41], v[32:33]
	v_mov_b32_e32 v38, v37
	v_pk_fma_f32 v[34:35], v[34:35], v[44:45], v[38:39]
	v_and_b32_sdwa v36, v33, v154 dst_sel:DWORD dst_unused:UNUSED_PAD src0_sel:WORD_1 src1_sel:DWORD
	v_and_b32_sdwa v37, v32, v154 dst_sel:DWORD dst_unused:UNUSED_PAD src0_sel:WORD_1 src1_sel:DWORD
	v_add3_u32 v32, v32, v37, s33
	v_add3_u32 v33, v33, v36, s33
	v_and_b32_sdwa v36, v35, v154 dst_sel:DWORD dst_unused:UNUSED_PAD src0_sel:WORD_1 src1_sel:DWORD
	v_and_b32_sdwa v37, v34, v154 dst_sel:DWORD dst_unused:UNUSED_PAD src0_sel:WORD_1 src1_sel:DWORD
	v_add3_u32 v35, v35, v36, s33
	v_add3_u32 v34, v34, v37, s33
	v_and_b32_e32 v35, 0xffff0000, v35
	v_and_b32_e32 v34, 0xffff0000, v34
	v_or_b32_sdwa v33, v35, v33 dst_sel:DWORD dst_unused:UNUSED_PAD src0_sel:DWORD src1_sel:WORD_1
	v_or_b32_sdwa v32, v34, v32 dst_sel:DWORD dst_unused:UNUSED_PAD src0_sel:DWORD src1_sel:WORD_1
	global_store_dwordx2 v[48:49], v[32:33], off offset:96
	v_add_u32_e32 v32, 48, v78
	v_mad_i64_i32 v[34:35], s[8:9], v32, s10, v[94:95]
	v_lshl_add_u64 v[36:37], v[34:35], 0, s[12:13]
	v_lshl_add_u64 v[38:39], v[36:37], 0, v[76:77]
	global_load_dwordx2 v[38:39], v[38:39], off
	v_ashrrev_i32_e32 v33, 31, v32
	v_lshlrev_b64 v[34:35], 12, v[32:33]
	v_lshl_add_u64 v[34:35], s[4:5], 0, v[34:35]
	v_lshl_add_u64 v[34:35], v[34:35], 0, v[100:101]
	v_mov_b32_e32 v44, v28
	v_mov_b32_e32 v45, v30
	v_mov_b32_e32 v30, v29
	v_lshlrev_b64 v[32:33], 11, v[32:33]
	v_lshl_add_u64 v[32:33], s[6:7], 0, v[32:33]
	v_lshl_add_u64 v[32:33], v[32:33], 0, v[76:77]
	s_waitcnt vmcnt(0)
	v_lshlrev_b32_e32 v43, 16, v39
	v_lshlrev_b32_e32 v42, 16, v38
	v_and_b32_e32 v47, 0xffff0000, v39
	v_and_b32_e32 v46, 0xffff0000, v38
	global_load_dwordx4 v[38:41], v[34:35], off
	s_waitcnt vmcnt(0)
	v_mov_b32_e32 v28, v38
	v_mov_b32_e32 v29, v40
	v_pk_fma_f32 v[28:29], v[44:45], v[42:43], v[28:29]
	v_mov_b32_e32 v40, v39
	v_pk_fma_f32 v[30:31], v[30:31], v[46:47], v[40:41]
	v_and_b32_sdwa v38, v29, v154 dst_sel:DWORD dst_unused:UNUSED_PAD src0_sel:WORD_1 src1_sel:DWORD
	v_and_b32_sdwa v39, v28, v154 dst_sel:DWORD dst_unused:UNUSED_PAD src0_sel:WORD_1 src1_sel:DWORD
	v_add3_u32 v28, v28, v39, s33
	v_add3_u32 v29, v29, v38, s33
	v_and_b32_sdwa v38, v31, v154 dst_sel:DWORD dst_unused:UNUSED_PAD src0_sel:WORD_1 src1_sel:DWORD
	v_and_b32_sdwa v39, v30, v154 dst_sel:DWORD dst_unused:UNUSED_PAD src0_sel:WORD_1 src1_sel:DWORD
	v_add3_u32 v31, v31, v38, s33
	v_add3_u32 v30, v30, v39, s33
	v_and_b32_e32 v31, 0xffff0000, v31
	v_and_b32_e32 v30, 0xffff0000, v30
	v_or_b32_sdwa v29, v31, v29 dst_sel:DWORD dst_unused:UNUSED_PAD src0_sel:DWORD src1_sel:WORD_1
	v_or_b32_sdwa v28, v30, v28 dst_sel:DWORD dst_unused:UNUSED_PAD src0_sel:DWORD src1_sel:WORD_1
	global_store_dwordx2 v[32:33], v[28:29], off
	v_lshl_add_u64 v[28:29], v[36:37], 0, v[102:103]
	global_load_dwordx2 v[28:29], v[28:29], off
	v_mov_b32_e32 v40, v24
	v_mov_b32_e32 v41, v26
	v_mov_b32_e32 v26, v25
	s_waitcnt vmcnt(0)
	v_lshlrev_b32_e32 v39, 16, v29
	v_lshlrev_b32_e32 v38, 16, v28
	v_and_b32_e32 v43, 0xffff0000, v29
	v_and_b32_e32 v42, 0xffff0000, v28
	global_load_dwordx4 v[28:31], v[34:35], off offset:64
	s_waitcnt vmcnt(0)
	v_mov_b32_e32 v24, v28
	v_mov_b32_e32 v25, v30
	v_pk_fma_f32 v[24:25], v[40:41], v[38:39], v[24:25]
	v_mov_b32_e32 v30, v29
	v_pk_fma_f32 v[26:27], v[26:27], v[42:43], v[30:31]
	v_and_b32_sdwa v28, v25, v154 dst_sel:DWORD dst_unused:UNUSED_PAD src0_sel:WORD_1 src1_sel:DWORD
	v_and_b32_sdwa v29, v24, v154 dst_sel:DWORD dst_unused:UNUSED_PAD src0_sel:WORD_1 src1_sel:DWORD
	v_add3_u32 v24, v24, v29, s33
	v_add3_u32 v25, v25, v28, s33
	v_and_b32_sdwa v28, v27, v154 dst_sel:DWORD dst_unused:UNUSED_PAD src0_sel:WORD_1 src1_sel:DWORD
	v_and_b32_sdwa v29, v26, v154 dst_sel:DWORD dst_unused:UNUSED_PAD src0_sel:WORD_1 src1_sel:DWORD
	v_add3_u32 v27, v27, v28, s33
	v_add3_u32 v26, v26, v29, s33
	v_and_b32_e32 v27, 0xffff0000, v27
	v_and_b32_e32 v26, 0xffff0000, v26
	v_or_b32_sdwa v25, v27, v25 dst_sel:DWORD dst_unused:UNUSED_PAD src0_sel:DWORD src1_sel:WORD_1
	v_or_b32_sdwa v24, v26, v24 dst_sel:DWORD dst_unused:UNUSED_PAD src0_sel:DWORD src1_sel:WORD_1
	global_store_dwordx2 v[32:33], v[24:25], off offset:32
	v_lshl_add_u64 v[24:25], v[36:37], 0, v[72:73]
	global_load_dwordx2 v[24:25], v[24:25], off
	v_mov_b32_e32 v30, v20
	v_mov_b32_e32 v31, v22
	v_mov_b32_e32 v22, v21
	s_waitcnt vmcnt(0)
	v_lshlrev_b32_e32 v29, 16, v25
	v_lshlrev_b32_e32 v28, 16, v24
	v_and_b32_e32 v39, 0xffff0000, v25
	v_and_b32_e32 v38, 0xffff0000, v24
	global_load_dwordx4 v[24:27], v[34:35], off offset:128
	s_waitcnt vmcnt(0)
	v_mov_b32_e32 v20, v24
	v_mov_b32_e32 v21, v26
	v_pk_fma_f32 v[20:21], v[30:31], v[28:29], v[20:21]
	v_mov_b32_e32 v26, v25
	v_pk_fma_f32 v[22:23], v[22:23], v[38:39], v[26:27]
	v_and_b32_sdwa v24, v21, v154 dst_sel:DWORD dst_unused:UNUSED_PAD src0_sel:WORD_1 src1_sel:DWORD
	v_and_b32_sdwa v25, v20, v154 dst_sel:DWORD dst_unused:UNUSED_PAD src0_sel:WORD_1 src1_sel:DWORD
	v_add3_u32 v20, v20, v25, s33
	v_add3_u32 v21, v21, v24, s33
	v_and_b32_sdwa v24, v23, v154 dst_sel:DWORD dst_unused:UNUSED_PAD src0_sel:WORD_1 src1_sel:DWORD
	v_and_b32_sdwa v25, v22, v154 dst_sel:DWORD dst_unused:UNUSED_PAD src0_sel:WORD_1 src1_sel:DWORD
	v_add3_u32 v23, v23, v24, s33
	v_add3_u32 v22, v22, v25, s33
	v_and_b32_e32 v23, 0xffff0000, v23
	v_and_b32_e32 v22, 0xffff0000, v22
	v_or_b32_sdwa v21, v23, v21 dst_sel:DWORD dst_unused:UNUSED_PAD src0_sel:DWORD src1_sel:WORD_1
	v_or_b32_sdwa v20, v22, v20 dst_sel:DWORD dst_unused:UNUSED_PAD src0_sel:DWORD src1_sel:WORD_1
	global_store_dwordx2 v[32:33], v[20:21], off offset:64
	v_lshl_add_u64 v[20:21], v[36:37], 0, v[68:69]
	global_load_dwordx2 v[20:21], v[20:21], off
	v_mov_b32_e32 v26, v16
	v_mov_b32_e32 v27, v18
	v_mov_b32_e32 v18, v17
	s_waitcnt vmcnt(0)
	v_lshlrev_b32_e32 v25, 16, v21
	v_lshlrev_b32_e32 v24, 16, v20
	v_and_b32_e32 v29, 0xffff0000, v21
	v_and_b32_e32 v28, 0xffff0000, v20
	global_load_dwordx4 v[20:23], v[34:35], off offset:192
	s_waitcnt vmcnt(0)
	v_mov_b32_e32 v16, v20
	v_mov_b32_e32 v17, v22
	v_pk_fma_f32 v[16:17], v[26:27], v[24:25], v[16:17]
	v_mov_b32_e32 v22, v21
	v_pk_fma_f32 v[18:19], v[18:19], v[28:29], v[22:23]
	v_and_b32_sdwa v20, v17, v154 dst_sel:DWORD dst_unused:UNUSED_PAD src0_sel:WORD_1 src1_sel:DWORD
	v_and_b32_sdwa v21, v16, v154 dst_sel:DWORD dst_unused:UNUSED_PAD src0_sel:WORD_1 src1_sel:DWORD
	v_add3_u32 v16, v16, v21, s33
	v_add3_u32 v17, v17, v20, s33
	v_and_b32_sdwa v20, v19, v154 dst_sel:DWORD dst_unused:UNUSED_PAD src0_sel:WORD_1 src1_sel:DWORD
	v_and_b32_sdwa v21, v18, v154 dst_sel:DWORD dst_unused:UNUSED_PAD src0_sel:WORD_1 src1_sel:DWORD
	v_add3_u32 v19, v19, v20, s33
	v_add3_u32 v18, v18, v21, s33
	v_and_b32_e32 v19, 0xffff0000, v19
	v_and_b32_e32 v18, 0xffff0000, v18
	v_or_b32_sdwa v17, v19, v17 dst_sel:DWORD dst_unused:UNUSED_PAD src0_sel:DWORD src1_sel:WORD_1
	v_or_b32_sdwa v16, v18, v16 dst_sel:DWORD dst_unused:UNUSED_PAD src0_sel:DWORD src1_sel:WORD_1
	global_store_dwordx2 v[32:33], v[16:17], off offset:96
	v_add_u32_e32 v20, 64, v78
	v_mad_i64_i32 v[16:17], s[8:9], v20, s10, v[94:95]
	v_lshl_add_u64 v[22:23], v[16:17], 0, s[12:13]
	v_ashrrev_i32_e32 v21, 31, v20
	v_lshl_add_u64 v[16:17], v[22:23], 0, v[76:77]
	global_load_dwordx2 v[24:25], v[16:17], off
	v_lshlrev_b64 v[16:17], 12, v[20:21]
	v_lshl_add_u64 v[16:17], s[4:5], 0, v[16:17]
	v_lshl_add_u64 v[26:27], v[16:17], 0, v[100:101]
	global_load_dwordx4 v[16:19], v[26:27], off
	v_mov_b32_e32 v28, v12
	v_mov_b32_e32 v29, v14
	v_mov_b32_e32 v14, v13
	v_lshlrev_b64 v[12:13], 11, v[20:21]
	v_lshl_add_u64 v[12:13], s[6:7], 0, v[12:13]
	v_lshl_add_u64 v[30:31], v[12:13], 0, v[76:77]
	v_lshl_add_u64 v[20:21], v[22:23], 0, v[102:103]
	global_load_dwordx2 v[20:21], v[20:21], off
	s_waitcnt vmcnt(2)
	v_lshlrev_b32_e32 v13, 16, v25
	v_lshlrev_b32_e32 v12, 16, v24
	v_and_b32_e32 v25, 0xffff0000, v25
	v_and_b32_e32 v24, 0xffff0000, v24
	s_waitcnt vmcnt(1)
	v_mov_b32_e32 v33, v18
	v_mov_b32_e32 v18, v17
	v_mov_b32_e32 v32, v16
	v_pk_fma_f32 v[14:15], v[14:15], v[24:25], v[18:19]
	v_pk_fma_f32 v[12:13], v[28:29], v[12:13], v[32:33]
	v_and_b32_sdwa v18, v15, v154 dst_sel:DWORD dst_unused:UNUSED_PAD src0_sel:WORD_1 src1_sel:DWORD
	v_and_b32_sdwa v19, v14, v154 dst_sel:DWORD dst_unused:UNUSED_PAD src0_sel:WORD_1 src1_sel:DWORD
	v_and_b32_sdwa v16, v13, v154 dst_sel:DWORD dst_unused:UNUSED_PAD src0_sel:WORD_1 src1_sel:DWORD
	v_and_b32_sdwa v17, v12, v154 dst_sel:DWORD dst_unused:UNUSED_PAD src0_sel:WORD_1 src1_sel:DWORD
	v_add3_u32 v15, v15, v18, s33
	v_add3_u32 v14, v14, v19, s33
	v_add3_u32 v12, v12, v17, s33
	v_add3_u32 v13, v13, v16, s33
	v_and_b32_e32 v15, 0xffff0000, v15
	v_and_b32_e32 v14, 0xffff0000, v14
	v_or_b32_sdwa v13, v15, v13 dst_sel:DWORD dst_unused:UNUSED_PAD src0_sel:DWORD src1_sel:WORD_1
	v_or_b32_sdwa v12, v14, v12 dst_sel:DWORD dst_unused:UNUSED_PAD src0_sel:DWORD src1_sel:WORD_1
	global_store_dwordx2 v[30:31], v[12:13], off
	global_load_dwordx4 v[12:15], v[26:27], off offset:64
	v_mov_b32_e32 v16, v8
	v_mov_b32_e32 v17, v10
	v_mov_b32_e32 v10, v9
	v_lshl_add_u64 v[8:9], v[22:23], 0, v[72:73]
	global_load_dwordx2 v[18:19], v[8:9], off
	s_waitcnt vmcnt(3)
	v_lshlrev_b32_e32 v9, 16, v21
	v_lshlrev_b32_e32 v8, 16, v20
	v_and_b32_e32 v21, 0xffff0000, v21
	v_and_b32_e32 v20, 0xffff0000, v20
	s_waitcnt vmcnt(1)
	v_mov_b32_e32 v25, v14
	v_mov_b32_e32 v14, v13
	v_mov_b32_e32 v24, v12
	v_pk_fma_f32 v[10:11], v[10:11], v[20:21], v[14:15]
	v_pk_fma_f32 v[8:9], v[16:17], v[8:9], v[24:25]
	v_and_b32_sdwa v14, v11, v154 dst_sel:DWORD dst_unused:UNUSED_PAD src0_sel:WORD_1 src1_sel:DWORD
	v_and_b32_sdwa v15, v10, v154 dst_sel:DWORD dst_unused:UNUSED_PAD src0_sel:WORD_1 src1_sel:DWORD
	v_and_b32_sdwa v12, v9, v154 dst_sel:DWORD dst_unused:UNUSED_PAD src0_sel:WORD_1 src1_sel:DWORD
	v_and_b32_sdwa v13, v8, v154 dst_sel:DWORD dst_unused:UNUSED_PAD src0_sel:WORD_1 src1_sel:DWORD
	v_add3_u32 v11, v11, v14, s33
	v_add3_u32 v10, v10, v15, s33
	v_add3_u32 v8, v8, v13, s33
	v_add3_u32 v9, v9, v12, s33
	v_and_b32_e32 v11, 0xffff0000, v11
	v_and_b32_e32 v10, 0xffff0000, v10
	v_or_b32_sdwa v9, v11, v9 dst_sel:DWORD dst_unused:UNUSED_PAD src0_sel:DWORD src1_sel:WORD_1
	v_or_b32_sdwa v8, v10, v8 dst_sel:DWORD dst_unused:UNUSED_PAD src0_sel:DWORD src1_sel:WORD_1
	global_store_dwordx2 v[30:31], v[8:9], off offset:32
	global_load_dwordx4 v[8:11], v[26:27], off offset:128
	v_mov_b32_e32 v12, v4
	v_mov_b32_e32 v13, v6
	v_mov_b32_e32 v6, v5
	v_lshl_add_u64 v[4:5], v[22:23], 0, v[68:69]
	global_load_dwordx2 v[14:15], v[4:5], off
	s_waitcnt vmcnt(3)
	v_lshlrev_b32_e32 v5, 16, v19
	v_and_b32_e32 v17, 0xffff0000, v19
	v_and_b32_e32 v16, 0xffff0000, v18
	v_lshlrev_b32_e32 v4, 16, v18
	s_waitcnt vmcnt(1)
	v_mov_b32_e32 v19, v10
	v_mov_b32_e32 v10, v9
	v_mov_b32_e32 v18, v8
	v_pk_fma_f32 v[6:7], v[6:7], v[16:17], v[10:11]
	v_pk_fma_f32 v[4:5], v[12:13], v[4:5], v[18:19]
	v_and_b32_sdwa v10, v7, v154 dst_sel:DWORD dst_unused:UNUSED_PAD src0_sel:WORD_1 src1_sel:DWORD
	v_and_b32_sdwa v11, v6, v154 dst_sel:DWORD dst_unused:UNUSED_PAD src0_sel:WORD_1 src1_sel:DWORD
	v_and_b32_sdwa v8, v5, v154 dst_sel:DWORD dst_unused:UNUSED_PAD src0_sel:WORD_1 src1_sel:DWORD
	v_and_b32_sdwa v9, v4, v154 dst_sel:DWORD dst_unused:UNUSED_PAD src0_sel:WORD_1 src1_sel:DWORD
	v_add3_u32 v7, v7, v10, s33
	v_add3_u32 v6, v6, v11, s33
	v_add3_u32 v4, v4, v9, s33
	v_add3_u32 v5, v5, v8, s33
	v_and_b32_e32 v7, 0xffff0000, v7
	v_and_b32_e32 v6, 0xffff0000, v6
	v_or_b32_sdwa v5, v7, v5 dst_sel:DWORD dst_unused:UNUSED_PAD src0_sel:DWORD src1_sel:WORD_1
	v_or_b32_sdwa v4, v6, v4 dst_sel:DWORD dst_unused:UNUSED_PAD src0_sel:DWORD src1_sel:WORD_1
	global_store_dwordx2 v[30:31], v[4:5], off offset:64
	global_load_dwordx4 v[4:7], v[26:27], off offset:192
	v_mov_b32_e32 v9, v2
	v_mov_b32_e32 v2, v1
	s_waitcnt vmcnt(2)
	v_and_b32_e32 v11, 0xffff0000, v15
	v_and_b32_e32 v10, 0xffff0000, v14
	v_mov_b32_e32 v8, v0
	v_lshlrev_b32_e32 v1, 16, v15
	v_lshlrev_b32_e32 v0, 16, v14
	s_waitcnt vmcnt(0)
	v_mov_b32_e32 v13, v6
	v_mov_b32_e32 v6, v5
	v_mov_b32_e32 v12, v4
	v_pk_fma_f32 v[2:3], v[2:3], v[10:11], v[6:7]
	v_pk_fma_f32 v[0:1], v[8:9], v[0:1], v[12:13]
	v_and_b32_sdwa v6, v3, v154 dst_sel:DWORD dst_unused:UNUSED_PAD src0_sel:WORD_1 src1_sel:DWORD
	v_and_b32_sdwa v7, v2, v154 dst_sel:DWORD dst_unused:UNUSED_PAD src0_sel:WORD_1 src1_sel:DWORD
	v_and_b32_sdwa v4, v1, v154 dst_sel:DWORD dst_unused:UNUSED_PAD src0_sel:WORD_1 src1_sel:DWORD
	v_and_b32_sdwa v5, v0, v154 dst_sel:DWORD dst_unused:UNUSED_PAD src0_sel:WORD_1 src1_sel:DWORD
	v_add3_u32 v3, v3, v6, s33
	v_add3_u32 v2, v2, v7, s33
	v_add3_u32 v0, v0, v5, s33
	v_add3_u32 v1, v1, v4, s33
	v_and_b32_e32 v3, 0xffff0000, v3
	v_and_b32_e32 v2, 0xffff0000, v2
	v_or_b32_sdwa v1, v3, v1 dst_sel:DWORD dst_unused:UNUSED_PAD src0_sel:DWORD src1_sel:WORD_1
	v_or_b32_sdwa v0, v2, v0 dst_sel:DWORD dst_unused:UNUSED_PAD src0_sel:DWORD src1_sel:WORD_1
	global_store_dwordx2 v[30:31], v[0:1], off offset:96

.LBB0_137:
	s_add_i32 s37, s11, 1
	s_bitcmp1_b32 s37, 0
	s_cselect_b32 s39, 0x9000, 0
	v_add_u32_e32 v94, s39, v177
	v_lshl_add_u64 v[90:91], v[86:87], 0, s[12:13]
	v_readfirstlane_b32 s39, v94
	v_add_u32_e32 v95, 0x1000, v94
	v_lshl_add_u64 v[92:93], v[90:91], 0, s[44:45]
	s_mov_b32 m0, s39
	v_readfirstlane_b32 s39, v95
	v_add_u32_e32 v95, 0x2000, v94
	global_load_lds_dwordx4 v[92:93], off
	v_lshl_add_u64 v[92:93], v[90:91], 0, s[46:47]
	s_mov_b32 m0, s39
	v_readfirstlane_b32 s39, v95
	v_add_u32_e32 v95, 0x3000, v94
	global_load_lds_dwordx4 v[92:93], off
	v_lshl_add_u64 v[92:93], v[90:91], 0, s[48:49]
	s_mov_b32 m0, s39
	v_readfirstlane_b32 s39, v95
	global_load_lds_dwordx4 v[92:93], off
	v_lshl_add_u64 v[92:93], v[90:91], 0, s[52:53]
	s_mov_b32 m0, s39
	s_mov_b64 s[40:41], 0x4141080
	global_load_lds_dwordx4 v[92:93], off
	v_add_u32_e32 v92, 0x4000, v94
	v_lshl_add_u64 v[90:91], v[90:91], 0, s[40:41]
	v_readfirstlane_b32 s39, v92
	s_mov_b32 m0, s39
	v_add_u32_e32 v95, 0x5000, v94
	global_load_lds_dwordx4 v[90:91], off
	v_lshl_add_u64 v[90:91], v[88:89], 0, s[12:13]
	v_readfirstlane_b32 s39, v95
	v_add_u32_e32 v95, 0x6000, v94
	v_lshl_add_u64 v[92:93], v[90:91], 0, s[54:55]
	s_mov_b32 m0, s39
	v_readfirstlane_b32 s39, v95
	v_add_u32_e32 v95, 0x7000, v94
	global_load_lds_dwordx4 v[92:93], off
	v_lshl_add_u64 v[92:93], v[90:91], 0, s[56:57]
	s_mov_b32 m0, s39
	v_readfirstlane_b32 s39, v95
	global_load_lds_dwordx4 v[92:93], off
	v_lshl_add_u64 v[92:93], v[90:91], 0, s[58:59]
	s_mov_b32 m0, s39
	v_lshl_add_u64 v[90:91], v[90:91], 0, s[60:61]
	global_load_lds_dwordx4 v[92:93], off
	v_add_u32_e32 v92, 0x8000, v94
	s_bitcmp1_b32 s11, 0
	v_readfirstlane_b32 s39, v92
	s_mov_b32 m0, s39
	s_cselect_b32 s11, 0x9000, 0
	global_load_lds_dwordx4 v[90:91], off
	s_add_i32 s11, s11, 0
	v_add_u32_e32 v94, s11, v178
	v_add_u32_e32 v95, v94, v179
	ds_read_b128 v[90:93], v95
	ds_read_b128 v[100:103], v95 offset:2048
	ds_read_b128 v[104:107], v95 offset:4096
	ds_read_b128 v[108:111], v95 offset:6144
	v_add_u32_e32 v94, v94, v180
	ds_read_b128 v[112:115], v95 offset:8192
	ds_read_b128 v[116:119], v94 offset:20480
	ds_read_b128 v[120:123], v94 offset:22528
	ds_read_b128 v[124:127], v94 offset:24576
	ds_read_b128 v[128:131], v94 offset:26624
	v_add_u32_e32 v206, s11, v181
	v_add_u32_e32 v207, v206, v179
	ds_read_b128 v[208:211], v207
	ds_read_b128 v[212:215], v207 offset:2048
	ds_read_b128 v[216:219], v207 offset:4096
	ds_read_b128 v[220:223], v207 offset:6144
	v_add_u32_e32 v224, v206, v180
	ds_read_b128 v[226:229], v207 offset:8192
	ds_read_b128 v[230:233], v224 offset:20480
	ds_read_b128 v[234:237], v224 offset:22528
	ds_read_b128 v[238:241], v224 offset:24576
	ds_read_b128 v[242:245], v224 offset:26624
	s_setprio 1
	s_waitcnt lgkmcnt(9)
	v_mfma_f32_16x16x32_bf16 v[76:79], v[116:119], v[90:93], v[76:79]
	v_mfma_f32_16x16x32_bf16 v[72:75], v[120:123], v[90:93], v[72:75]
	v_mfma_f32_16x16x32_bf16 v[68:71], v[124:127], v[90:93], v[68:71]
	v_mfma_f32_16x16x32_bf16 v[64:67], v[128:131], v[90:93], v[64:67]
	v_mfma_f32_16x16x32_bf16 v[60:63], v[116:119], v[100:103], v[60:63]
	v_mfma_f32_16x16x32_bf16 v[56:59], v[120:123], v[100:103], v[56:59]
	v_mfma_f32_16x16x32_bf16 v[52:55], v[124:127], v[100:103], v[52:55]
	v_mfma_f32_16x16x32_bf16 v[48:51], v[128:131], v[100:103], v[48:51]
	v_mfma_f32_16x16x32_bf16 v[44:47], v[116:119], v[104:107], v[44:47]
	v_mfma_f32_16x16x32_bf16 v[40:43], v[120:123], v[104:107], v[40:43]
	v_mfma_f32_16x16x32_bf16 v[36:39], v[124:127], v[104:107], v[36:39]
	v_mfma_f32_16x16x32_bf16 v[32:35], v[128:131], v[104:107], v[32:35]
	v_mfma_f32_16x16x32_bf16 v[28:31], v[116:119], v[108:111], v[28:31]
	v_mfma_f32_16x16x32_bf16 v[24:27], v[120:123], v[108:111], v[24:27]
	v_mfma_f32_16x16x32_bf16 v[20:23], v[124:127], v[108:111], v[20:23]
	v_mfma_f32_16x16x32_bf16 v[16:19], v[128:131], v[108:111], v[16:19]
	v_mfma_f32_16x16x32_bf16 v[12:15], v[116:119], v[112:115], v[12:15]
	v_mfma_f32_16x16x32_bf16 v[8:11], v[120:123], v[112:115], v[8:11]
	v_mfma_f32_16x16x32_bf16 v[4:7], v[124:127], v[112:115], v[4:7]
	v_mfma_f32_16x16x32_bf16 v[0:3], v[128:131], v[112:115], v[0:3]
	s_setprio 0
	s_setprio 1
	s_waitcnt lgkmcnt(0)
	v_mfma_f32_16x16x32_bf16 v[76:79], v[230:233], v[208:211], v[76:79]
	v_mfma_f32_16x16x32_bf16 v[72:75], v[234:237], v[208:211], v[72:75]
	v_mfma_f32_16x16x32_bf16 v[68:71], v[238:241], v[208:211], v[68:71]
	v_mfma_f32_16x16x32_bf16 v[64:67], v[242:245], v[208:211], v[64:67]
	v_mfma_f32_16x16x32_bf16 v[60:63], v[230:233], v[212:215], v[60:63]
	v_mfma_f32_16x16x32_bf16 v[56:59], v[234:237], v[212:215], v[56:59]
	v_mfma_f32_16x16x32_bf16 v[52:55], v[238:241], v[212:215], v[52:55]
	v_mfma_f32_16x16x32_bf16 v[48:51], v[242:245], v[212:215], v[48:51]
	v_mfma_f32_16x16x32_bf16 v[44:47], v[230:233], v[216:219], v[44:47]
	v_mfma_f32_16x16x32_bf16 v[40:43], v[234:237], v[216:219], v[40:43]
	v_mfma_f32_16x16x32_bf16 v[36:39], v[238:241], v[216:219], v[36:39]
	v_mfma_f32_16x16x32_bf16 v[32:35], v[242:245], v[216:219], v[32:35]
	v_mfma_f32_16x16x32_bf16 v[28:31], v[230:233], v[220:223], v[28:31]
	v_mfma_f32_16x16x32_bf16 v[24:27], v[234:237], v[220:223], v[24:27]
	v_mfma_f32_16x16x32_bf16 v[20:23], v[238:241], v[220:223], v[20:23]
	v_mfma_f32_16x16x32_bf16 v[16:19], v[242:245], v[220:223], v[16:19]
	v_mfma_f32_16x16x32_bf16 v[12:15], v[230:233], v[226:229], v[12:15]
	v_mfma_f32_16x16x32_bf16 v[8:11], v[234:237], v[226:229], v[8:11]
	v_mfma_f32_16x16x32_bf16 v[4:7], v[238:241], v[226:229], v[4:7]
	v_mfma_f32_16x16x32_bf16 v[0:3], v[242:245], v[226:229], v[0:3]
	s_setprio 0
	s_waitcnt vmcnt(0)
	s_add_u32 s12, s12, 0x80
	s_addc_u32 s13, s13, 0
	s_cmpk_lg_i32 s12, 0x780
	s_mov_b32 s11, s37
	s_waitcnt vmcnt(0)
	s_barrier
	s_cbranch_scc1 .LBB0_137
	v_add_u32_e32 v94, v182, v180
	ds_read_b128 v[86:89], v94 offset:63488
	ds_read_b128 v[90:93], v94 offset:61440
	ds_read_b128 v[100:103], v94 offset:59392
	ds_read_b128 v[104:107], v94 offset:57344
	v_add_u32_e32 v94, v182, v179
	ds_read_b128 v[108:111], v94 offset:45056
	ds_read_b128 v[112:115], v94 offset:43008
	ds_read_b128 v[116:119], v94 offset:40960
	ds_read_b128 v[120:123], v94 offset:38912
	ds_read_b128 v[124:127], v94 offset:36864
	s_setprio 1
	s_waitcnt lgkmcnt(0)
	v_mfma_f32_16x16x32_bf16 v[76:79], v[104:107], v[124:127], v[76:79]
	v_mfma_f32_16x16x32_bf16 v[72:75], v[100:103], v[124:127], v[72:75]
	v_mfma_f32_16x16x32_bf16 v[68:71], v[90:93], v[124:127], v[68:71]
	v_mfma_f32_16x16x32_bf16 v[64:67], v[86:89], v[124:127], v[64:67]
	v_mfma_f32_16x16x32_bf16 v[60:63], v[104:107], v[120:123], v[60:63]
	v_mfma_f32_16x16x32_bf16 v[56:59], v[100:103], v[120:123], v[56:59]
	v_mfma_f32_16x16x32_bf16 v[52:55], v[90:93], v[120:123], v[52:55]
	v_mfma_f32_16x16x32_bf16 v[48:51], v[86:89], v[120:123], v[48:51]
	v_mfma_f32_16x16x32_bf16 v[44:47], v[104:107], v[116:119], v[44:47]
	v_mfma_f32_16x16x32_bf16 v[40:43], v[100:103], v[116:119], v[40:43]
	v_mfma_f32_16x16x32_bf16 v[36:39], v[90:93], v[116:119], v[36:39]
	v_mfma_f32_16x16x32_bf16 v[32:35], v[86:89], v[116:119], v[32:35]
	v_mfma_f32_16x16x32_bf16 v[28:31], v[104:107], v[112:115], v[28:31]
	v_mfma_f32_16x16x32_bf16 v[24:27], v[100:103], v[112:115], v[24:27]
	v_mfma_f32_16x16x32_bf16 v[20:23], v[90:93], v[112:115], v[20:23]
	v_mfma_f32_16x16x32_bf16 v[16:19], v[86:89], v[112:115], v[16:19]
	v_mfma_f32_16x16x32_bf16 v[12:15], v[104:107], v[108:111], v[12:15]
	v_mfma_f32_16x16x32_bf16 v[8:11], v[100:103], v[108:111], v[8:11]
	v_mfma_f32_16x16x32_bf16 v[4:7], v[90:93], v[108:111], v[4:7]
	v_mfma_f32_16x16x32_bf16 v[0:3], v[86:89], v[108:111], v[0:3]
	s_setprio 0
	v_add_u32_e32 v94, v183, v179
	ds_read_b128 v[86:89], v94 offset:36864
	ds_read_b128 v[90:93], v94 offset:38912
	ds_read_b128 v[100:103], v94 offset:40960
	ds_read_b128 v[104:107], v94 offset:43008
	v_add_u32_e32 v95, v183, v180
	ds_read_b128 v[108:111], v94 offset:45056
	ds_read_b128 v[112:115], v95 offset:57344
	ds_read_b128 v[116:119], v95 offset:59392
	ds_read_b128 v[120:123], v95 offset:61440
	ds_read_b128 v[124:127], v95 offset:63488
	s_setprio 1
	s_waitcnt lgkmcnt(3)
	v_mfma_f32_16x16x32_bf16 v[76:79], v[112:115], v[86:89], v[76:79]
	s_waitcnt lgkmcnt(2)
	v_mfma_f32_16x16x32_bf16 v[72:75], v[116:119], v[86:89], v[72:75]
	s_waitcnt lgkmcnt(1)
	v_mfma_f32_16x16x32_bf16 v[68:71], v[120:123], v[86:89], v[68:71]
	s_waitcnt lgkmcnt(0)
	v_mfma_f32_16x16x32_bf16 v[64:67], v[124:127], v[86:89], v[64:67]
	v_mfma_f32_16x16x32_bf16 v[60:63], v[112:115], v[90:93], v[60:63]
	v_mfma_f32_16x16x32_bf16 v[56:59], v[116:119], v[90:93], v[56:59]
	v_mfma_f32_16x16x32_bf16 v[52:55], v[120:123], v[90:93], v[52:55]
	v_mfma_f32_16x16x32_bf16 v[48:51], v[124:127], v[90:93], v[48:51]
	v_mfma_f32_16x16x32_bf16 v[44:47], v[112:115], v[100:103], v[44:47]
	v_mfma_f32_16x16x32_bf16 v[40:43], v[116:119], v[100:103], v[40:43]
	v_mfma_f32_16x16x32_bf16 v[36:39], v[120:123], v[100:103], v[36:39]
	v_mfma_f32_16x16x32_bf16 v[32:35], v[124:127], v[100:103], v[32:35]
	v_mfma_f32_16x16x32_bf16 v[28:31], v[112:115], v[104:107], v[28:31]
	v_mfma_f32_16x16x32_bf16 v[24:27], v[116:119], v[104:107], v[24:27]
	v_mfma_f32_16x16x32_bf16 v[20:23], v[120:123], v[104:107], v[20:23]
	v_mfma_f32_16x16x32_bf16 v[16:19], v[124:127], v[104:107], v[16:19]
	v_mfma_f32_16x16x32_bf16 v[12:15], v[112:115], v[108:111], v[12:15]
	v_mfma_f32_16x16x32_bf16 v[8:11], v[116:119], v[108:111], v[8:11]
	v_mfma_f32_16x16x32_bf16 v[4:7], v[120:123], v[108:111], v[4:7]
	v_mfma_f32_16x16x32_bf16 v[0:3], v[124:127], v[108:111], v[0:3]
	s_setprio 0
	v_mov_b32_e32 v86, v97
	s_waitcnt vmcnt(0)
	s_barrier
	s_mulk_i32 s38, 0xa0
	v_add_u32_e32 v87, v86, v176
	v_ashrrev_i32_e32 v88, 7, v87
	v_and_or_b32 v86, v87, 15, s38
	s_movk_i32 s11, 0x50
	v_mad_u64_u32 v[88:89], s[12:13], v88, s11, v[86:87]
	s_lshl_b32 s10, s10, 7
	v_lshrrev_b32_e32 v86, 2, v87
	v_and_b32_e32 v92, 64, v87
	s_and_b32 s11, s10, 0x380
	v_and_b32_e32 v89, 12, v86
	v_or3_b32 v158, v92, s11, v89
	v_cmp_lt_i32_e32 vcc, v140, v138
	s_ashr_i32 s11, s10, 31
	s_lshl_b64 s[10:11], s[10:11], 1
	v_cndmask_b32_e32 v86, v137, v140, vcc
	v_cmp_lt_i32_e32 vcc, v139, v138
	v_lshlrev_b32_e32 v184, 2, v86
	s_add_u32 s10, s34, s10
	v_cndmask_b32_e32 v86, v137, v139, vcc
	v_lshlrev_b32_e32 v185, 2, v86
	s_addc_u32 s11, s35, s11
	v_lshlrev_b32_e32 v86, 1, v92
	v_mov_b32_e32 v87, v97
	s_mov_b32 s37, 0
	v_lshlrev_b32_e32 v96, 1, v158
	v_lshl_add_u64 v[86:87], s[10:11], 0, v[86:87]
	v_lshlrev_b32_e32 v92, 1, v89
	v_mov_b32_e32 v93, v97
	v_lshl_add_u64 v[90:91], s[6:7], 0, v[96:97]
	v_lshl_add_u64 v[86:87], v[86:87], 0, v[92:93]
	v_ashrrev_i32_e32 v89, 31, v88
	v_lshlrev_b64 v[92:93], 11, v[88:89]
	v_lshl_add_u64 v[94:95], v[90:91], 0, v[92:93]
	global_load_dwordx2 v[102:103], v[94:95], off
	global_load_dwordx2 v[100:101], v[94:95], off offset:32
	s_mov_b32 s38, 0x3c800000
	s_mov_b32 s12, 0x800000
	s_movk_i32 s13, 0x3200
	s_waitcnt vmcnt(1)
	v_lshlrev_b32_e32 v132, 16, v102
	s_waitcnt vmcnt(0)
	v_lshlrev_b32_e32 v123, 16, v100
	v_and_b32_e32 v119, 0xffff0000, v100
	v_alignbit_b32 v89, v101, v100, 16
	v_and_b32_e32 v121, 0xffff0000, v101
	global_load_dwordx2 v[100:101], v[94:95], off offset:64
	v_and_b32_e32 v125, 0xffff0000, v89
	v_and_b32_e32 v129, 0xffff0000, v103
	v_and_b32_e32 v130, 0xffff0000, v102
	v_mov_b32_e32 v128, v132
	v_mov_b32_e32 v131, v132
	v_mul_f32_e32 v108, v132, v132
	v_mul_f32_e32 v122, v123, v123
	v_mul_f32_e32 v118, v119, v119
	v_mul_f32_e32 v124, v125, v125
	v_mul_f32_e32 v120, v121, v121
	s_waitcnt vmcnt(0)
	v_lshlrev_b32_e32 v115, 16, v100
	v_and_b32_e32 v111, 0xffff0000, v100
	v_alignbit_b32 v89, v101, v100, 16
	v_and_b32_e32 v113, 0xffff0000, v101
	global_load_dwordx2 v[100:101], v[94:95], off offset:96
	v_and_b32_e32 v117, 0xffff0000, v89
	v_mul_f32_e32 v114, v115, v115
	v_mul_f32_e32 v110, v111, v111
	v_mul_f32_e32 v116, v117, v117
	v_mul_f32_e32 v112, v113, v113
	s_waitcnt vmcnt(0)
	v_alignbit_b32 v89, v101, v100, 16
	v_and_b32_e32 v107, 0xffff0000, v89
	v_alignbit_b32 v89, v103, v102, 16
	v_and_b32_e32 v103, 0xffff0000, v89
	v_and_b32_e32 v102, 16, v102
	v_mov_b32_e32 v89, v132
	v_pk_add_f32 v[126:127], v[102:103], v[128:129]
	v_pk_add_f32 v[156:157], v[130:131], v[88:89] op_sel_hi:[0,1]
	v_mov_b32_e32 v109, v127
	v_pk_mul_f32 v[126:127], v[130:131], v[130:131]
	v_mov_b32_e32 v128, v103
	v_mul_f32_e32 v102, v129, v129
	v_mov_b32_e32 v133, v103
	v_mov_b32_e32 v127, v157
	v_pk_fma_f32 v[102:103], v[128:129], v[128:129], v[102:103] op_sel_hi:[1,1,0]
	v_pk_add_f32 v[108:109], v[108:109], v[126:127]
	v_mov_b32_e32 v103, v97
	v_pk_add_f32 v[102:103], v[108:109], v[102:103]
	v_pk_add_f32 v[108:109], v[122:123], v[118:119]
	v_pk_add_f32 v[126:127], v[124:125], v[120:121]
	v_lshlrev_b32_e32 v105, 16, v100
	v_pk_add_f32 v[108:109], v[108:109], v[126:127]
	v_and_b32_e32 v95, 0xffff0000, v100
	v_and_b32_e32 v101, 0xffff0000, v101
	v_pk_add_f32 v[102:103], v[102:103], v[108:109]
	v_pk_add_f32 v[108:109], v[114:115], v[110:111]
	v_pk_add_f32 v[126:127], v[116:117], v[112:113]
	v_mul_f32_e32 v104, v105, v105
	v_mul_f32_e32 v94, v95, v95
	v_mul_f32_e32 v106, v107, v107
	v_mul_f32_e32 v100, v101, v101
	v_pk_add_f32 v[108:109], v[108:109], v[126:127]
	v_pk_add_f32 v[126:127], v[106:107], v[100:101]
	v_pk_add_f32 v[102:103], v[102:103], v[108:109]
	v_pk_add_f32 v[108:109], v[104:105], v[94:95]
	v_mul_f32_e32 v100, 0xbfb8aa3b, v76
	v_pk_add_f32 v[108:109], v[108:109], v[126:127]
	v_exp_f32_e32 v186, v100
	v_pk_add_f32 v[102:103], v[102:103], v[108:109]
	ds_bpermute_b32 v109, v184, v103
	ds_bpermute_b32 v108, v184, v102
	v_mul_f32_e32 v100, 0xbfb8aa3b, v77
	v_exp_f32_e32 v126, v100
	v_mul_f32_e32 v100, 0xbfb8aa3b, v78
	v_exp_f32_e32 v187, v100
	s_waitcnt lgkmcnt(0)
	v_pk_add_f32 v[102:103], v[102:103], v[108:109]
	ds_bpermute_b32 v109, v185, v103
	ds_bpermute_b32 v108, v185, v102
	v_mov_b32_e32 v131, v129
	v_mul_f32_e32 v100, 0xbfb8aa3b, v79
	v_exp_f32_e32 v127, v100
	v_mov_b32_e32 v124, v123
	s_waitcnt lgkmcnt(0)
	v_pk_add_f32 v[102:103], v[102:103], v[108:109]
	v_lshl_add_u64 v[108:109], s[8:9], 0, v[92:93]
	v_pk_mul_f32 v[102:103], v[102:103], s[38:39] op_sel_hi:[1,0]
	v_lshl_add_u64 v[108:109], v[108:109], 0, v[96:97]
	v_fma_f32 v89, -v103, v103, v102
	v_max_f32_e32 v89, 0, v89
	v_add_f32_e32 v89, 0x3a27c5ac, v89
	v_cmp_gt_f32_e32 vcc, s12, v89
	v_mul_f32_e32 v94, 0x4b800000, v89
	v_pk_add_f32 v[132:133], v[132:133], v[102:103] op_sel:[0,1] neg_lo:[0,1] neg_hi:[0,1]
	v_cndmask_b32_e32 v89, v89, v94, vcc
	v_rsq_f32_e32 v89, v89
	v_pk_add_f32 v[128:129], v[130:131], v[102:103] op_sel:[0,1] neg_lo:[0,1] neg_hi:[0,1]
	v_pk_add_f32 v[126:127], v[126:127], 1.0 op_sel_hi:[1,0]
	v_mad_i64_i32 v[92:93], s[10:11], v88, s13, v[86:87]
	v_mul_f32_e32 v94, 0x45800000, v89
	v_cndmask_b32_e32 v94, v89, v94, vcc
	v_lshlrev_b32_e32 v89, 2, v158
	global_load_dwordx4 v[156:159], v89, s[0:1]
	global_load_dwordx4 v[166:169], v89, s[4:5]
	v_pk_mul_f32 v[132:133], v[132:133], v[94:95] op_sel_hi:[1,0]
	v_pk_mul_f32 v[128:129], v[128:129], v[94:95] op_sel_hi:[1,0]
	v_pk_add_f32 v[122:123], v[124:125], v[102:103] op_sel:[0,1] neg_lo:[0,1] neg_hi:[0,1]
	v_mov_b32_e32 v120, v119
	v_pk_mul_f32 v[122:123], v[122:123], v[94:95] op_sel_hi:[1,0]
	v_pk_add_f32 v[118:119], v[120:121], v[102:103] op_sel:[0,1] neg_lo:[0,1] neg_hi:[0,1]
	v_mov_b32_e32 v116, v115
	v_pk_mul_f32 v[118:119], v[118:119], v[94:95] op_sel_hi:[1,0]
	v_pk_add_f32 v[114:115], v[116:117], v[102:103] op_sel:[0,1] neg_lo:[0,1] neg_hi:[0,1]
	s_waitcnt vmcnt(1)
	v_mov_b32_e32 v188, v156
	v_mov_b32_e32 v189, v158
	s_waitcnt vmcnt(0)
	v_mov_b32_e32 v190, v166
	v_mov_b32_e32 v191, v168
	v_pk_fma_f32 v[132:133], v[188:189], v[132:133], v[190:191]
	global_load_dwordx2 v[188:189], v[108:109], off
	v_mov_b32_e32 v158, v157
	v_mov_b32_e32 v168, v167
	v_pk_fma_f32 v[128:129], v[158:159], v[128:129], v[168:169]
	v_pk_mul_f32 v[114:115], v[114:115], v[94:95] op_sel_hi:[1,0]
	s_waitcnt vmcnt(0)
	v_and_b32_e32 v131, 0xffff0000, v189
	v_and_b32_e32 v130, 0xffff0000, v188
	v_pk_add_f32 v[128:129], v[128:129], v[130:131]
	v_pk_add_f32 v[130:131], v[186:187], 1.0 op_sel_hi:[1,0]
	v_lshlrev_b32_e32 v191, 16, v189
	v_div_scale_f32 v100, s[10:11], v131, v131, v78
	v_rcp_f32_e32 v104, v100
	v_lshlrev_b32_e32 v190, 16, v188
	v_pk_add_f32 v[132:133], v[132:133], v[190:191]
	v_fma_f32 v106, -v100, v104, 1.0
	v_fmac_f32_e32 v104, v106, v104
	v_div_scale_f32 v106, vcc, v78, v131, v78
	v_mul_f32_e32 v110, v106, v104
	v_fma_f32 v112, -v100, v110, v106
	v_fmac_f32_e32 v110, v112, v104
	v_fma_f32 v100, -v100, v110, v106
	v_div_fmas_f32 v100, v100, v104, v110
	v_div_fixup_f32 v131, v100, v131, v78
	v_div_scale_f32 v78, s[10:11], v130, v130, v76
	v_rcp_f32_e32 v100, v78
	s_nop 0
	v_fma_f32 v104, -v78, v100, 1.0
	v_fmac_f32_e32 v100, v104, v100
	v_div_scale_f32 v104, vcc, v76, v130, v76
	v_mul_f32_e32 v106, v104, v100
	v_fma_f32 v110, -v78, v106, v104
	v_fmac_f32_e32 v106, v110, v100
	v_fma_f32 v78, -v78, v106, v104
	v_div_fmas_f32 v78, v78, v100, v106
	v_div_fixup_f32 v130, v78, v130, v76
	v_div_scale_f32 v76, s[10:11], v127, v127, v79
	v_rcp_f32_e32 v78, v76
	v_pk_mul_f32 v[130:131], v[130:131], v[132:133]
	v_fma_f32 v100, -v76, v78, 1.0
	v_fmac_f32_e32 v78, v100, v78
	v_div_scale_f32 v100, vcc, v79, v127, v79
	v_mul_f32_e32 v104, v100, v78
	v_fma_f32 v106, -v76, v104, v100
	v_fmac_f32_e32 v104, v106, v78
	v_fma_f32 v76, -v76, v104, v100
	v_div_fmas_f32 v76, v76, v78, v104
	v_div_fixup_f32 v79, v76, v127, v79
	v_div_scale_f32 v76, s[10:11], v126, v126, v77
	v_rcp_f32_e32 v78, v76
	s_nop 0
	v_fma_f32 v100, -v76, v78, 1.0
	v_fmac_f32_e32 v78, v100, v78
	v_div_scale_f32 v100, vcc, v77, v126, v77
	v_mul_f32_e32 v104, v100, v78
	v_fma_f32 v106, -v76, v104, v100
	v_fmac_f32_e32 v104, v106, v78
	v_fma_f32 v76, -v76, v104, v100
	v_div_fmas_f32 v76, v76, v78, v104
	v_div_fixup_f32 v78, v76, v126, v77
	v_pk_mul_f32 v[76:77], v[78:79], v[128:129]
	v_and_b32_sdwa v78, v131, v154 dst_sel:DWORD dst_unused:UNUSED_PAD src0_sel:WORD_1 src1_sel:DWORD
	v_and_b32_sdwa v100, v77, v154 dst_sel:DWORD dst_unused:UNUSED_PAD src0_sel:WORD_1 src1_sel:DWORD
	v_and_b32_sdwa v104, v76, v154 dst_sel:DWORD dst_unused:UNUSED_PAD src0_sel:WORD_1 src1_sel:DWORD
	v_and_b32_sdwa v79, v130, v154 dst_sel:DWORD dst_unused:UNUSED_PAD src0_sel:WORD_1 src1_sel:DWORD
	v_add3_u32 v77, v77, v100, s33
	v_add3_u32 v76, v76, v104, s33
	v_add3_u32 v79, v130, v79, s33
	v_add3_u32 v78, v131, v78, s33
	v_and_b32_e32 v77, 0xffff0000, v77
	v_and_b32_e32 v76, 0xffff0000, v76
	v_or_b32_sdwa v77, v77, v78 dst_sel:DWORD dst_unused:UNUSED_PAD src0_sel:DWORD src1_sel:WORD_1
	v_or_b32_sdwa v76, v76, v79 dst_sel:DWORD dst_unused:UNUSED_PAD src0_sel:DWORD src1_sel:WORD_1
	global_store_dwordx2 v[92:93], v[76:77], off
	global_load_dwordx4 v[126:129], v89, s[0:1] offset:64
	global_load_dwordx4 v[130:133], v89, s[4:5] offset:64
	v_mul_f32_e32 v76, 0xbfb8aa3b, v72
	v_mul_f32_e32 v77, 0xbfb8aa3b, v74
	v_exp_f32_e32 v78, v76
	v_exp_f32_e32 v79, v77
	v_mul_f32_e32 v76, 0xbfb8aa3b, v73
	v_mul_f32_e32 v77, 0xbfb8aa3b, v75
	v_exp_f32_e32 v76, v76
	v_pk_add_f32 v[78:79], v[78:79], 1.0 op_sel_hi:[1,0]
	v_exp_f32_e32 v77, v77
	v_div_scale_f32 v100, s[10:11], v79, v79, v74
	v_rcp_f32_e32 v104, v100
	v_pk_add_f32 v[76:77], v[76:77], 1.0 op_sel_hi:[1,0]
	v_fma_f32 v106, -v100, v104, 1.0
	v_fmac_f32_e32 v104, v106, v104
	v_div_scale_f32 v106, vcc, v74, v79, v74
	v_mul_f32_e32 v110, v106, v104
	v_fma_f32 v112, -v100, v110, v106
	v_fmac_f32_e32 v110, v112, v104
	v_fma_f32 v100, -v100, v110, v106
	v_div_fmas_f32 v100, v100, v104, v110
	v_div_fixup_f32 v79, v100, v79, v74
	v_div_scale_f32 v74, s[10:11], v78, v78, v72
	v_rcp_f32_e32 v100, v74
	v_mov_b32_e32 v112, v111
	v_fma_f32 v104, -v74, v100, 1.0
	v_fmac_f32_e32 v100, v104, v100
	v_div_scale_f32 v104, vcc, v72, v78, v72
	v_mul_f32_e32 v106, v104, v100
	v_fma_f32 v110, -v74, v106, v104
	v_fmac_f32_e32 v106, v110, v100
	v_fma_f32 v74, -v74, v106, v104
	v_div_fmas_f32 v74, v74, v100, v106
	v_div_fixup_f32 v78, v74, v78, v72
	v_div_scale_f32 v72, s[10:11], v77, v77, v75
	v_rcp_f32_e32 v74, v72
	v_pk_add_f32 v[110:111], v[112:113], v[102:103] op_sel:[0,1] neg_lo:[0,1] neg_hi:[0,1]
	v_fma_f32 v100, -v72, v74, 1.0
	v_fmac_f32_e32 v74, v100, v74
	v_div_scale_f32 v100, vcc, v75, v77, v75
	v_mul_f32_e32 v104, v100, v74
	v_fma_f32 v106, -v72, v104, v100
	v_fmac_f32_e32 v104, v106, v74
	v_fma_f32 v72, -v72, v104, v100
	v_div_fmas_f32 v72, v72, v74, v104
	v_div_fixup_f32 v75, v72, v77, v75
	v_div_scale_f32 v72, s[10:11], v76, v76, v73
	v_rcp_f32_e32 v74, v72
	v_pk_mul_f32 v[110:111], v[110:111], v[94:95] op_sel_hi:[1,0]
	v_fma_f32 v77, -v72, v74, 1.0
	v_fmac_f32_e32 v74, v77, v74
	v_div_scale_f32 v77, vcc, v73, v76, v73
	v_mul_f32_e32 v100, v77, v74
	v_fma_f32 v104, -v72, v100, v77
	v_fmac_f32_e32 v100, v104, v74
	v_fma_f32 v72, -v72, v100, v77
	v_div_fmas_f32 v72, v72, v74, v100
	v_div_fixup_f32 v74, v72, v76, v73
	s_waitcnt vmcnt(1)
	v_mov_b32_e32 v124, v126
	v_mov_b32_e32 v125, v128
	s_waitcnt vmcnt(0)
	v_mov_b32_e32 v156, v130
	v_mov_b32_e32 v157, v132
	v_pk_fma_f32 v[122:123], v[122:123], v[124:125], v[156:157]
	global_load_dwordx2 v[124:125], v[108:109], off offset:32
	v_mov_b32_e32 v128, v127
	v_mov_b32_e32 v132, v131
	v_pk_fma_f32 v[118:119], v[118:119], v[128:129], v[132:133]
	s_waitcnt vmcnt(0)
	v_and_b32_e32 v121, 0xffff0000, v125
	v_and_b32_e32 v120, 0xffff0000, v124
	v_lshlrev_b32_e32 v157, 16, v125
	v_lshlrev_b32_e32 v156, 16, v124
	v_pk_add_f32 v[118:119], v[118:119], v[120:121]
	v_pk_add_f32 v[122:123], v[122:123], v[156:157]
	v_pk_mul_f32 v[72:73], v[74:75], v[118:119]
	v_pk_mul_f32 v[78:79], v[78:79], v[122:123]
	v_and_b32_sdwa v76, v73, v154 dst_sel:DWORD dst_unused:UNUSED_PAD src0_sel:WORD_1 src1_sel:DWORD
	v_and_b32_sdwa v77, v72, v154 dst_sel:DWORD dst_unused:UNUSED_PAD src0_sel:WORD_1 src1_sel:DWORD
	v_and_b32_sdwa v74, v79, v154 dst_sel:DWORD dst_unused:UNUSED_PAD src0_sel:WORD_1 src1_sel:DWORD
	v_and_b32_sdwa v75, v78, v154 dst_sel:DWORD dst_unused:UNUSED_PAD src0_sel:WORD_1 src1_sel:DWORD
	v_add3_u32 v73, v73, v76, s33
	v_add3_u32 v72, v72, v77, s33
	v_add3_u32 v75, v78, v75, s33
	v_add3_u32 v74, v79, v74, s33
	v_and_b32_e32 v73, 0xffff0000, v73
	v_and_b32_e32 v72, 0xffff0000, v72
	v_or_b32_sdwa v73, v73, v74 dst_sel:DWORD dst_unused:UNUSED_PAD src0_sel:DWORD src1_sel:WORD_1
	v_or_b32_sdwa v72, v72, v75 dst_sel:DWORD dst_unused:UNUSED_PAD src0_sel:DWORD src1_sel:WORD_1
	global_store_dwordx2 v[92:93], v[72:73], off offset:32
	global_load_dwordx4 v[74:77], v89, s[0:1] offset:128
	global_load_dwordx4 v[118:121], v89, s[4:5] offset:128
	v_mul_f32_e32 v72, 0xbfb8aa3b, v68
	v_mul_f32_e32 v73, 0xbfb8aa3b, v70
	v_exp_f32_e32 v78, v72
	v_exp_f32_e32 v79, v73
	v_mul_f32_e32 v72, 0xbfb8aa3b, v69
	v_mul_f32_e32 v73, 0xbfb8aa3b, v71
	v_exp_f32_e32 v72, v72
	v_exp_f32_e32 v73, v73
	s_waitcnt vmcnt(1)
	v_mov_b32_e32 v116, v74
	v_mov_b32_e32 v117, v76
	s_waitcnt vmcnt(0)
	v_mov_b32_e32 v122, v118
	v_mov_b32_e32 v123, v120
	v_pk_fma_f32 v[114:115], v[114:115], v[116:117], v[122:123]
	global_load_dwordx2 v[116:117], v[108:109], off offset:64
	v_mov_b32_e32 v76, v75
	v_mov_b32_e32 v120, v119
	v_pk_fma_f32 v[74:75], v[110:111], v[76:77], v[120:121]
	v_pk_add_f32 v[72:73], v[72:73], 1.0 op_sel_hi:[1,0]
	s_waitcnt vmcnt(0)
	v_and_b32_e32 v77, 0xffff0000, v117
	v_and_b32_e32 v76, 0xffff0000, v116
	v_pk_add_f32 v[74:75], v[74:75], v[76:77]
	v_pk_add_f32 v[76:77], v[78:79], 1.0 op_sel_hi:[1,0]
	v_lshlrev_b32_e32 v123, 16, v117
	v_div_scale_f32 v78, s[10:11], v77, v77, v70
	v_rcp_f32_e32 v79, v78
	v_lshlrev_b32_e32 v122, 16, v116
	v_pk_add_f32 v[114:115], v[114:115], v[122:123]
	v_fma_f32 v100, -v78, v79, 1.0
	v_fmac_f32_e32 v79, v100, v79
	v_div_scale_f32 v100, vcc, v70, v77, v70
	v_mul_f32_e32 v104, v100, v79
	v_fma_f32 v106, -v78, v104, v100
	v_fmac_f32_e32 v104, v106, v79
	v_fma_f32 v78, -v78, v104, v100
	v_div_fmas_f32 v78, v78, v79, v104
	v_div_fixup_f32 v77, v78, v77, v70
	v_div_scale_f32 v70, s[10:11], v76, v76, v68
	v_rcp_f32_e32 v78, v70
	v_mov_b32_e32 v106, v105
	v_fma_f32 v79, -v70, v78, 1.0
	v_fmac_f32_e32 v78, v79, v78
	v_div_scale_f32 v79, vcc, v68, v76, v68
	v_mul_f32_e32 v100, v79, v78
	v_fma_f32 v104, -v70, v100, v79
	v_fmac_f32_e32 v100, v104, v78
	v_fma_f32 v70, -v70, v100, v79
	v_div_fmas_f32 v70, v70, v78, v100
	v_div_fixup_f32 v76, v70, v76, v68
	v_div_scale_f32 v68, s[10:11], v73, v73, v71
	v_rcp_f32_e32 v70, v68
	v_pk_mul_f32 v[76:77], v[76:77], v[114:115]
	v_pk_add_f32 v[104:105], v[106:107], v[102:103] op_sel:[0,1] neg_lo:[0,1] neg_hi:[0,1]
	v_fma_f32 v78, -v68, v70, 1.0
	v_fmac_f32_e32 v70, v78, v70
	v_div_scale_f32 v78, vcc, v71, v73, v71
	v_mul_f32_e32 v79, v78, v70
	v_fma_f32 v100, -v68, v79, v78
	v_fmac_f32_e32 v79, v100, v70
	v_fma_f32 v68, -v68, v79, v78
	v_div_fmas_f32 v68, v68, v70, v79
	v_div_fixup_f32 v71, v68, v73, v71
	v_div_scale_f32 v68, s[10:11], v72, v72, v69
	v_rcp_f32_e32 v70, v68
	v_pk_mul_f32 v[104:105], v[104:105], v[94:95] op_sel_hi:[1,0]
	v_mov_b32_e32 v100, v95
	v_pk_add_f32 v[100:101], v[100:101], v[102:103] op_sel:[0,1] neg_lo:[0,1] neg_hi:[0,1]
	v_fma_f32 v73, -v68, v70, 1.0
	v_fmac_f32_e32 v70, v73, v70
	v_div_scale_f32 v73, vcc, v69, v72, v69
	v_mul_f32_e32 v78, v73, v70
	v_fma_f32 v79, -v68, v78, v73
	v_fmac_f32_e32 v78, v79, v70
	v_fma_f32 v68, -v68, v78, v73
	v_div_fmas_f32 v68, v68, v70, v78
	v_div_fixup_f32 v70, v68, v72, v69
	v_pk_mul_f32 v[68:69], v[70:71], v[74:75]
	v_and_b32_sdwa v70, v77, v154 dst_sel:DWORD dst_unused:UNUSED_PAD src0_sel:WORD_1 src1_sel:DWORD
	v_and_b32_sdwa v72, v69, v154 dst_sel:DWORD dst_unused:UNUSED_PAD src0_sel:WORD_1 src1_sel:DWORD
	v_and_b32_sdwa v73, v68, v154 dst_sel:DWORD dst_unused:UNUSED_PAD src0_sel:WORD_1 src1_sel:DWORD
	v_and_b32_sdwa v71, v76, v154 dst_sel:DWORD dst_unused:UNUSED_PAD src0_sel:WORD_1 src1_sel:DWORD
	v_add3_u32 v69, v69, v72, s33
	v_add3_u32 v68, v68, v73, s33
	v_add3_u32 v71, v76, v71, s33
	v_add3_u32 v70, v77, v70, s33
	v_and_b32_e32 v69, 0xffff0000, v69
	v_and_b32_e32 v68, 0xffff0000, v68
	v_or_b32_sdwa v69, v69, v70 dst_sel:DWORD dst_unused:UNUSED_PAD src0_sel:DWORD src1_sel:WORD_1
	v_or_b32_sdwa v68, v68, v71 dst_sel:DWORD dst_unused:UNUSED_PAD src0_sel:DWORD src1_sel:WORD_1
	global_store_dwordx2 v[92:93], v[68:69], off offset:64
	global_load_dwordx4 v[70:73], v89, s[0:1] offset:192
	global_load_dwordx4 v[74:77], v89, s[4:5] offset:192
	v_mul_f32_e32 v68, 0xbfb8aa3b, v64
	v_mul_f32_e32 v69, 0xbfb8aa3b, v66
	v_exp_f32_e32 v78, v68
	v_exp_f32_e32 v79, v69
	v_pk_mul_f32 v[94:95], v[100:101], v[94:95] op_sel_hi:[1,0]
	v_mul_f32_e32 v68, 0xbfb8aa3b, v65
	v_mul_f32_e32 v69, 0xbfb8aa3b, v67
	v_exp_f32_e32 v68, v68
	v_exp_f32_e32 v69, v69
	s_waitcnt vmcnt(1)
	v_mov_b32_e32 v106, v70
	v_mov_b32_e32 v107, v72
	s_waitcnt vmcnt(0)
	v_mov_b32_e32 v110, v74
	v_mov_b32_e32 v111, v76
	v_pk_fma_f32 v[104:105], v[104:105], v[106:107], v[110:111]
	global_load_dwordx2 v[106:107], v[108:109], off offset:96
	v_mov_b32_e32 v72, v71
	v_mov_b32_e32 v76, v75
	v_pk_fma_f32 v[70:71], v[94:95], v[72:73], v[76:77]
	v_pk_add_f32 v[68:69], v[68:69], 1.0 op_sel_hi:[1,0]
	s_waitcnt vmcnt(0)
	v_and_b32_e32 v73, 0xffff0000, v107
	v_and_b32_e32 v72, 0xffff0000, v106
	v_pk_add_f32 v[70:71], v[70:71], v[72:73]
	v_pk_add_f32 v[72:73], v[78:79], 1.0 op_sel_hi:[1,0]
	v_lshlrev_b32_e32 v109, 16, v107
	v_div_scale_f32 v74, s[10:11], v73, v73, v66
	v_rcp_f32_e32 v75, v74
	v_lshlrev_b32_e32 v108, 16, v106
	v_pk_add_f32 v[104:105], v[104:105], v[108:109]
	v_fma_f32 v76, -v74, v75, 1.0
	v_fmac_f32_e32 v75, v76, v75
	v_div_scale_f32 v76, vcc, v66, v73, v66
	v_mul_f32_e32 v77, v76, v75
	v_fma_f32 v78, -v74, v77, v76
	v_fmac_f32_e32 v77, v78, v75
	v_fma_f32 v74, -v74, v77, v76
	v_div_fmas_f32 v74, v74, v75, v77
	v_div_fixup_f32 v73, v74, v73, v66
	v_div_scale_f32 v66, s[10:11], v72, v72, v64
	v_rcp_f32_e32 v74, v66
	s_nop 0
	v_fma_f32 v75, -v66, v74, 1.0
	v_fmac_f32_e32 v74, v75, v74
	v_div_scale_f32 v75, vcc, v64, v72, v64
	v_mul_f32_e32 v76, v75, v74
	v_fma_f32 v77, -v66, v76, v75
	v_fmac_f32_e32 v76, v77, v74
	v_fma_f32 v66, -v66, v76, v75
	v_div_fmas_f32 v66, v66, v74, v76
	v_div_fixup_f32 v72, v66, v72, v64
	v_div_scale_f32 v64, s[10:11], v69, v69, v67
	v_rcp_f32_e32 v66, v64
	v_pk_mul_f32 v[72:73], v[72:73], v[104:105]
	v_fma_f32 v74, -v64, v66, 1.0
	v_fmac_f32_e32 v66, v74, v66
	v_div_scale_f32 v74, vcc, v67, v69, v67
	v_mul_f32_e32 v75, v74, v66
	v_fma_f32 v76, -v64, v75, v74
	v_fmac_f32_e32 v75, v76, v66
	v_fma_f32 v64, -v64, v75, v74
	v_div_fmas_f32 v64, v64, v66, v75
	v_div_fixup_f32 v67, v64, v69, v67
	v_div_scale_f32 v64, s[10:11], v68, v68, v65
	v_rcp_f32_e32 v66, v64
	s_nop 0
	v_fma_f32 v69, -v64, v66, 1.0
	v_fmac_f32_e32 v66, v69, v66
	v_div_scale_f32 v69, vcc, v65, v68, v65
	v_mul_f32_e32 v74, v69, v66
	v_fma_f32 v75, -v64, v74, v69
	v_fmac_f32_e32 v74, v75, v66
	v_fma_f32 v64, -v64, v74, v69
	v_div_fmas_f32 v64, v64, v66, v74
	v_div_fixup_f32 v66, v64, v68, v65
	v_pk_mul_f32 v[64:65], v[66:67], v[70:71]
	v_and_b32_sdwa v66, v73, v154 dst_sel:DWORD dst_unused:UNUSED_PAD src0_sel:WORD_1 src1_sel:DWORD
	v_and_b32_sdwa v68, v65, v154 dst_sel:DWORD dst_unused:UNUSED_PAD src0_sel:WORD_1 src1_sel:DWORD
	v_and_b32_sdwa v69, v64, v154 dst_sel:DWORD dst_unused:UNUSED_PAD src0_sel:WORD_1 src1_sel:DWORD
	v_and_b32_sdwa v67, v72, v154 dst_sel:DWORD dst_unused:UNUSED_PAD src0_sel:WORD_1 src1_sel:DWORD
	v_add3_u32 v65, v65, v68, s33
	v_add3_u32 v64, v64, v69, s33
	v_add3_u32 v67, v72, v67, s33
	v_add3_u32 v66, v73, v66, s33
	v_and_b32_e32 v65, 0xffff0000, v65
	v_and_b32_e32 v64, 0xffff0000, v64
	v_or_b32_sdwa v65, v65, v66 dst_sel:DWORD dst_unused:UNUSED_PAD src0_sel:DWORD src1_sel:WORD_1
	v_or_b32_sdwa v64, v64, v67 dst_sel:DWORD dst_unused:UNUSED_PAD src0_sel:DWORD src1_sel:WORD_1
	global_store_dwordx2 v[92:93], v[64:65], off offset:96
	v_add_u32_e32 v64, 16, v88
	v_ashrrev_i32_e32 v65, 31, v64
	v_lshlrev_b64 v[76:77], 11, v[64:65]
	v_lshl_add_u64 v[66:67], v[90:91], 0, v[76:77]
	global_load_dwordx2 v[70:71], v[66:67], off
	global_load_dwordx2 v[68:69], v[66:67], off offset:32
	v_lshl_add_u64 v[76:77], s[8:9], 0, v[76:77]
	v_lshl_add_u64 v[76:77], v[76:77], 0, v[96:97]
	s_waitcnt vmcnt(1)
	v_lshlrev_b32_e32 v118, 16, v70
	s_waitcnt vmcnt(0)
	v_lshlrev_b32_e32 v107, 16, v68
	v_and_b32_e32 v103, 0xffff0000, v68
	v_alignbit_b32 v65, v69, v68, 16
	v_and_b32_e32 v105, 0xffff0000, v69
	global_load_dwordx2 v[68:69], v[66:67], off offset:64
	v_and_b32_e32 v109, 0xffff0000, v65
	v_and_b32_e32 v113, 0xffff0000, v71
	v_and_b32_e32 v116, 0xffff0000, v70
	v_mov_b32_e32 v112, v118
	v_mov_b32_e32 v117, v118
	v_mul_f32_e32 v110, v118, v118
	v_mul_f32_e32 v106, v107, v107
	v_mul_f32_e32 v102, v103, v103
	v_mul_f32_e32 v108, v109, v109
	v_mul_f32_e32 v104, v105, v105
	s_waitcnt vmcnt(0)
	v_lshlrev_b32_e32 v95, 16, v68
	v_and_b32_e32 v79, 0xffff0000, v68
	v_alignbit_b32 v65, v69, v68, 16
	v_and_b32_e32 v93, 0xffff0000, v69
	global_load_dwordx2 v[68:69], v[66:67], off offset:96
	v_and_b32_e32 v101, 0xffff0000, v65
	v_mul_f32_e32 v94, v95, v95
	v_mul_f32_e32 v78, v79, v79
	v_mul_f32_e32 v100, v101, v101
	v_mul_f32_e32 v92, v93, v93
	s_waitcnt vmcnt(0)
	v_alignbit_b32 v65, v69, v68, 16
	v_and_b32_e32 v75, 0xffff0000, v65
	v_alignbit_b32 v65, v71, v70, 16
	v_and_b32_e32 v71, 0xffff0000, v65
	v_and_b32_e32 v70, 16, v70
	v_mov_b32_e32 v65, v118
	v_pk_add_f32 v[114:115], v[70:71], v[112:113]
	v_pk_add_f32 v[120:121], v[116:117], v[64:65] op_sel_hi:[0,1]
	v_mov_b32_e32 v111, v115
	v_pk_mul_f32 v[114:115], v[116:117], v[116:117]
	v_mov_b32_e32 v112, v71
	v_mov_b32_e32 v115, v121
	global_load_dwordx4 v[120:123], v89, s[0:1]
	global_load_dwordx4 v[124:127], v89, s[4:5]
	v_mul_f32_e32 v70, v113, v113
	v_mov_b32_e32 v119, v71
	v_pk_fma_f32 v[70:71], v[112:113], v[112:113], v[70:71] op_sel_hi:[1,1,0]
	v_pk_add_f32 v[110:111], v[110:111], v[114:115]
	v_mov_b32_e32 v71, v97
	v_pk_add_f32 v[70:71], v[110:111], v[70:71]
	v_pk_add_f32 v[110:111], v[106:107], v[102:103]
	v_pk_add_f32 v[114:115], v[108:109], v[104:105]
	v_lshlrev_b32_e32 v73, 16, v68
	v_pk_add_f32 v[110:111], v[110:111], v[114:115]
	v_and_b32_e32 v67, 0xffff0000, v68
	v_and_b32_e32 v69, 0xffff0000, v69
	v_pk_add_f32 v[70:71], v[70:71], v[110:111]
	v_pk_add_f32 v[110:111], v[94:95], v[78:79]
	v_pk_add_f32 v[114:115], v[100:101], v[92:93]
	v_mul_f32_e32 v72, v73, v73
	v_mul_f32_e32 v66, v67, v67
	v_mul_f32_e32 v74, v75, v75
	v_mul_f32_e32 v68, v69, v69
	v_pk_add_f32 v[110:111], v[110:111], v[114:115]
	v_pk_add_f32 v[114:115], v[74:75], v[68:69]
	v_pk_add_f32 v[70:71], v[70:71], v[110:111]
	v_pk_add_f32 v[110:111], v[72:73], v[66:67]
	v_mul_f32_e32 v68, 0xbfb8aa3b, v60
	v_pk_add_f32 v[110:111], v[110:111], v[114:115]
	v_exp_f32_e32 v114, v68
	v_pk_add_f32 v[70:71], v[70:71], v[110:111]
	ds_bpermute_b32 v111, v184, v71
	ds_bpermute_b32 v110, v184, v70
	v_mul_f32_e32 v68, 0xbfb8aa3b, v61
	v_mov_b32_e32 v117, v113
	v_mov_b32_e32 v108, v107
	v_mov_b32_e32 v104, v103
	s_waitcnt lgkmcnt(0)
	v_pk_add_f32 v[70:71], v[70:71], v[110:111]
	ds_bpermute_b32 v111, v185, v71
	ds_bpermute_b32 v110, v185, v70
	v_mov_b32_e32 v100, v95
	s_waitcnt lgkmcnt(0)
	v_pk_add_f32 v[70:71], v[70:71], v[110:111]
	s_nop 0
	v_pk_mul_f32 v[70:71], v[70:71], s[38:39] op_sel_hi:[1,0]
	v_exp_f32_e32 v110, v68
	v_fma_f32 v65, -v71, v71, v70
	v_max_f32_e32 v65, 0, v65
	v_add_f32_e32 v65, 0x3a27c5ac, v65
	v_cmp_gt_f32_e32 vcc, s12, v65
	v_mul_f32_e32 v66, 0x4b800000, v65
	v_pk_add_f32 v[118:119], v[118:119], v[70:71] op_sel:[0,1] neg_lo:[0,1] neg_hi:[0,1]
	v_cndmask_b32_e32 v65, v65, v66, vcc
	v_rsq_f32_e32 v65, v65
	v_mul_f32_e32 v68, 0xbfb8aa3b, v62
	v_exp_f32_e32 v115, v68
	v_mul_f32_e32 v68, 0xbfb8aa3b, v63
	v_mul_f32_e32 v66, 0x45800000, v65
	v_cndmask_b32_e32 v66, v65, v66, vcc
	v_pk_mul_f32 v[118:119], v[118:119], v[66:67] op_sel_hi:[1,0]
	v_pk_add_f32 v[114:115], v[114:115], 1.0 op_sel_hi:[1,0]
	v_exp_f32_e32 v111, v68
	v_div_scale_f32 v68, s[10:11], v115, v115, v62
	v_rcp_f32_e32 v72, v68
	v_pk_add_f32 v[110:111], v[110:111], 1.0 op_sel_hi:[1,0]
	v_pk_add_f32 v[112:113], v[116:117], v[70:71] op_sel:[0,1] neg_lo:[0,1] neg_hi:[0,1]
	v_mad_i64_i32 v[64:65], s[10:11], v64, s13, v[86:87]
	v_fma_f32 v74, -v68, v72, 1.0
	v_fmac_f32_e32 v72, v74, v72
	v_div_scale_f32 v74, vcc, v62, v115, v62
	v_mul_f32_e32 v78, v74, v72
	v_fma_f32 v92, -v68, v78, v74
	v_fmac_f32_e32 v78, v92, v72
	v_fma_f32 v68, -v68, v78, v74
	v_div_fmas_f32 v68, v68, v72, v78
	v_div_fixup_f32 v115, v68, v115, v62
	v_div_scale_f32 v62, s[10:11], v114, v114, v60
	s_waitcnt vmcnt(1)
	v_mov_b32_e32 v128, v120
	v_mov_b32_e32 v129, v122
	s_waitcnt vmcnt(0)
	v_mov_b32_e32 v130, v124
	v_mov_b32_e32 v131, v126
	v_pk_fma_f32 v[118:119], v[128:129], v[118:119], v[130:131]
	global_load_dwordx2 v[128:129], v[76:77], off
	v_rcp_f32_e32 v68, v62
	v_pk_mul_f32 v[112:113], v[112:113], v[66:67] op_sel_hi:[1,0]
	v_mov_b32_e32 v122, v121
	v_mov_b32_e32 v126, v125
	v_fma_f32 v72, -v62, v68, 1.0
	v_fmac_f32_e32 v68, v72, v68
	v_div_scale_f32 v72, vcc, v60, v114, v60
	v_mul_f32_e32 v74, v72, v68
	v_fma_f32 v78, -v62, v74, v72
	v_fmac_f32_e32 v74, v78, v68
	v_fma_f32 v62, -v62, v74, v72
	v_div_fmas_f32 v62, v62, v68, v74
	v_div_fixup_f32 v114, v62, v114, v60
	v_div_scale_f32 v60, s[10:11], v111, v111, v63
	v_rcp_f32_e32 v62, v60
	v_pk_fma_f32 v[112:113], v[122:123], v[112:113], v[126:127]
	v_pk_add_f32 v[106:107], v[108:109], v[70:71] op_sel:[0,1] neg_lo:[0,1] neg_hi:[0,1]
	v_pk_add_f32 v[102:103], v[104:105], v[70:71] op_sel:[0,1] neg_lo:[0,1] neg_hi:[0,1]
	v_fma_f32 v68, -v60, v62, 1.0
	v_fmac_f32_e32 v62, v68, v62
	v_div_scale_f32 v68, vcc, v63, v111, v63
	v_mul_f32_e32 v72, v68, v62
	v_fma_f32 v74, -v60, v72, v68
	v_fmac_f32_e32 v72, v74, v62
	v_fma_f32 v60, -v60, v72, v68
	v_div_fmas_f32 v60, v60, v62, v72
	v_div_fixup_f32 v63, v60, v111, v63
	v_div_scale_f32 v60, s[10:11], v110, v110, v61
	v_rcp_f32_e32 v62, v60
	v_pk_mul_f32 v[106:107], v[106:107], v[66:67] op_sel_hi:[1,0]
	v_pk_mul_f32 v[102:103], v[102:103], v[66:67] op_sel_hi:[1,0]
	v_pk_add_f32 v[94:95], v[100:101], v[70:71] op_sel:[0,1] neg_lo:[0,1] neg_hi:[0,1]
	v_fma_f32 v68, -v60, v62, 1.0
	v_fmac_f32_e32 v62, v68, v62
	v_div_scale_f32 v68, vcc, v61, v110, v61
	v_mul_f32_e32 v72, v68, v62
	v_fma_f32 v74, -v60, v72, v68
	v_fmac_f32_e32 v72, v74, v62
	v_fma_f32 v60, -v60, v72, v68
	v_div_fmas_f32 v60, v60, v62, v72
	v_div_fixup_f32 v62, v60, v110, v61
	v_pk_mul_f32 v[94:95], v[94:95], v[66:67] op_sel_hi:[1,0]
	s_waitcnt vmcnt(0)
	v_and_b32_e32 v117, 0xffff0000, v129
	v_and_b32_e32 v116, 0xffff0000, v128
	v_lshlrev_b32_e32 v131, 16, v129
	v_lshlrev_b32_e32 v130, 16, v128
	v_pk_add_f32 v[112:113], v[112:113], v[116:117]
	v_pk_add_f32 v[118:119], v[118:119], v[130:131]
	v_pk_mul_f32 v[60:61], v[62:63], v[112:113]
	v_pk_mul_f32 v[114:115], v[114:115], v[118:119]
	v_and_b32_sdwa v68, v61, v154 dst_sel:DWORD dst_unused:UNUSED_PAD src0_sel:WORD_1 src1_sel:DWORD
	v_and_b32_sdwa v72, v60, v154 dst_sel:DWORD dst_unused:UNUSED_PAD src0_sel:WORD_1 src1_sel:DWORD
	v_and_b32_sdwa v62, v115, v154 dst_sel:DWORD dst_unused:UNUSED_PAD src0_sel:WORD_1 src1_sel:DWORD
	v_and_b32_sdwa v63, v114, v154 dst_sel:DWORD dst_unused:UNUSED_PAD src0_sel:WORD_1 src1_sel:DWORD
	v_add3_u32 v61, v61, v68, s33
	v_add3_u32 v60, v60, v72, s33
	v_add3_u32 v63, v114, v63, s33
	v_add3_u32 v62, v115, v62, s33
	v_and_b32_e32 v61, 0xffff0000, v61
	v_and_b32_e32 v60, 0xffff0000, v60
	v_or_b32_sdwa v61, v61, v62 dst_sel:DWORD dst_unused:UNUSED_PAD src0_sel:DWORD src1_sel:WORD_1
	v_or_b32_sdwa v60, v60, v63 dst_sel:DWORD dst_unused:UNUSED_PAD src0_sel:DWORD src1_sel:WORD_1
	global_store_dwordx2 v[64:65], v[60:61], off
	global_load_dwordx4 v[110:113], v89, s[0:1] offset:64
	global_load_dwordx4 v[114:117], v89, s[4:5] offset:64
	v_mul_f32_e32 v60, 0xbfb8aa3b, v56
	v_mul_f32_e32 v61, 0xbfb8aa3b, v58
	v_exp_f32_e32 v62, v60
	v_exp_f32_e32 v63, v61
	v_mul_f32_e32 v60, 0xbfb8aa3b, v57
	v_mul_f32_e32 v61, 0xbfb8aa3b, v59
	v_exp_f32_e32 v60, v60
	v_pk_add_f32 v[62:63], v[62:63], 1.0 op_sel_hi:[1,0]
	v_exp_f32_e32 v61, v61
	v_div_scale_f32 v68, s[10:11], v63, v63, v58
	v_rcp_f32_e32 v72, v68
	v_pk_add_f32 v[60:61], v[60:61], 1.0 op_sel_hi:[1,0]
	v_fma_f32 v74, -v68, v72, 1.0
	v_fmac_f32_e32 v72, v74, v72
	v_div_scale_f32 v74, vcc, v58, v63, v58
	v_mul_f32_e32 v78, v74, v72
	v_fma_f32 v92, -v68, v78, v74
	v_fmac_f32_e32 v78, v92, v72
	v_fma_f32 v68, -v68, v78, v74
	v_div_fmas_f32 v68, v68, v72, v78
	v_div_fixup_f32 v63, v68, v63, v58
	v_div_scale_f32 v58, s[10:11], v62, v62, v56
	v_rcp_f32_e32 v68, v58
	v_mov_b32_e32 v92, v79
	v_fma_f32 v72, -v58, v68, 1.0
	v_fmac_f32_e32 v68, v72, v68
	v_div_scale_f32 v72, vcc, v56, v62, v56
	v_mul_f32_e32 v74, v72, v68
	v_fma_f32 v78, -v58, v74, v72
	v_fmac_f32_e32 v74, v78, v68
	v_fma_f32 v58, -v58, v74, v72
	v_div_fmas_f32 v58, v58, v68, v74
	v_div_fixup_f32 v62, v58, v62, v56
	v_div_scale_f32 v56, s[10:11], v61, v61, v59
	v_rcp_f32_e32 v58, v56
	v_pk_add_f32 v[78:79], v[92:93], v[70:71] op_sel:[0,1] neg_lo:[0,1] neg_hi:[0,1]
	v_fma_f32 v68, -v56, v58, 1.0
	v_fmac_f32_e32 v58, v68, v58
	v_div_scale_f32 v68, vcc, v59, v61, v59
	v_mul_f32_e32 v72, v68, v58
	v_fma_f32 v74, -v56, v72, v68
	v_fmac_f32_e32 v72, v74, v58
	v_fma_f32 v56, -v56, v72, v68
	v_div_fmas_f32 v56, v56, v58, v72
	v_div_fixup_f32 v59, v56, v61, v59
	v_div_scale_f32 v56, s[10:11], v60, v60, v57
	v_rcp_f32_e32 v58, v56
	v_pk_mul_f32 v[78:79], v[78:79], v[66:67] op_sel_hi:[1,0]
	v_fma_f32 v61, -v56, v58, 1.0
	v_fmac_f32_e32 v58, v61, v58
	v_div_scale_f32 v61, vcc, v57, v60, v57
	v_mul_f32_e32 v68, v61, v58
	v_fma_f32 v72, -v56, v68, v61
	v_fmac_f32_e32 v68, v72, v58
	v_fma_f32 v56, -v56, v68, v61
	v_div_fmas_f32 v56, v56, v58, v68
	v_div_fixup_f32 v58, v56, v60, v57
	s_waitcnt vmcnt(1)
	v_mov_b32_e32 v108, v110
	v_mov_b32_e32 v109, v112
	s_waitcnt vmcnt(0)
	v_mov_b32_e32 v118, v114
	v_mov_b32_e32 v119, v116
	v_pk_fma_f32 v[106:107], v[106:107], v[108:109], v[118:119]
	global_load_dwordx2 v[108:109], v[76:77], off offset:32
	v_mov_b32_e32 v112, v111
	v_mov_b32_e32 v116, v115
	v_pk_fma_f32 v[102:103], v[102:103], v[112:113], v[116:117]
	s_waitcnt vmcnt(0)
	v_and_b32_e32 v105, 0xffff0000, v109
	v_and_b32_e32 v104, 0xffff0000, v108
	v_lshlrev_b32_e32 v119, 16, v109
	v_lshlrev_b32_e32 v118, 16, v108
	v_pk_add_f32 v[102:103], v[102:103], v[104:105]
	v_pk_add_f32 v[106:107], v[106:107], v[118:119]
	v_pk_mul_f32 v[56:57], v[58:59], v[102:103]
	v_pk_mul_f32 v[62:63], v[62:63], v[106:107]
	v_and_b32_sdwa v60, v57, v154 dst_sel:DWORD dst_unused:UNUSED_PAD src0_sel:WORD_1 src1_sel:DWORD
	v_and_b32_sdwa v61, v56, v154 dst_sel:DWORD dst_unused:UNUSED_PAD src0_sel:WORD_1 src1_sel:DWORD
	v_and_b32_sdwa v58, v63, v154 dst_sel:DWORD dst_unused:UNUSED_PAD src0_sel:WORD_1 src1_sel:DWORD
	v_and_b32_sdwa v59, v62, v154 dst_sel:DWORD dst_unused:UNUSED_PAD src0_sel:WORD_1 src1_sel:DWORD
	v_add3_u32 v57, v57, v60, s33
	v_add3_u32 v56, v56, v61, s33
	v_add3_u32 v59, v62, v59, s33
	v_add3_u32 v58, v63, v58, s33
	v_and_b32_e32 v57, 0xffff0000, v57
	v_and_b32_e32 v56, 0xffff0000, v56
	v_or_b32_sdwa v57, v57, v58 dst_sel:DWORD dst_unused:UNUSED_PAD src0_sel:DWORD src1_sel:WORD_1
	v_or_b32_sdwa v56, v56, v59 dst_sel:DWORD dst_unused:UNUSED_PAD src0_sel:DWORD src1_sel:WORD_1
	global_store_dwordx2 v[64:65], v[56:57], off offset:32
	global_load_dwordx4 v[58:61], v89, s[0:1] offset:128
	global_load_dwordx4 v[102:105], v89, s[4:5] offset:128
	v_mul_f32_e32 v56, 0xbfb8aa3b, v52
	v_mul_f32_e32 v57, 0xbfb8aa3b, v54
	v_exp_f32_e32 v62, v56
	v_exp_f32_e32 v63, v57
	v_mul_f32_e32 v56, 0xbfb8aa3b, v53
	v_mul_f32_e32 v57, 0xbfb8aa3b, v55
	v_exp_f32_e32 v56, v56
	v_exp_f32_e32 v57, v57
	s_waitcnt vmcnt(1)
	v_mov_b32_e32 v100, v58
	v_mov_b32_e32 v101, v60
	s_waitcnt vmcnt(0)
	v_mov_b32_e32 v106, v102
	v_mov_b32_e32 v107, v104
	v_pk_fma_f32 v[94:95], v[94:95], v[100:101], v[106:107]
	global_load_dwordx2 v[100:101], v[76:77], off offset:64
	v_mov_b32_e32 v60, v59
	v_mov_b32_e32 v104, v103
	v_pk_fma_f32 v[58:59], v[78:79], v[60:61], v[104:105]
	v_pk_add_f32 v[56:57], v[56:57], 1.0 op_sel_hi:[1,0]
	s_waitcnt vmcnt(0)
	v_and_b32_e32 v61, 0xffff0000, v101
	v_and_b32_e32 v60, 0xffff0000, v100
	v_pk_add_f32 v[58:59], v[58:59], v[60:61]
	v_pk_add_f32 v[60:61], v[62:63], 1.0 op_sel_hi:[1,0]
	v_lshlrev_b32_e32 v107, 16, v101
	v_div_scale_f32 v62, s[10:11], v61, v61, v54
	v_rcp_f32_e32 v63, v62
	v_lshlrev_b32_e32 v106, 16, v100
	v_pk_add_f32 v[94:95], v[94:95], v[106:107]
	v_fma_f32 v68, -v62, v63, 1.0
	v_fmac_f32_e32 v63, v68, v63
	v_div_scale_f32 v68, vcc, v54, v61, v54
	v_mul_f32_e32 v72, v68, v63
	v_fma_f32 v74, -v62, v72, v68
	v_fmac_f32_e32 v72, v74, v63
	v_fma_f32 v62, -v62, v72, v68
	v_div_fmas_f32 v62, v62, v63, v72
	v_div_fixup_f32 v61, v62, v61, v54
	v_div_scale_f32 v54, s[10:11], v60, v60, v52
	v_rcp_f32_e32 v62, v54
	v_mov_b32_e32 v74, v73
	v_fma_f32 v63, -v54, v62, 1.0
	v_fmac_f32_e32 v62, v63, v62
	v_div_scale_f32 v63, vcc, v52, v60, v52
	v_mul_f32_e32 v68, v63, v62
	v_fma_f32 v72, -v54, v68, v63
	v_fmac_f32_e32 v68, v72, v62
	v_fma_f32 v54, -v54, v68, v63
	v_div_fmas_f32 v54, v54, v62, v68
	v_div_fixup_f32 v60, v54, v60, v52
	v_div_scale_f32 v52, s[10:11], v57, v57, v55
	v_rcp_f32_e32 v54, v52
	v_pk_mul_f32 v[60:61], v[60:61], v[94:95]
	v_pk_add_f32 v[72:73], v[74:75], v[70:71] op_sel:[0,1] neg_lo:[0,1] neg_hi:[0,1]
	v_fma_f32 v62, -v52, v54, 1.0
	v_fmac_f32_e32 v54, v62, v54
	v_div_scale_f32 v62, vcc, v55, v57, v55
	v_mul_f32_e32 v63, v62, v54
	v_fma_f32 v68, -v52, v63, v62
	v_fmac_f32_e32 v63, v68, v54
	v_fma_f32 v52, -v52, v63, v62
	v_div_fmas_f32 v52, v52, v54, v63
	v_div_fixup_f32 v55, v52, v57, v55
	v_div_scale_f32 v52, s[10:11], v56, v56, v53
	v_rcp_f32_e32 v54, v52
	v_pk_mul_f32 v[72:73], v[72:73], v[66:67] op_sel_hi:[1,0]
	v_mov_b32_e32 v68, v67
	v_pk_add_f32 v[68:69], v[68:69], v[70:71] op_sel:[0,1] neg_lo:[0,1] neg_hi:[0,1]
	v_fma_f32 v57, -v52, v54, 1.0
	v_fmac_f32_e32 v54, v57, v54
	v_div_scale_f32 v57, vcc, v53, v56, v53
	v_mul_f32_e32 v62, v57, v54
	v_fma_f32 v63, -v52, v62, v57
	v_fmac_f32_e32 v62, v63, v54
	v_fma_f32 v52, -v52, v62, v57
	v_div_fmas_f32 v52, v52, v54, v62
	v_div_fixup_f32 v54, v52, v56, v53
	v_pk_mul_f32 v[52:53], v[54:55], v[58:59]
	v_and_b32_sdwa v54, v61, v154 dst_sel:DWORD dst_unused:UNUSED_PAD src0_sel:WORD_1 src1_sel:DWORD
	v_and_b32_sdwa v56, v53, v154 dst_sel:DWORD dst_unused:UNUSED_PAD src0_sel:WORD_1 src1_sel:DWORD
	v_and_b32_sdwa v57, v52, v154 dst_sel:DWORD dst_unused:UNUSED_PAD src0_sel:WORD_1 src1_sel:DWORD
	v_and_b32_sdwa v55, v60, v154 dst_sel:DWORD dst_unused:UNUSED_PAD src0_sel:WORD_1 src1_sel:DWORD
	v_add3_u32 v53, v53, v56, s33
	v_add3_u32 v52, v52, v57, s33
	v_add3_u32 v55, v60, v55, s33
	v_add3_u32 v54, v61, v54, s33
	v_and_b32_e32 v53, 0xffff0000, v53
	v_and_b32_e32 v52, 0xffff0000, v52
	v_or_b32_sdwa v53, v53, v54 dst_sel:DWORD dst_unused:UNUSED_PAD src0_sel:DWORD src1_sel:WORD_1
	v_or_b32_sdwa v52, v52, v55 dst_sel:DWORD dst_unused:UNUSED_PAD src0_sel:DWORD src1_sel:WORD_1
	global_store_dwordx2 v[64:65], v[52:53], off offset:64
	global_load_dwordx4 v[54:57], v89, s[0:1] offset:192
	global_load_dwordx4 v[58:61], v89, s[4:5] offset:192
	v_mul_f32_e32 v52, 0xbfb8aa3b, v48
	v_mul_f32_e32 v53, 0xbfb8aa3b, v50
	v_exp_f32_e32 v62, v52
	v_exp_f32_e32 v63, v53
	v_pk_mul_f32 v[66:67], v[68:69], v[66:67] op_sel_hi:[1,0]
	v_mul_f32_e32 v52, 0xbfb8aa3b, v49
	v_mul_f32_e32 v53, 0xbfb8aa3b, v51
	v_exp_f32_e32 v52, v52
	v_exp_f32_e32 v53, v53
	s_waitcnt vmcnt(1)
	v_mov_b32_e32 v74, v54
	v_mov_b32_e32 v75, v56
	s_waitcnt vmcnt(0)
	v_mov_b32_e32 v78, v58
	v_mov_b32_e32 v79, v60
	v_pk_fma_f32 v[72:73], v[72:73], v[74:75], v[78:79]
	global_load_dwordx2 v[74:75], v[76:77], off offset:96
	v_mov_b32_e32 v56, v55
	v_mov_b32_e32 v60, v59
	v_pk_fma_f32 v[54:55], v[66:67], v[56:57], v[60:61]
	v_pk_add_f32 v[52:53], v[52:53], 1.0 op_sel_hi:[1,0]
	s_waitcnt vmcnt(0)
	v_and_b32_e32 v57, 0xffff0000, v75
	v_and_b32_e32 v56, 0xffff0000, v74
	v_pk_add_f32 v[54:55], v[54:55], v[56:57]
	v_pk_add_f32 v[56:57], v[62:63], 1.0 op_sel_hi:[1,0]
	v_lshlrev_b32_e32 v77, 16, v75
	v_div_scale_f32 v58, s[10:11], v57, v57, v50
	v_rcp_f32_e32 v59, v58
	v_lshlrev_b32_e32 v76, 16, v74
	v_pk_add_f32 v[72:73], v[72:73], v[76:77]
	v_fma_f32 v60, -v58, v59, 1.0
	v_fmac_f32_e32 v59, v60, v59
	v_div_scale_f32 v60, vcc, v50, v57, v50
	v_mul_f32_e32 v61, v60, v59
	v_fma_f32 v62, -v58, v61, v60
	v_fmac_f32_e32 v61, v62, v59
	v_fma_f32 v58, -v58, v61, v60
	v_div_fmas_f32 v58, v58, v59, v61
	v_div_fixup_f32 v57, v58, v57, v50
	v_div_scale_f32 v50, s[10:11], v56, v56, v48
	v_rcp_f32_e32 v58, v50
	s_nop 0
	v_fma_f32 v59, -v50, v58, 1.0
	v_fmac_f32_e32 v58, v59, v58
	v_div_scale_f32 v59, vcc, v48, v56, v48
	v_mul_f32_e32 v60, v59, v58
	v_fma_f32 v61, -v50, v60, v59
	v_fmac_f32_e32 v60, v61, v58
	v_fma_f32 v50, -v50, v60, v59
	v_div_fmas_f32 v50, v50, v58, v60
	v_div_fixup_f32 v56, v50, v56, v48
	v_div_scale_f32 v48, s[10:11], v53, v53, v51
	v_rcp_f32_e32 v50, v48
	v_pk_mul_f32 v[56:57], v[56:57], v[72:73]
	v_fma_f32 v58, -v48, v50, 1.0
	v_fmac_f32_e32 v50, v58, v50
	v_div_scale_f32 v58, vcc, v51, v53, v51
	v_mul_f32_e32 v59, v58, v50
	v_fma_f32 v60, -v48, v59, v58
	v_fmac_f32_e32 v59, v60, v50
	v_fma_f32 v48, -v48, v59, v58
	v_div_fmas_f32 v48, v48, v50, v59
	v_div_fixup_f32 v51, v48, v53, v51
	v_div_scale_f32 v48, s[10:11], v52, v52, v49
	v_rcp_f32_e32 v50, v48
	s_nop 0
	v_fma_f32 v53, -v48, v50, 1.0
	v_fmac_f32_e32 v50, v53, v50
	v_div_scale_f32 v53, vcc, v49, v52, v49
	v_mul_f32_e32 v58, v53, v50
	v_fma_f32 v59, -v48, v58, v53
	v_fmac_f32_e32 v58, v59, v50
	v_fma_f32 v48, -v48, v58, v53
	v_div_fmas_f32 v48, v48, v50, v58
	v_div_fixup_f32 v50, v48, v52, v49
	v_pk_mul_f32 v[48:49], v[50:51], v[54:55]
	v_and_b32_sdwa v50, v57, v154 dst_sel:DWORD dst_unused:UNUSED_PAD src0_sel:WORD_1 src1_sel:DWORD
	v_and_b32_sdwa v52, v49, v154 dst_sel:DWORD dst_unused:UNUSED_PAD src0_sel:WORD_1 src1_sel:DWORD
	v_and_b32_sdwa v53, v48, v154 dst_sel:DWORD dst_unused:UNUSED_PAD src0_sel:WORD_1 src1_sel:DWORD
	v_and_b32_sdwa v51, v56, v154 dst_sel:DWORD dst_unused:UNUSED_PAD src0_sel:WORD_1 src1_sel:DWORD
	v_add3_u32 v49, v49, v52, s33
	v_add3_u32 v48, v48, v53, s33
	v_add3_u32 v51, v56, v51, s33
	v_add3_u32 v50, v57, v50, s33
	v_and_b32_e32 v49, 0xffff0000, v49
	v_and_b32_e32 v48, 0xffff0000, v48
	v_or_b32_sdwa v49, v49, v50 dst_sel:DWORD dst_unused:UNUSED_PAD src0_sel:DWORD src1_sel:WORD_1
	v_or_b32_sdwa v48, v48, v51 dst_sel:DWORD dst_unused:UNUSED_PAD src0_sel:DWORD src1_sel:WORD_1
	global_store_dwordx2 v[64:65], v[48:49], off offset:96
	v_add_u32_e32 v48, 32, v88
	v_ashrrev_i32_e32 v49, 31, v48
	v_lshlrev_b64 v[60:61], 11, v[48:49]
	v_lshl_add_u64 v[50:51], v[90:91], 0, v[60:61]
	global_load_dwordx2 v[54:55], v[50:51], off
	global_load_dwordx2 v[52:53], v[50:51], off offset:32
	v_lshl_add_u64 v[60:61], s[8:9], 0, v[60:61]
	v_lshl_add_u64 v[60:61], v[60:61], 0, v[96:97]
	s_waitcnt vmcnt(1)
	v_lshlrev_b32_e32 v102, 16, v54
	s_waitcnt vmcnt(0)
	v_lshlrev_b32_e32 v75, 16, v52
	v_and_b32_e32 v71, 0xffff0000, v52
	v_alignbit_b32 v49, v53, v52, 16
	v_and_b32_e32 v73, 0xffff0000, v53
	global_load_dwordx2 v[52:53], v[50:51], off offset:64
	v_and_b32_e32 v77, 0xffff0000, v49
	v_and_b32_e32 v93, 0xffff0000, v55
	v_and_b32_e32 v100, 0xffff0000, v54
	v_mov_b32_e32 v92, v102
	v_mov_b32_e32 v101, v102
	v_mul_f32_e32 v78, v102, v102
	v_mul_f32_e32 v74, v75, v75
	v_mul_f32_e32 v70, v71, v71
	v_mul_f32_e32 v76, v77, v77
	v_mul_f32_e32 v72, v73, v73
	s_waitcnt vmcnt(0)
	v_lshlrev_b32_e32 v67, 16, v52
	v_and_b32_e32 v63, 0xffff0000, v52
	v_alignbit_b32 v49, v53, v52, 16
	v_and_b32_e32 v65, 0xffff0000, v53
	global_load_dwordx2 v[52:53], v[50:51], off offset:96
	v_and_b32_e32 v69, 0xffff0000, v49
	v_mul_f32_e32 v66, v67, v67
	v_mul_f32_e32 v62, v63, v63
	v_mul_f32_e32 v68, v69, v69
	v_mul_f32_e32 v64, v65, v65
	s_waitcnt vmcnt(0)
	v_alignbit_b32 v49, v53, v52, 16
	v_and_b32_e32 v59, 0xffff0000, v49
	v_alignbit_b32 v49, v55, v54, 16
	v_and_b32_e32 v55, 0xffff0000, v49
	v_and_b32_e32 v54, 16, v54
	v_mov_b32_e32 v49, v102
	v_pk_add_f32 v[94:95], v[54:55], v[92:93]
	v_pk_add_f32 v[104:105], v[100:101], v[48:49] op_sel_hi:[0,1]
	v_mov_b32_e32 v79, v95
	v_pk_mul_f32 v[94:95], v[100:101], v[100:101]
	v_mov_b32_e32 v92, v55
	v_mov_b32_e32 v95, v105
	global_load_dwordx4 v[104:107], v89, s[0:1]
	global_load_dwordx4 v[108:111], v89, s[4:5]
	v_mul_f32_e32 v54, v93, v93
	v_mov_b32_e32 v103, v55
	v_pk_fma_f32 v[54:55], v[92:93], v[92:93], v[54:55] op_sel_hi:[1,1,0]
	v_pk_add_f32 v[78:79], v[78:79], v[94:95]
	v_mov_b32_e32 v55, v97
	v_pk_add_f32 v[54:55], v[78:79], v[54:55]
	v_pk_add_f32 v[78:79], v[74:75], v[70:71]
	v_pk_add_f32 v[94:95], v[76:77], v[72:73]
	v_lshlrev_b32_e32 v57, 16, v52
	v_pk_add_f32 v[78:79], v[78:79], v[94:95]
	v_and_b32_e32 v51, 0xffff0000, v52
	v_and_b32_e32 v53, 0xffff0000, v53
	v_pk_add_f32 v[54:55], v[54:55], v[78:79]
	v_pk_add_f32 v[78:79], v[66:67], v[62:63]
	v_pk_add_f32 v[94:95], v[68:69], v[64:65]
	v_mul_f32_e32 v56, v57, v57
	v_mul_f32_e32 v50, v51, v51
	v_mul_f32_e32 v58, v59, v59
	v_mul_f32_e32 v52, v53, v53
	v_pk_add_f32 v[78:79], v[78:79], v[94:95]
	v_pk_add_f32 v[94:95], v[58:59], v[52:53]
	v_pk_add_f32 v[54:55], v[54:55], v[78:79]
	v_pk_add_f32 v[78:79], v[56:57], v[50:51]
	v_mul_f32_e32 v52, 0xbfb8aa3b, v44
	v_pk_add_f32 v[78:79], v[78:79], v[94:95]
	v_exp_f32_e32 v94, v52
	v_pk_add_f32 v[54:55], v[54:55], v[78:79]
	ds_bpermute_b32 v79, v184, v55
	ds_bpermute_b32 v78, v184, v54
	v_mul_f32_e32 v52, 0xbfb8aa3b, v45
	v_mov_b32_e32 v101, v93
	v_mov_b32_e32 v76, v75
	v_mov_b32_e32 v72, v71
	s_waitcnt lgkmcnt(0)
	v_pk_add_f32 v[54:55], v[54:55], v[78:79]
	ds_bpermute_b32 v79, v185, v55
	ds_bpermute_b32 v78, v185, v54
	v_mov_b32_e32 v68, v67
	s_waitcnt lgkmcnt(0)
	v_pk_add_f32 v[54:55], v[54:55], v[78:79]
	s_nop 0
	v_pk_mul_f32 v[54:55], v[54:55], s[38:39] op_sel_hi:[1,0]
	v_exp_f32_e32 v78, v52
	v_fma_f32 v49, -v55, v55, v54
	v_max_f32_e32 v49, 0, v49
	v_add_f32_e32 v49, 0x3a27c5ac, v49
	v_cmp_gt_f32_e32 vcc, s12, v49
	v_mul_f32_e32 v50, 0x4b800000, v49
	v_pk_add_f32 v[102:103], v[102:103], v[54:55] op_sel:[0,1] neg_lo:[0,1] neg_hi:[0,1]
	v_cndmask_b32_e32 v49, v49, v50, vcc
	v_rsq_f32_e32 v49, v49
	v_mul_f32_e32 v52, 0xbfb8aa3b, v46
	v_exp_f32_e32 v95, v52
	v_mul_f32_e32 v52, 0xbfb8aa3b, v47
	v_mul_f32_e32 v50, 0x45800000, v49
	v_cndmask_b32_e32 v50, v49, v50, vcc
	v_pk_mul_f32 v[102:103], v[102:103], v[50:51] op_sel_hi:[1,0]
	v_pk_add_f32 v[94:95], v[94:95], 1.0 op_sel_hi:[1,0]
	v_exp_f32_e32 v79, v52
	v_div_scale_f32 v52, s[10:11], v95, v95, v46
	v_rcp_f32_e32 v56, v52
	v_pk_add_f32 v[78:79], v[78:79], 1.0 op_sel_hi:[1,0]
	v_pk_add_f32 v[92:93], v[100:101], v[54:55] op_sel:[0,1] neg_lo:[0,1] neg_hi:[0,1]
	v_mad_i64_i32 v[48:49], s[10:11], v48, s13, v[86:87]
	v_fma_f32 v58, -v52, v56, 1.0
	v_fmac_f32_e32 v56, v58, v56
	v_div_scale_f32 v58, vcc, v46, v95, v46
	v_mul_f32_e32 v62, v58, v56
	v_fma_f32 v64, -v52, v62, v58
	v_fmac_f32_e32 v62, v64, v56
	v_fma_f32 v52, -v52, v62, v58
	v_div_fmas_f32 v52, v52, v56, v62
	v_div_fixup_f32 v95, v52, v95, v46
	v_div_scale_f32 v46, s[10:11], v94, v94, v44
	s_waitcnt vmcnt(1)
	v_mov_b32_e32 v112, v104
	v_mov_b32_e32 v113, v106
	s_waitcnt vmcnt(0)
	v_mov_b32_e32 v114, v108
	v_mov_b32_e32 v115, v110
	v_pk_fma_f32 v[102:103], v[112:113], v[102:103], v[114:115]
	global_load_dwordx2 v[112:113], v[60:61], off
	v_rcp_f32_e32 v52, v46
	v_pk_mul_f32 v[92:93], v[92:93], v[50:51] op_sel_hi:[1,0]
	v_mov_b32_e32 v106, v105
	v_mov_b32_e32 v110, v109
	v_fma_f32 v56, -v46, v52, 1.0
	v_fmac_f32_e32 v52, v56, v52
	v_div_scale_f32 v56, vcc, v44, v94, v44
	v_mul_f32_e32 v58, v56, v52
	v_fma_f32 v62, -v46, v58, v56
	v_fmac_f32_e32 v58, v62, v52
	v_fma_f32 v46, -v46, v58, v56
	v_div_fmas_f32 v46, v46, v52, v58
	v_div_fixup_f32 v94, v46, v94, v44
	v_div_scale_f32 v44, s[10:11], v79, v79, v47
	v_rcp_f32_e32 v46, v44
	v_pk_fma_f32 v[92:93], v[106:107], v[92:93], v[110:111]
	v_pk_add_f32 v[74:75], v[76:77], v[54:55] op_sel:[0,1] neg_lo:[0,1] neg_hi:[0,1]
	v_pk_add_f32 v[70:71], v[72:73], v[54:55] op_sel:[0,1] neg_lo:[0,1] neg_hi:[0,1]
	v_fma_f32 v52, -v44, v46, 1.0
	v_fmac_f32_e32 v46, v52, v46
	v_div_scale_f32 v52, vcc, v47, v79, v47
	v_mul_f32_e32 v56, v52, v46
	v_fma_f32 v58, -v44, v56, v52
	v_fmac_f32_e32 v56, v58, v46
	v_fma_f32 v44, -v44, v56, v52
	v_div_fmas_f32 v44, v44, v46, v56
	v_div_fixup_f32 v47, v44, v79, v47
	v_div_scale_f32 v44, s[10:11], v78, v78, v45
	v_rcp_f32_e32 v46, v44
	v_pk_mul_f32 v[74:75], v[74:75], v[50:51] op_sel_hi:[1,0]
	v_pk_mul_f32 v[70:71], v[70:71], v[50:51] op_sel_hi:[1,0]
	v_pk_add_f32 v[66:67], v[68:69], v[54:55] op_sel:[0,1] neg_lo:[0,1] neg_hi:[0,1]
	v_fma_f32 v52, -v44, v46, 1.0
	v_fmac_f32_e32 v46, v52, v46
	v_div_scale_f32 v52, vcc, v45, v78, v45
	v_mul_f32_e32 v56, v52, v46
	v_fma_f32 v58, -v44, v56, v52
	v_fmac_f32_e32 v56, v58, v46
	v_fma_f32 v44, -v44, v56, v52
	v_div_fmas_f32 v44, v44, v46, v56
	v_div_fixup_f32 v46, v44, v78, v45
	v_pk_mul_f32 v[66:67], v[66:67], v[50:51] op_sel_hi:[1,0]
	s_waitcnt vmcnt(0)
	v_and_b32_e32 v101, 0xffff0000, v113
	v_and_b32_e32 v100, 0xffff0000, v112
	v_lshlrev_b32_e32 v115, 16, v113
	v_lshlrev_b32_e32 v114, 16, v112
	v_pk_add_f32 v[92:93], v[92:93], v[100:101]
	v_pk_add_f32 v[102:103], v[102:103], v[114:115]
	v_pk_mul_f32 v[44:45], v[46:47], v[92:93]
	v_pk_mul_f32 v[94:95], v[94:95], v[102:103]
	v_and_b32_sdwa v52, v45, v154 dst_sel:DWORD dst_unused:UNUSED_PAD src0_sel:WORD_1 src1_sel:DWORD
	v_and_b32_sdwa v56, v44, v154 dst_sel:DWORD dst_unused:UNUSED_PAD src0_sel:WORD_1 src1_sel:DWORD
	v_and_b32_sdwa v46, v95, v154 dst_sel:DWORD dst_unused:UNUSED_PAD src0_sel:WORD_1 src1_sel:DWORD
	v_and_b32_sdwa v47, v94, v154 dst_sel:DWORD dst_unused:UNUSED_PAD src0_sel:WORD_1 src1_sel:DWORD
	v_add3_u32 v45, v45, v52, s33
	v_add3_u32 v44, v44, v56, s33
	v_add3_u32 v47, v94, v47, s33
	v_add3_u32 v46, v95, v46, s33
	v_and_b32_e32 v45, 0xffff0000, v45
	v_and_b32_e32 v44, 0xffff0000, v44
	v_or_b32_sdwa v45, v45, v46 dst_sel:DWORD dst_unused:UNUSED_PAD src0_sel:DWORD src1_sel:WORD_1
	v_or_b32_sdwa v44, v44, v47 dst_sel:DWORD dst_unused:UNUSED_PAD src0_sel:DWORD src1_sel:WORD_1
	global_store_dwordx2 v[48:49], v[44:45], off
	global_load_dwordx4 v[92:95], v89, s[0:1] offset:64
	global_load_dwordx4 v[100:103], v89, s[4:5] offset:64
	v_mul_f32_e32 v44, 0xbfb8aa3b, v40
	v_mul_f32_e32 v45, 0xbfb8aa3b, v42
	v_exp_f32_e32 v46, v44
	v_exp_f32_e32 v47, v45
	v_mul_f32_e32 v44, 0xbfb8aa3b, v41
	v_mul_f32_e32 v45, 0xbfb8aa3b, v43
	v_exp_f32_e32 v44, v44
	v_pk_add_f32 v[46:47], v[46:47], 1.0 op_sel_hi:[1,0]
	v_exp_f32_e32 v45, v45
	v_div_scale_f32 v52, s[10:11], v47, v47, v42
	v_rcp_f32_e32 v56, v52
	v_pk_add_f32 v[44:45], v[44:45], 1.0 op_sel_hi:[1,0]
	v_fma_f32 v58, -v52, v56, 1.0
	v_fmac_f32_e32 v56, v58, v56
	v_div_scale_f32 v58, vcc, v42, v47, v42
	v_mul_f32_e32 v62, v58, v56
	v_fma_f32 v64, -v52, v62, v58
	v_fmac_f32_e32 v62, v64, v56
	v_fma_f32 v52, -v52, v62, v58
	v_div_fmas_f32 v52, v52, v56, v62
	v_div_fixup_f32 v47, v52, v47, v42
	v_div_scale_f32 v42, s[10:11], v46, v46, v40
	v_rcp_f32_e32 v52, v42
	v_mov_b32_e32 v64, v63
	v_fma_f32 v56, -v42, v52, 1.0
	v_fmac_f32_e32 v52, v56, v52
	v_div_scale_f32 v56, vcc, v40, v46, v40
	v_mul_f32_e32 v58, v56, v52
	v_fma_f32 v62, -v42, v58, v56
	v_fmac_f32_e32 v58, v62, v52
	v_fma_f32 v42, -v42, v58, v56
	v_div_fmas_f32 v42, v42, v52, v58
	v_div_fixup_f32 v46, v42, v46, v40
	v_div_scale_f32 v40, s[10:11], v45, v45, v43
	v_rcp_f32_e32 v42, v40
	v_pk_add_f32 v[62:63], v[64:65], v[54:55] op_sel:[0,1] neg_lo:[0,1] neg_hi:[0,1]
	v_fma_f32 v52, -v40, v42, 1.0
	v_fmac_f32_e32 v42, v52, v42
	v_div_scale_f32 v52, vcc, v43, v45, v43
	v_mul_f32_e32 v56, v52, v42
	v_fma_f32 v58, -v40, v56, v52
	v_fmac_f32_e32 v56, v58, v42
	v_fma_f32 v40, -v40, v56, v52
	v_div_fmas_f32 v40, v40, v42, v56
	v_div_fixup_f32 v43, v40, v45, v43
	v_div_scale_f32 v40, s[10:11], v44, v44, v41
	v_rcp_f32_e32 v42, v40
	v_pk_mul_f32 v[62:63], v[62:63], v[50:51] op_sel_hi:[1,0]
	v_fma_f32 v45, -v40, v42, 1.0
	v_fmac_f32_e32 v42, v45, v42
	v_div_scale_f32 v45, vcc, v41, v44, v41
	v_mul_f32_e32 v52, v45, v42
	v_fma_f32 v56, -v40, v52, v45
	v_fmac_f32_e32 v52, v56, v42
	v_fma_f32 v40, -v40, v52, v45
	v_div_fmas_f32 v40, v40, v42, v52
	v_div_fixup_f32 v42, v40, v44, v41
	s_waitcnt vmcnt(1)
	v_mov_b32_e32 v76, v92
	v_mov_b32_e32 v77, v94
	s_waitcnt vmcnt(0)
	v_mov_b32_e32 v78, v100
	v_mov_b32_e32 v79, v102
	v_pk_fma_f32 v[74:75], v[74:75], v[76:77], v[78:79]
	global_load_dwordx2 v[76:77], v[60:61], off offset:32
	v_mov_b32_e32 v94, v93
	v_mov_b32_e32 v102, v101
	v_pk_fma_f32 v[70:71], v[70:71], v[94:95], v[102:103]
	s_waitcnt vmcnt(0)
	v_and_b32_e32 v73, 0xffff0000, v77
	v_and_b32_e32 v72, 0xffff0000, v76
	v_lshlrev_b32_e32 v79, 16, v77
	v_lshlrev_b32_e32 v78, 16, v76
	v_pk_add_f32 v[70:71], v[70:71], v[72:73]
	v_pk_add_f32 v[74:75], v[74:75], v[78:79]
	v_pk_mul_f32 v[40:41], v[42:43], v[70:71]
	v_pk_mul_f32 v[46:47], v[46:47], v[74:75]
	v_and_b32_sdwa v44, v41, v154 dst_sel:DWORD dst_unused:UNUSED_PAD src0_sel:WORD_1 src1_sel:DWORD
	v_and_b32_sdwa v45, v40, v154 dst_sel:DWORD dst_unused:UNUSED_PAD src0_sel:WORD_1 src1_sel:DWORD
	v_and_b32_sdwa v42, v47, v154 dst_sel:DWORD dst_unused:UNUSED_PAD src0_sel:WORD_1 src1_sel:DWORD
	v_and_b32_sdwa v43, v46, v154 dst_sel:DWORD dst_unused:UNUSED_PAD src0_sel:WORD_1 src1_sel:DWORD
	v_add3_u32 v41, v41, v44, s33
	v_add3_u32 v40, v40, v45, s33
	v_add3_u32 v43, v46, v43, s33
	v_add3_u32 v42, v47, v42, s33
	v_and_b32_e32 v41, 0xffff0000, v41
	v_and_b32_e32 v40, 0xffff0000, v40
	v_or_b32_sdwa v41, v41, v42 dst_sel:DWORD dst_unused:UNUSED_PAD src0_sel:DWORD src1_sel:WORD_1
	v_or_b32_sdwa v40, v40, v43 dst_sel:DWORD dst_unused:UNUSED_PAD src0_sel:DWORD src1_sel:WORD_1
	global_store_dwordx2 v[48:49], v[40:41], off offset:32
	global_load_dwordx4 v[42:45], v89, s[0:1] offset:128
	global_load_dwordx4 v[70:73], v89, s[4:5] offset:128
	v_mul_f32_e32 v40, 0xbfb8aa3b, v36
	v_mul_f32_e32 v41, 0xbfb8aa3b, v38
	v_exp_f32_e32 v46, v40
	v_exp_f32_e32 v47, v41
	v_mul_f32_e32 v40, 0xbfb8aa3b, v37
	v_mul_f32_e32 v41, 0xbfb8aa3b, v39
	v_exp_f32_e32 v40, v40
	v_exp_f32_e32 v41, v41
	s_waitcnt vmcnt(1)
	v_mov_b32_e32 v68, v42
	v_mov_b32_e32 v69, v44
	s_waitcnt vmcnt(0)
	v_mov_b32_e32 v74, v70
	v_mov_b32_e32 v75, v72
	v_pk_fma_f32 v[66:67], v[66:67], v[68:69], v[74:75]
	global_load_dwordx2 v[68:69], v[60:61], off offset:64
	v_mov_b32_e32 v44, v43
	v_mov_b32_e32 v72, v71
	v_pk_fma_f32 v[42:43], v[62:63], v[44:45], v[72:73]
	v_pk_add_f32 v[40:41], v[40:41], 1.0 op_sel_hi:[1,0]
	s_waitcnt vmcnt(0)
	v_and_b32_e32 v45, 0xffff0000, v69
	v_and_b32_e32 v44, 0xffff0000, v68
	v_pk_add_f32 v[42:43], v[42:43], v[44:45]
	v_pk_add_f32 v[44:45], v[46:47], 1.0 op_sel_hi:[1,0]
	v_lshlrev_b32_e32 v75, 16, v69
	v_div_scale_f32 v46, s[10:11], v45, v45, v38
	v_rcp_f32_e32 v47, v46
	v_lshlrev_b32_e32 v74, 16, v68
	v_pk_add_f32 v[66:67], v[66:67], v[74:75]
	v_fma_f32 v52, -v46, v47, 1.0
	v_fmac_f32_e32 v47, v52, v47
	v_div_scale_f32 v52, vcc, v38, v45, v38
	v_mul_f32_e32 v56, v52, v47
	v_fma_f32 v58, -v46, v56, v52
	v_fmac_f32_e32 v56, v58, v47
	v_fma_f32 v46, -v46, v56, v52
	v_div_fmas_f32 v46, v46, v47, v56
	v_div_fixup_f32 v45, v46, v45, v38
	v_div_scale_f32 v38, s[10:11], v44, v44, v36
	v_rcp_f32_e32 v46, v38
	v_mov_b32_e32 v58, v57
	v_fma_f32 v47, -v38, v46, 1.0
	v_fmac_f32_e32 v46, v47, v46
	v_div_scale_f32 v47, vcc, v36, v44, v36
	v_mul_f32_e32 v52, v47, v46
	v_fma_f32 v56, -v38, v52, v47
	v_fmac_f32_e32 v52, v56, v46
	v_fma_f32 v38, -v38, v52, v47
	v_div_fmas_f32 v38, v38, v46, v52
	v_div_fixup_f32 v44, v38, v44, v36
	v_div_scale_f32 v36, s[10:11], v41, v41, v39
	v_rcp_f32_e32 v38, v36
	v_pk_mul_f32 v[44:45], v[44:45], v[66:67]
	v_pk_add_f32 v[56:57], v[58:59], v[54:55] op_sel:[0,1] neg_lo:[0,1] neg_hi:[0,1]
	v_fma_f32 v46, -v36, v38, 1.0
	v_fmac_f32_e32 v38, v46, v38
	v_div_scale_f32 v46, vcc, v39, v41, v39
	v_mul_f32_e32 v47, v46, v38
	v_fma_f32 v52, -v36, v47, v46
	v_fmac_f32_e32 v47, v52, v38
	v_fma_f32 v36, -v36, v47, v46
	v_div_fmas_f32 v36, v36, v38, v47
	v_div_fixup_f32 v39, v36, v41, v39
	v_div_scale_f32 v36, s[10:11], v40, v40, v37
	v_rcp_f32_e32 v38, v36
	v_pk_mul_f32 v[56:57], v[56:57], v[50:51] op_sel_hi:[1,0]
	v_mov_b32_e32 v52, v51
	v_pk_add_f32 v[52:53], v[52:53], v[54:55] op_sel:[0,1] neg_lo:[0,1] neg_hi:[0,1]
	v_fma_f32 v41, -v36, v38, 1.0
	v_fmac_f32_e32 v38, v41, v38
	v_div_scale_f32 v41, vcc, v37, v40, v37
	v_mul_f32_e32 v46, v41, v38
	v_fma_f32 v47, -v36, v46, v41
	v_fmac_f32_e32 v46, v47, v38
	v_fma_f32 v36, -v36, v46, v41
	v_div_fmas_f32 v36, v36, v38, v46
	v_div_fixup_f32 v38, v36, v40, v37
	v_pk_mul_f32 v[36:37], v[38:39], v[42:43]
	v_and_b32_sdwa v38, v45, v154 dst_sel:DWORD dst_unused:UNUSED_PAD src0_sel:WORD_1 src1_sel:DWORD
	v_and_b32_sdwa v40, v37, v154 dst_sel:DWORD dst_unused:UNUSED_PAD src0_sel:WORD_1 src1_sel:DWORD
	v_and_b32_sdwa v41, v36, v154 dst_sel:DWORD dst_unused:UNUSED_PAD src0_sel:WORD_1 src1_sel:DWORD
	v_and_b32_sdwa v39, v44, v154 dst_sel:DWORD dst_unused:UNUSED_PAD src0_sel:WORD_1 src1_sel:DWORD
	v_add3_u32 v37, v37, v40, s33
	v_add3_u32 v36, v36, v41, s33
	v_add3_u32 v39, v44, v39, s33
	v_add3_u32 v38, v45, v38, s33
	v_and_b32_e32 v37, 0xffff0000, v37
	v_and_b32_e32 v36, 0xffff0000, v36
	v_or_b32_sdwa v37, v37, v38 dst_sel:DWORD dst_unused:UNUSED_PAD src0_sel:DWORD src1_sel:WORD_1
	v_or_b32_sdwa v36, v36, v39 dst_sel:DWORD dst_unused:UNUSED_PAD src0_sel:DWORD src1_sel:WORD_1
	global_store_dwordx2 v[48:49], v[36:37], off offset:64
	global_load_dwordx4 v[38:41], v89, s[0:1] offset:192
	global_load_dwordx4 v[42:45], v89, s[4:5] offset:192
	v_mul_f32_e32 v36, 0xbfb8aa3b, v32
	v_mul_f32_e32 v37, 0xbfb8aa3b, v34
	v_exp_f32_e32 v46, v36
	v_exp_f32_e32 v47, v37
	v_pk_mul_f32 v[50:51], v[52:53], v[50:51] op_sel_hi:[1,0]
	v_mul_f32_e32 v36, 0xbfb8aa3b, v33
	v_mul_f32_e32 v37, 0xbfb8aa3b, v35
	v_exp_f32_e32 v36, v36
	v_exp_f32_e32 v37, v37
	s_waitcnt vmcnt(1)
	v_mov_b32_e32 v58, v38
	v_mov_b32_e32 v59, v40
	s_waitcnt vmcnt(0)
	v_mov_b32_e32 v62, v42
	v_mov_b32_e32 v63, v44
	v_pk_fma_f32 v[56:57], v[56:57], v[58:59], v[62:63]
	global_load_dwordx2 v[58:59], v[60:61], off offset:96
	v_mov_b32_e32 v40, v39
	v_mov_b32_e32 v44, v43
	v_pk_fma_f32 v[38:39], v[50:51], v[40:41], v[44:45]
	v_pk_add_f32 v[36:37], v[36:37], 1.0 op_sel_hi:[1,0]
	s_waitcnt vmcnt(0)
	v_and_b32_e32 v41, 0xffff0000, v59
	v_and_b32_e32 v40, 0xffff0000, v58
	v_pk_add_f32 v[38:39], v[38:39], v[40:41]
	v_pk_add_f32 v[40:41], v[46:47], 1.0 op_sel_hi:[1,0]
	v_lshlrev_b32_e32 v61, 16, v59
	v_div_scale_f32 v42, s[10:11], v41, v41, v34
	v_rcp_f32_e32 v43, v42
	v_lshlrev_b32_e32 v60, 16, v58
	v_pk_add_f32 v[56:57], v[56:57], v[60:61]
	v_fma_f32 v44, -v42, v43, 1.0
	v_fmac_f32_e32 v43, v44, v43
	v_div_scale_f32 v44, vcc, v34, v41, v34
	v_mul_f32_e32 v45, v44, v43
	v_fma_f32 v46, -v42, v45, v44
	v_fmac_f32_e32 v45, v46, v43
	v_fma_f32 v42, -v42, v45, v44
	v_div_fmas_f32 v42, v42, v43, v45
	v_div_fixup_f32 v41, v42, v41, v34
	v_div_scale_f32 v34, s[10:11], v40, v40, v32
	v_rcp_f32_e32 v42, v34
	s_nop 0
	v_fma_f32 v43, -v34, v42, 1.0
	v_fmac_f32_e32 v42, v43, v42
	v_div_scale_f32 v43, vcc, v32, v40, v32
	v_mul_f32_e32 v44, v43, v42
	v_fma_f32 v45, -v34, v44, v43
	v_fmac_f32_e32 v44, v45, v42
	v_fma_f32 v34, -v34, v44, v43
	v_div_fmas_f32 v34, v34, v42, v44
	v_div_fixup_f32 v40, v34, v40, v32
	v_div_scale_f32 v32, s[10:11], v37, v37, v35
	v_rcp_f32_e32 v34, v32
	v_pk_mul_f32 v[40:41], v[40:41], v[56:57]
	v_fma_f32 v42, -v32, v34, 1.0
	v_fmac_f32_e32 v34, v42, v34
	v_div_scale_f32 v42, vcc, v35, v37, v35
	v_mul_f32_e32 v43, v42, v34
	v_fma_f32 v44, -v32, v43, v42
	v_fmac_f32_e32 v43, v44, v34
	v_fma_f32 v32, -v32, v43, v42
	v_div_fmas_f32 v32, v32, v34, v43
	v_div_fixup_f32 v35, v32, v37, v35
	v_div_scale_f32 v32, s[10:11], v36, v36, v33
	v_rcp_f32_e32 v34, v32
	s_nop 0
	v_fma_f32 v37, -v32, v34, 1.0
	v_fmac_f32_e32 v34, v37, v34
	v_div_scale_f32 v37, vcc, v33, v36, v33
	v_mul_f32_e32 v42, v37, v34
	v_fma_f32 v43, -v32, v42, v37
	v_fmac_f32_e32 v42, v43, v34
	v_fma_f32 v32, -v32, v42, v37
	v_div_fmas_f32 v32, v32, v34, v42
	v_div_fixup_f32 v34, v32, v36, v33
	v_pk_mul_f32 v[32:33], v[34:35], v[38:39]
	v_and_b32_sdwa v34, v41, v154 dst_sel:DWORD dst_unused:UNUSED_PAD src0_sel:WORD_1 src1_sel:DWORD
	v_and_b32_sdwa v36, v33, v154 dst_sel:DWORD dst_unused:UNUSED_PAD src0_sel:WORD_1 src1_sel:DWORD
	v_and_b32_sdwa v37, v32, v154 dst_sel:DWORD dst_unused:UNUSED_PAD src0_sel:WORD_1 src1_sel:DWORD
	v_and_b32_sdwa v35, v40, v154 dst_sel:DWORD dst_unused:UNUSED_PAD src0_sel:WORD_1 src1_sel:DWORD
	v_add3_u32 v33, v33, v36, s33
	v_add3_u32 v32, v32, v37, s33
	v_add3_u32 v35, v40, v35, s33
	v_add3_u32 v34, v41, v34, s33
	v_and_b32_e32 v33, 0xffff0000, v33
	v_and_b32_e32 v32, 0xffff0000, v32
	v_or_b32_sdwa v33, v33, v34 dst_sel:DWORD dst_unused:UNUSED_PAD src0_sel:DWORD src1_sel:WORD_1
	v_or_b32_sdwa v32, v32, v35 dst_sel:DWORD dst_unused:UNUSED_PAD src0_sel:DWORD src1_sel:WORD_1
	global_store_dwordx2 v[48:49], v[32:33], off offset:96
	v_add_u32_e32 v32, 48, v88
	v_ashrrev_i32_e32 v33, 31, v32
	v_lshlrev_b64 v[44:45], 11, v[32:33]
	v_lshl_add_u64 v[34:35], v[90:91], 0, v[44:45]
	global_load_dwordx2 v[38:39], v[34:35], off
	global_load_dwordx2 v[36:37], v[34:35], off offset:32
	v_lshl_add_u64 v[44:45], s[8:9], 0, v[44:45]
	v_lshl_add_u64 v[44:45], v[44:45], 0, v[96:97]
	s_waitcnt vmcnt(1)
	v_lshlrev_b32_e32 v70, 16, v38
	s_waitcnt vmcnt(0)
	v_lshlrev_b32_e32 v59, 16, v36
	v_and_b32_e32 v55, 0xffff0000, v36
	v_alignbit_b32 v33, v37, v36, 16
	v_and_b32_e32 v57, 0xffff0000, v37
	global_load_dwordx2 v[36:37], v[34:35], off offset:64
	v_and_b32_e32 v61, 0xffff0000, v33
	v_and_b32_e32 v65, 0xffff0000, v39
	v_and_b32_e32 v68, 0xffff0000, v38
	v_mov_b32_e32 v64, v70
	v_mov_b32_e32 v69, v70
	v_mul_f32_e32 v62, v70, v70
	v_mul_f32_e32 v58, v59, v59
	v_mul_f32_e32 v54, v55, v55
	v_mul_f32_e32 v60, v61, v61
	v_mul_f32_e32 v56, v57, v57
	s_waitcnt vmcnt(0)
	v_lshlrev_b32_e32 v51, 16, v36
	v_and_b32_e32 v47, 0xffff0000, v36
	v_alignbit_b32 v33, v37, v36, 16
	v_and_b32_e32 v49, 0xffff0000, v37
	global_load_dwordx2 v[36:37], v[34:35], off offset:96
	v_and_b32_e32 v53, 0xffff0000, v33
	v_mul_f32_e32 v50, v51, v51
	v_mul_f32_e32 v46, v47, v47
	v_mul_f32_e32 v52, v53, v53
	v_mul_f32_e32 v48, v49, v49
	s_waitcnt vmcnt(0)
	v_alignbit_b32 v33, v37, v36, 16
	v_and_b32_e32 v43, 0xffff0000, v33
	v_alignbit_b32 v33, v39, v38, 16
	v_and_b32_e32 v39, 0xffff0000, v33
	v_and_b32_e32 v38, 16, v38
	v_mov_b32_e32 v33, v70
	v_pk_add_f32 v[66:67], v[38:39], v[64:65]
	v_pk_add_f32 v[72:73], v[68:69], v[32:33] op_sel_hi:[0,1]
	v_mov_b32_e32 v63, v67
	v_pk_mul_f32 v[66:67], v[68:69], v[68:69]
	v_mov_b32_e32 v64, v39
	v_mov_b32_e32 v67, v73
	global_load_dwordx4 v[72:75], v89, s[0:1]
	global_load_dwordx4 v[76:79], v89, s[4:5]
	v_mul_f32_e32 v38, v65, v65
	v_mov_b32_e32 v71, v39
	v_pk_fma_f32 v[38:39], v[64:65], v[64:65], v[38:39] op_sel_hi:[1,1,0]
	v_pk_add_f32 v[62:63], v[62:63], v[66:67]
	v_mov_b32_e32 v39, v97
	v_pk_add_f32 v[38:39], v[62:63], v[38:39]
	v_pk_add_f32 v[62:63], v[58:59], v[54:55]
	v_pk_add_f32 v[66:67], v[60:61], v[56:57]
	v_lshlrev_b32_e32 v41, 16, v36
	v_pk_add_f32 v[62:63], v[62:63], v[66:67]
	v_and_b32_e32 v35, 0xffff0000, v36
	v_and_b32_e32 v37, 0xffff0000, v37
	v_pk_add_f32 v[38:39], v[38:39], v[62:63]
	v_pk_add_f32 v[62:63], v[50:51], v[46:47]
	v_pk_add_f32 v[66:67], v[52:53], v[48:49]
	v_mul_f32_e32 v40, v41, v41
	v_mul_f32_e32 v34, v35, v35
	v_mul_f32_e32 v42, v43, v43
	v_mul_f32_e32 v36, v37, v37
	v_pk_add_f32 v[62:63], v[62:63], v[66:67]
	v_pk_add_f32 v[66:67], v[42:43], v[36:37]
	v_pk_add_f32 v[38:39], v[38:39], v[62:63]
	v_pk_add_f32 v[62:63], v[40:41], v[34:35]
	v_mul_f32_e32 v36, 0xbfb8aa3b, v28
	v_pk_add_f32 v[62:63], v[62:63], v[66:67]
	v_exp_f32_e32 v66, v36
	v_pk_add_f32 v[38:39], v[38:39], v[62:63]
	ds_bpermute_b32 v63, v184, v39
	ds_bpermute_b32 v62, v184, v38
	v_mul_f32_e32 v36, 0xbfb8aa3b, v29
	v_mov_b32_e32 v69, v65
	v_mov_b32_e32 v60, v59
	v_mov_b32_e32 v56, v55
	s_waitcnt lgkmcnt(0)
	v_pk_add_f32 v[38:39], v[38:39], v[62:63]
	ds_bpermute_b32 v63, v185, v39
	ds_bpermute_b32 v62, v185, v38
	v_mov_b32_e32 v52, v51
	s_waitcnt lgkmcnt(0)
	v_pk_add_f32 v[38:39], v[38:39], v[62:63]
	s_nop 0
	v_pk_mul_f32 v[38:39], v[38:39], s[38:39] op_sel_hi:[1,0]
	v_exp_f32_e32 v62, v36
	v_fma_f32 v33, -v39, v39, v38
	v_max_f32_e32 v33, 0, v33
	v_add_f32_e32 v33, 0x3a27c5ac, v33
	v_cmp_gt_f32_e32 vcc, s12, v33
	v_mul_f32_e32 v34, 0x4b800000, v33
	v_pk_add_f32 v[70:71], v[70:71], v[38:39] op_sel:[0,1] neg_lo:[0,1] neg_hi:[0,1]
	v_cndmask_b32_e32 v33, v33, v34, vcc
	v_rsq_f32_e32 v33, v33
	v_mul_f32_e32 v36, 0xbfb8aa3b, v30
	v_exp_f32_e32 v67, v36
	v_mul_f32_e32 v36, 0xbfb8aa3b, v31
	v_mul_f32_e32 v34, 0x45800000, v33
	v_cndmask_b32_e32 v34, v33, v34, vcc
	v_pk_mul_f32 v[70:71], v[70:71], v[34:35] op_sel_hi:[1,0]
	v_pk_add_f32 v[66:67], v[66:67], 1.0 op_sel_hi:[1,0]
	v_exp_f32_e32 v63, v36
	v_div_scale_f32 v36, s[10:11], v67, v67, v30
	v_rcp_f32_e32 v40, v36
	v_pk_add_f32 v[62:63], v[62:63], 1.0 op_sel_hi:[1,0]
	v_pk_add_f32 v[64:65], v[68:69], v[38:39] op_sel:[0,1] neg_lo:[0,1] neg_hi:[0,1]
	v_mad_i64_i32 v[32:33], s[10:11], v32, s13, v[86:87]
	v_fma_f32 v42, -v36, v40, 1.0
	v_fmac_f32_e32 v40, v42, v40
	v_div_scale_f32 v42, vcc, v30, v67, v30
	v_mul_f32_e32 v46, v42, v40
	v_fma_f32 v48, -v36, v46, v42
	v_fmac_f32_e32 v46, v48, v40
	v_fma_f32 v36, -v36, v46, v42
	v_div_fmas_f32 v36, v36, v40, v46
	v_div_fixup_f32 v67, v36, v67, v30
	v_div_scale_f32 v30, s[10:11], v66, v66, v28
	s_waitcnt vmcnt(1)
	v_mov_b32_e32 v92, v72
	v_mov_b32_e32 v93, v74
	s_waitcnt vmcnt(0)
	v_mov_b32_e32 v94, v76
	v_mov_b32_e32 v95, v78
	v_pk_fma_f32 v[70:71], v[92:93], v[70:71], v[94:95]
	global_load_dwordx2 v[92:93], v[44:45], off
	v_rcp_f32_e32 v36, v30
	v_pk_mul_f32 v[64:65], v[64:65], v[34:35] op_sel_hi:[1,0]
	v_mov_b32_e32 v74, v73
	v_mov_b32_e32 v78, v77
	v_fma_f32 v40, -v30, v36, 1.0
	v_fmac_f32_e32 v36, v40, v36
	v_div_scale_f32 v40, vcc, v28, v66, v28
	v_mul_f32_e32 v42, v40, v36
	v_fma_f32 v46, -v30, v42, v40
	v_fmac_f32_e32 v42, v46, v36
	v_fma_f32 v30, -v30, v42, v40
	v_div_fmas_f32 v30, v30, v36, v42
	v_div_fixup_f32 v66, v30, v66, v28
	v_div_scale_f32 v28, s[10:11], v63, v63, v31
	v_rcp_f32_e32 v30, v28
	v_pk_fma_f32 v[64:65], v[74:75], v[64:65], v[78:79]
	v_pk_add_f32 v[58:59], v[60:61], v[38:39] op_sel:[0,1] neg_lo:[0,1] neg_hi:[0,1]
	v_pk_add_f32 v[54:55], v[56:57], v[38:39] op_sel:[0,1] neg_lo:[0,1] neg_hi:[0,1]
	v_fma_f32 v36, -v28, v30, 1.0
	v_fmac_f32_e32 v30, v36, v30
	v_div_scale_f32 v36, vcc, v31, v63, v31
	v_mul_f32_e32 v40, v36, v30
	v_fma_f32 v42, -v28, v40, v36
	v_fmac_f32_e32 v40, v42, v30
	v_fma_f32 v28, -v28, v40, v36
	v_div_fmas_f32 v28, v28, v30, v40
	v_div_fixup_f32 v31, v28, v63, v31
	v_div_scale_f32 v28, s[10:11], v62, v62, v29
	v_rcp_f32_e32 v30, v28
	v_pk_mul_f32 v[58:59], v[58:59], v[34:35] op_sel_hi:[1,0]
	v_pk_mul_f32 v[54:55], v[54:55], v[34:35] op_sel_hi:[1,0]
	v_pk_add_f32 v[50:51], v[52:53], v[38:39] op_sel:[0,1] neg_lo:[0,1] neg_hi:[0,1]
	v_fma_f32 v36, -v28, v30, 1.0
	v_fmac_f32_e32 v30, v36, v30
	v_div_scale_f32 v36, vcc, v29, v62, v29
	v_mul_f32_e32 v40, v36, v30
	v_fma_f32 v42, -v28, v40, v36
	v_fmac_f32_e32 v40, v42, v30
	v_fma_f32 v28, -v28, v40, v36
	v_div_fmas_f32 v28, v28, v30, v40
	v_div_fixup_f32 v30, v28, v62, v29
	v_pk_mul_f32 v[50:51], v[50:51], v[34:35] op_sel_hi:[1,0]
	s_waitcnt vmcnt(0)
	v_and_b32_e32 v69, 0xffff0000, v93
	v_and_b32_e32 v68, 0xffff0000, v92
	v_lshlrev_b32_e32 v95, 16, v93
	v_lshlrev_b32_e32 v94, 16, v92
	v_pk_add_f32 v[64:65], v[64:65], v[68:69]
	v_pk_add_f32 v[70:71], v[70:71], v[94:95]
	v_pk_mul_f32 v[28:29], v[30:31], v[64:65]
	v_pk_mul_f32 v[66:67], v[66:67], v[70:71]
	v_and_b32_sdwa v36, v29, v154 dst_sel:DWORD dst_unused:UNUSED_PAD src0_sel:WORD_1 src1_sel:DWORD
	v_and_b32_sdwa v40, v28, v154 dst_sel:DWORD dst_unused:UNUSED_PAD src0_sel:WORD_1 src1_sel:DWORD
	v_and_b32_sdwa v30, v67, v154 dst_sel:DWORD dst_unused:UNUSED_PAD src0_sel:WORD_1 src1_sel:DWORD
	v_and_b32_sdwa v31, v66, v154 dst_sel:DWORD dst_unused:UNUSED_PAD src0_sel:WORD_1 src1_sel:DWORD
	v_add3_u32 v29, v29, v36, s33
	v_add3_u32 v28, v28, v40, s33
	v_add3_u32 v31, v66, v31, s33
	v_add3_u32 v30, v67, v30, s33
	v_and_b32_e32 v29, 0xffff0000, v29
	v_and_b32_e32 v28, 0xffff0000, v28
	v_or_b32_sdwa v29, v29, v30 dst_sel:DWORD dst_unused:UNUSED_PAD src0_sel:DWORD src1_sel:WORD_1
	v_or_b32_sdwa v28, v28, v31 dst_sel:DWORD dst_unused:UNUSED_PAD src0_sel:DWORD src1_sel:WORD_1
	global_store_dwordx2 v[32:33], v[28:29], off
	global_load_dwordx4 v[62:65], v89, s[0:1] offset:64
	global_load_dwordx4 v[66:69], v89, s[4:5] offset:64
	v_mul_f32_e32 v28, 0xbfb8aa3b, v24
	v_mul_f32_e32 v29, 0xbfb8aa3b, v26
	v_exp_f32_e32 v30, v28
	v_exp_f32_e32 v31, v29
	v_mul_f32_e32 v28, 0xbfb8aa3b, v25
	v_mul_f32_e32 v29, 0xbfb8aa3b, v27
	v_exp_f32_e32 v28, v28
	v_pk_add_f32 v[30:31], v[30:31], 1.0 op_sel_hi:[1,0]
	v_exp_f32_e32 v29, v29
	v_div_scale_f32 v36, s[10:11], v31, v31, v26
	v_rcp_f32_e32 v40, v36
	v_pk_add_f32 v[28:29], v[28:29], 1.0 op_sel_hi:[1,0]
	v_fma_f32 v42, -v36, v40, 1.0
	v_fmac_f32_e32 v40, v42, v40
	v_div_scale_f32 v42, vcc, v26, v31, v26
	v_mul_f32_e32 v46, v42, v40
	v_fma_f32 v48, -v36, v46, v42
	v_fmac_f32_e32 v46, v48, v40
	v_fma_f32 v36, -v36, v46, v42
	v_div_fmas_f32 v36, v36, v40, v46
	v_div_fixup_f32 v31, v36, v31, v26
	v_div_scale_f32 v26, s[10:11], v30, v30, v24
	v_rcp_f32_e32 v36, v26
	v_mov_b32_e32 v48, v47
	v_fma_f32 v40, -v26, v36, 1.0
	v_fmac_f32_e32 v36, v40, v36
	v_div_scale_f32 v40, vcc, v24, v30, v24
	v_mul_f32_e32 v42, v40, v36
	v_fma_f32 v46, -v26, v42, v40
	v_fmac_f32_e32 v42, v46, v36
	v_fma_f32 v26, -v26, v42, v40
	v_div_fmas_f32 v26, v26, v36, v42
	v_div_fixup_f32 v30, v26, v30, v24
	v_div_scale_f32 v24, s[10:11], v29, v29, v27
	v_rcp_f32_e32 v26, v24
	v_pk_add_f32 v[46:47], v[48:49], v[38:39] op_sel:[0,1] neg_lo:[0,1] neg_hi:[0,1]
	v_fma_f32 v36, -v24, v26, 1.0
	v_fmac_f32_e32 v26, v36, v26
	v_div_scale_f32 v36, vcc, v27, v29, v27
	v_mul_f32_e32 v40, v36, v26
	v_fma_f32 v42, -v24, v40, v36
	v_fmac_f32_e32 v40, v42, v26
	v_fma_f32 v24, -v24, v40, v36
	v_div_fmas_f32 v24, v24, v26, v40
	v_div_fixup_f32 v27, v24, v29, v27
	v_div_scale_f32 v24, s[10:11], v28, v28, v25
	v_rcp_f32_e32 v26, v24
	v_pk_mul_f32 v[46:47], v[46:47], v[34:35] op_sel_hi:[1,0]
	v_fma_f32 v29, -v24, v26, 1.0
	v_fmac_f32_e32 v26, v29, v26
	v_div_scale_f32 v29, vcc, v25, v28, v25
	v_mul_f32_e32 v36, v29, v26
	v_fma_f32 v40, -v24, v36, v29
	v_fmac_f32_e32 v36, v40, v26
	v_fma_f32 v24, -v24, v36, v29
	v_div_fmas_f32 v24, v24, v26, v36
	v_div_fixup_f32 v26, v24, v28, v25
	s_waitcnt vmcnt(1)
	v_mov_b32_e32 v60, v62
	v_mov_b32_e32 v61, v64
	s_waitcnt vmcnt(0)
	v_mov_b32_e32 v70, v66
	v_mov_b32_e32 v71, v68
	v_pk_fma_f32 v[58:59], v[58:59], v[60:61], v[70:71]
	global_load_dwordx2 v[60:61], v[44:45], off offset:32
	v_mov_b32_e32 v64, v63
	v_mov_b32_e32 v68, v67
	v_pk_fma_f32 v[54:55], v[54:55], v[64:65], v[68:69]
	s_waitcnt vmcnt(0)
	v_and_b32_e32 v57, 0xffff0000, v61
	v_and_b32_e32 v56, 0xffff0000, v60
	v_lshlrev_b32_e32 v71, 16, v61
	v_lshlrev_b32_e32 v70, 16, v60
	v_pk_add_f32 v[54:55], v[54:55], v[56:57]
	v_pk_add_f32 v[58:59], v[58:59], v[70:71]
	v_pk_mul_f32 v[24:25], v[26:27], v[54:55]
	v_pk_mul_f32 v[30:31], v[30:31], v[58:59]
	v_and_b32_sdwa v28, v25, v154 dst_sel:DWORD dst_unused:UNUSED_PAD src0_sel:WORD_1 src1_sel:DWORD
	v_and_b32_sdwa v29, v24, v154 dst_sel:DWORD dst_unused:UNUSED_PAD src0_sel:WORD_1 src1_sel:DWORD
	v_and_b32_sdwa v26, v31, v154 dst_sel:DWORD dst_unused:UNUSED_PAD src0_sel:WORD_1 src1_sel:DWORD
	v_and_b32_sdwa v27, v30, v154 dst_sel:DWORD dst_unused:UNUSED_PAD src0_sel:WORD_1 src1_sel:DWORD
	v_add3_u32 v25, v25, v28, s33
	v_add3_u32 v24, v24, v29, s33
	v_add3_u32 v27, v30, v27, s33
	v_add3_u32 v26, v31, v26, s33
	v_and_b32_e32 v25, 0xffff0000, v25
	v_and_b32_e32 v24, 0xffff0000, v24
	v_or_b32_sdwa v25, v25, v26 dst_sel:DWORD dst_unused:UNUSED_PAD src0_sel:DWORD src1_sel:WORD_1
	v_or_b32_sdwa v24, v24, v27 dst_sel:DWORD dst_unused:UNUSED_PAD src0_sel:DWORD src1_sel:WORD_1
	global_store_dwordx2 v[32:33], v[24:25], off offset:32
	global_load_dwordx4 v[26:29], v89, s[0:1] offset:128
	global_load_dwordx4 v[54:57], v89, s[4:5] offset:128
	v_mul_f32_e32 v24, 0xbfb8aa3b, v20
	v_mul_f32_e32 v25, 0xbfb8aa3b, v22
	v_exp_f32_e32 v30, v24
	v_exp_f32_e32 v31, v25
	v_mul_f32_e32 v24, 0xbfb8aa3b, v21
	v_mul_f32_e32 v25, 0xbfb8aa3b, v23
	v_exp_f32_e32 v24, v24
	v_exp_f32_e32 v25, v25
	s_waitcnt vmcnt(1)
	v_mov_b32_e32 v52, v26
	v_mov_b32_e32 v53, v28
	s_waitcnt vmcnt(0)
	v_mov_b32_e32 v58, v54
	v_mov_b32_e32 v59, v56
	v_pk_fma_f32 v[50:51], v[50:51], v[52:53], v[58:59]
	global_load_dwordx2 v[52:53], v[44:45], off offset:64
	v_mov_b32_e32 v28, v27
	v_mov_b32_e32 v56, v55
	v_pk_fma_f32 v[26:27], v[46:47], v[28:29], v[56:57]
	v_pk_add_f32 v[24:25], v[24:25], 1.0 op_sel_hi:[1,0]
	s_waitcnt vmcnt(0)
	v_and_b32_e32 v29, 0xffff0000, v53
	v_and_b32_e32 v28, 0xffff0000, v52
	v_pk_add_f32 v[26:27], v[26:27], v[28:29]
	v_pk_add_f32 v[28:29], v[30:31], 1.0 op_sel_hi:[1,0]
	v_lshlrev_b32_e32 v59, 16, v53
	v_div_scale_f32 v30, s[10:11], v29, v29, v22
	v_rcp_f32_e32 v31, v30
	v_lshlrev_b32_e32 v58, 16, v52
	v_pk_add_f32 v[50:51], v[50:51], v[58:59]
	v_fma_f32 v36, -v30, v31, 1.0
	v_fmac_f32_e32 v31, v36, v31
	v_div_scale_f32 v36, vcc, v22, v29, v22
	v_mul_f32_e32 v40, v36, v31
	v_fma_f32 v42, -v30, v40, v36
	v_fmac_f32_e32 v40, v42, v31
	v_fma_f32 v30, -v30, v40, v36
	v_div_fmas_f32 v30, v30, v31, v40
	v_div_fixup_f32 v29, v30, v29, v22
	v_div_scale_f32 v22, s[10:11], v28, v28, v20
	v_rcp_f32_e32 v30, v22
	v_mov_b32_e32 v42, v41
	v_fma_f32 v31, -v22, v30, 1.0
	v_fmac_f32_e32 v30, v31, v30
	v_div_scale_f32 v31, vcc, v20, v28, v20
	v_mul_f32_e32 v36, v31, v30
	v_fma_f32 v40, -v22, v36, v31
	v_fmac_f32_e32 v36, v40, v30
	v_fma_f32 v22, -v22, v36, v31
	v_div_fmas_f32 v22, v22, v30, v36
	v_div_fixup_f32 v28, v22, v28, v20
	v_div_scale_f32 v20, s[10:11], v25, v25, v23
	v_rcp_f32_e32 v22, v20
	v_pk_mul_f32 v[28:29], v[28:29], v[50:51]
	v_pk_add_f32 v[40:41], v[42:43], v[38:39] op_sel:[0,1] neg_lo:[0,1] neg_hi:[0,1]
	v_fma_f32 v30, -v20, v22, 1.0
	v_fmac_f32_e32 v22, v30, v22
	v_div_scale_f32 v30, vcc, v23, v25, v23
	v_mul_f32_e32 v31, v30, v22
	v_fma_f32 v36, -v20, v31, v30
	v_fmac_f32_e32 v31, v36, v22
	v_fma_f32 v20, -v20, v31, v30
	v_div_fmas_f32 v20, v20, v22, v31
	v_div_fixup_f32 v23, v20, v25, v23
	v_div_scale_f32 v20, s[10:11], v24, v24, v21
	v_rcp_f32_e32 v22, v20
	v_pk_mul_f32 v[40:41], v[40:41], v[34:35] op_sel_hi:[1,0]
	v_mov_b32_e32 v36, v35
	v_pk_add_f32 v[36:37], v[36:37], v[38:39] op_sel:[0,1] neg_lo:[0,1] neg_hi:[0,1]
	v_fma_f32 v25, -v20, v22, 1.0
	v_fmac_f32_e32 v22, v25, v22
	v_div_scale_f32 v25, vcc, v21, v24, v21
	v_mul_f32_e32 v30, v25, v22
	v_fma_f32 v31, -v20, v30, v25
	v_fmac_f32_e32 v30, v31, v22
	v_fma_f32 v20, -v20, v30, v25
	v_div_fmas_f32 v20, v20, v22, v30
	v_div_fixup_f32 v22, v20, v24, v21
	v_pk_mul_f32 v[20:21], v[22:23], v[26:27]
	v_and_b32_sdwa v22, v29, v154 dst_sel:DWORD dst_unused:UNUSED_PAD src0_sel:WORD_1 src1_sel:DWORD
	v_and_b32_sdwa v24, v21, v154 dst_sel:DWORD dst_unused:UNUSED_PAD src0_sel:WORD_1 src1_sel:DWORD
	v_and_b32_sdwa v25, v20, v154 dst_sel:DWORD dst_unused:UNUSED_PAD src0_sel:WORD_1 src1_sel:DWORD
	v_and_b32_sdwa v23, v28, v154 dst_sel:DWORD dst_unused:UNUSED_PAD src0_sel:WORD_1 src1_sel:DWORD
	v_add3_u32 v21, v21, v24, s33
	v_add3_u32 v20, v20, v25, s33
	v_add3_u32 v23, v28, v23, s33
	v_add3_u32 v22, v29, v22, s33
	v_and_b32_e32 v21, 0xffff0000, v21
	v_and_b32_e32 v20, 0xffff0000, v20
	v_or_b32_sdwa v21, v21, v22 dst_sel:DWORD dst_unused:UNUSED_PAD src0_sel:DWORD src1_sel:WORD_1
	v_or_b32_sdwa v20, v20, v23 dst_sel:DWORD dst_unused:UNUSED_PAD src0_sel:DWORD src1_sel:WORD_1
	global_store_dwordx2 v[32:33], v[20:21], off offset:64
	global_load_dwordx4 v[22:25], v89, s[0:1] offset:192
	global_load_dwordx4 v[26:29], v89, s[4:5] offset:192
	v_mul_f32_e32 v20, 0xbfb8aa3b, v16
	v_mul_f32_e32 v21, 0xbfb8aa3b, v18
	v_exp_f32_e32 v30, v20
	v_exp_f32_e32 v31, v21
	v_pk_mul_f32 v[34:35], v[36:37], v[34:35] op_sel_hi:[1,0]
	v_mul_f32_e32 v20, 0xbfb8aa3b, v17
	v_mul_f32_e32 v21, 0xbfb8aa3b, v19
	v_exp_f32_e32 v20, v20
	v_exp_f32_e32 v21, v21
	s_waitcnt vmcnt(1)
	v_mov_b32_e32 v42, v22
	v_mov_b32_e32 v43, v24
	s_waitcnt vmcnt(0)
	v_mov_b32_e32 v46, v26
	v_mov_b32_e32 v47, v28
	v_pk_fma_f32 v[40:41], v[40:41], v[42:43], v[46:47]
	global_load_dwordx2 v[42:43], v[44:45], off offset:96
	v_mov_b32_e32 v24, v23
	v_mov_b32_e32 v28, v27
	v_pk_fma_f32 v[22:23], v[34:35], v[24:25], v[28:29]
	v_pk_add_f32 v[20:21], v[20:21], 1.0 op_sel_hi:[1,0]
	s_waitcnt vmcnt(0)
	v_and_b32_e32 v25, 0xffff0000, v43
	v_and_b32_e32 v24, 0xffff0000, v42
	v_pk_add_f32 v[22:23], v[22:23], v[24:25]
	v_pk_add_f32 v[24:25], v[30:31], 1.0 op_sel_hi:[1,0]
	v_lshlrev_b32_e32 v45, 16, v43
	v_div_scale_f32 v26, s[10:11], v25, v25, v18
	v_rcp_f32_e32 v27, v26
	v_lshlrev_b32_e32 v44, 16, v42
	v_pk_add_f32 v[40:41], v[40:41], v[44:45]
	v_fma_f32 v28, -v26, v27, 1.0
	v_fmac_f32_e32 v27, v28, v27
	v_div_scale_f32 v28, vcc, v18, v25, v18
	v_mul_f32_e32 v29, v28, v27
	v_fma_f32 v30, -v26, v29, v28
	v_fmac_f32_e32 v29, v30, v27
	v_fma_f32 v26, -v26, v29, v28
	v_div_fmas_f32 v26, v26, v27, v29
	v_div_fixup_f32 v25, v26, v25, v18
	v_div_scale_f32 v18, s[10:11], v24, v24, v16
	v_rcp_f32_e32 v26, v18
	s_nop 0
	v_fma_f32 v27, -v18, v26, 1.0
	v_fmac_f32_e32 v26, v27, v26
	v_div_scale_f32 v27, vcc, v16, v24, v16
	v_mul_f32_e32 v28, v27, v26
	v_fma_f32 v29, -v18, v28, v27
	v_fmac_f32_e32 v28, v29, v26
	v_fma_f32 v18, -v18, v28, v27
	v_div_fmas_f32 v18, v18, v26, v28
	v_div_fixup_f32 v24, v18, v24, v16
	v_div_scale_f32 v16, s[10:11], v21, v21, v19
	v_rcp_f32_e32 v18, v16
	v_pk_mul_f32 v[24:25], v[24:25], v[40:41]
	v_fma_f32 v26, -v16, v18, 1.0
	v_fmac_f32_e32 v18, v26, v18
	v_div_scale_f32 v26, vcc, v19, v21, v19
	v_mul_f32_e32 v27, v26, v18
	v_fma_f32 v28, -v16, v27, v26
	v_fmac_f32_e32 v27, v28, v18
	v_fma_f32 v16, -v16, v27, v26
	v_div_fmas_f32 v16, v16, v18, v27
	v_div_fixup_f32 v19, v16, v21, v19
	v_div_scale_f32 v16, s[10:11], v20, v20, v17
	v_rcp_f32_e32 v18, v16
	s_nop 0
	v_fma_f32 v21, -v16, v18, 1.0
	v_fmac_f32_e32 v18, v21, v18
	v_div_scale_f32 v21, vcc, v17, v20, v17
	v_mul_f32_e32 v26, v21, v18
	v_fma_f32 v27, -v16, v26, v21
	v_fmac_f32_e32 v26, v27, v18
	v_fma_f32 v16, -v16, v26, v21
	v_div_fmas_f32 v16, v16, v18, v26
	v_div_fixup_f32 v18, v16, v20, v17
	v_pk_mul_f32 v[16:17], v[18:19], v[22:23]
	v_and_b32_sdwa v18, v25, v154 dst_sel:DWORD dst_unused:UNUSED_PAD src0_sel:WORD_1 src1_sel:DWORD
	v_and_b32_sdwa v20, v17, v154 dst_sel:DWORD dst_unused:UNUSED_PAD src0_sel:WORD_1 src1_sel:DWORD
	v_and_b32_sdwa v21, v16, v154 dst_sel:DWORD dst_unused:UNUSED_PAD src0_sel:WORD_1 src1_sel:DWORD
	v_and_b32_sdwa v19, v24, v154 dst_sel:DWORD dst_unused:UNUSED_PAD src0_sel:WORD_1 src1_sel:DWORD
	v_add3_u32 v17, v17, v20, s33
	v_add3_u32 v16, v16, v21, s33
	v_add3_u32 v19, v24, v19, s33
	v_add3_u32 v18, v25, v18, s33
	v_and_b32_e32 v17, 0xffff0000, v17
	v_and_b32_e32 v16, 0xffff0000, v16
	v_or_b32_sdwa v17, v17, v18 dst_sel:DWORD dst_unused:UNUSED_PAD src0_sel:DWORD src1_sel:WORD_1
	v_or_b32_sdwa v16, v16, v19 dst_sel:DWORD dst_unused:UNUSED_PAD src0_sel:DWORD src1_sel:WORD_1
	global_store_dwordx2 v[32:33], v[16:17], off offset:96
	v_add_u32_e32 v16, 64, v88
	v_ashrrev_i32_e32 v17, 31, v16
	v_lshlrev_b64 v[28:29], 11, v[16:17]
	v_lshl_add_u64 v[18:19], v[90:91], 0, v[28:29]
	global_load_dwordx2 v[22:23], v[18:19], off
	global_load_dwordx2 v[20:21], v[18:19], off offset:32
	v_lshl_add_u64 v[28:29], s[8:9], 0, v[28:29]
	v_lshl_add_u64 v[28:29], v[28:29], 0, v[96:97]
	s_waitcnt vmcnt(1)
	v_lshlrev_b32_e32 v54, 16, v22
	s_waitcnt vmcnt(0)
	v_lshlrev_b32_e32 v43, 16, v20
	v_and_b32_e32 v39, 0xffff0000, v20
	v_alignbit_b32 v17, v21, v20, 16
	v_and_b32_e32 v41, 0xffff0000, v21
	global_load_dwordx2 v[20:21], v[18:19], off offset:64
	v_and_b32_e32 v45, 0xffff0000, v17
	v_and_b32_e32 v49, 0xffff0000, v23
	v_and_b32_e32 v52, 0xffff0000, v22
	v_mov_b32_e32 v48, v54
	v_mov_b32_e32 v53, v54
	v_mul_f32_e32 v46, v54, v54
	v_mul_f32_e32 v42, v43, v43
	v_mul_f32_e32 v38, v39, v39
	v_mul_f32_e32 v44, v45, v45
	v_mul_f32_e32 v40, v41, v41
	s_waitcnt vmcnt(0)
	v_lshlrev_b32_e32 v35, 16, v20
	v_and_b32_e32 v31, 0xffff0000, v20
	v_alignbit_b32 v17, v21, v20, 16
	v_and_b32_e32 v33, 0xffff0000, v21
	global_load_dwordx2 v[20:21], v[18:19], off offset:96
	v_and_b32_e32 v37, 0xffff0000, v17
	v_mul_f32_e32 v34, v35, v35
	v_mul_f32_e32 v30, v31, v31
	v_mul_f32_e32 v36, v37, v37
	v_mul_f32_e32 v32, v33, v33
	s_waitcnt vmcnt(0)
	v_alignbit_b32 v17, v21, v20, 16
	v_and_b32_e32 v27, 0xffff0000, v17
	v_alignbit_b32 v17, v23, v22, 16
	v_and_b32_e32 v23, 0xffff0000, v17
	v_and_b32_e32 v22, 16, v22
	v_mov_b32_e32 v17, v54
	v_pk_add_f32 v[50:51], v[22:23], v[48:49]
	v_pk_add_f32 v[56:57], v[52:53], v[16:17] op_sel_hi:[0,1]
	v_mov_b32_e32 v47, v51
	v_pk_mul_f32 v[50:51], v[52:53], v[52:53]
	v_mov_b32_e32 v48, v23
	v_mov_b32_e32 v51, v57
	global_load_dwordx4 v[56:59], v89, s[0:1]
	global_load_dwordx4 v[60:63], v89, s[4:5]
	v_mul_f32_e32 v22, v49, v49
	v_mov_b32_e32 v55, v23
	v_pk_fma_f32 v[22:23], v[48:49], v[48:49], v[22:23] op_sel_hi:[1,1,0]
	v_pk_add_f32 v[46:47], v[46:47], v[50:51]
	v_mov_b32_e32 v23, v97
	v_pk_add_f32 v[22:23], v[46:47], v[22:23]
	v_pk_add_f32 v[46:47], v[42:43], v[38:39]
	v_pk_add_f32 v[50:51], v[44:45], v[40:41]
	v_lshlrev_b32_e32 v25, 16, v20
	v_pk_add_f32 v[46:47], v[46:47], v[50:51]
	v_and_b32_e32 v19, 0xffff0000, v20
	v_and_b32_e32 v21, 0xffff0000, v21
	v_pk_add_f32 v[22:23], v[22:23], v[46:47]
	v_pk_add_f32 v[46:47], v[34:35], v[30:31]
	v_pk_add_f32 v[50:51], v[36:37], v[32:33]
	v_mul_f32_e32 v24, v25, v25
	v_mul_f32_e32 v18, v19, v19
	v_mul_f32_e32 v26, v27, v27
	v_mul_f32_e32 v20, v21, v21
	v_pk_add_f32 v[46:47], v[46:47], v[50:51]
	v_pk_add_f32 v[50:51], v[26:27], v[20:21]
	v_pk_add_f32 v[22:23], v[22:23], v[46:47]
	v_pk_add_f32 v[46:47], v[24:25], v[18:19]
	v_mul_f32_e32 v20, 0xbfb8aa3b, v12
	v_pk_add_f32 v[46:47], v[46:47], v[50:51]
	v_exp_f32_e32 v50, v20
	v_pk_add_f32 v[22:23], v[22:23], v[46:47]
	ds_bpermute_b32 v47, v184, v23
	ds_bpermute_b32 v46, v184, v22
	v_mul_f32_e32 v20, 0xbfb8aa3b, v13
	v_mov_b32_e32 v53, v49
	v_mov_b32_e32 v44, v43
	v_mov_b32_e32 v40, v39
	s_waitcnt lgkmcnt(0)
	v_pk_add_f32 v[22:23], v[22:23], v[46:47]
	ds_bpermute_b32 v47, v185, v23
	ds_bpermute_b32 v46, v185, v22
	v_mov_b32_e32 v36, v35
	s_waitcnt lgkmcnt(0)
	v_pk_add_f32 v[22:23], v[22:23], v[46:47]
	s_nop 0
	v_pk_mul_f32 v[22:23], v[22:23], s[38:39] op_sel_hi:[1,0]
	v_exp_f32_e32 v46, v20
	v_fma_f32 v17, -v23, v23, v22
	v_max_f32_e32 v17, 0, v17
	v_add_f32_e32 v17, 0x3a27c5ac, v17
	v_cmp_gt_f32_e32 vcc, s12, v17
	v_mul_f32_e32 v18, 0x4b800000, v17
	v_pk_add_f32 v[54:55], v[54:55], v[22:23] op_sel:[0,1] neg_lo:[0,1] neg_hi:[0,1]
	v_cndmask_b32_e32 v17, v17, v18, vcc
	v_rsq_f32_e32 v17, v17
	v_mul_f32_e32 v20, 0xbfb8aa3b, v14
	v_exp_f32_e32 v51, v20
	v_mul_f32_e32 v20, 0xbfb8aa3b, v15
	v_mul_f32_e32 v18, 0x45800000, v17
	v_cndmask_b32_e32 v18, v17, v18, vcc
	v_pk_mul_f32 v[54:55], v[54:55], v[18:19] op_sel_hi:[1,0]
	v_pk_add_f32 v[50:51], v[50:51], 1.0 op_sel_hi:[1,0]
	v_exp_f32_e32 v47, v20
	v_div_scale_f32 v20, s[10:11], v51, v51, v14
	v_rcp_f32_e32 v24, v20
	v_pk_add_f32 v[46:47], v[46:47], 1.0 op_sel_hi:[1,0]
	v_pk_add_f32 v[48:49], v[52:53], v[22:23] op_sel:[0,1] neg_lo:[0,1] neg_hi:[0,1]
	v_mad_i64_i32 v[16:17], s[10:11], v16, s13, v[86:87]
	v_fma_f32 v26, -v20, v24, 1.0
	v_fmac_f32_e32 v24, v26, v24
	v_div_scale_f32 v26, vcc, v14, v51, v14
	v_mul_f32_e32 v30, v26, v24
	v_fma_f32 v32, -v20, v30, v26
	v_fmac_f32_e32 v30, v32, v24
	v_fma_f32 v20, -v20, v30, v26
	v_div_fmas_f32 v20, v20, v24, v30
	v_div_fixup_f32 v51, v20, v51, v14
	v_div_scale_f32 v14, s[10:11], v50, v50, v12
	s_waitcnt vmcnt(1)
	v_mov_b32_e32 v64, v56
	v_mov_b32_e32 v65, v58
	s_waitcnt vmcnt(0)
	v_mov_b32_e32 v66, v60
	v_mov_b32_e32 v67, v62
	v_pk_fma_f32 v[54:55], v[64:65], v[54:55], v[66:67]
	global_load_dwordx2 v[64:65], v[28:29], off
	v_rcp_f32_e32 v20, v14
	v_pk_mul_f32 v[48:49], v[48:49], v[18:19] op_sel_hi:[1,0]
	v_mov_b32_e32 v58, v57
	v_mov_b32_e32 v62, v61
	v_fma_f32 v24, -v14, v20, 1.0
	v_fmac_f32_e32 v20, v24, v20
	v_div_scale_f32 v24, vcc, v12, v50, v12
	v_mul_f32_e32 v26, v24, v20
	v_fma_f32 v30, -v14, v26, v24
	v_fmac_f32_e32 v26, v30, v20
	v_fma_f32 v14, -v14, v26, v24
	v_div_fmas_f32 v14, v14, v20, v26
	v_div_fixup_f32 v50, v14, v50, v12
	v_div_scale_f32 v12, s[10:11], v47, v47, v15
	v_rcp_f32_e32 v14, v12
	v_pk_fma_f32 v[48:49], v[58:59], v[48:49], v[62:63]
	v_pk_add_f32 v[42:43], v[44:45], v[22:23] op_sel:[0,1] neg_lo:[0,1] neg_hi:[0,1]
	v_pk_add_f32 v[38:39], v[40:41], v[22:23] op_sel:[0,1] neg_lo:[0,1] neg_hi:[0,1]
	v_fma_f32 v20, -v12, v14, 1.0
	v_fmac_f32_e32 v14, v20, v14
	v_div_scale_f32 v20, vcc, v15, v47, v15
	v_mul_f32_e32 v24, v20, v14
	v_fma_f32 v26, -v12, v24, v20
	v_fmac_f32_e32 v24, v26, v14
	v_fma_f32 v12, -v12, v24, v20
	v_div_fmas_f32 v12, v12, v14, v24
	v_div_fixup_f32 v15, v12, v47, v15
	v_div_scale_f32 v12, s[10:11], v46, v46, v13
	v_rcp_f32_e32 v14, v12
	v_pk_mul_f32 v[42:43], v[42:43], v[18:19] op_sel_hi:[1,0]
	v_pk_mul_f32 v[38:39], v[38:39], v[18:19] op_sel_hi:[1,0]
	v_pk_add_f32 v[34:35], v[36:37], v[22:23] op_sel:[0,1] neg_lo:[0,1] neg_hi:[0,1]
	v_fma_f32 v20, -v12, v14, 1.0
	v_fmac_f32_e32 v14, v20, v14
	v_div_scale_f32 v20, vcc, v13, v46, v13
	v_mul_f32_e32 v24, v20, v14
	v_fma_f32 v26, -v12, v24, v20
	v_fmac_f32_e32 v24, v26, v14
	v_fma_f32 v12, -v12, v24, v20
	v_div_fmas_f32 v12, v12, v14, v24
	v_div_fixup_f32 v14, v12, v46, v13
	v_pk_mul_f32 v[34:35], v[34:35], v[18:19] op_sel_hi:[1,0]
	s_waitcnt vmcnt(0)
	v_and_b32_e32 v53, 0xffff0000, v65
	v_and_b32_e32 v52, 0xffff0000, v64
	v_lshlrev_b32_e32 v67, 16, v65
	v_lshlrev_b32_e32 v66, 16, v64
	v_pk_add_f32 v[48:49], v[48:49], v[52:53]
	v_pk_add_f32 v[54:55], v[54:55], v[66:67]
	v_pk_mul_f32 v[12:13], v[14:15], v[48:49]
	v_pk_mul_f32 v[50:51], v[50:51], v[54:55]
	v_and_b32_sdwa v20, v13, v154 dst_sel:DWORD dst_unused:UNUSED_PAD src0_sel:WORD_1 src1_sel:DWORD
	v_and_b32_sdwa v24, v12, v154 dst_sel:DWORD dst_unused:UNUSED_PAD src0_sel:WORD_1 src1_sel:DWORD
	v_and_b32_sdwa v14, v51, v154 dst_sel:DWORD dst_unused:UNUSED_PAD src0_sel:WORD_1 src1_sel:DWORD
	v_and_b32_sdwa v15, v50, v154 dst_sel:DWORD dst_unused:UNUSED_PAD src0_sel:WORD_1 src1_sel:DWORD
	v_add3_u32 v13, v13, v20, s33
	v_add3_u32 v12, v12, v24, s33
	v_add3_u32 v15, v50, v15, s33
	v_add3_u32 v14, v51, v14, s33
	v_and_b32_e32 v13, 0xffff0000, v13
	v_and_b32_e32 v12, 0xffff0000, v12
	v_or_b32_sdwa v13, v13, v14 dst_sel:DWORD dst_unused:UNUSED_PAD src0_sel:DWORD src1_sel:WORD_1
	v_or_b32_sdwa v12, v12, v15 dst_sel:DWORD dst_unused:UNUSED_PAD src0_sel:DWORD src1_sel:WORD_1
	global_store_dwordx2 v[16:17], v[12:13], off
	global_load_dwordx4 v[46:49], v89, s[0:1] offset:64
	global_load_dwordx4 v[50:53], v89, s[4:5] offset:64
	v_mul_f32_e32 v12, 0xbfb8aa3b, v8
	v_mul_f32_e32 v13, 0xbfb8aa3b, v10
	v_exp_f32_e32 v14, v12
	v_exp_f32_e32 v15, v13
	v_mul_f32_e32 v12, 0xbfb8aa3b, v9
	v_mul_f32_e32 v13, 0xbfb8aa3b, v11
	v_exp_f32_e32 v12, v12
	v_pk_add_f32 v[14:15], v[14:15], 1.0 op_sel_hi:[1,0]
	v_exp_f32_e32 v13, v13
	v_div_scale_f32 v20, s[10:11], v15, v15, v10
	v_rcp_f32_e32 v24, v20
	v_pk_add_f32 v[12:13], v[12:13], 1.0 op_sel_hi:[1,0]
	v_fma_f32 v26, -v20, v24, 1.0
	v_fmac_f32_e32 v24, v26, v24
	v_div_scale_f32 v26, vcc, v10, v15, v10
	v_mul_f32_e32 v30, v26, v24
	v_fma_f32 v32, -v20, v30, v26
	v_fmac_f32_e32 v30, v32, v24
	v_fma_f32 v20, -v20, v30, v26
	v_div_fmas_f32 v20, v20, v24, v30
	v_div_fixup_f32 v15, v20, v15, v10
	v_div_scale_f32 v10, s[10:11], v14, v14, v8
	v_rcp_f32_e32 v20, v10
	v_mov_b32_e32 v32, v31
	v_fma_f32 v24, -v10, v20, 1.0
	v_fmac_f32_e32 v20, v24, v20
	v_div_scale_f32 v24, vcc, v8, v14, v8
	v_mul_f32_e32 v26, v24, v20
	v_fma_f32 v30, -v10, v26, v24
	v_fmac_f32_e32 v26, v30, v20
	v_fma_f32 v10, -v10, v26, v24
	v_div_fmas_f32 v10, v10, v20, v26
	v_div_fixup_f32 v14, v10, v14, v8
	v_div_scale_f32 v8, s[10:11], v13, v13, v11
	v_rcp_f32_e32 v10, v8
	v_pk_add_f32 v[30:31], v[32:33], v[22:23] op_sel:[0,1] neg_lo:[0,1] neg_hi:[0,1]
	v_fma_f32 v20, -v8, v10, 1.0
	v_fmac_f32_e32 v10, v20, v10
	v_div_scale_f32 v20, vcc, v11, v13, v11
	v_mul_f32_e32 v24, v20, v10
	v_fma_f32 v26, -v8, v24, v20
	v_fmac_f32_e32 v24, v26, v10
	v_fma_f32 v8, -v8, v24, v20
	v_div_fmas_f32 v8, v8, v10, v24
	v_div_fixup_f32 v11, v8, v13, v11
	v_div_scale_f32 v8, s[10:11], v12, v12, v9
	v_rcp_f32_e32 v10, v8
	v_pk_mul_f32 v[30:31], v[30:31], v[18:19] op_sel_hi:[1,0]
	v_fma_f32 v13, -v8, v10, 1.0
	v_fmac_f32_e32 v10, v13, v10
	v_div_scale_f32 v13, vcc, v9, v12, v9
	v_mul_f32_e32 v20, v13, v10
	v_fma_f32 v24, -v8, v20, v13
	v_fmac_f32_e32 v20, v24, v10
	v_fma_f32 v8, -v8, v20, v13
	v_div_fmas_f32 v8, v8, v10, v20
	v_div_fixup_f32 v10, v8, v12, v9
	s_waitcnt vmcnt(1)
	v_mov_b32_e32 v44, v46
	v_mov_b32_e32 v45, v48
	s_waitcnt vmcnt(0)
	v_mov_b32_e32 v54, v50
	v_mov_b32_e32 v55, v52
	v_pk_fma_f32 v[42:43], v[42:43], v[44:45], v[54:55]
	global_load_dwordx2 v[44:45], v[28:29], off offset:32
	v_mov_b32_e32 v48, v47
	v_mov_b32_e32 v52, v51
	v_pk_fma_f32 v[38:39], v[38:39], v[48:49], v[52:53]
	s_waitcnt vmcnt(0)
	v_and_b32_e32 v41, 0xffff0000, v45
	v_and_b32_e32 v40, 0xffff0000, v44
	v_lshlrev_b32_e32 v55, 16, v45
	v_lshlrev_b32_e32 v54, 16, v44
	v_pk_add_f32 v[38:39], v[38:39], v[40:41]
	v_pk_add_f32 v[42:43], v[42:43], v[54:55]
	v_pk_mul_f32 v[8:9], v[10:11], v[38:39]
	v_pk_mul_f32 v[14:15], v[14:15], v[42:43]
	v_and_b32_sdwa v12, v9, v154 dst_sel:DWORD dst_unused:UNUSED_PAD src0_sel:WORD_1 src1_sel:DWORD
	v_and_b32_sdwa v13, v8, v154 dst_sel:DWORD dst_unused:UNUSED_PAD src0_sel:WORD_1 src1_sel:DWORD
	v_and_b32_sdwa v10, v15, v154 dst_sel:DWORD dst_unused:UNUSED_PAD src0_sel:WORD_1 src1_sel:DWORD
	v_and_b32_sdwa v11, v14, v154 dst_sel:DWORD dst_unused:UNUSED_PAD src0_sel:WORD_1 src1_sel:DWORD
	v_add3_u32 v9, v9, v12, s33
	v_add3_u32 v8, v8, v13, s33
	v_add3_u32 v11, v14, v11, s33
	v_add3_u32 v10, v15, v10, s33
	v_and_b32_e32 v9, 0xffff0000, v9
	v_and_b32_e32 v8, 0xffff0000, v8
	v_or_b32_sdwa v9, v9, v10 dst_sel:DWORD dst_unused:UNUSED_PAD src0_sel:DWORD src1_sel:WORD_1
	v_or_b32_sdwa v8, v8, v11 dst_sel:DWORD dst_unused:UNUSED_PAD src0_sel:DWORD src1_sel:WORD_1
	global_store_dwordx2 v[16:17], v[8:9], off offset:32
	global_load_dwordx4 v[10:13], v89, s[0:1] offset:128
	global_load_dwordx4 v[38:41], v89, s[4:5] offset:128
	v_mul_f32_e32 v8, 0xbfb8aa3b, v4
	v_mul_f32_e32 v9, 0xbfb8aa3b, v6
	v_exp_f32_e32 v14, v8
	v_exp_f32_e32 v15, v9
	v_mul_f32_e32 v8, 0xbfb8aa3b, v5
	v_mul_f32_e32 v9, 0xbfb8aa3b, v7
	v_exp_f32_e32 v8, v8
	v_exp_f32_e32 v9, v9
	s_waitcnt vmcnt(1)
	v_mov_b32_e32 v36, v10
	v_mov_b32_e32 v37, v12
	s_waitcnt vmcnt(0)
	v_mov_b32_e32 v42, v38
	v_mov_b32_e32 v43, v40
	v_pk_fma_f32 v[34:35], v[34:35], v[36:37], v[42:43]
	global_load_dwordx2 v[36:37], v[28:29], off offset:64
	v_mov_b32_e32 v12, v11
	v_mov_b32_e32 v40, v39
	v_pk_fma_f32 v[10:11], v[30:31], v[12:13], v[40:41]
	v_pk_add_f32 v[8:9], v[8:9], 1.0 op_sel_hi:[1,0]
	s_waitcnt vmcnt(0)
	v_and_b32_e32 v13, 0xffff0000, v37
	v_and_b32_e32 v12, 0xffff0000, v36
	v_pk_add_f32 v[10:11], v[10:11], v[12:13]
	v_pk_add_f32 v[12:13], v[14:15], 1.0 op_sel_hi:[1,0]
	v_lshlrev_b32_e32 v43, 16, v37
	v_div_scale_f32 v14, s[10:11], v13, v13, v6
	v_rcp_f32_e32 v15, v14
	v_lshlrev_b32_e32 v42, 16, v36
	v_pk_add_f32 v[34:35], v[34:35], v[42:43]
	v_fma_f32 v20, -v14, v15, 1.0
	v_fmac_f32_e32 v15, v20, v15
	v_div_scale_f32 v20, vcc, v6, v13, v6
	v_mul_f32_e32 v24, v20, v15
	v_fma_f32 v26, -v14, v24, v20
	v_fmac_f32_e32 v24, v26, v15
	v_fma_f32 v14, -v14, v24, v20
	v_div_fmas_f32 v14, v14, v15, v24
	v_div_fixup_f32 v13, v14, v13, v6
	v_div_scale_f32 v6, s[10:11], v12, v12, v4
	v_rcp_f32_e32 v14, v6
	v_mov_b32_e32 v26, v25
	v_fma_f32 v15, -v6, v14, 1.0
	v_fmac_f32_e32 v14, v15, v14
	v_div_scale_f32 v15, vcc, v4, v12, v4
	v_mul_f32_e32 v20, v15, v14
	v_fma_f32 v24, -v6, v20, v15
	v_fmac_f32_e32 v20, v24, v14
	v_fma_f32 v6, -v6, v20, v15
	v_div_fmas_f32 v6, v6, v14, v20
	v_div_fixup_f32 v12, v6, v12, v4
	v_div_scale_f32 v4, s[10:11], v9, v9, v7
	v_rcp_f32_e32 v6, v4
	v_pk_mul_f32 v[12:13], v[12:13], v[34:35]
	v_pk_add_f32 v[24:25], v[26:27], v[22:23] op_sel:[0,1] neg_lo:[0,1] neg_hi:[0,1]
	v_fma_f32 v14, -v4, v6, 1.0
	v_fmac_f32_e32 v6, v14, v6
	v_div_scale_f32 v14, vcc, v7, v9, v7
	v_mul_f32_e32 v15, v14, v6
	v_fma_f32 v20, -v4, v15, v14
	v_fmac_f32_e32 v15, v20, v6
	v_fma_f32 v4, -v4, v15, v14
	v_div_fmas_f32 v4, v4, v6, v15
	v_div_fixup_f32 v7, v4, v9, v7
	v_div_scale_f32 v4, s[10:11], v8, v8, v5
	v_rcp_f32_e32 v6, v4
	v_pk_mul_f32 v[24:25], v[24:25], v[18:19] op_sel_hi:[1,0]
	v_mov_b32_e32 v20, v19
	v_pk_add_f32 v[20:21], v[20:21], v[22:23] op_sel:[0,1] neg_lo:[0,1] neg_hi:[0,1]
	v_fma_f32 v9, -v4, v6, 1.0
	v_fmac_f32_e32 v6, v9, v6
	v_div_scale_f32 v9, vcc, v5, v8, v5
	v_mul_f32_e32 v14, v9, v6
	v_fma_f32 v15, -v4, v14, v9
	v_fmac_f32_e32 v14, v15, v6
	v_fma_f32 v4, -v4, v14, v9
	v_div_fmas_f32 v4, v4, v6, v14
	v_div_fixup_f32 v6, v4, v8, v5
	v_pk_mul_f32 v[4:5], v[6:7], v[10:11]
	v_and_b32_sdwa v6, v13, v154 dst_sel:DWORD dst_unused:UNUSED_PAD src0_sel:WORD_1 src1_sel:DWORD
	v_and_b32_sdwa v8, v5, v154 dst_sel:DWORD dst_unused:UNUSED_PAD src0_sel:WORD_1 src1_sel:DWORD
	v_and_b32_sdwa v9, v4, v154 dst_sel:DWORD dst_unused:UNUSED_PAD src0_sel:WORD_1 src1_sel:DWORD
	v_and_b32_sdwa v7, v12, v154 dst_sel:DWORD dst_unused:UNUSED_PAD src0_sel:WORD_1 src1_sel:DWORD
	v_add3_u32 v5, v5, v8, s33
	v_add3_u32 v4, v4, v9, s33
	v_add3_u32 v7, v12, v7, s33
	v_add3_u32 v6, v13, v6, s33
	v_and_b32_e32 v5, 0xffff0000, v5
	v_and_b32_e32 v4, 0xffff0000, v4
	v_or_b32_sdwa v5, v5, v6 dst_sel:DWORD dst_unused:UNUSED_PAD src0_sel:DWORD src1_sel:WORD_1
	v_or_b32_sdwa v4, v4, v7 dst_sel:DWORD dst_unused:UNUSED_PAD src0_sel:DWORD src1_sel:WORD_1
	global_store_dwordx2 v[16:17], v[4:5], off offset:64
	global_load_dwordx4 v[6:9], v89, s[0:1] offset:192
	global_load_dwordx4 v[10:13], v89, s[4:5] offset:192
	v_mul_f32_e32 v4, 0xbfb8aa3b, v0
	v_mul_f32_e32 v5, 0xbfb8aa3b, v2
	v_exp_f32_e32 v14, v4
	v_exp_f32_e32 v15, v5
	v_pk_mul_f32 v[18:19], v[20:21], v[18:19] op_sel_hi:[1,0]
	v_mul_f32_e32 v4, 0xbfb8aa3b, v1
	v_mul_f32_e32 v5, 0xbfb8aa3b, v3
	v_exp_f32_e32 v4, v4
	v_exp_f32_e32 v5, v5
	s_waitcnt vmcnt(1)
	v_mov_b32_e32 v26, v6
	v_mov_b32_e32 v27, v8
	s_waitcnt vmcnt(0)
	v_mov_b32_e32 v30, v10
	v_mov_b32_e32 v31, v12
	v_pk_fma_f32 v[24:25], v[24:25], v[26:27], v[30:31]
	global_load_dwordx2 v[26:27], v[28:29], off offset:96
	v_mov_b32_e32 v8, v7
	v_mov_b32_e32 v12, v11
	v_pk_fma_f32 v[6:7], v[18:19], v[8:9], v[12:13]
	v_pk_add_f32 v[4:5], v[4:5], 1.0 op_sel_hi:[1,0]
	s_waitcnt vmcnt(0)
	v_and_b32_e32 v9, 0xffff0000, v27
	v_and_b32_e32 v8, 0xffff0000, v26
	v_pk_add_f32 v[6:7], v[6:7], v[8:9]
	v_pk_add_f32 v[8:9], v[14:15], 1.0 op_sel_hi:[1,0]
	v_lshlrev_b32_e32 v29, 16, v27
	v_div_scale_f32 v10, s[10:11], v9, v9, v2
	v_rcp_f32_e32 v11, v10
	v_lshlrev_b32_e32 v28, 16, v26
	v_pk_add_f32 v[24:25], v[24:25], v[28:29]
	v_fma_f32 v12, -v10, v11, 1.0
	v_fmac_f32_e32 v11, v12, v11
	v_div_scale_f32 v12, vcc, v2, v9, v2
	v_mul_f32_e32 v13, v12, v11
	v_fma_f32 v14, -v10, v13, v12
	v_fmac_f32_e32 v13, v14, v11
	v_fma_f32 v10, -v10, v13, v12
	v_div_fmas_f32 v10, v10, v11, v13
	v_div_fixup_f32 v9, v10, v9, v2
	v_div_scale_f32 v2, s[10:11], v8, v8, v0
	v_rcp_f32_e32 v10, v2
	s_nop 0
	v_fma_f32 v11, -v2, v10, 1.0
	v_fmac_f32_e32 v10, v11, v10
	v_div_scale_f32 v11, vcc, v0, v8, v0
	v_mul_f32_e32 v12, v11, v10
	v_fma_f32 v13, -v2, v12, v11
	v_fmac_f32_e32 v12, v13, v10
	v_fma_f32 v2, -v2, v12, v11
	v_div_fmas_f32 v2, v2, v10, v12
	v_div_fixup_f32 v8, v2, v8, v0
	v_div_scale_f32 v0, s[10:11], v5, v5, v3
	v_rcp_f32_e32 v2, v0
	v_pk_mul_f32 v[8:9], v[8:9], v[24:25]
	v_fma_f32 v10, -v0, v2, 1.0
	v_fmac_f32_e32 v2, v10, v2
	v_div_scale_f32 v10, vcc, v3, v5, v3
	v_mul_f32_e32 v11, v10, v2
	v_fma_f32 v12, -v0, v11, v10
	v_fmac_f32_e32 v11, v12, v2
	v_fma_f32 v0, -v0, v11, v10
	v_div_fmas_f32 v0, v0, v2, v11
	v_div_fixup_f32 v3, v0, v5, v3
	v_div_scale_f32 v0, s[10:11], v4, v4, v1
	v_rcp_f32_e32 v2, v0
	s_nop 0
	v_fma_f32 v5, -v0, v2, 1.0
	v_fmac_f32_e32 v2, v5, v2
	v_div_scale_f32 v5, vcc, v1, v4, v1
	v_mul_f32_e32 v10, v5, v2
	v_fma_f32 v11, -v0, v10, v5
	v_fmac_f32_e32 v10, v11, v2
	v_fma_f32 v0, -v0, v10, v5
	v_div_fmas_f32 v0, v0, v2, v10
	v_div_fixup_f32 v2, v0, v4, v1
	v_pk_mul_f32 v[0:1], v[2:3], v[6:7]
	v_and_b32_sdwa v2, v9, v154 dst_sel:DWORD dst_unused:UNUSED_PAD src0_sel:WORD_1 src1_sel:DWORD
	v_and_b32_sdwa v4, v1, v154 dst_sel:DWORD dst_unused:UNUSED_PAD src0_sel:WORD_1 src1_sel:DWORD
	v_and_b32_sdwa v5, v0, v154 dst_sel:DWORD dst_unused:UNUSED_PAD src0_sel:WORD_1 src1_sel:DWORD
	v_and_b32_sdwa v3, v8, v154 dst_sel:DWORD dst_unused:UNUSED_PAD src0_sel:WORD_1 src1_sel:DWORD
	v_add3_u32 v1, v1, v4, s33
	v_add3_u32 v0, v0, v5, s33
	v_add3_u32 v3, v8, v3, s33
	v_add3_u32 v2, v9, v2, s33
	v_and_b32_e32 v1, 0xffff0000, v1
	v_and_b32_e32 v0, 0xffff0000, v0
	v_or_b32_sdwa v1, v1, v2 dst_sel:DWORD dst_unused:UNUSED_PAD src0_sel:DWORD src1_sel:WORD_1
	v_or_b32_sdwa v0, v0, v3 dst_sel:DWORD dst_unused:UNUSED_PAD src0_sel:DWORD src1_sel:WORD_1
	global_store_dwordx2 v[16:17], v[0:1], off offset:96

.Lscan_tiles:
	ds_read_b128 v[16:19], v94 offset:12288
	ds_read_b128 v[12:15], v94 offset:8192
	ds_read_b32 v74, v39 offset:20480
	ds_read_b128 v[24:27], v94 offset:4096
	ds_read_b128 v[20:23], v94 offset:16384
	ds_read_b128 v[28:31], v94 offset:0
	ds_read_b128 v[84:87], v94 offset:12544
	ds_read_b128 v[80:83], v94 offset:8448
	ds_read_b32 v88, v39 offset:20736
	ds_read_b128 v[114:117], v94 offset:4352
	ds_read_b128 v[110:113], v94 offset:16640
	ds_read_b128 v[118:121], v94 offset:256
	s_waitcnt lgkmcnt(6)
	v_pk_mul_f32 v[16:17], v[8:9], v[16:17]
	v_pk_mul_f32 v[12:13], v[12:13], v[74:75] op_sel_hi:[1,0]
	v_pk_fma_f32 v[16:17], v[10:11], v[18:19], v[16:17]
	v_pk_mul_f32 v[14:15], v[14:15], v[74:75] op_sel_hi:[1,0]
	v_add_f32_e32 v16, v16, v17
	v_pk_fma_f32 v[12:13], v[8:9], v[24:25], v[12:13]
	v_pk_fma_f32 v[14:15], v[10:11], v[26:27], v[14:15]
	v_add_f32_dpp v16, v16, v16 quad_perm:[1,0,3,2] row_mask:0xf bank_mask:0xf bound_ctrl:1
	ds_read_b128 v[184:187], v94 offset:12800
	ds_read_b128 v[188:191], v94 offset:8704
	v_add_f32_dpp v16, v16, v16 quad_perm:[2,3,0,1] row_mask:0xf bank_mask:0xf bound_ctrl:1
	ds_read_b32 v204, v39 offset:20992
	ds_read_b128 v[196:199], v94 offset:4608
	v_add_f32_dpp v16, v16, v16 row_half_mirror row_mask:0xf bank_mask:0xf bound_ctrl:1
	ds_read_b128 v[192:195], v94 offset:16896
	ds_read_b128 v[200:203], v94 offset:512
	v_add_f32_dpp v16, v16, v16 row_mirror row_mask:0xf bank_mask:0xf bound_ctrl:1
	s_nop 0
	v_pk_fma_f32 v[8:9], v[20:21], v[16:17], v[12:13] op_sel_hi:[1,0,1] neg_lo:[0,1,0] neg_hi:[0,1,0]
	v_pk_fma_f32 v[10:11], v[22:23], v[16:17], v[14:15] op_sel_hi:[1,0,1] neg_lo:[0,1,0] neg_hi:[0,1,0]
	s_waitcnt lgkmcnt(6)
	v_pk_mul_f32 v[84:85], v[8:9], v[84:85]
	v_pk_mul_f32 v[28:29], v[8:9], v[28:29]
	v_pk_fma_f32 v[84:85], v[10:11], v[86:87], v[84:85]
	v_pk_fma_f32 v[28:29], v[10:11], v[30:31], v[28:29]
	v_add_f32_e32 v84, v84, v85
	v_add_f32_e32 v28, v28, v29
	v_pk_mul_f32 v[80:81], v[80:81], v[88:89] op_sel_hi:[1,0]
	v_pk_mul_f32 v[82:83], v[82:83], v[88:89] op_sel_hi:[1,0]
	v_add_f32_dpp v84, v84, v84 quad_perm:[1,0,3,2] row_mask:0xf bank_mask:0xf bound_ctrl:1
	v_add_f32_dpp v28, v28, v28 quad_perm:[1,0,3,2] row_mask:0xf bank_mask:0xf bound_ctrl:1
	v_pk_fma_f32 v[80:81], v[8:9], v[114:115], v[80:81]
	v_pk_fma_f32 v[82:83], v[10:11], v[116:117], v[82:83]
	v_add_f32_dpp v84, v84, v84 quad_perm:[2,3,0,1] row_mask:0xf bank_mask:0xf bound_ctrl:1
	v_add_f32_dpp v28, v28, v28 quad_perm:[2,3,0,1] row_mask:0xf bank_mask:0xf bound_ctrl:1
	ds_read_b128 v[16:19], v94 offset:13056
	ds_read_b128 v[12:15], v94 offset:8960
	v_add_f32_dpp v84, v84, v84 row_half_mirror row_mask:0xf bank_mask:0xf bound_ctrl:1
	v_add_f32_dpp v28, v28, v28 row_half_mirror row_mask:0xf bank_mask:0xf bound_ctrl:1
	ds_read_b32 v74, v39 offset:21248
	ds_read_b128 v[24:27], v94 offset:4864
	v_add_f32_dpp v84, v84, v84 row_mirror row_mask:0xf bank_mask:0xf bound_ctrl:1
	v_add_f32_dpp v28, v28, v28 row_mirror row_mask:0xf bank_mask:0xf bound_ctrl:1
	v_cmp_eq_u32_e32 vcc, 0, v177
	s_waitcnt vmcnt(7)
	v_and_b32_e32 v77, 0xffff0000, v56
	v_lshlrev_b32_e32 v76, 16, v56
	v_and_b32_e32 v79, 0xffff0000, v57
	v_lshlrev_b32_e32 v78, 16, v57
	ds_write_b128 v103, v[76:79] offset:24576
	v_pk_fma_f32 v[8:9], v[110:111], v[84:85], v[80:81] op_sel_hi:[1,0,1] neg_lo:[0,1,0] neg_hi:[0,1,0]
	v_pk_fma_f32 v[10:11], v[112:113], v[84:85], v[82:83] op_sel_hi:[1,0,1] neg_lo:[0,1,0] neg_hi:[0,1,0]
	v_cndmask_b32_e32 v67, v67, v28, vcc
	ds_read_b128 v[20:23], v94 offset:17152
	ds_read_b128 v[28:31], v94 offset:768
	s_waitcnt lgkmcnt(7)
	v_pk_mul_f32 v[184:185], v[8:9], v[184:185]
	v_pk_mul_f32 v[118:119], v[8:9], v[118:119]
	v_pk_fma_f32 v[184:185], v[10:11], v[186:187], v[184:185]
	v_pk_fma_f32 v[118:119], v[10:11], v[120:121], v[118:119]
	v_add_f32_e32 v184, v184, v185
	v_add_f32_e32 v118, v118, v119
	v_pk_mul_f32 v[188:189], v[188:189], v[204:205] op_sel_hi:[1,0]
	v_pk_mul_f32 v[190:191], v[190:191], v[204:205] op_sel_hi:[1,0]
	v_add_f32_dpp v184, v184, v184 quad_perm:[1,0,3,2] row_mask:0xf bank_mask:0xf bound_ctrl:1
	v_add_f32_dpp v118, v118, v118 quad_perm:[1,0,3,2] row_mask:0xf bank_mask:0xf bound_ctrl:1
	v_pk_fma_f32 v[188:189], v[8:9], v[196:197], v[188:189]
	v_pk_fma_f32 v[190:191], v[10:11], v[198:199], v[190:191]
	v_add_f32_dpp v184, v184, v184 quad_perm:[2,3,0,1] row_mask:0xf bank_mask:0xf bound_ctrl:1
	v_add_f32_dpp v118, v118, v118 quad_perm:[2,3,0,1] row_mask:0xf bank_mask:0xf bound_ctrl:1
	ds_read_b128 v[84:87], v94 offset:13312
	ds_read_b128 v[80:83], v94 offset:9216
	v_add_f32_dpp v184, v184, v184 row_half_mirror row_mask:0xf bank_mask:0xf bound_ctrl:1
	v_add_f32_dpp v118, v118, v118 row_half_mirror row_mask:0xf bank_mask:0xf bound_ctrl:1
	ds_read_b32 v88, v39 offset:21504
	ds_read_b128 v[114:117], v94 offset:5120
	v_add_f32_dpp v184, v184, v184 row_mirror row_mask:0xf bank_mask:0xf bound_ctrl:1
	v_add_f32_dpp v118, v118, v118 row_mirror row_mask:0xf bank_mask:0xf bound_ctrl:1
	v_cmp_eq_u32_e32 vcc, 1, v177
	v_and_b32_e32 v77, 0xffff0000, v58
	v_lshlrev_b32_e32 v76, 16, v58
	v_and_b32_e32 v79, 0xffff0000, v59
	v_lshlrev_b32_e32 v78, 16, v59
	ds_write_b128 v103, v[76:79] offset:32768
	v_and_b32_e32 v77, 0xffff0000, v60
	v_pk_fma_f32 v[8:9], v[192:193], v[184:185], v[188:189] op_sel_hi:[1,0,1] neg_lo:[0,1,0] neg_hi:[0,1,0]
	v_pk_fma_f32 v[10:11], v[194:195], v[184:185], v[190:191] op_sel_hi:[1,0,1] neg_lo:[0,1,0] neg_hi:[0,1,0]
	v_cndmask_b32_e32 v67, v67, v118, vcc
	ds_read_b128 v[110:113], v94 offset:17408
	ds_read_b128 v[118:121], v94 offset:1024
	s_waitcnt lgkmcnt(7)
	v_pk_mul_f32 v[16:17], v[8:9], v[16:17]
	v_pk_mul_f32 v[200:201], v[8:9], v[200:201]
	v_pk_fma_f32 v[16:17], v[10:11], v[18:19], v[16:17]
	v_pk_fma_f32 v[200:201], v[10:11], v[202:203], v[200:201]
	v_add_f32_e32 v16, v16, v17
	v_add_f32_e32 v200, v200, v201
	v_pk_mul_f32 v[12:13], v[12:13], v[74:75] op_sel_hi:[1,0]
	v_pk_mul_f32 v[14:15], v[14:15], v[74:75] op_sel_hi:[1,0]
	v_add_f32_dpp v16, v16, v16 quad_perm:[1,0,3,2] row_mask:0xf bank_mask:0xf bound_ctrl:1
	v_add_f32_dpp v200, v200, v200 quad_perm:[1,0,3,2] row_mask:0xf bank_mask:0xf bound_ctrl:1
	v_pk_fma_f32 v[12:13], v[8:9], v[24:25], v[12:13]
	v_pk_fma_f32 v[14:15], v[10:11], v[26:27], v[14:15]
	v_add_f32_dpp v16, v16, v16 quad_perm:[2,3,0,1] row_mask:0xf bank_mask:0xf bound_ctrl:1
	v_add_f32_dpp v200, v200, v200 quad_perm:[2,3,0,1] row_mask:0xf bank_mask:0xf bound_ctrl:1
	ds_read_b128 v[184:187], v94 offset:13568
	ds_read_b128 v[188:191], v94 offset:9472
	v_add_f32_dpp v16, v16, v16 row_half_mirror row_mask:0xf bank_mask:0xf bound_ctrl:1
	v_add_f32_dpp v200, v200, v200 row_half_mirror row_mask:0xf bank_mask:0xf bound_ctrl:1
	ds_read_b32 v204, v39 offset:21760
	ds_read_b128 v[196:199], v94 offset:5376
	v_add_f32_dpp v16, v16, v16 row_mirror row_mask:0xf bank_mask:0xf bound_ctrl:1
	v_add_f32_dpp v200, v200, v200 row_mirror row_mask:0xf bank_mask:0xf bound_ctrl:1
	v_cmp_eq_u32_e32 vcc, 2, v177
	v_lshlrev_b32_e32 v76, 16, v60
	v_and_b32_e32 v79, 0xffff0000, v61
	v_lshlrev_b32_e32 v78, 16, v61
	ds_write_b128 v103, v[76:79] offset:36864
	v_and_b32_e32 v77, 0xffff0000, v62
	v_lshlrev_b32_e32 v76, 16, v62
	v_pk_fma_f32 v[8:9], v[20:21], v[16:17], v[12:13] op_sel_hi:[1,0,1] neg_lo:[0,1,0] neg_hi:[0,1,0]
	v_pk_fma_f32 v[10:11], v[22:23], v[16:17], v[14:15] op_sel_hi:[1,0,1] neg_lo:[0,1,0] neg_hi:[0,1,0]
	v_cndmask_b32_e32 v67, v67, v200, vcc
	ds_read_b128 v[192:195], v94 offset:17664
	ds_read_b128 v[200:203], v94 offset:1280
	s_waitcnt lgkmcnt(7)
	v_pk_mul_f32 v[84:85], v[8:9], v[84:85]
	v_pk_mul_f32 v[28:29], v[8:9], v[28:29]
	v_pk_fma_f32 v[84:85], v[10:11], v[86:87], v[84:85]
	v_pk_fma_f32 v[28:29], v[10:11], v[30:31], v[28:29]
	v_add_f32_e32 v84, v84, v85
	v_add_f32_e32 v28, v28, v29
	v_pk_mul_f32 v[80:81], v[80:81], v[88:89] op_sel_hi:[1,0]
	v_pk_mul_f32 v[82:83], v[82:83], v[88:89] op_sel_hi:[1,0]
	v_add_f32_dpp v84, v84, v84 quad_perm:[1,0,3,2] row_mask:0xf bank_mask:0xf bound_ctrl:1
	v_add_f32_dpp v28, v28, v28 quad_perm:[1,0,3,2] row_mask:0xf bank_mask:0xf bound_ctrl:1
	v_pk_fma_f32 v[80:81], v[8:9], v[114:115], v[80:81]
	v_pk_fma_f32 v[82:83], v[10:11], v[116:117], v[82:83]
	v_add_f32_dpp v84, v84, v84 quad_perm:[2,3,0,1] row_mask:0xf bank_mask:0xf bound_ctrl:1
	v_add_f32_dpp v28, v28, v28 quad_perm:[2,3,0,1] row_mask:0xf bank_mask:0xf bound_ctrl:1
	ds_read_b128 v[16:19], v94 offset:13824
	ds_read_b128 v[12:15], v94 offset:9728
	v_add_f32_dpp v84, v84, v84 row_half_mirror row_mask:0xf bank_mask:0xf bound_ctrl:1
	v_add_f32_dpp v28, v28, v28 row_half_mirror row_mask:0xf bank_mask:0xf bound_ctrl:1
	ds_read_b32 v74, v39 offset:22016
	ds_read_b128 v[24:27], v94 offset:5632
	v_add_f32_dpp v84, v84, v84 row_mirror row_mask:0xf bank_mask:0xf bound_ctrl:1
	v_add_f32_dpp v28, v28, v28 row_mirror row_mask:0xf bank_mask:0xf bound_ctrl:1
	v_cmp_eq_u32_e32 vcc, 3, v177
	v_and_b32_e32 v79, 0xffff0000, v63
	v_lshlrev_b32_e32 v78, 16, v63
	ds_write_b128 v103, v[76:79] offset:40960
	v_and_b32_e32 v77, 0xffff0000, v54
	v_lshlrev_b32_e32 v76, 16, v54
	v_and_b32_e32 v79, 0xffff0000, v55
	v_pk_fma_f32 v[8:9], v[110:111], v[84:85], v[80:81] op_sel_hi:[1,0,1] neg_lo:[0,1,0] neg_hi:[0,1,0]
	v_pk_fma_f32 v[10:11], v[112:113], v[84:85], v[82:83] op_sel_hi:[1,0,1] neg_lo:[0,1,0] neg_hi:[0,1,0]
	v_cndmask_b32_e32 v67, v67, v28, vcc
	ds_read_b128 v[20:23], v94 offset:17920
	ds_read_b128 v[28:31], v94 offset:1536
	s_waitcnt lgkmcnt(7)
	v_pk_mul_f32 v[184:185], v[8:9], v[184:185]
	v_pk_mul_f32 v[118:119], v[8:9], v[118:119]
	v_pk_fma_f32 v[184:185], v[10:11], v[186:187], v[184:185]
	v_pk_fma_f32 v[118:119], v[10:11], v[120:121], v[118:119]
	v_add_f32_e32 v184, v184, v185
	v_add_f32_e32 v118, v118, v119
	v_pk_mul_f32 v[188:189], v[188:189], v[204:205] op_sel_hi:[1,0]
	v_pk_mul_f32 v[190:191], v[190:191], v[204:205] op_sel_hi:[1,0]
	v_add_f32_dpp v184, v184, v184 quad_perm:[1,0,3,2] row_mask:0xf bank_mask:0xf bound_ctrl:1
	v_add_f32_dpp v118, v118, v118 quad_perm:[1,0,3,2] row_mask:0xf bank_mask:0xf bound_ctrl:1
	v_pk_fma_f32 v[188:189], v[8:9], v[196:197], v[188:189]
	v_pk_fma_f32 v[190:191], v[10:11], v[198:199], v[190:191]
	v_add_f32_dpp v184, v184, v184 quad_perm:[2,3,0,1] row_mask:0xf bank_mask:0xf bound_ctrl:1
	v_add_f32_dpp v118, v118, v118 quad_perm:[2,3,0,1] row_mask:0xf bank_mask:0xf bound_ctrl:1
	ds_read_b128 v[84:87], v94 offset:14080
	ds_read_b128 v[80:83], v94 offset:9984
	v_add_f32_dpp v184, v184, v184 row_half_mirror row_mask:0xf bank_mask:0xf bound_ctrl:1
	v_add_f32_dpp v118, v118, v118 row_half_mirror row_mask:0xf bank_mask:0xf bound_ctrl:1
	ds_read_b32 v88, v39 offset:22272
	ds_read_b128 v[114:117], v94 offset:5888
	v_add_f32_dpp v184, v184, v184 row_mirror row_mask:0xf bank_mask:0xf bound_ctrl:1
	v_add_f32_dpp v118, v118, v118 row_mirror row_mask:0xf bank_mask:0xf bound_ctrl:1
	v_cmp_eq_u32_e32 vcc, 4, v177
	v_lshlrev_b32_e32 v78, 16, v55
	ds_write_b128 v103, v[76:79] offset:45056
	ds_write_b128 v103, v[4:7] offset:28672
	s_add_i32 s6, s88, 3
	s_add_i32 s7, s89, -1
	s_min_u32 s6, s6, s7
	v_pk_fma_f32 v[8:9], v[192:193], v[184:185], v[188:189] op_sel_hi:[1,0,1] neg_lo:[0,1,0] neg_hi:[0,1,0]
	v_pk_fma_f32 v[10:11], v[194:195], v[184:185], v[190:191] op_sel_hi:[1,0,1] neg_lo:[0,1,0] neg_hi:[0,1,0]
	v_cndmask_b32_e32 v67, v67, v118, vcc
	ds_read_b128 v[110:113], v94 offset:18176
	ds_read_b128 v[118:121], v94 offset:1792
	s_waitcnt lgkmcnt(8)
	v_pk_mul_f32 v[16:17], v[8:9], v[16:17]
	v_pk_mul_f32 v[200:201], v[8:9], v[200:201]
	v_pk_fma_f32 v[16:17], v[10:11], v[18:19], v[16:17]
	v_pk_fma_f32 v[200:201], v[10:11], v[202:203], v[200:201]
	v_add_f32_e32 v16, v16, v17
	v_add_f32_e32 v200, v200, v201
	v_pk_mul_f32 v[12:13], v[12:13], v[74:75] op_sel_hi:[1,0]
	v_pk_mul_f32 v[14:15], v[14:15], v[74:75] op_sel_hi:[1,0]
	v_add_f32_dpp v16, v16, v16 quad_perm:[1,0,3,2] row_mask:0xf bank_mask:0xf bound_ctrl:1
	v_add_f32_dpp v200, v200, v200 quad_perm:[1,0,3,2] row_mask:0xf bank_mask:0xf bound_ctrl:1
	v_pk_fma_f32 v[12:13], v[8:9], v[24:25], v[12:13]
	v_pk_fma_f32 v[14:15], v[10:11], v[26:27], v[14:15]
	v_add_f32_dpp v16, v16, v16 quad_perm:[2,3,0,1] row_mask:0xf bank_mask:0xf bound_ctrl:1
	v_add_f32_dpp v200, v200, v200 quad_perm:[2,3,0,1] row_mask:0xf bank_mask:0xf bound_ctrl:1
	ds_read_b128 v[184:187], v94 offset:14336
	ds_read_b128 v[188:191], v94 offset:10240
	v_add_f32_dpp v16, v16, v16 row_half_mirror row_mask:0xf bank_mask:0xf bound_ctrl:1
	v_add_f32_dpp v200, v200, v200 row_half_mirror row_mask:0xf bank_mask:0xf bound_ctrl:1
	ds_read_b32 v204, v39 offset:22528
	ds_read_b128 v[196:199], v94 offset:6144
	v_add_f32_dpp v16, v16, v16 row_mirror row_mask:0xf bank_mask:0xf bound_ctrl:1
	v_add_f32_dpp v200, v200, v200 row_mirror row_mask:0xf bank_mask:0xf bound_ctrl:1
	v_cmp_eq_u32_e32 vcc, 5, v177
	v_lshl_add_u32 v122, s6, 4, v38
	v_ashrrev_i32_e32 v123, 31, v122
	v_lshlrev_b64 v[122:123], 10, v[122:123]
	v_or_b32_e32 v123, v123, v35
	v_or_b32_e32 v122, v122, v52
	v_lshlrev_b64 v[124:125], 1, v[122:123]
	v_pk_fma_f32 v[8:9], v[20:21], v[16:17], v[12:13] op_sel_hi:[1,0,1] neg_lo:[0,1,0] neg_hi:[0,1,0]
	v_pk_fma_f32 v[10:11], v[22:23], v[16:17], v[14:15] op_sel_hi:[1,0,1] neg_lo:[0,1,0] neg_hi:[0,1,0]
	v_cndmask_b32_e32 v67, v67, v200, vcc
	ds_read_b128 v[192:195], v94 offset:18432
	ds_read_b128 v[200:203], v94 offset:2048
	s_waitcnt lgkmcnt(6)
	v_pk_mul_f32 v[84:85], v[8:9], v[84:85]
	v_pk_mul_f32 v[28:29], v[8:9], v[28:29]
	v_pk_fma_f32 v[84:85], v[10:11], v[86:87], v[84:85]
	v_pk_fma_f32 v[28:29], v[10:11], v[30:31], v[28:29]
	v_add_f32_e32 v84, v84, v85
	v_add_f32_e32 v28, v28, v29
	v_pk_mul_f32 v[80:81], v[80:81], v[88:89] op_sel_hi:[1,0]
	v_pk_mul_f32 v[82:83], v[82:83], v[88:89] op_sel_hi:[1,0]
	v_add_f32_dpp v84, v84, v84 quad_perm:[1,0,3,2] row_mask:0xf bank_mask:0xf bound_ctrl:1
	v_add_f32_dpp v28, v28, v28 quad_perm:[1,0,3,2] row_mask:0xf bank_mask:0xf bound_ctrl:1
	v_pk_fma_f32 v[80:81], v[8:9], v[114:115], v[80:81]
	v_pk_fma_f32 v[82:83], v[10:11], v[116:117], v[82:83]
	v_add_f32_dpp v84, v84, v84 quad_perm:[2,3,0,1] row_mask:0xf bank_mask:0xf bound_ctrl:1
	v_add_f32_dpp v28, v28, v28 quad_perm:[2,3,0,1] row_mask:0xf bank_mask:0xf bound_ctrl:1
	ds_read_b128 v[16:19], v94 offset:14592
	ds_read_b128 v[12:15], v94 offset:10496
	v_add_f32_dpp v84, v84, v84 row_half_mirror row_mask:0xf bank_mask:0xf bound_ctrl:1
	v_add_f32_dpp v28, v28, v28 row_half_mirror row_mask:0xf bank_mask:0xf bound_ctrl:1
	ds_read_b32 v74, v39 offset:22784
	ds_read_b128 v[24:27], v94 offset:6400
	v_add_f32_dpp v84, v84, v84 row_mirror row_mask:0xf bank_mask:0xf bound_ctrl:1
	v_add_f32_dpp v28, v28, v28 row_mirror row_mask:0xf bank_mask:0xf bound_ctrl:1
	v_cmp_eq_u32_e32 vcc, 6, v177
	v_lshl_add_u64 v[126:127], s[8:9], 0, v[124:125]
	global_load_dwordx2 v[56:57], v[126:127], off
	v_lshl_add_u64 v[128:129], s[10:11], 0, v[124:125]
	global_load_dwordx2 v[58:59], v[128:129], off
	v_lshl_add_u64 v[130:131], s[12:13], 0, v[124:125]
	global_load_dwordx2 v[60:61], v[130:131], off
	v_pk_fma_f32 v[8:9], v[110:111], v[84:85], v[80:81] op_sel_hi:[1,0,1] neg_lo:[0,1,0] neg_hi:[0,1,0]
	v_pk_fma_f32 v[10:11], v[112:113], v[84:85], v[82:83] op_sel_hi:[1,0,1] neg_lo:[0,1,0] neg_hi:[0,1,0]
	v_cndmask_b32_e32 v67, v67, v28, vcc
	ds_read_b128 v[20:23], v94 offset:18688
	ds_read_b128 v[28:31], v94 offset:2304
	s_waitcnt lgkmcnt(6)
	v_pk_mul_f32 v[184:185], v[8:9], v[184:185]
	v_pk_mul_f32 v[118:119], v[8:9], v[118:119]
	v_pk_fma_f32 v[184:185], v[10:11], v[186:187], v[184:185]
	v_pk_fma_f32 v[118:119], v[10:11], v[120:121], v[118:119]
	v_add_f32_e32 v184, v184, v185
	v_add_f32_e32 v118, v118, v119
	v_pk_mul_f32 v[188:189], v[188:189], v[204:205] op_sel_hi:[1,0]
	v_pk_mul_f32 v[190:191], v[190:191], v[204:205] op_sel_hi:[1,0]
	v_add_f32_dpp v184, v184, v184 quad_perm:[1,0,3,2] row_mask:0xf bank_mask:0xf bound_ctrl:1
	v_add_f32_dpp v118, v118, v118 quad_perm:[1,0,3,2] row_mask:0xf bank_mask:0xf bound_ctrl:1
	v_pk_fma_f32 v[188:189], v[8:9], v[196:197], v[188:189]
	v_pk_fma_f32 v[190:191], v[10:11], v[198:199], v[190:191]
	v_add_f32_dpp v184, v184, v184 quad_perm:[2,3,0,1] row_mask:0xf bank_mask:0xf bound_ctrl:1
	v_add_f32_dpp v118, v118, v118 quad_perm:[2,3,0,1] row_mask:0xf bank_mask:0xf bound_ctrl:1
	ds_read_b128 v[84:87], v94 offset:14848
	ds_read_b128 v[80:83], v94 offset:10752
	v_add_f32_dpp v184, v184, v184 row_half_mirror row_mask:0xf bank_mask:0xf bound_ctrl:1
	v_add_f32_dpp v118, v118, v118 row_half_mirror row_mask:0xf bank_mask:0xf bound_ctrl:1
	ds_read_b32 v88, v39 offset:23040
	ds_read_b128 v[114:117], v94 offset:6656
	v_add_f32_dpp v184, v184, v184 row_mirror row_mask:0xf bank_mask:0xf bound_ctrl:1
	v_add_f32_dpp v118, v118, v118 row_mirror row_mask:0xf bank_mask:0xf bound_ctrl:1
	v_cmp_eq_u32_e32 vcc, 7, v177
	v_lshl_add_u64 v[132:133], s[14:15], 0, v[124:125]
	global_load_dwordx2 v[62:63], v[132:133], off
	v_lshl_add_u64 v[124:125], s[34:35], 0, v[124:125]
	global_load_dwordx2 v[54:55], v[124:125], off
	v_lshl_add_u64 v[122:123], v[122:123], 2, s[36:37]
	global_load_dwordx4 v[4:7], v[122:123], off
	v_pk_fma_f32 v[8:9], v[192:193], v[184:185], v[188:189] op_sel_hi:[1,0,1] neg_lo:[0,1,0] neg_hi:[0,1,0]
	v_pk_fma_f32 v[10:11], v[194:195], v[184:185], v[190:191] op_sel_hi:[1,0,1] neg_lo:[0,1,0] neg_hi:[0,1,0]
	v_cndmask_b32_e32 v67, v67, v118, vcc
	ds_read_b128 v[110:113], v94 offset:18944
	ds_read_b128 v[118:121], v94 offset:2560
	s_waitcnt lgkmcnt(6)
	v_pk_mul_f32 v[16:17], v[8:9], v[16:17]
	v_pk_mul_f32 v[200:201], v[8:9], v[200:201]
	v_pk_fma_f32 v[16:17], v[10:11], v[18:19], v[16:17]
	v_pk_fma_f32 v[200:201], v[10:11], v[202:203], v[200:201]
	v_add_f32_e32 v16, v16, v17
	v_add_f32_e32 v200, v200, v201
	v_pk_mul_f32 v[12:13], v[12:13], v[74:75] op_sel_hi:[1,0]
	v_pk_mul_f32 v[14:15], v[14:15], v[74:75] op_sel_hi:[1,0]
	v_add_f32_dpp v16, v16, v16 quad_perm:[1,0,3,2] row_mask:0xf bank_mask:0xf bound_ctrl:1
	v_add_f32_dpp v200, v200, v200 quad_perm:[1,0,3,2] row_mask:0xf bank_mask:0xf bound_ctrl:1
	v_pk_fma_f32 v[12:13], v[8:9], v[24:25], v[12:13]
	v_pk_fma_f32 v[14:15], v[10:11], v[26:27], v[14:15]
	v_add_f32_dpp v16, v16, v16 quad_perm:[2,3,0,1] row_mask:0xf bank_mask:0xf bound_ctrl:1
	v_add_f32_dpp v200, v200, v200 quad_perm:[2,3,0,1] row_mask:0xf bank_mask:0xf bound_ctrl:1
	ds_read_b128 v[184:187], v94 offset:15104
	ds_read_b128 v[188:191], v94 offset:11008
	v_add_f32_dpp v16, v16, v16 row_half_mirror row_mask:0xf bank_mask:0xf bound_ctrl:1
	v_add_f32_dpp v200, v200, v200 row_half_mirror row_mask:0xf bank_mask:0xf bound_ctrl:1
	ds_read_b32 v204, v39 offset:23296
	ds_read_b128 v[196:199], v94 offset:6912
	v_add_f32_dpp v16, v16, v16 row_mirror row_mask:0xf bank_mask:0xf bound_ctrl:1
	v_add_f32_dpp v200, v200, v200 row_mirror row_mask:0xf bank_mask:0xf bound_ctrl:1
	v_cmp_eq_u32_e32 vcc, 8, v177
	v_pk_fma_f32 v[8:9], v[20:21], v[16:17], v[12:13] op_sel_hi:[1,0,1] neg_lo:[0,1,0] neg_hi:[0,1,0]
	v_pk_fma_f32 v[10:11], v[22:23], v[16:17], v[14:15] op_sel_hi:[1,0,1] neg_lo:[0,1,0] neg_hi:[0,1,0]
	v_cndmask_b32_e32 v67, v67, v200, vcc
	ds_read_b128 v[192:195], v94 offset:19200
	ds_read_b128 v[200:203], v94 offset:2816
	s_waitcnt lgkmcnt(6)
	v_pk_mul_f32 v[84:85], v[8:9], v[84:85]
	v_pk_mul_f32 v[28:29], v[8:9], v[28:29]
	v_pk_fma_f32 v[84:85], v[10:11], v[86:87], v[84:85]
	v_pk_fma_f32 v[28:29], v[10:11], v[30:31], v[28:29]
	v_add_f32_e32 v84, v84, v85
	v_add_f32_e32 v28, v28, v29
	v_pk_mul_f32 v[80:81], v[80:81], v[88:89] op_sel_hi:[1,0]
	v_pk_mul_f32 v[82:83], v[82:83], v[88:89] op_sel_hi:[1,0]
	v_add_f32_dpp v84, v84, v84 quad_perm:[1,0,3,2] row_mask:0xf bank_mask:0xf bound_ctrl:1
	v_add_f32_dpp v28, v28, v28 quad_perm:[1,0,3,2] row_mask:0xf bank_mask:0xf bound_ctrl:1
	v_pk_fma_f32 v[80:81], v[8:9], v[114:115], v[80:81]
	v_pk_fma_f32 v[82:83], v[10:11], v[116:117], v[82:83]
	v_add_f32_dpp v84, v84, v84 quad_perm:[2,3,0,1] row_mask:0xf bank_mask:0xf bound_ctrl:1
	v_add_f32_dpp v28, v28, v28 quad_perm:[2,3,0,1] row_mask:0xf bank_mask:0xf bound_ctrl:1
	ds_read_b128 v[16:19], v94 offset:15360
	ds_read_b128 v[12:15], v94 offset:11264
	v_add_f32_dpp v84, v84, v84 row_half_mirror row_mask:0xf bank_mask:0xf bound_ctrl:1
	v_add_f32_dpp v28, v28, v28 row_half_mirror row_mask:0xf bank_mask:0xf bound_ctrl:1
	ds_read_b32 v74, v39 offset:23552
	ds_read_b128 v[24:27], v94 offset:7168
	v_add_f32_dpp v84, v84, v84 row_mirror row_mask:0xf bank_mask:0xf bound_ctrl:1
	v_add_f32_dpp v28, v28, v28 row_mirror row_mask:0xf bank_mask:0xf bound_ctrl:1
	v_cmp_eq_u32_e32 vcc, 9, v177
	v_pk_fma_f32 v[8:9], v[110:111], v[84:85], v[80:81] op_sel_hi:[1,0,1] neg_lo:[0,1,0] neg_hi:[0,1,0]
	v_pk_fma_f32 v[10:11], v[112:113], v[84:85], v[82:83] op_sel_hi:[1,0,1] neg_lo:[0,1,0] neg_hi:[0,1,0]
	v_cndmask_b32_e32 v67, v67, v28, vcc
	ds_read_b128 v[20:23], v94 offset:19456
	ds_read_b128 v[28:31], v94 offset:3072
	s_waitcnt lgkmcnt(6)
	v_pk_mul_f32 v[184:185], v[8:9], v[184:185]
	v_pk_mul_f32 v[118:119], v[8:9], v[118:119]
	v_pk_fma_f32 v[184:185], v[10:11], v[186:187], v[184:185]
	v_pk_fma_f32 v[118:119], v[10:11], v[120:121], v[118:119]
	v_add_f32_e32 v184, v184, v185
	v_add_f32_e32 v118, v118, v119
	v_pk_mul_f32 v[188:189], v[188:189], v[204:205] op_sel_hi:[1,0]
	v_pk_mul_f32 v[190:191], v[190:191], v[204:205] op_sel_hi:[1,0]
	v_add_f32_dpp v184, v184, v184 quad_perm:[1,0,3,2] row_mask:0xf bank_mask:0xf bound_ctrl:1
	v_add_f32_dpp v118, v118, v118 quad_perm:[1,0,3,2] row_mask:0xf bank_mask:0xf bound_ctrl:1
	v_pk_fma_f32 v[188:189], v[8:9], v[196:197], v[188:189]
	v_pk_fma_f32 v[190:191], v[10:11], v[198:199], v[190:191]
	v_add_f32_dpp v184, v184, v184 quad_perm:[2,3,0,1] row_mask:0xf bank_mask:0xf bound_ctrl:1
	v_add_f32_dpp v118, v118, v118 quad_perm:[2,3,0,1] row_mask:0xf bank_mask:0xf bound_ctrl:1
	ds_read_b128 v[84:87], v94 offset:15616
	ds_read_b128 v[80:83], v94 offset:11520
	v_add_f32_dpp v184, v184, v184 row_half_mirror row_mask:0xf bank_mask:0xf bound_ctrl:1
	v_add_f32_dpp v118, v118, v118 row_half_mirror row_mask:0xf bank_mask:0xf bound_ctrl:1
	ds_read_b32 v88, v39 offset:23808
	ds_read_b128 v[114:117], v94 offset:7424
	v_add_f32_dpp v184, v184, v184 row_mirror row_mask:0xf bank_mask:0xf bound_ctrl:1
	v_add_f32_dpp v118, v118, v118 row_mirror row_mask:0xf bank_mask:0xf bound_ctrl:1
	v_cmp_eq_u32_e32 vcc, 10, v177
	v_pk_fma_f32 v[8:9], v[192:193], v[184:185], v[188:189] op_sel_hi:[1,0,1] neg_lo:[0,1,0] neg_hi:[0,1,0]
	v_pk_fma_f32 v[10:11], v[194:195], v[184:185], v[190:191] op_sel_hi:[1,0,1] neg_lo:[0,1,0] neg_hi:[0,1,0]
	v_cndmask_b32_e32 v67, v67, v118, vcc
	ds_read_b128 v[110:113], v94 offset:19712
	ds_read_b128 v[118:121], v94 offset:3328
	s_waitcnt lgkmcnt(6)
	v_pk_mul_f32 v[16:17], v[8:9], v[16:17]
	v_pk_mul_f32 v[200:201], v[8:9], v[200:201]
	v_pk_fma_f32 v[16:17], v[10:11], v[18:19], v[16:17]
	v_pk_fma_f32 v[200:201], v[10:11], v[202:203], v[200:201]
	v_add_f32_e32 v16, v16, v17
	v_add_f32_e32 v200, v200, v201
	v_pk_mul_f32 v[12:13], v[12:13], v[74:75] op_sel_hi:[1,0]
	v_pk_mul_f32 v[14:15], v[14:15], v[74:75] op_sel_hi:[1,0]
	v_add_f32_dpp v16, v16, v16 quad_perm:[1,0,3,2] row_mask:0xf bank_mask:0xf bound_ctrl:1
	v_add_f32_dpp v200, v200, v200 quad_perm:[1,0,3,2] row_mask:0xf bank_mask:0xf bound_ctrl:1
	v_pk_fma_f32 v[12:13], v[8:9], v[24:25], v[12:13]
	v_pk_fma_f32 v[14:15], v[10:11], v[26:27], v[14:15]
	v_add_f32_dpp v16, v16, v16 quad_perm:[2,3,0,1] row_mask:0xf bank_mask:0xf bound_ctrl:1
	v_add_f32_dpp v200, v200, v200 quad_perm:[2,3,0,1] row_mask:0xf bank_mask:0xf bound_ctrl:1
	ds_read_b128 v[184:187], v94 offset:15872
	ds_read_b128 v[188:191], v94 offset:11776
	v_add_f32_dpp v16, v16, v16 row_half_mirror row_mask:0xf bank_mask:0xf bound_ctrl:1
	v_add_f32_dpp v200, v200, v200 row_half_mirror row_mask:0xf bank_mask:0xf bound_ctrl:1
	ds_read_b32 v204, v39 offset:24064
	ds_read_b128 v[196:199], v94 offset:7680
	v_add_f32_dpp v16, v16, v16 row_mirror row_mask:0xf bank_mask:0xf bound_ctrl:1
	v_add_f32_dpp v200, v200, v200 row_mirror row_mask:0xf bank_mask:0xf bound_ctrl:1
	v_cmp_eq_u32_e32 vcc, 11, v177
	v_pk_fma_f32 v[8:9], v[20:21], v[16:17], v[12:13] op_sel_hi:[1,0,1] neg_lo:[0,1,0] neg_hi:[0,1,0]
	v_pk_fma_f32 v[10:11], v[22:23], v[16:17], v[14:15] op_sel_hi:[1,0,1] neg_lo:[0,1,0] neg_hi:[0,1,0]
	v_cndmask_b32_e32 v67, v67, v200, vcc
	ds_read_b128 v[192:195], v94 offset:19968
	ds_read_b128 v[200:203], v94 offset:3584
	s_waitcnt lgkmcnt(6)
	v_pk_mul_f32 v[84:85], v[8:9], v[84:85]
	v_pk_mul_f32 v[28:29], v[8:9], v[28:29]
	v_pk_fma_f32 v[84:85], v[10:11], v[86:87], v[84:85]
	v_pk_fma_f32 v[28:29], v[10:11], v[30:31], v[28:29]
	v_add_f32_e32 v84, v84, v85
	v_add_f32_e32 v28, v28, v29
	v_pk_mul_f32 v[80:81], v[80:81], v[88:89] op_sel_hi:[1,0]
	v_pk_mul_f32 v[82:83], v[82:83], v[88:89] op_sel_hi:[1,0]
	v_add_f32_dpp v84, v84, v84 quad_perm:[1,0,3,2] row_mask:0xf bank_mask:0xf bound_ctrl:1
	v_add_f32_dpp v28, v28, v28 quad_perm:[1,0,3,2] row_mask:0xf bank_mask:0xf bound_ctrl:1
	v_pk_fma_f32 v[80:81], v[8:9], v[114:115], v[80:81]
	v_pk_fma_f32 v[82:83], v[10:11], v[116:117], v[82:83]
	v_add_f32_dpp v84, v84, v84 quad_perm:[2,3,0,1] row_mask:0xf bank_mask:0xf bound_ctrl:1
	v_add_f32_dpp v28, v28, v28 quad_perm:[2,3,0,1] row_mask:0xf bank_mask:0xf bound_ctrl:1
	ds_read_b128 v[16:19], v94 offset:16128
	ds_read_b128 v[12:15], v94 offset:12032
	v_add_f32_dpp v84, v84, v84 row_half_mirror row_mask:0xf bank_mask:0xf bound_ctrl:1
	v_add_f32_dpp v28, v28, v28 row_half_mirror row_mask:0xf bank_mask:0xf bound_ctrl:1
	ds_read_b32 v74, v39 offset:24320
	ds_read_b128 v[24:27], v94 offset:7936
	v_add_f32_dpp v84, v84, v84 row_mirror row_mask:0xf bank_mask:0xf bound_ctrl:1
	v_add_f32_dpp v28, v28, v28 row_mirror row_mask:0xf bank_mask:0xf bound_ctrl:1
	v_cmp_eq_u32_e32 vcc, 12, v177
	v_pk_fma_f32 v[8:9], v[110:111], v[84:85], v[80:81] op_sel_hi:[1,0,1] neg_lo:[0,1,0] neg_hi:[0,1,0]
	v_pk_fma_f32 v[10:11], v[112:113], v[84:85], v[82:83] op_sel_hi:[1,0,1] neg_lo:[0,1,0] neg_hi:[0,1,0]
	v_cndmask_b32_e32 v67, v67, v28, vcc
	ds_read_b128 v[20:23], v94 offset:20224
	ds_read_b128 v[28:31], v94 offset:3840
	s_waitcnt lgkmcnt(6)
	v_pk_mul_f32 v[184:185], v[8:9], v[184:185]
	v_pk_mul_f32 v[118:119], v[8:9], v[118:119]
	v_pk_fma_f32 v[184:185], v[10:11], v[186:187], v[184:185]
	v_pk_fma_f32 v[118:119], v[10:11], v[120:121], v[118:119]
	v_add_f32_e32 v184, v184, v185
	v_add_f32_e32 v118, v118, v119
	v_pk_mul_f32 v[188:189], v[188:189], v[204:205] op_sel_hi:[1,0]
	v_pk_mul_f32 v[190:191], v[190:191], v[204:205] op_sel_hi:[1,0]
	v_add_f32_dpp v184, v184, v184 quad_perm:[1,0,3,2] row_mask:0xf bank_mask:0xf bound_ctrl:1
	v_add_f32_dpp v118, v118, v118 quad_perm:[1,0,3,2] row_mask:0xf bank_mask:0xf bound_ctrl:1
	v_pk_fma_f32 v[188:189], v[8:9], v[196:197], v[188:189]
	v_pk_fma_f32 v[190:191], v[10:11], v[198:199], v[190:191]
	v_add_f32_dpp v184, v184, v184 quad_perm:[2,3,0,1] row_mask:0xf bank_mask:0xf bound_ctrl:1
	v_add_f32_dpp v118, v118, v118 quad_perm:[2,3,0,1] row_mask:0xf bank_mask:0xf bound_ctrl:1
	s_nop 1
	v_add_f32_dpp v184, v184, v184 row_half_mirror row_mask:0xf bank_mask:0xf bound_ctrl:1
	v_add_f32_dpp v118, v118, v118 row_half_mirror row_mask:0xf bank_mask:0xf bound_ctrl:1
	s_nop 1
	v_add_f32_dpp v184, v184, v184 row_mirror row_mask:0xf bank_mask:0xf bound_ctrl:1
	v_add_f32_dpp v118, v118, v118 row_mirror row_mask:0xf bank_mask:0xf bound_ctrl:1
	v_cmp_eq_u32_e32 vcc, 13, v177
	v_pk_fma_f32 v[8:9], v[192:193], v[184:185], v[188:189] op_sel_hi:[1,0,1] neg_lo:[0,1,0] neg_hi:[0,1,0]
	v_pk_fma_f32 v[10:11], v[194:195], v[184:185], v[190:191] op_sel_hi:[1,0,1] neg_lo:[0,1,0] neg_hi:[0,1,0]
	v_cndmask_b32_e32 v67, v67, v118, vcc
	s_waitcnt lgkmcnt(0)
	v_pk_mul_f32 v[16:17], v[8:9], v[16:17]
	v_pk_mul_f32 v[200:201], v[8:9], v[200:201]
	v_pk_fma_f32 v[16:17], v[10:11], v[18:19], v[16:17]
	v_pk_fma_f32 v[200:201], v[10:11], v[202:203], v[200:201]
	v_add_f32_e32 v16, v16, v17
	v_add_f32_e32 v200, v200, v201
	v_pk_mul_f32 v[12:13], v[12:13], v[74:75] op_sel_hi:[1,0]
	v_pk_mul_f32 v[14:15], v[14:15], v[74:75] op_sel_hi:[1,0]
	v_add_f32_dpp v16, v16, v16 quad_perm:[1,0,3,2] row_mask:0xf bank_mask:0xf bound_ctrl:1
	v_add_f32_dpp v200, v200, v200 quad_perm:[1,0,3,2] row_mask:0xf bank_mask:0xf bound_ctrl:1
	v_pk_fma_f32 v[12:13], v[8:9], v[24:25], v[12:13]
	v_pk_fma_f32 v[14:15], v[10:11], v[26:27], v[14:15]
	v_add_f32_dpp v16, v16, v16 quad_perm:[2,3,0,1] row_mask:0xf bank_mask:0xf bound_ctrl:1
	v_add_f32_dpp v200, v200, v200 quad_perm:[2,3,0,1] row_mask:0xf bank_mask:0xf bound_ctrl:1
	s_nop 1
	v_add_f32_dpp v16, v16, v16 row_half_mirror row_mask:0xf bank_mask:0xf bound_ctrl:1
	v_add_f32_dpp v200, v200, v200 row_half_mirror row_mask:0xf bank_mask:0xf bound_ctrl:1
	s_nop 1
	v_add_f32_dpp v16, v16, v16 row_mirror row_mask:0xf bank_mask:0xf bound_ctrl:1
	v_add_f32_dpp v200, v200, v200 row_mirror row_mask:0xf bank_mask:0xf bound_ctrl:1
	v_cmp_eq_u32_e32 vcc, 14, v177
	v_pk_fma_f32 v[8:9], v[20:21], v[16:17], v[12:13] op_sel_hi:[1,0,1] neg_lo:[0,1,0] neg_hi:[0,1,0]
	v_pk_fma_f32 v[10:11], v[22:23], v[16:17], v[14:15] op_sel_hi:[1,0,1] neg_lo:[0,1,0] neg_hi:[0,1,0]
	v_cndmask_b32_e32 v67, v67, v200, vcc
	v_pk_mul_f32 v[28:29], v[8:9], v[28:29]
	s_nop 0
	v_pk_fma_f32 v[28:29], v[10:11], v[30:31], v[28:29]
	s_add_i32 s6, s88, 0
	v_add_f32_e32 v28, v28, v29
	v_lshl_add_u32 v78, s6, 4, v178
	v_ashrrev_i32_e32 v79, 31, v78
	v_add_f32_dpp v28, v28, v28 quad_perm:[1,0,3,2] row_mask:0xf bank_mask:0xf bound_ctrl:1
	v_lshlrev_b64 v[78:79], 11, v[78:79]
	v_cmp_eq_u32_e32 vcc, 15, v177
	v_add_f32_dpp v28, v28, v28 quad_perm:[2,3,0,1] row_mask:0xf bank_mask:0xf bound_ctrl:1
	v_lshl_add_u64 v[78:79], v[180:181], 0, v[78:79]
	s_nop 0
	v_add_f32_dpp v28, v28, v28 row_half_mirror row_mask:0xf bank_mask:0xf bound_ctrl:1
	s_nop 1
	v_add_f32_dpp v28, v28, v28 row_mirror row_mask:0xf bank_mask:0xf bound_ctrl:1
	s_nop 0
	v_cndmask_b32_e32 v67, v67, v28, vcc
	v_bfe_u32 v76, v67, 16, 1
	v_add3_u32 v76, v67, v76, s33
	global_store_short_d16_hi v[78:79], v76, off
	s_waitcnt lgkmcnt(0)
	s_barrier
	s_add_i32 s6, s88, 1
	s_cmp_ge_u32 s6, s89
	s_cbranch_scc1 .Lscan_tiles_done
	ds_read_b128 v[16:19], v94 offset:36864
	ds_read_b128 v[12:15], v94 offset:32768
	ds_read_b32 v74, v39 offset:45056
	ds_read_b128 v[24:27], v94 offset:28672
	ds_read_b128 v[20:23], v94 offset:40960
	ds_read_b128 v[28:31], v94 offset:24576
	ds_read_b128 v[84:87], v94 offset:37120
	ds_read_b128 v[80:83], v94 offset:33024
	ds_read_b32 v88, v39 offset:45312
	ds_read_b128 v[114:117], v94 offset:28928
	ds_read_b128 v[110:113], v94 offset:41216
	ds_read_b128 v[118:121], v94 offset:24832
	s_waitcnt lgkmcnt(6)
	v_pk_mul_f32 v[16:17], v[8:9], v[16:17]
	v_pk_mul_f32 v[12:13], v[12:13], v[74:75] op_sel_hi:[1,0]
	v_pk_fma_f32 v[16:17], v[10:11], v[18:19], v[16:17]
	v_pk_mul_f32 v[14:15], v[14:15], v[74:75] op_sel_hi:[1,0]
	v_add_f32_e32 v16, v16, v17
	v_pk_fma_f32 v[12:13], v[8:9], v[24:25], v[12:13]
	v_pk_fma_f32 v[14:15], v[10:11], v[26:27], v[14:15]
	v_add_f32_dpp v16, v16, v16 quad_perm:[1,0,3,2] row_mask:0xf bank_mask:0xf bound_ctrl:1
	ds_read_b128 v[184:187], v94 offset:37376
	ds_read_b128 v[188:191], v94 offset:33280
	v_add_f32_dpp v16, v16, v16 quad_perm:[2,3,0,1] row_mask:0xf bank_mask:0xf bound_ctrl:1
	ds_read_b32 v204, v39 offset:45568
	ds_read_b128 v[196:199], v94 offset:29184
	v_add_f32_dpp v16, v16, v16 row_half_mirror row_mask:0xf bank_mask:0xf bound_ctrl:1
	ds_read_b128 v[192:195], v94 offset:41472
	ds_read_b128 v[200:203], v94 offset:25088
	v_add_f32_dpp v16, v16, v16 row_mirror row_mask:0xf bank_mask:0xf bound_ctrl:1
	s_nop 0
	v_pk_fma_f32 v[8:9], v[20:21], v[16:17], v[12:13] op_sel_hi:[1,0,1] neg_lo:[0,1,0] neg_hi:[0,1,0]
	v_pk_fma_f32 v[10:11], v[22:23], v[16:17], v[14:15] op_sel_hi:[1,0,1] neg_lo:[0,1,0] neg_hi:[0,1,0]
	s_waitcnt lgkmcnt(6)
	v_pk_mul_f32 v[84:85], v[8:9], v[84:85]
	v_pk_mul_f32 v[28:29], v[8:9], v[28:29]
	v_pk_fma_f32 v[84:85], v[10:11], v[86:87], v[84:85]
	v_pk_fma_f32 v[28:29], v[10:11], v[30:31], v[28:29]
	v_add_f32_e32 v84, v84, v85
	v_add_f32_e32 v28, v28, v29
	v_pk_mul_f32 v[80:81], v[80:81], v[88:89] op_sel_hi:[1,0]
	v_pk_mul_f32 v[82:83], v[82:83], v[88:89] op_sel_hi:[1,0]
	v_add_f32_dpp v84, v84, v84 quad_perm:[1,0,3,2] row_mask:0xf bank_mask:0xf bound_ctrl:1
	v_add_f32_dpp v28, v28, v28 quad_perm:[1,0,3,2] row_mask:0xf bank_mask:0xf bound_ctrl:1
	v_pk_fma_f32 v[80:81], v[8:9], v[114:115], v[80:81]
	v_pk_fma_f32 v[82:83], v[10:11], v[116:117], v[82:83]
	v_add_f32_dpp v84, v84, v84 quad_perm:[2,3,0,1] row_mask:0xf bank_mask:0xf bound_ctrl:1
	v_add_f32_dpp v28, v28, v28 quad_perm:[2,3,0,1] row_mask:0xf bank_mask:0xf bound_ctrl:1
	ds_read_b128 v[16:19], v94 offset:37632
	ds_read_b128 v[12:15], v94 offset:33536
	v_add_f32_dpp v84, v84, v84 row_half_mirror row_mask:0xf bank_mask:0xf bound_ctrl:1
	v_add_f32_dpp v28, v28, v28 row_half_mirror row_mask:0xf bank_mask:0xf bound_ctrl:1
	ds_read_b32 v74, v39 offset:45824
	ds_read_b128 v[24:27], v94 offset:29440
	v_add_f32_dpp v84, v84, v84 row_mirror row_mask:0xf bank_mask:0xf bound_ctrl:1
	v_add_f32_dpp v28, v28, v28 row_mirror row_mask:0xf bank_mask:0xf bound_ctrl:1
	v_cmp_eq_u32_e32 vcc, 0, v177
	s_waitcnt vmcnt(7)
	v_and_b32_e32 v77, 0xffff0000, v40
	v_lshlrev_b32_e32 v76, 16, v40
	v_and_b32_e32 v79, 0xffff0000, v41
	v_lshlrev_b32_e32 v78, 16, v41
	ds_write_b128 v103, v[76:79]
	v_pk_fma_f32 v[8:9], v[110:111], v[84:85], v[80:81] op_sel_hi:[1,0,1] neg_lo:[0,1,0] neg_hi:[0,1,0]
	v_pk_fma_f32 v[10:11], v[112:113], v[84:85], v[82:83] op_sel_hi:[1,0,1] neg_lo:[0,1,0] neg_hi:[0,1,0]
	v_cndmask_b32_e32 v67, v67, v28, vcc
	ds_read_b128 v[20:23], v94 offset:41728
	ds_read_b128 v[28:31], v94 offset:25344
	s_waitcnt lgkmcnt(7)
	v_pk_mul_f32 v[184:185], v[8:9], v[184:185]
	v_pk_mul_f32 v[118:119], v[8:9], v[118:119]
	v_pk_fma_f32 v[184:185], v[10:11], v[186:187], v[184:185]
	v_pk_fma_f32 v[118:119], v[10:11], v[120:121], v[118:119]
	v_add_f32_e32 v184, v184, v185
	v_add_f32_e32 v118, v118, v119
	v_pk_mul_f32 v[188:189], v[188:189], v[204:205] op_sel_hi:[1,0]
	v_pk_mul_f32 v[190:191], v[190:191], v[204:205] op_sel_hi:[1,0]
	v_add_f32_dpp v184, v184, v184 quad_perm:[1,0,3,2] row_mask:0xf bank_mask:0xf bound_ctrl:1
	v_add_f32_dpp v118, v118, v118 quad_perm:[1,0,3,2] row_mask:0xf bank_mask:0xf bound_ctrl:1
	v_pk_fma_f32 v[188:189], v[8:9], v[196:197], v[188:189]
	v_pk_fma_f32 v[190:191], v[10:11], v[198:199], v[190:191]
	v_add_f32_dpp v184, v184, v184 quad_perm:[2,3,0,1] row_mask:0xf bank_mask:0xf bound_ctrl:1
	v_add_f32_dpp v118, v118, v118 quad_perm:[2,3,0,1] row_mask:0xf bank_mask:0xf bound_ctrl:1
	ds_read_b128 v[84:87], v94 offset:37888
	ds_read_b128 v[80:83], v94 offset:33792
	v_add_f32_dpp v184, v184, v184 row_half_mirror row_mask:0xf bank_mask:0xf bound_ctrl:1
	v_add_f32_dpp v118, v118, v118 row_half_mirror row_mask:0xf bank_mask:0xf bound_ctrl:1
	ds_read_b32 v88, v39 offset:46080
	ds_read_b128 v[114:117], v94 offset:29696
	v_add_f32_dpp v184, v184, v184 row_mirror row_mask:0xf bank_mask:0xf bound_ctrl:1
	v_add_f32_dpp v118, v118, v118 row_mirror row_mask:0xf bank_mask:0xf bound_ctrl:1
	v_cmp_eq_u32_e32 vcc, 1, v177
	v_and_b32_e32 v77, 0xffff0000, v42
	v_lshlrev_b32_e32 v76, 16, v42
	v_and_b32_e32 v79, 0xffff0000, v43
	v_lshlrev_b32_e32 v78, 16, v43
	ds_write_b128 v103, v[76:79] offset:8192
	v_and_b32_e32 v77, 0xffff0000, v44
	v_pk_fma_f32 v[8:9], v[192:193], v[184:185], v[188:189] op_sel_hi:[1,0,1] neg_lo:[0,1,0] neg_hi:[0,1,0]
	v_pk_fma_f32 v[10:11], v[194:195], v[184:185], v[190:191] op_sel_hi:[1,0,1] neg_lo:[0,1,0] neg_hi:[0,1,0]
	v_cndmask_b32_e32 v67, v67, v118, vcc
	ds_read_b128 v[110:113], v94 offset:41984
	ds_read_b128 v[118:121], v94 offset:25600
	s_waitcnt lgkmcnt(7)
	v_pk_mul_f32 v[16:17], v[8:9], v[16:17]
	v_pk_mul_f32 v[200:201], v[8:9], v[200:201]
	v_pk_fma_f32 v[16:17], v[10:11], v[18:19], v[16:17]
	v_pk_fma_f32 v[200:201], v[10:11], v[202:203], v[200:201]
	v_add_f32_e32 v16, v16, v17
	v_add_f32_e32 v200, v200, v201
	v_pk_mul_f32 v[12:13], v[12:13], v[74:75] op_sel_hi:[1,0]
	v_pk_mul_f32 v[14:15], v[14:15], v[74:75] op_sel_hi:[1,0]
	v_add_f32_dpp v16, v16, v16 quad_perm:[1,0,3,2] row_mask:0xf bank_mask:0xf bound_ctrl:1
	v_add_f32_dpp v200, v200, v200 quad_perm:[1,0,3,2] row_mask:0xf bank_mask:0xf bound_ctrl:1
	v_pk_fma_f32 v[12:13], v[8:9], v[24:25], v[12:13]
	v_pk_fma_f32 v[14:15], v[10:11], v[26:27], v[14:15]
	v_add_f32_dpp v16, v16, v16 quad_perm:[2,3,0,1] row_mask:0xf bank_mask:0xf bound_ctrl:1
	v_add_f32_dpp v200, v200, v200 quad_perm:[2,3,0,1] row_mask:0xf bank_mask:0xf bound_ctrl:1
	ds_read_b128 v[184:187], v94 offset:38144
	ds_read_b128 v[188:191], v94 offset:34048
	v_add_f32_dpp v16, v16, v16 row_half_mirror row_mask:0xf bank_mask:0xf bound_ctrl:1
	v_add_f32_dpp v200, v200, v200 row_half_mirror row_mask:0xf bank_mask:0xf bound_ctrl:1
	ds_read_b32 v204, v39 offset:46336
	ds_read_b128 v[196:199], v94 offset:29952
	v_add_f32_dpp v16, v16, v16 row_mirror row_mask:0xf bank_mask:0xf bound_ctrl:1
	v_add_f32_dpp v200, v200, v200 row_mirror row_mask:0xf bank_mask:0xf bound_ctrl:1
	v_cmp_eq_u32_e32 vcc, 2, v177
	v_lshlrev_b32_e32 v76, 16, v44
	v_and_b32_e32 v79, 0xffff0000, v45
	v_lshlrev_b32_e32 v78, 16, v45
	ds_write_b128 v103, v[76:79] offset:12288
	v_and_b32_e32 v77, 0xffff0000, v46
	v_lshlrev_b32_e32 v76, 16, v46
	v_pk_fma_f32 v[8:9], v[20:21], v[16:17], v[12:13] op_sel_hi:[1,0,1] neg_lo:[0,1,0] neg_hi:[0,1,0]
	v_pk_fma_f32 v[10:11], v[22:23], v[16:17], v[14:15] op_sel_hi:[1,0,1] neg_lo:[0,1,0] neg_hi:[0,1,0]
	v_cndmask_b32_e32 v67, v67, v200, vcc
	ds_read_b128 v[192:195], v94 offset:42240
	ds_read_b128 v[200:203], v94 offset:25856
	s_waitcnt lgkmcnt(7)
	v_pk_mul_f32 v[84:85], v[8:9], v[84:85]
	v_pk_mul_f32 v[28:29], v[8:9], v[28:29]
	v_pk_fma_f32 v[84:85], v[10:11], v[86:87], v[84:85]
	v_pk_fma_f32 v[28:29], v[10:11], v[30:31], v[28:29]
	v_add_f32_e32 v84, v84, v85
	v_add_f32_e32 v28, v28, v29
	v_pk_mul_f32 v[80:81], v[80:81], v[88:89] op_sel_hi:[1,0]
	v_pk_mul_f32 v[82:83], v[82:83], v[88:89] op_sel_hi:[1,0]
	v_add_f32_dpp v84, v84, v84 quad_perm:[1,0,3,2] row_mask:0xf bank_mask:0xf bound_ctrl:1
	v_add_f32_dpp v28, v28, v28 quad_perm:[1,0,3,2] row_mask:0xf bank_mask:0xf bound_ctrl:1
	v_pk_fma_f32 v[80:81], v[8:9], v[114:115], v[80:81]
	v_pk_fma_f32 v[82:83], v[10:11], v[116:117], v[82:83]
	v_add_f32_dpp v84, v84, v84 quad_perm:[2,3,0,1] row_mask:0xf bank_mask:0xf bound_ctrl:1
	v_add_f32_dpp v28, v28, v28 quad_perm:[2,3,0,1] row_mask:0xf bank_mask:0xf bound_ctrl:1
	ds_read_b128 v[16:19], v94 offset:38400
	ds_read_b128 v[12:15], v94 offset:34304
	v_add_f32_dpp v84, v84, v84 row_half_mirror row_mask:0xf bank_mask:0xf bound_ctrl:1
	v_add_f32_dpp v28, v28, v28 row_half_mirror row_mask:0xf bank_mask:0xf bound_ctrl:1
	ds_read_b32 v74, v39 offset:46592
	ds_read_b128 v[24:27], v94 offset:30208
	v_add_f32_dpp v84, v84, v84 row_mirror row_mask:0xf bank_mask:0xf bound_ctrl:1
	v_add_f32_dpp v28, v28, v28 row_mirror row_mask:0xf bank_mask:0xf bound_ctrl:1
	v_cmp_eq_u32_e32 vcc, 3, v177
	v_and_b32_e32 v79, 0xffff0000, v47
	v_lshlrev_b32_e32 v78, 16, v47
	ds_write_b128 v103, v[76:79] offset:16384
	v_and_b32_e32 v77, 0xffff0000, v48
	v_lshlrev_b32_e32 v76, 16, v48
	v_and_b32_e32 v79, 0xffff0000, v49
	v_pk_fma_f32 v[8:9], v[110:111], v[84:85], v[80:81] op_sel_hi:[1,0,1] neg_lo:[0,1,0] neg_hi:[0,1,0]
	v_pk_fma_f32 v[10:11], v[112:113], v[84:85], v[82:83] op_sel_hi:[1,0,1] neg_lo:[0,1,0] neg_hi:[0,1,0]
	v_cndmask_b32_e32 v67, v67, v28, vcc
	ds_read_b128 v[20:23], v94 offset:42496
	ds_read_b128 v[28:31], v94 offset:26112
	s_waitcnt lgkmcnt(7)
	v_pk_mul_f32 v[184:185], v[8:9], v[184:185]
	v_pk_mul_f32 v[118:119], v[8:9], v[118:119]
	v_pk_fma_f32 v[184:185], v[10:11], v[186:187], v[184:185]
	v_pk_fma_f32 v[118:119], v[10:11], v[120:121], v[118:119]
	v_add_f32_e32 v184, v184, v185
	v_add_f32_e32 v118, v118, v119
	v_pk_mul_f32 v[188:189], v[188:189], v[204:205] op_sel_hi:[1,0]
	v_pk_mul_f32 v[190:191], v[190:191], v[204:205] op_sel_hi:[1,0]
	v_add_f32_dpp v184, v184, v184 quad_perm:[1,0,3,2] row_mask:0xf bank_mask:0xf bound_ctrl:1
	v_add_f32_dpp v118, v118, v118 quad_perm:[1,0,3,2] row_mask:0xf bank_mask:0xf bound_ctrl:1
	v_pk_fma_f32 v[188:189], v[8:9], v[196:197], v[188:189]
	v_pk_fma_f32 v[190:191], v[10:11], v[198:199], v[190:191]
	v_add_f32_dpp v184, v184, v184 quad_perm:[2,3,0,1] row_mask:0xf bank_mask:0xf bound_ctrl:1
	v_add_f32_dpp v118, v118, v118 quad_perm:[2,3,0,1] row_mask:0xf bank_mask:0xf bound_ctrl:1
	ds_read_b128 v[84:87], v94 offset:38656
	ds_read_b128 v[80:83], v94 offset:34560
	v_add_f32_dpp v184, v184, v184 row_half_mirror row_mask:0xf bank_mask:0xf bound_ctrl:1
	v_add_f32_dpp v118, v118, v118 row_half_mirror row_mask:0xf bank_mask:0xf bound_ctrl:1
	ds_read_b32 v88, v39 offset:46848
	ds_read_b128 v[114:117], v94 offset:30464
	v_add_f32_dpp v184, v184, v184 row_mirror row_mask:0xf bank_mask:0xf bound_ctrl:1
	v_add_f32_dpp v118, v118, v118 row_mirror row_mask:0xf bank_mask:0xf bound_ctrl:1
	v_cmp_eq_u32_e32 vcc, 4, v177
	v_lshlrev_b32_e32 v78, 16, v49
	ds_write_b128 v103, v[76:79] offset:20480
	ds_write_b128 v103, v[0:3] offset:4096
	s_add_i32 s6, s88, 4
	s_add_i32 s7, s89, -1
	s_min_u32 s6, s6, s7
	v_pk_fma_f32 v[8:9], v[192:193], v[184:185], v[188:189] op_sel_hi:[1,0,1] neg_lo:[0,1,0] neg_hi:[0,1,0]
	v_pk_fma_f32 v[10:11], v[194:195], v[184:185], v[190:191] op_sel_hi:[1,0,1] neg_lo:[0,1,0] neg_hi:[0,1,0]
	v_cndmask_b32_e32 v67, v67, v118, vcc
	ds_read_b128 v[110:113], v94 offset:42752
	ds_read_b128 v[118:121], v94 offset:26368
	s_waitcnt lgkmcnt(8)
	v_pk_mul_f32 v[16:17], v[8:9], v[16:17]
	v_pk_mul_f32 v[200:201], v[8:9], v[200:201]
	v_pk_fma_f32 v[16:17], v[10:11], v[18:19], v[16:17]
	v_pk_fma_f32 v[200:201], v[10:11], v[202:203], v[200:201]
	v_add_f32_e32 v16, v16, v17
	v_add_f32_e32 v200, v200, v201
	v_pk_mul_f32 v[12:13], v[12:13], v[74:75] op_sel_hi:[1,0]
	v_pk_mul_f32 v[14:15], v[14:15], v[74:75] op_sel_hi:[1,0]
	v_add_f32_dpp v16, v16, v16 quad_perm:[1,0,3,2] row_mask:0xf bank_mask:0xf bound_ctrl:1
	v_add_f32_dpp v200, v200, v200 quad_perm:[1,0,3,2] row_mask:0xf bank_mask:0xf bound_ctrl:1
	v_pk_fma_f32 v[12:13], v[8:9], v[24:25], v[12:13]
	v_pk_fma_f32 v[14:15], v[10:11], v[26:27], v[14:15]
	v_add_f32_dpp v16, v16, v16 quad_perm:[2,3,0,1] row_mask:0xf bank_mask:0xf bound_ctrl:1
	v_add_f32_dpp v200, v200, v200 quad_perm:[2,3,0,1] row_mask:0xf bank_mask:0xf bound_ctrl:1
	ds_read_b128 v[184:187], v94 offset:38912
	ds_read_b128 v[188:191], v94 offset:34816
	v_add_f32_dpp v16, v16, v16 row_half_mirror row_mask:0xf bank_mask:0xf bound_ctrl:1
	v_add_f32_dpp v200, v200, v200 row_half_mirror row_mask:0xf bank_mask:0xf bound_ctrl:1
	ds_read_b32 v204, v39 offset:47104
	ds_read_b128 v[196:199], v94 offset:30720
	v_add_f32_dpp v16, v16, v16 row_mirror row_mask:0xf bank_mask:0xf bound_ctrl:1
	v_add_f32_dpp v200, v200, v200 row_mirror row_mask:0xf bank_mask:0xf bound_ctrl:1
	v_cmp_eq_u32_e32 vcc, 5, v177
	v_lshl_add_u32 v122, s6, 4, v38
	v_ashrrev_i32_e32 v123, 31, v122
	v_lshlrev_b64 v[122:123], 10, v[122:123]
	v_or_b32_e32 v123, v123, v35
	v_or_b32_e32 v122, v122, v52
	v_lshlrev_b64 v[124:125], 1, v[122:123]
	v_pk_fma_f32 v[8:9], v[20:21], v[16:17], v[12:13] op_sel_hi:[1,0,1] neg_lo:[0,1,0] neg_hi:[0,1,0]
	v_pk_fma_f32 v[10:11], v[22:23], v[16:17], v[14:15] op_sel_hi:[1,0,1] neg_lo:[0,1,0] neg_hi:[0,1,0]
	v_cndmask_b32_e32 v67, v67, v200, vcc
	ds_read_b128 v[192:195], v94 offset:43008
	ds_read_b128 v[200:203], v94 offset:26624
	s_waitcnt lgkmcnt(6)
	v_pk_mul_f32 v[84:85], v[8:9], v[84:85]
	v_pk_mul_f32 v[28:29], v[8:9], v[28:29]
	v_pk_fma_f32 v[84:85], v[10:11], v[86:87], v[84:85]
	v_pk_fma_f32 v[28:29], v[10:11], v[30:31], v[28:29]
	v_add_f32_e32 v84, v84, v85
	v_add_f32_e32 v28, v28, v29
	v_pk_mul_f32 v[80:81], v[80:81], v[88:89] op_sel_hi:[1,0]
	v_pk_mul_f32 v[82:83], v[82:83], v[88:89] op_sel_hi:[1,0]
	v_add_f32_dpp v84, v84, v84 quad_perm:[1,0,3,2] row_mask:0xf bank_mask:0xf bound_ctrl:1
	v_add_f32_dpp v28, v28, v28 quad_perm:[1,0,3,2] row_mask:0xf bank_mask:0xf bound_ctrl:1
	v_pk_fma_f32 v[80:81], v[8:9], v[114:115], v[80:81]
	v_pk_fma_f32 v[82:83], v[10:11], v[116:117], v[82:83]
	v_add_f32_dpp v84, v84, v84 quad_perm:[2,3,0,1] row_mask:0xf bank_mask:0xf bound_ctrl:1
	v_add_f32_dpp v28, v28, v28 quad_perm:[2,3,0,1] row_mask:0xf bank_mask:0xf bound_ctrl:1
	ds_read_b128 v[16:19], v94 offset:39168
	ds_read_b128 v[12:15], v94 offset:35072
	v_add_f32_dpp v84, v84, v84 row_half_mirror row_mask:0xf bank_mask:0xf bound_ctrl:1
	v_add_f32_dpp v28, v28, v28 row_half_mirror row_mask:0xf bank_mask:0xf bound_ctrl:1
	ds_read_b32 v74, v39 offset:47360
	ds_read_b128 v[24:27], v94 offset:30976
	v_add_f32_dpp v84, v84, v84 row_mirror row_mask:0xf bank_mask:0xf bound_ctrl:1
	v_add_f32_dpp v28, v28, v28 row_mirror row_mask:0xf bank_mask:0xf bound_ctrl:1
	v_cmp_eq_u32_e32 vcc, 6, v177
	v_lshl_add_u64 v[126:127], s[8:9], 0, v[124:125]
	global_load_dwordx2 v[40:41], v[126:127], off
	v_lshl_add_u64 v[128:129], s[10:11], 0, v[124:125]
	global_load_dwordx2 v[42:43], v[128:129], off
	v_lshl_add_u64 v[130:131], s[12:13], 0, v[124:125]
	global_load_dwordx2 v[44:45], v[130:131], off
	v_pk_fma_f32 v[8:9], v[110:111], v[84:85], v[80:81] op_sel_hi:[1,0,1] neg_lo:[0,1,0] neg_hi:[0,1,0]
	v_pk_fma_f32 v[10:11], v[112:113], v[84:85], v[82:83] op_sel_hi:[1,0,1] neg_lo:[0,1,0] neg_hi:[0,1,0]
	v_cndmask_b32_e32 v67, v67, v28, vcc
	ds_read_b128 v[20:23], v94 offset:43264
	ds_read_b128 v[28:31], v94 offset:26880
	s_waitcnt lgkmcnt(6)
	v_pk_mul_f32 v[184:185], v[8:9], v[184:185]
	v_pk_mul_f32 v[118:119], v[8:9], v[118:119]
	v_pk_fma_f32 v[184:185], v[10:11], v[186:187], v[184:185]
	v_pk_fma_f32 v[118:119], v[10:11], v[120:121], v[118:119]
	v_add_f32_e32 v184, v184, v185
	v_add_f32_e32 v118, v118, v119
	v_pk_mul_f32 v[188:189], v[188:189], v[204:205] op_sel_hi:[1,0]
	v_pk_mul_f32 v[190:191], v[190:191], v[204:205] op_sel_hi:[1,0]
	v_add_f32_dpp v184, v184, v184 quad_perm:[1,0,3,2] row_mask:0xf bank_mask:0xf bound_ctrl:1
	v_add_f32_dpp v118, v118, v118 quad_perm:[1,0,3,2] row_mask:0xf bank_mask:0xf bound_ctrl:1
	v_pk_fma_f32 v[188:189], v[8:9], v[196:197], v[188:189]
	v_pk_fma_f32 v[190:191], v[10:11], v[198:199], v[190:191]
	v_add_f32_dpp v184, v184, v184 quad_perm:[2,3,0,1] row_mask:0xf bank_mask:0xf bound_ctrl:1
	v_add_f32_dpp v118, v118, v118 quad_perm:[2,3,0,1] row_mask:0xf bank_mask:0xf bound_ctrl:1
	ds_read_b128 v[84:87], v94 offset:39424
	ds_read_b128 v[80:83], v94 offset:35328
	v_add_f32_dpp v184, v184, v184 row_half_mirror row_mask:0xf bank_mask:0xf bound_ctrl:1
	v_add_f32_dpp v118, v118, v118 row_half_mirror row_mask:0xf bank_mask:0xf bound_ctrl:1
	ds_read_b32 v88, v39 offset:47616
	ds_read_b128 v[114:117], v94 offset:31232
	v_add_f32_dpp v184, v184, v184 row_mirror row_mask:0xf bank_mask:0xf bound_ctrl:1
	v_add_f32_dpp v118, v118, v118 row_mirror row_mask:0xf bank_mask:0xf bound_ctrl:1
	v_cmp_eq_u32_e32 vcc, 7, v177
	v_lshl_add_u64 v[132:133], s[14:15], 0, v[124:125]
	global_load_dwordx2 v[46:47], v[132:133], off
	v_lshl_add_u64 v[124:125], s[34:35], 0, v[124:125]
	global_load_dwordx2 v[48:49], v[124:125], off
	v_lshl_add_u64 v[122:123], v[122:123], 2, s[36:37]
	global_load_dwordx4 v[0:3], v[122:123], off
	v_pk_fma_f32 v[8:9], v[192:193], v[184:185], v[188:189] op_sel_hi:[1,0,1] neg_lo:[0,1,0] neg_hi:[0,1,0]
	v_pk_fma_f32 v[10:11], v[194:195], v[184:185], v[190:191] op_sel_hi:[1,0,1] neg_lo:[0,1,0] neg_hi:[0,1,0]
	v_cndmask_b32_e32 v67, v67, v118, vcc
	ds_read_b128 v[110:113], v94 offset:43520
	ds_read_b128 v[118:121], v94 offset:27136
	s_waitcnt lgkmcnt(6)
	v_pk_mul_f32 v[16:17], v[8:9], v[16:17]
	v_pk_mul_f32 v[200:201], v[8:9], v[200:201]
	v_pk_fma_f32 v[16:17], v[10:11], v[18:19], v[16:17]
	v_pk_fma_f32 v[200:201], v[10:11], v[202:203], v[200:201]
	v_add_f32_e32 v16, v16, v17
	v_add_f32_e32 v200, v200, v201
	v_pk_mul_f32 v[12:13], v[12:13], v[74:75] op_sel_hi:[1,0]
	v_pk_mul_f32 v[14:15], v[14:15], v[74:75] op_sel_hi:[1,0]
	v_add_f32_dpp v16, v16, v16 quad_perm:[1,0,3,2] row_mask:0xf bank_mask:0xf bound_ctrl:1
	v_add_f32_dpp v200, v200, v200 quad_perm:[1,0,3,2] row_mask:0xf bank_mask:0xf bound_ctrl:1
	v_pk_fma_f32 v[12:13], v[8:9], v[24:25], v[12:13]
	v_pk_fma_f32 v[14:15], v[10:11], v[26:27], v[14:15]
	v_add_f32_dpp v16, v16, v16 quad_perm:[2,3,0,1] row_mask:0xf bank_mask:0xf bound_ctrl:1
	v_add_f32_dpp v200, v200, v200 quad_perm:[2,3,0,1] row_mask:0xf bank_mask:0xf bound_ctrl:1
	ds_read_b128 v[184:187], v94 offset:39680
	ds_read_b128 v[188:191], v94 offset:35584
	v_add_f32_dpp v16, v16, v16 row_half_mirror row_mask:0xf bank_mask:0xf bound_ctrl:1
	v_add_f32_dpp v200, v200, v200 row_half_mirror row_mask:0xf bank_mask:0xf bound_ctrl:1
	ds_read_b32 v204, v39 offset:47872
	ds_read_b128 v[196:199], v94 offset:31488
	v_add_f32_dpp v16, v16, v16 row_mirror row_mask:0xf bank_mask:0xf bound_ctrl:1
	v_add_f32_dpp v200, v200, v200 row_mirror row_mask:0xf bank_mask:0xf bound_ctrl:1
	v_cmp_eq_u32_e32 vcc, 8, v177
	v_pk_fma_f32 v[8:9], v[20:21], v[16:17], v[12:13] op_sel_hi:[1,0,1] neg_lo:[0,1,0] neg_hi:[0,1,0]
	v_pk_fma_f32 v[10:11], v[22:23], v[16:17], v[14:15] op_sel_hi:[1,0,1] neg_lo:[0,1,0] neg_hi:[0,1,0]
	v_cndmask_b32_e32 v67, v67, v200, vcc
	ds_read_b128 v[192:195], v94 offset:43776
	ds_read_b128 v[200:203], v94 offset:27392
	s_waitcnt lgkmcnt(6)
	v_pk_mul_f32 v[84:85], v[8:9], v[84:85]
	v_pk_mul_f32 v[28:29], v[8:9], v[28:29]
	v_pk_fma_f32 v[84:85], v[10:11], v[86:87], v[84:85]
	v_pk_fma_f32 v[28:29], v[10:11], v[30:31], v[28:29]
	v_add_f32_e32 v84, v84, v85
	v_add_f32_e32 v28, v28, v29
	v_pk_mul_f32 v[80:81], v[80:81], v[88:89] op_sel_hi:[1,0]
	v_pk_mul_f32 v[82:83], v[82:83], v[88:89] op_sel_hi:[1,0]
	v_add_f32_dpp v84, v84, v84 quad_perm:[1,0,3,2] row_mask:0xf bank_mask:0xf bound_ctrl:1
	v_add_f32_dpp v28, v28, v28 quad_perm:[1,0,3,2] row_mask:0xf bank_mask:0xf bound_ctrl:1
	v_pk_fma_f32 v[80:81], v[8:9], v[114:115], v[80:81]
	v_pk_fma_f32 v[82:83], v[10:11], v[116:117], v[82:83]
	v_add_f32_dpp v84, v84, v84 quad_perm:[2,3,0,1] row_mask:0xf bank_mask:0xf bound_ctrl:1
	v_add_f32_dpp v28, v28, v28 quad_perm:[2,3,0,1] row_mask:0xf bank_mask:0xf bound_ctrl:1
	ds_read_b128 v[16:19], v94 offset:39936
	ds_read_b128 v[12:15], v94 offset:35840
	v_add_f32_dpp v84, v84, v84 row_half_mirror row_mask:0xf bank_mask:0xf bound_ctrl:1
	v_add_f32_dpp v28, v28, v28 row_half_mirror row_mask:0xf bank_mask:0xf bound_ctrl:1
	ds_read_b32 v74, v39 offset:48128
	ds_read_b128 v[24:27], v94 offset:31744
	v_add_f32_dpp v84, v84, v84 row_mirror row_mask:0xf bank_mask:0xf bound_ctrl:1
	v_add_f32_dpp v28, v28, v28 row_mirror row_mask:0xf bank_mask:0xf bound_ctrl:1
	v_cmp_eq_u32_e32 vcc, 9, v177
	v_pk_fma_f32 v[8:9], v[110:111], v[84:85], v[80:81] op_sel_hi:[1,0,1] neg_lo:[0,1,0] neg_hi:[0,1,0]
	v_pk_fma_f32 v[10:11], v[112:113], v[84:85], v[82:83] op_sel_hi:[1,0,1] neg_lo:[0,1,0] neg_hi:[0,1,0]
	v_cndmask_b32_e32 v67, v67, v28, vcc
	ds_read_b128 v[20:23], v94 offset:44032
	ds_read_b128 v[28:31], v94 offset:27648
	s_waitcnt lgkmcnt(6)
	v_pk_mul_f32 v[184:185], v[8:9], v[184:185]
	v_pk_mul_f32 v[118:119], v[8:9], v[118:119]
	v_pk_fma_f32 v[184:185], v[10:11], v[186:187], v[184:185]
	v_pk_fma_f32 v[118:119], v[10:11], v[120:121], v[118:119]
	v_add_f32_e32 v184, v184, v185
	v_add_f32_e32 v118, v118, v119
	v_pk_mul_f32 v[188:189], v[188:189], v[204:205] op_sel_hi:[1,0]
	v_pk_mul_f32 v[190:191], v[190:191], v[204:205] op_sel_hi:[1,0]
	v_add_f32_dpp v184, v184, v184 quad_perm:[1,0,3,2] row_mask:0xf bank_mask:0xf bound_ctrl:1
	v_add_f32_dpp v118, v118, v118 quad_perm:[1,0,3,2] row_mask:0xf bank_mask:0xf bound_ctrl:1
	v_pk_fma_f32 v[188:189], v[8:9], v[196:197], v[188:189]
	v_pk_fma_f32 v[190:191], v[10:11], v[198:199], v[190:191]
	v_add_f32_dpp v184, v184, v184 quad_perm:[2,3,0,1] row_mask:0xf bank_mask:0xf bound_ctrl:1
	v_add_f32_dpp v118, v118, v118 quad_perm:[2,3,0,1] row_mask:0xf bank_mask:0xf bound_ctrl:1
	ds_read_b128 v[84:87], v94 offset:40192
	ds_read_b128 v[80:83], v94 offset:36096
	v_add_f32_dpp v184, v184, v184 row_half_mirror row_mask:0xf bank_mask:0xf bound_ctrl:1
	v_add_f32_dpp v118, v118, v118 row_half_mirror row_mask:0xf bank_mask:0xf bound_ctrl:1
	ds_read_b32 v88, v39 offset:48384
	ds_read_b128 v[114:117], v94 offset:32000
	v_add_f32_dpp v184, v184, v184 row_mirror row_mask:0xf bank_mask:0xf bound_ctrl:1
	v_add_f32_dpp v118, v118, v118 row_mirror row_mask:0xf bank_mask:0xf bound_ctrl:1
	v_cmp_eq_u32_e32 vcc, 10, v177
	v_pk_fma_f32 v[8:9], v[192:193], v[184:185], v[188:189] op_sel_hi:[1,0,1] neg_lo:[0,1,0] neg_hi:[0,1,0]
	v_pk_fma_f32 v[10:11], v[194:195], v[184:185], v[190:191] op_sel_hi:[1,0,1] neg_lo:[0,1,0] neg_hi:[0,1,0]
	v_cndmask_b32_e32 v67, v67, v118, vcc
	ds_read_b128 v[110:113], v94 offset:44288
	ds_read_b128 v[118:121], v94 offset:27904
	s_waitcnt lgkmcnt(6)
	v_pk_mul_f32 v[16:17], v[8:9], v[16:17]
	v_pk_mul_f32 v[200:201], v[8:9], v[200:201]
	v_pk_fma_f32 v[16:17], v[10:11], v[18:19], v[16:17]
	v_pk_fma_f32 v[200:201], v[10:11], v[202:203], v[200:201]
	v_add_f32_e32 v16, v16, v17
	v_add_f32_e32 v200, v200, v201
	v_pk_mul_f32 v[12:13], v[12:13], v[74:75] op_sel_hi:[1,0]
	v_pk_mul_f32 v[14:15], v[14:15], v[74:75] op_sel_hi:[1,0]
	v_add_f32_dpp v16, v16, v16 quad_perm:[1,0,3,2] row_mask:0xf bank_mask:0xf bound_ctrl:1
	v_add_f32_dpp v200, v200, v200 quad_perm:[1,0,3,2] row_mask:0xf bank_mask:0xf bound_ctrl:1
	v_pk_fma_f32 v[12:13], v[8:9], v[24:25], v[12:13]
	v_pk_fma_f32 v[14:15], v[10:11], v[26:27], v[14:15]
	v_add_f32_dpp v16, v16, v16 quad_perm:[2,3,0,1] row_mask:0xf bank_mask:0xf bound_ctrl:1
	v_add_f32_dpp v200, v200, v200 quad_perm:[2,3,0,1] row_mask:0xf bank_mask:0xf bound_ctrl:1
	ds_read_b128 v[184:187], v94 offset:40448
	ds_read_b128 v[188:191], v94 offset:36352
	v_add_f32_dpp v16, v16, v16 row_half_mirror row_mask:0xf bank_mask:0xf bound_ctrl:1
	v_add_f32_dpp v200, v200, v200 row_half_mirror row_mask:0xf bank_mask:0xf bound_ctrl:1
	ds_read_b32 v204, v39 offset:48640
	ds_read_b128 v[196:199], v94 offset:32256
	v_add_f32_dpp v16, v16, v16 row_mirror row_mask:0xf bank_mask:0xf bound_ctrl:1
	v_add_f32_dpp v200, v200, v200 row_mirror row_mask:0xf bank_mask:0xf bound_ctrl:1
	v_cmp_eq_u32_e32 vcc, 11, v177
	v_pk_fma_f32 v[8:9], v[20:21], v[16:17], v[12:13] op_sel_hi:[1,0,1] neg_lo:[0,1,0] neg_hi:[0,1,0]
	v_pk_fma_f32 v[10:11], v[22:23], v[16:17], v[14:15] op_sel_hi:[1,0,1] neg_lo:[0,1,0] neg_hi:[0,1,0]
	v_cndmask_b32_e32 v67, v67, v200, vcc
	ds_read_b128 v[192:195], v94 offset:44544
	ds_read_b128 v[200:203], v94 offset:28160
	s_waitcnt lgkmcnt(6)
	v_pk_mul_f32 v[84:85], v[8:9], v[84:85]
	v_pk_mul_f32 v[28:29], v[8:9], v[28:29]
	v_pk_fma_f32 v[84:85], v[10:11], v[86:87], v[84:85]
	v_pk_fma_f32 v[28:29], v[10:11], v[30:31], v[28:29]
	v_add_f32_e32 v84, v84, v85
	v_add_f32_e32 v28, v28, v29
	v_pk_mul_f32 v[80:81], v[80:81], v[88:89] op_sel_hi:[1,0]
	v_pk_mul_f32 v[82:83], v[82:83], v[88:89] op_sel_hi:[1,0]
	v_add_f32_dpp v84, v84, v84 quad_perm:[1,0,3,2] row_mask:0xf bank_mask:0xf bound_ctrl:1
	v_add_f32_dpp v28, v28, v28 quad_perm:[1,0,3,2] row_mask:0xf bank_mask:0xf bound_ctrl:1
	v_pk_fma_f32 v[80:81], v[8:9], v[114:115], v[80:81]
	v_pk_fma_f32 v[82:83], v[10:11], v[116:117], v[82:83]
	v_add_f32_dpp v84, v84, v84 quad_perm:[2,3,0,1] row_mask:0xf bank_mask:0xf bound_ctrl:1
	v_add_f32_dpp v28, v28, v28 quad_perm:[2,3,0,1] row_mask:0xf bank_mask:0xf bound_ctrl:1
	ds_read_b128 v[16:19], v94 offset:40704
	ds_read_b128 v[12:15], v94 offset:36608
	v_add_f32_dpp v84, v84, v84 row_half_mirror row_mask:0xf bank_mask:0xf bound_ctrl:1
	v_add_f32_dpp v28, v28, v28 row_half_mirror row_mask:0xf bank_mask:0xf bound_ctrl:1
	ds_read_b32 v74, v39 offset:48896
	ds_read_b128 v[24:27], v94 offset:32512
	v_add_f32_dpp v84, v84, v84 row_mirror row_mask:0xf bank_mask:0xf bound_ctrl:1
	v_add_f32_dpp v28, v28, v28 row_mirror row_mask:0xf bank_mask:0xf bound_ctrl:1
	v_cmp_eq_u32_e32 vcc, 12, v177
	v_pk_fma_f32 v[8:9], v[110:111], v[84:85], v[80:81] op_sel_hi:[1,0,1] neg_lo:[0,1,0] neg_hi:[0,1,0]
	v_pk_fma_f32 v[10:11], v[112:113], v[84:85], v[82:83] op_sel_hi:[1,0,1] neg_lo:[0,1,0] neg_hi:[0,1,0]
	v_cndmask_b32_e32 v67, v67, v28, vcc
	ds_read_b128 v[20:23], v94 offset:44800
	ds_read_b128 v[28:31], v94 offset:28416
	s_waitcnt lgkmcnt(6)
	v_pk_mul_f32 v[184:185], v[8:9], v[184:185]
	v_pk_mul_f32 v[118:119], v[8:9], v[118:119]
	v_pk_fma_f32 v[184:185], v[10:11], v[186:187], v[184:185]
	v_pk_fma_f32 v[118:119], v[10:11], v[120:121], v[118:119]
	v_add_f32_e32 v184, v184, v185
	v_add_f32_e32 v118, v118, v119
	v_pk_mul_f32 v[188:189], v[188:189], v[204:205] op_sel_hi:[1,0]
	v_pk_mul_f32 v[190:191], v[190:191], v[204:205] op_sel_hi:[1,0]
	v_add_f32_dpp v184, v184, v184 quad_perm:[1,0,3,2] row_mask:0xf bank_mask:0xf bound_ctrl:1
	v_add_f32_dpp v118, v118, v118 quad_perm:[1,0,3,2] row_mask:0xf bank_mask:0xf bound_ctrl:1
	v_pk_fma_f32 v[188:189], v[8:9], v[196:197], v[188:189]
	v_pk_fma_f32 v[190:191], v[10:11], v[198:199], v[190:191]
	v_add_f32_dpp v184, v184, v184 quad_perm:[2,3,0,1] row_mask:0xf bank_mask:0xf bound_ctrl:1
	v_add_f32_dpp v118, v118, v118 quad_perm:[2,3,0,1] row_mask:0xf bank_mask:0xf bound_ctrl:1
	s_nop 1
	v_add_f32_dpp v184, v184, v184 row_half_mirror row_mask:0xf bank_mask:0xf bound_ctrl:1
	v_add_f32_dpp v118, v118, v118 row_half_mirror row_mask:0xf bank_mask:0xf bound_ctrl:1
	s_nop 1
	v_add_f32_dpp v184, v184, v184 row_mirror row_mask:0xf bank_mask:0xf bound_ctrl:1
	v_add_f32_dpp v118, v118, v118 row_mirror row_mask:0xf bank_mask:0xf bound_ctrl:1
	v_cmp_eq_u32_e32 vcc, 13, v177
	v_pk_fma_f32 v[8:9], v[192:193], v[184:185], v[188:189] op_sel_hi:[1,0,1] neg_lo:[0,1,0] neg_hi:[0,1,0]
	v_pk_fma_f32 v[10:11], v[194:195], v[184:185], v[190:191] op_sel_hi:[1,0,1] neg_lo:[0,1,0] neg_hi:[0,1,0]
	v_cndmask_b32_e32 v67, v67, v118, vcc
	s_waitcnt lgkmcnt(0)
	v_pk_mul_f32 v[16:17], v[8:9], v[16:17]
	v_pk_mul_f32 v[200:201], v[8:9], v[200:201]
	v_pk_fma_f32 v[16:17], v[10:11], v[18:19], v[16:17]
	v_pk_fma_f32 v[200:201], v[10:11], v[202:203], v[200:201]
	v_add_f32_e32 v16, v16, v17
	v_add_f32_e32 v200, v200, v201
	v_pk_mul_f32 v[12:13], v[12:13], v[74:75] op_sel_hi:[1,0]
	v_pk_mul_f32 v[14:15], v[14:15], v[74:75] op_sel_hi:[1,0]
	v_add_f32_dpp v16, v16, v16 quad_perm:[1,0,3,2] row_mask:0xf bank_mask:0xf bound_ctrl:1
	v_add_f32_dpp v200, v200, v200 quad_perm:[1,0,3,2] row_mask:0xf bank_mask:0xf bound_ctrl:1
	v_pk_fma_f32 v[12:13], v[8:9], v[24:25], v[12:13]
	v_pk_fma_f32 v[14:15], v[10:11], v[26:27], v[14:15]
	v_add_f32_dpp v16, v16, v16 quad_perm:[2,3,0,1] row_mask:0xf bank_mask:0xf bound_ctrl:1
	v_add_f32_dpp v200, v200, v200 quad_perm:[2,3,0,1] row_mask:0xf bank_mask:0xf bound_ctrl:1
	s_nop 1
	v_add_f32_dpp v16, v16, v16 row_half_mirror row_mask:0xf bank_mask:0xf bound_ctrl:1
	v_add_f32_dpp v200, v200, v200 row_half_mirror row_mask:0xf bank_mask:0xf bound_ctrl:1
	s_nop 1
	v_add_f32_dpp v16, v16, v16 row_mirror row_mask:0xf bank_mask:0xf bound_ctrl:1
	v_add_f32_dpp v200, v200, v200 row_mirror row_mask:0xf bank_mask:0xf bound_ctrl:1
	v_cmp_eq_u32_e32 vcc, 14, v177
	v_pk_fma_f32 v[8:9], v[20:21], v[16:17], v[12:13] op_sel_hi:[1,0,1] neg_lo:[0,1,0] neg_hi:[0,1,0]
	v_pk_fma_f32 v[10:11], v[22:23], v[16:17], v[14:15] op_sel_hi:[1,0,1] neg_lo:[0,1,0] neg_hi:[0,1,0]
	v_cndmask_b32_e32 v67, v67, v200, vcc
	v_pk_mul_f32 v[28:29], v[8:9], v[28:29]
	s_nop 0
	v_pk_fma_f32 v[28:29], v[10:11], v[30:31], v[28:29]
	s_add_i32 s6, s88, 1
	v_add_f32_e32 v28, v28, v29
	v_lshl_add_u32 v78, s6, 4, v178
	v_ashrrev_i32_e32 v79, 31, v78
	v_add_f32_dpp v28, v28, v28 quad_perm:[1,0,3,2] row_mask:0xf bank_mask:0xf bound_ctrl:1
	v_lshlrev_b64 v[78:79], 11, v[78:79]
	v_cmp_eq_u32_e32 vcc, 15, v177
	v_add_f32_dpp v28, v28, v28 quad_perm:[2,3,0,1] row_mask:0xf bank_mask:0xf bound_ctrl:1
	v_lshl_add_u64 v[78:79], v[180:181], 0, v[78:79]
	s_nop 0
	v_add_f32_dpp v28, v28, v28 row_half_mirror row_mask:0xf bank_mask:0xf bound_ctrl:1
	s_nop 1
	v_add_f32_dpp v28, v28, v28 row_mirror row_mask:0xf bank_mask:0xf bound_ctrl:1
	s_nop 0
	v_cndmask_b32_e32 v67, v67, v28, vcc
	v_bfe_u32 v76, v67, 16, 1
	v_add3_u32 v76, v67, v76, s33
	global_store_short_d16_hi v[78:79], v76, off
	s_waitcnt lgkmcnt(0)
	s_barrier
	s_add_i32 s88, s88, 2
	s_cmp_lt_u32 s88, s89
	s_cbranch_scc1 .Lscan_tiles

.LBB0_214:
	s_add_i32 s59, s58, 0x8000
	s_and_b32 s60, s59, 0x8000
	v_add_u32_e32 v79, s60, v91
	v_lshl_add_u64 v[80:81], v[74:75], 0, s[6:7]
	v_add_u32_e32 v88, 0x4000, v79
	v_readfirstlane_b32 s60, v79
	v_lshl_add_u64 v[82:83], v[80:81], 0, s[88:89]
	v_lshl_add_u64 v[84:85], v[76:77], 0, s[6:7]
	s_mov_b32 m0, s60
	v_readfirstlane_b32 s60, v88
	v_lshl_add_u64 v[86:87], v[84:85], 0, s[92:93]
	global_load_lds_dwordx4 v[82:83], off
	s_mov_b32 m0, s60
	v_lshl_add_u64 v[82:83], v[80:81], 0, s[90:91]
	global_load_lds_dwordx4 v[86:87], off
	v_add_u32_e32 v86, 0x1000, v79
	s_and_b32 s58, s58, 0x8000
	v_readfirstlane_b32 s60, v86
	v_add_u32_e32 v86, 0x5000, v79
	s_mov_b32 m0, s60
	v_readfirstlane_b32 s60, v86
	v_add_u32_e32 v86, 0x2000, v79
	global_load_lds_dwordx4 v[82:83], off
	v_lshl_add_u64 v[82:83], v[84:85], 0, s[38:39]
	s_mov_b32 m0, s60
	v_readfirstlane_b32 s60, v86
	v_add_u32_e32 v86, 0x6000, v79
	global_load_lds_dwordx4 v[82:83], off
	v_lshl_add_u64 v[82:83], v[80:81], 0, s[94:95]
	s_mov_b32 m0, s60
	v_readfirstlane_b32 s60, v86
	global_load_lds_dwordx4 v[82:83], off
	v_lshl_add_u64 v[82:83], v[84:85], 0, s[62:63]
	s_mov_b32 m0, s60
	v_lshl_add_u64 v[80:81], v[80:81], 0, vcc
	global_load_lds_dwordx4 v[82:83], off
	v_add_u32_e32 v82, 0x3000, v79
	v_add_u32_e32 v79, 0x7000, v79
	v_readfirstlane_b32 s60, v82
	s_mov_b32 m0, s60
	v_readfirstlane_b32 s60, v79
	global_load_lds_dwordx4 v[80:81], off
	v_lshl_add_u64 v[80:81], v[84:85], 0, s[68:69]
	s_mov_b32 m0, s60
	s_add_i32 s58, s58, 0
	global_load_lds_dwordx4 v[80:81], off
	v_add_u32_e32 v79, s58, v95
	v_add_u32_e32 v88, v79, v100
	v_add_u32_e32 v79, v79, v93
	ds_read_b128 v[80:83], v88
	ds_read_b128 v[84:87], v88 offset:2048
	ds_read_b128 v[110:113], v88 offset:4096
	ds_read_b128 v[114:117], v88 offset:6144
	ds_read_b128 v[118:121], v79 offset:16384
	ds_read_b128 v[122:125], v79 offset:18432
	ds_read_b128 v[126:129], v79 offset:20480
	ds_read_b128 v[130:133], v79 offset:22528
	v_add_u32_e32 v206, s58, v101
	v_add_u32_e32 v207, v206, v100
	v_add_u32_e32 v208, v206, v93
	ds_read_b128 v[210:213], v207
	ds_read_b128 v[214:217], v207 offset:2048
	ds_read_b128 v[218:221], v207 offset:4096
	ds_read_b128 v[222:225], v207 offset:6144
	ds_read_b128 v[226:229], v208 offset:16384
	ds_read_b128 v[230:233], v208 offset:18432
	ds_read_b128 v[234:237], v208 offset:20480
	ds_read_b128 v[238:241], v208 offset:22528
	s_setprio 1
	s_waitcnt lgkmcnt(8)
	v_mfma_f32_16x16x32_bf16 v[60:63], v[118:121], v[80:83], v[60:63]
	v_mfma_f32_16x16x32_bf16 v[56:59], v[122:125], v[80:83], v[56:59]
	v_mfma_f32_16x16x32_bf16 v[52:55], v[126:129], v[80:83], v[52:55]
	v_mfma_f32_16x16x32_bf16 v[48:51], v[130:133], v[80:83], v[48:51]
	v_mfma_f32_16x16x32_bf16 v[44:47], v[118:121], v[84:87], v[44:47]
	v_mfma_f32_16x16x32_bf16 v[40:43], v[122:125], v[84:87], v[40:43]
	v_mfma_f32_16x16x32_bf16 v[36:39], v[126:129], v[84:87], v[36:39]
	v_mfma_f32_16x16x32_bf16 v[32:35], v[130:133], v[84:87], v[32:35]
	v_mfma_f32_16x16x32_bf16 v[28:31], v[118:121], v[110:113], v[28:31]
	v_mfma_f32_16x16x32_bf16 v[24:27], v[122:125], v[110:113], v[24:27]
	v_mfma_f32_16x16x32_bf16 v[20:23], v[126:129], v[110:113], v[20:23]
	v_mfma_f32_16x16x32_bf16 v[16:19], v[130:133], v[110:113], v[16:19]
	v_mfma_f32_16x16x32_bf16 v[12:15], v[118:121], v[114:117], v[12:15]
	v_mfma_f32_16x16x32_bf16 v[8:11], v[122:125], v[114:117], v[8:11]
	v_mfma_f32_16x16x32_bf16 v[4:7], v[126:129], v[114:117], v[4:7]
	v_mfma_f32_16x16x32_bf16 v[0:3], v[130:133], v[114:117], v[0:3]
	s_setprio 0
	s_setprio 1
	s_waitcnt lgkmcnt(0)
	v_mfma_f32_16x16x32_bf16 v[60:63], v[226:229], v[210:213], v[60:63]
	v_mfma_f32_16x16x32_bf16 v[56:59], v[230:233], v[210:213], v[56:59]
	v_mfma_f32_16x16x32_bf16 v[52:55], v[234:237], v[210:213], v[52:55]
	v_mfma_f32_16x16x32_bf16 v[48:51], v[238:241], v[210:213], v[48:51]
	v_mfma_f32_16x16x32_bf16 v[44:47], v[226:229], v[214:217], v[44:47]
	v_mfma_f32_16x16x32_bf16 v[40:43], v[230:233], v[214:217], v[40:43]
	v_mfma_f32_16x16x32_bf16 v[36:39], v[234:237], v[214:217], v[36:39]
	v_mfma_f32_16x16x32_bf16 v[32:35], v[238:241], v[214:217], v[32:35]
	v_mfma_f32_16x16x32_bf16 v[28:31], v[226:229], v[218:221], v[28:31]
	v_mfma_f32_16x16x32_bf16 v[24:27], v[230:233], v[218:221], v[24:27]
	v_mfma_f32_16x16x32_bf16 v[20:23], v[234:237], v[218:221], v[20:23]
	v_mfma_f32_16x16x32_bf16 v[16:19], v[238:241], v[218:221], v[16:19]
	v_mfma_f32_16x16x32_bf16 v[12:15], v[226:229], v[222:225], v[12:15]
	v_mfma_f32_16x16x32_bf16 v[8:11], v[230:233], v[222:225], v[8:11]
	v_mfma_f32_16x16x32_bf16 v[4:7], v[234:237], v[222:225], v[4:7]
	v_mfma_f32_16x16x32_bf16 v[0:3], v[238:241], v[222:225], v[0:3]
	s_setprio 0
	s_waitcnt vmcnt(0)
	s_add_u32 s6, s6, 0x80
	s_addc_u32 s7, s7, 0
	s_cmpk_lg_i32 s6, 0x780
	s_mov_b32 s58, s59
	s_waitcnt vmcnt(0)
	s_barrier
	s_cbranch_scc1 .LBB0_214
	v_add_u32_e32 v79, v104, v93
	ds_read_b128 v[74:77], v79 offset:55296
	ds_read_b128 v[80:83], v79 offset:53248
	ds_read_b128 v[84:87], v79 offset:51200
	ds_read_b128 v[110:113], v79 offset:49152
	v_add_u32_e32 v79, v104, v100
	ds_read_b128 v[114:117], v79 offset:38912
	ds_read_b128 v[118:121], v79 offset:36864
	ds_read_b128 v[122:125], v79 offset:34816
	ds_read_b128 v[126:129], v79 offset:32768
	s_setprio 1
	s_waitcnt lgkmcnt(0)
	v_mfma_f32_16x16x32_bf16 v[60:63], v[110:113], v[126:129], v[60:63]
	v_mfma_f32_16x16x32_bf16 v[56:59], v[84:87], v[126:129], v[56:59]
	v_mfma_f32_16x16x32_bf16 v[52:55], v[80:83], v[126:129], v[52:55]
	v_mfma_f32_16x16x32_bf16 v[48:51], v[74:77], v[126:129], v[48:51]
	v_mfma_f32_16x16x32_bf16 v[44:47], v[110:113], v[122:125], v[44:47]
	v_mfma_f32_16x16x32_bf16 v[40:43], v[84:87], v[122:125], v[40:43]
	v_mfma_f32_16x16x32_bf16 v[36:39], v[80:83], v[122:125], v[36:39]
	v_mfma_f32_16x16x32_bf16 v[32:35], v[74:77], v[122:125], v[32:35]
	v_mfma_f32_16x16x32_bf16 v[28:31], v[110:113], v[118:121], v[28:31]
	v_mfma_f32_16x16x32_bf16 v[24:27], v[84:87], v[118:121], v[24:27]
	v_mfma_f32_16x16x32_bf16 v[20:23], v[80:83], v[118:121], v[20:23]
	v_mfma_f32_16x16x32_bf16 v[16:19], v[74:77], v[118:121], v[16:19]
	v_mfma_f32_16x16x32_bf16 v[12:15], v[110:113], v[114:117], v[12:15]
	v_mfma_f32_16x16x32_bf16 v[8:11], v[84:87], v[114:117], v[8:11]
	v_mfma_f32_16x16x32_bf16 v[4:7], v[80:83], v[114:117], v[4:7]
	v_mfma_f32_16x16x32_bf16 v[0:3], v[74:77], v[114:117], v[0:3]
	s_setprio 0
	v_add_u32_e32 v79, v105, v100
	ds_read_b128 v[74:77], v79 offset:32768
	ds_read_b128 v[80:83], v79 offset:34816
	ds_read_b128 v[84:87], v79 offset:36864
	ds_read_b128 v[110:113], v79 offset:38912
	v_add_u32_e32 v79, v105, v93
	ds_read_b128 v[114:117], v79 offset:49152
	ds_read_b128 v[118:121], v79 offset:51200
	ds_read_b128 v[122:125], v79 offset:53248
	ds_read_b128 v[126:129], v79 offset:55296
	s_setprio 1
	s_waitcnt lgkmcnt(3)
	v_mfma_f32_16x16x32_bf16 v[60:63], v[114:117], v[74:77], v[60:63]
	s_waitcnt lgkmcnt(2)
	v_mfma_f32_16x16x32_bf16 v[56:59], v[118:121], v[74:77], v[56:59]
	s_waitcnt lgkmcnt(1)
	v_mfma_f32_16x16x32_bf16 v[52:55], v[122:125], v[74:77], v[52:55]
	s_waitcnt lgkmcnt(0)
	v_mfma_f32_16x16x32_bf16 v[48:51], v[126:129], v[74:77], v[48:51]
	v_mfma_f32_16x16x32_bf16 v[44:47], v[114:117], v[80:83], v[44:47]
	v_mfma_f32_16x16x32_bf16 v[40:43], v[118:121], v[80:83], v[40:43]
	v_mfma_f32_16x16x32_bf16 v[36:39], v[122:125], v[80:83], v[36:39]
	v_mfma_f32_16x16x32_bf16 v[32:35], v[126:129], v[80:83], v[32:35]
	v_mfma_f32_16x16x32_bf16 v[28:31], v[114:117], v[84:87], v[28:31]
	v_mfma_f32_16x16x32_bf16 v[24:27], v[118:121], v[84:87], v[24:27]
	v_mfma_f32_16x16x32_bf16 v[20:23], v[122:125], v[84:87], v[20:23]
	v_mfma_f32_16x16x32_bf16 v[16:19], v[126:129], v[84:87], v[16:19]
	v_mfma_f32_16x16x32_bf16 v[12:15], v[114:117], v[110:113], v[12:15]
	v_mfma_f32_16x16x32_bf16 v[8:11], v[118:121], v[110:113], v[8:11]
	v_mfma_f32_16x16x32_bf16 v[4:7], v[122:125], v[110:113], v[4:7]
	v_mfma_f32_16x16x32_bf16 v[0:3], v[126:129], v[110:113], v[0:3]
	s_setprio 0
	s_waitcnt vmcnt(0)
	v_and_b32_e32 v74, 0xfffff8, v78
	v_cmp_ne_u32_e32 vcc, 16, v74
	s_mov_b64 s[6:7], s[0:1]
	s_barrier
	s_and_saveexec_b64 s[58:59], vcc
	s_mov_b64 s[92:93], s[52:53]
	s_cbranch_execz .LBB0_160
	v_readlane_b32 s6, v254, 29
	v_readlane_b32 s7, v254, 30
	v_cmp_lt_u32_e32 vcc, 23, v78
	v_lshlrev_b32_e32 v80, 7, v67
	v_lshl_add_u64 v[74:75], v[96:97], 1, s[6:7]
	v_mul_f32_e32 v83, 0xbfb8aa3b, v60
	v_mul_f32_e32 v84, 0xbfb8aa3b, v61
	v_mul_f32_e32 v79, 0xbfb8aa3b, v62
	v_mul_f32_e32 v82, 0xbfb8aa3b, v63
	v_mul_f32_e32 v126, 0xbfb8aa3b, v56
	v_mul_f32_e32 v127, 0xbfb8aa3b, v57
	v_mul_f32_e32 v124, 0xbfb8aa3b, v58
	v_mul_f32_e32 v125, 0xbfb8aa3b, v59
	v_mul_f32_e32 v122, 0xbfb8aa3b, v52
	v_mul_f32_e32 v123, 0xbfb8aa3b, v53
	v_mul_f32_e32 v120, 0xbfb8aa3b, v54
	v_mul_f32_e32 v121, 0xbfb8aa3b, v55
	v_mul_f32_e32 v118, 0xbfb8aa3b, v48
	v_mul_f32_e32 v119, 0xbfb8aa3b, v49
	v_mul_f32_e32 v116, 0xbfb8aa3b, v50
	v_mul_f32_e32 v117, 0xbfb8aa3b, v51
	v_mul_f32_e32 v114, 0xbfb8aa3b, v44
	v_mul_f32_e32 v115, 0xbfb8aa3b, v45
	v_mul_f32_e32 v112, 0xbfb8aa3b, v46
	v_mul_f32_e32 v113, 0xbfb8aa3b, v47
	v_mul_f32_e32 v110, 0xbfb8aa3b, v40
	v_mul_f32_e32 v111, 0xbfb8aa3b, v41
	v_mul_f32_e32 v67, 0xbfb8aa3b, v42
	v_mul_f32_e32 v109, 0xbfb8aa3b, v43
	s_and_saveexec_b64 s[6:7], vcc
	s_xor_b64 s[60:61], exec, s[6:7]
	s_cbranch_execz .LBB0_218
	v_mov_b32_e32 v40, v97
	s_nop 0
	v_add_u32_e32 v40, v40, v176
	v_ashrrev_i32_e32 v42, 1, v40
	v_and_b32_e32 v41, 64, v40
	v_and_b32_e32 v42, 0xffffffc0, v42
	v_lshrrev_b32_e32 v43, 2, v40
	v_and_or_b32 v40, v40, 15, v80
	v_and_or_b32 v43, v43, 12, v41
	v_add_u32_e32 v42, v40, v42
	v_exp_f32_e32 v44, v83
	v_exp_f32_e32 v45, v79
	v_lshlrev_b32_e32 v96, 1, v43
	v_exp_f32_e32 v46, v84
	v_exp_f32_e32 v47, v82
	v_pk_add_f32 v[44:45], v[44:45], 1.0 op_sel_hi:[1,0]
	s_movk_i32 s67, 0x3200
	v_div_scale_f32 v43, s[6:7], v44, v44, 1.0
	v_rcp_f32_e32 v48, v43
	v_mad_i64_i32 v[40:41], s[6:7], v42, s67, v[74:75]
	v_lshl_add_u64 v[40:41], v[40:41], 0, v[96:97]
	v_fma_f32 v49, -v43, v48, 1.0
	v_fmac_f32_e32 v48, v49, v48
	v_div_scale_f32 v49, vcc, 1.0, v44, 1.0
	v_mul_f32_e32 v50, v49, v48
	v_fma_f32 v51, -v43, v50, v49
	v_fmac_f32_e32 v50, v51, v48
	v_fma_f32 v43, -v43, v50, v49
	v_div_fmas_f32 v43, v43, v48, v50
	v_div_fixup_f32 v43, v43, v44, 1.0
	v_div_scale_f32 v44, s[6:7], v45, v45, 1.0
	v_rcp_f32_e32 v48, v44
	s_nop 0
	v_fma_f32 v49, -v44, v48, 1.0
	v_fmac_f32_e32 v48, v49, v48
	v_div_scale_f32 v49, vcc, 1.0, v45, 1.0
	v_mul_f32_e32 v50, v49, v48
	v_fma_f32 v51, -v44, v50, v49
	v_fmac_f32_e32 v50, v51, v48
	v_fma_f32 v44, -v44, v50, v49
	v_div_fmas_f32 v44, v44, v48, v50
	v_div_fixup_f32 v48, v44, v45, 1.0
	v_pk_add_f32 v[44:45], v[46:47], 1.0 op_sel_hi:[1,0]
	s_nop 0
	v_div_scale_f32 v46, s[6:7], v44, v44, 1.0
	v_rcp_f32_e32 v47, v46
	s_nop 0
	v_fma_f32 v49, -v46, v47, 1.0
	v_fmac_f32_e32 v47, v49, v47
	v_div_scale_f32 v49, vcc, 1.0, v44, 1.0
	v_mul_f32_e32 v50, v49, v47
	v_fma_f32 v51, -v46, v50, v49
	v_fmac_f32_e32 v50, v51, v47
	v_fma_f32 v46, -v46, v50, v49
	v_div_fmas_f32 v46, v46, v47, v50
	v_div_fixup_f32 v44, v46, v44, 1.0
	v_div_scale_f32 v46, s[6:7], v45, v45, 1.0
	v_rcp_f32_e32 v47, v46
	s_nop 0
	v_fma_f32 v49, -v46, v47, 1.0
	v_fmac_f32_e32 v47, v49, v47
	v_div_scale_f32 v49, vcc, 1.0, v45, 1.0
	v_mul_f32_e32 v50, v49, v47
	v_fma_f32 v51, -v46, v50, v49
	v_fmac_f32_e32 v50, v51, v47
	v_fma_f32 v46, -v46, v50, v49
	v_div_fmas_f32 v46, v46, v47, v50
	v_div_fixup_f32 v45, v46, v45, 1.0
	v_and_b32_sdwa v46, v48, v154 dst_sel:DWORD dst_unused:UNUSED_PAD src0_sel:WORD_1 src1_sel:DWORD
	v_and_b32_sdwa v47, v43, v154 dst_sel:DWORD dst_unused:UNUSED_PAD src0_sel:WORD_1 src1_sel:DWORD
	v_add3_u32 v43, v43, v47, s33
	v_add3_u32 v46, v48, v46, s33
	v_and_b32_sdwa v47, v45, v154 dst_sel:DWORD dst_unused:UNUSED_PAD src0_sel:WORD_1 src1_sel:DWORD
	v_and_b32_sdwa v48, v44, v154 dst_sel:DWORD dst_unused:UNUSED_PAD src0_sel:WORD_1 src1_sel:DWORD
	v_add3_u32 v45, v45, v47, s33
	v_add3_u32 v44, v44, v48, s33
	v_and_b32_e32 v45, 0xffff0000, v45
	v_and_b32_e32 v44, 0xffff0000, v44
	v_or_b32_sdwa v45, v45, v46 dst_sel:DWORD dst_unused:UNUSED_PAD src0_sel:DWORD src1_sel:WORD_1
	v_or_b32_sdwa v44, v44, v43 dst_sel:DWORD dst_unused:UNUSED_PAD src0_sel:DWORD src1_sel:WORD_1
	global_store_dwordx2 v[40:41], v[44:45], off
	v_exp_f32_e32 v44, v126
	v_exp_f32_e32 v45, v124
	v_exp_f32_e32 v46, v127
	v_exp_f32_e32 v47, v125
	v_pk_add_f32 v[44:45], v[44:45], 1.0 op_sel_hi:[1,0]
	s_nop 0
	v_div_scale_f32 v43, s[6:7], v44, v44, 1.0
	v_rcp_f32_e32 v48, v43
	s_nop 0
	v_fma_f32 v49, -v43, v48, 1.0
	v_fmac_f32_e32 v48, v49, v48
	v_div_scale_f32 v49, vcc, 1.0, v44, 1.0
	v_mul_f32_e32 v50, v49, v48
	v_fma_f32 v51, -v43, v50, v49
	v_fmac_f32_e32 v50, v51, v48
	v_fma_f32 v43, -v43, v50, v49
	v_div_fmas_f32 v43, v43, v48, v50
	v_div_fixup_f32 v43, v43, v44, 1.0
	v_div_scale_f32 v44, s[6:7], v45, v45, 1.0
	v_rcp_f32_e32 v48, v44
	s_nop 0
	v_fma_f32 v49, -v44, v48, 1.0
	v_fmac_f32_e32 v48, v49, v48
	v_div_scale_f32 v49, vcc, 1.0, v45, 1.0
	v_mul_f32_e32 v50, v49, v48
	v_fma_f32 v51, -v44, v50, v49
	v_fmac_f32_e32 v50, v51, v48
	v_fma_f32 v44, -v44, v50, v49
	v_div_fmas_f32 v44, v44, v48, v50
	v_div_fixup_f32 v48, v44, v45, 1.0
	v_pk_add_f32 v[44:45], v[46:47], 1.0 op_sel_hi:[1,0]
	s_nop 0
	v_div_scale_f32 v46, s[6:7], v44, v44, 1.0
	v_rcp_f32_e32 v47, v46
	s_nop 0
	v_fma_f32 v49, -v46, v47, 1.0
	v_fmac_f32_e32 v47, v49, v47
	v_div_scale_f32 v49, vcc, 1.0, v44, 1.0
	v_mul_f32_e32 v50, v49, v47
	v_fma_f32 v51, -v46, v50, v49
	v_fmac_f32_e32 v50, v51, v47
	v_fma_f32 v46, -v46, v50, v49
	v_div_fmas_f32 v46, v46, v47, v50
	v_div_fixup_f32 v44, v46, v44, 1.0
	v_div_scale_f32 v46, s[6:7], v45, v45, 1.0
	v_rcp_f32_e32 v47, v46
	s_nop 0
	v_fma_f32 v49, -v46, v47, 1.0
	v_fmac_f32_e32 v47, v49, v47
	v_div_scale_f32 v49, vcc, 1.0, v45, 1.0
	v_mul_f32_e32 v50, v49, v47
	v_fma_f32 v51, -v46, v50, v49
	v_fmac_f32_e32 v50, v51, v47
	v_fma_f32 v46, -v46, v50, v49
	v_div_fmas_f32 v46, v46, v47, v50
	v_div_fixup_f32 v45, v46, v45, 1.0
	v_and_b32_sdwa v46, v48, v154 dst_sel:DWORD dst_unused:UNUSED_PAD src0_sel:WORD_1 src1_sel:DWORD
	v_and_b32_sdwa v47, v43, v154 dst_sel:DWORD dst_unused:UNUSED_PAD src0_sel:WORD_1 src1_sel:DWORD
	v_add3_u32 v43, v43, v47, s33
	v_add3_u32 v46, v48, v46, s33
	v_and_b32_sdwa v47, v45, v154 dst_sel:DWORD dst_unused:UNUSED_PAD src0_sel:WORD_1 src1_sel:DWORD
	v_and_b32_sdwa v48, v44, v154 dst_sel:DWORD dst_unused:UNUSED_PAD src0_sel:WORD_1 src1_sel:DWORD
	v_add3_u32 v45, v45, v47, s33
	v_add3_u32 v44, v44, v48, s33
	v_and_b32_e32 v45, 0xffff0000, v45
	v_and_b32_e32 v44, 0xffff0000, v44
	v_or_b32_sdwa v45, v45, v46 dst_sel:DWORD dst_unused:UNUSED_PAD src0_sel:DWORD src1_sel:WORD_1
	v_or_b32_sdwa v44, v44, v43 dst_sel:DWORD dst_unused:UNUSED_PAD src0_sel:DWORD src1_sel:WORD_1
	global_store_dwordx2 v[40:41], v[44:45], off offset:32
	v_exp_f32_e32 v44, v122
	v_exp_f32_e32 v45, v120
	v_exp_f32_e32 v46, v123
	v_exp_f32_e32 v47, v121
	v_pk_add_f32 v[44:45], v[44:45], 1.0 op_sel_hi:[1,0]
	s_nop 0
	v_div_scale_f32 v43, s[6:7], v44, v44, 1.0
	v_rcp_f32_e32 v48, v43
	s_nop 0
	v_fma_f32 v49, -v43, v48, 1.0
	v_fmac_f32_e32 v48, v49, v48
	v_div_scale_f32 v49, vcc, 1.0, v44, 1.0
	v_mul_f32_e32 v50, v49, v48
	v_fma_f32 v51, -v43, v50, v49
	v_fmac_f32_e32 v50, v51, v48
	v_fma_f32 v43, -v43, v50, v49
	v_div_fmas_f32 v43, v43, v48, v50
	v_div_fixup_f32 v43, v43, v44, 1.0
	v_div_scale_f32 v44, s[6:7], v45, v45, 1.0
	v_rcp_f32_e32 v48, v44
	s_nop 0
	v_fma_f32 v49, -v44, v48, 1.0
	v_fmac_f32_e32 v48, v49, v48
	v_div_scale_f32 v49, vcc, 1.0, v45, 1.0
	v_mul_f32_e32 v50, v49, v48
	v_fma_f32 v51, -v44, v50, v49
	v_fmac_f32_e32 v50, v51, v48
	v_fma_f32 v44, -v44, v50, v49
	v_div_fmas_f32 v44, v44, v48, v50
	v_div_fixup_f32 v48, v44, v45, 1.0
	v_pk_add_f32 v[44:45], v[46:47], 1.0 op_sel_hi:[1,0]
	s_nop 0
	v_div_scale_f32 v46, s[6:7], v44, v44, 1.0
	v_rcp_f32_e32 v47, v46
	s_nop 0
	v_fma_f32 v49, -v46, v47, 1.0
	v_fmac_f32_e32 v47, v49, v47
	v_div_scale_f32 v49, vcc, 1.0, v44, 1.0
	v_mul_f32_e32 v50, v49, v47
	v_fma_f32 v51, -v46, v50, v49
	v_fmac_f32_e32 v50, v51, v47
	v_fma_f32 v46, -v46, v50, v49
	v_div_fmas_f32 v46, v46, v47, v50
	v_div_fixup_f32 v44, v46, v44, 1.0
	v_div_scale_f32 v46, s[6:7], v45, v45, 1.0
	v_rcp_f32_e32 v47, v46
	s_nop 0
	v_fma_f32 v49, -v46, v47, 1.0
	v_fmac_f32_e32 v47, v49, v47
	v_div_scale_f32 v49, vcc, 1.0, v45, 1.0
	v_mul_f32_e32 v50, v49, v47
	v_fma_f32 v51, -v46, v50, v49
	v_fmac_f32_e32 v50, v51, v47
	v_fma_f32 v46, -v46, v50, v49
	v_div_fmas_f32 v46, v46, v47, v50
	v_div_fixup_f32 v45, v46, v45, 1.0
	v_and_b32_sdwa v46, v48, v154 dst_sel:DWORD dst_unused:UNUSED_PAD src0_sel:WORD_1 src1_sel:DWORD
	v_and_b32_sdwa v47, v43, v154 dst_sel:DWORD dst_unused:UNUSED_PAD src0_sel:WORD_1 src1_sel:DWORD
	v_add3_u32 v43, v43, v47, s33
	v_add3_u32 v46, v48, v46, s33
	v_and_b32_sdwa v47, v45, v154 dst_sel:DWORD dst_unused:UNUSED_PAD src0_sel:WORD_1 src1_sel:DWORD
	v_and_b32_sdwa v48, v44, v154 dst_sel:DWORD dst_unused:UNUSED_PAD src0_sel:WORD_1 src1_sel:DWORD
	v_add3_u32 v45, v45, v47, s33
	v_add3_u32 v44, v44, v48, s33
	v_and_b32_e32 v45, 0xffff0000, v45
	v_and_b32_e32 v44, 0xffff0000, v44
	v_or_b32_sdwa v45, v45, v46 dst_sel:DWORD dst_unused:UNUSED_PAD src0_sel:DWORD src1_sel:WORD_1
	v_or_b32_sdwa v44, v44, v43 dst_sel:DWORD dst_unused:UNUSED_PAD src0_sel:DWORD src1_sel:WORD_1
	global_store_dwordx2 v[40:41], v[44:45], off offset:64
	v_exp_f32_e32 v44, v118
	v_exp_f32_e32 v45, v116
	v_exp_f32_e32 v46, v119
	v_exp_f32_e32 v47, v117
	v_pk_add_f32 v[44:45], v[44:45], 1.0 op_sel_hi:[1,0]
	s_nop 0
	v_div_scale_f32 v43, s[6:7], v44, v44, 1.0
	v_rcp_f32_e32 v48, v43
	s_nop 0
	v_fma_f32 v49, -v43, v48, 1.0
	v_fmac_f32_e32 v48, v49, v48
	v_div_scale_f32 v49, vcc, 1.0, v44, 1.0
	v_mul_f32_e32 v50, v49, v48
	v_fma_f32 v51, -v43, v50, v49
	v_fmac_f32_e32 v50, v51, v48
	v_fma_f32 v43, -v43, v50, v49
	v_div_fmas_f32 v43, v43, v48, v50
	v_div_fixup_f32 v43, v43, v44, 1.0
	v_div_scale_f32 v44, s[6:7], v45, v45, 1.0
	v_rcp_f32_e32 v48, v44
	s_nop 0
	v_fma_f32 v49, -v44, v48, 1.0
	v_fmac_f32_e32 v48, v49, v48
	v_div_scale_f32 v49, vcc, 1.0, v45, 1.0
	v_mul_f32_e32 v50, v49, v48
	v_fma_f32 v51, -v44, v50, v49
	v_fmac_f32_e32 v50, v51, v48
	v_fma_f32 v44, -v44, v50, v49
	v_div_fmas_f32 v44, v44, v48, v50
	v_div_fixup_f32 v48, v44, v45, 1.0
	v_pk_add_f32 v[44:45], v[46:47], 1.0 op_sel_hi:[1,0]
	s_nop 0
	v_div_scale_f32 v46, s[6:7], v44, v44, 1.0
	v_rcp_f32_e32 v47, v46
	s_nop 0
	v_fma_f32 v49, -v46, v47, 1.0
	v_fmac_f32_e32 v47, v49, v47
	v_div_scale_f32 v49, vcc, 1.0, v44, 1.0
	v_mul_f32_e32 v50, v49, v47
	v_fma_f32 v51, -v46, v50, v49
	v_fmac_f32_e32 v50, v51, v47
	v_fma_f32 v46, -v46, v50, v49
	v_div_fmas_f32 v46, v46, v47, v50
	v_div_fixup_f32 v44, v46, v44, 1.0
	v_div_scale_f32 v46, s[6:7], v45, v45, 1.0
	v_rcp_f32_e32 v47, v46
	s_nop 0
	v_fma_f32 v49, -v46, v47, 1.0
	v_fmac_f32_e32 v47, v49, v47
	v_div_scale_f32 v49, vcc, 1.0, v45, 1.0
	v_mul_f32_e32 v50, v49, v47
	v_fma_f32 v51, -v46, v50, v49
	v_fmac_f32_e32 v50, v51, v47
	v_fma_f32 v46, -v46, v50, v49
	v_div_fmas_f32 v46, v46, v47, v50
	v_div_fixup_f32 v45, v46, v45, 1.0
	v_and_b32_sdwa v46, v48, v154 dst_sel:DWORD dst_unused:UNUSED_PAD src0_sel:WORD_1 src1_sel:DWORD
	v_and_b32_sdwa v47, v43, v154 dst_sel:DWORD dst_unused:UNUSED_PAD src0_sel:WORD_1 src1_sel:DWORD
	v_add3_u32 v43, v43, v47, s33
	v_add3_u32 v46, v48, v46, s33
	v_and_b32_sdwa v47, v45, v154 dst_sel:DWORD dst_unused:UNUSED_PAD src0_sel:WORD_1 src1_sel:DWORD
	v_and_b32_sdwa v48, v44, v154 dst_sel:DWORD dst_unused:UNUSED_PAD src0_sel:WORD_1 src1_sel:DWORD
	v_add3_u32 v45, v45, v47, s33
	v_add3_u32 v44, v44, v48, s33
	v_and_b32_e32 v45, 0xffff0000, v45
	v_and_b32_e32 v44, 0xffff0000, v44
	v_or_b32_sdwa v45, v45, v46 dst_sel:DWORD dst_unused:UNUSED_PAD src0_sel:DWORD src1_sel:WORD_1
	v_or_b32_sdwa v44, v44, v43 dst_sel:DWORD dst_unused:UNUSED_PAD src0_sel:DWORD src1_sel:WORD_1
	global_store_dwordx2 v[40:41], v[44:45], off offset:96
	v_exp_f32_e32 v44, v114
	v_exp_f32_e32 v45, v112
	v_exp_f32_e32 v46, v115
	v_exp_f32_e32 v47, v113
	v_or_b32_e32 v40, 16, v42
	v_pk_add_f32 v[44:45], v[44:45], 1.0 op_sel_hi:[1,0]
	v_mad_i64_i32 v[40:41], s[6:7], v40, s67, v[74:75]
	v_div_scale_f32 v43, s[6:7], v44, v44, 1.0
	v_rcp_f32_e32 v48, v43
	v_lshl_add_u64 v[40:41], v[40:41], 0, v[96:97]
	v_mul_f32_e32 v37, 0xbfb8aa3b, v37
	v_mul_f32_e32 v36, 0xbfb8aa3b, v36
	v_fma_f32 v49, -v43, v48, 1.0
	v_fmac_f32_e32 v48, v49, v48
	v_div_scale_f32 v49, vcc, 1.0, v44, 1.0
	v_mul_f32_e32 v50, v49, v48
	v_fma_f32 v51, -v43, v50, v49
	v_fmac_f32_e32 v50, v51, v48
	v_fma_f32 v43, -v43, v50, v49
	v_div_fmas_f32 v43, v43, v48, v50
	v_div_fixup_f32 v43, v43, v44, 1.0
	v_div_scale_f32 v44, s[6:7], v45, v45, 1.0
	v_rcp_f32_e32 v48, v44
	v_exp_f32_e32 v36, v36
	v_mul_f32_e32 v33, 0xbfb8aa3b, v33
	v_mul_f32_e32 v32, 0xbfb8aa3b, v32
	v_fma_f32 v49, -v44, v48, 1.0
	v_fmac_f32_e32 v48, v49, v48
	v_div_scale_f32 v49, vcc, 1.0, v45, 1.0
	v_mul_f32_e32 v50, v49, v48
	v_fma_f32 v51, -v44, v50, v49
	v_fmac_f32_e32 v50, v51, v48
	v_fma_f32 v44, -v44, v50, v49
	v_div_fmas_f32 v44, v44, v48, v50
	v_div_fixup_f32 v48, v44, v45, 1.0
	v_pk_add_f32 v[44:45], v[46:47], 1.0 op_sel_hi:[1,0]
	v_exp_f32_e32 v32, v32
	v_div_scale_f32 v46, s[6:7], v44, v44, 1.0
	v_rcp_f32_e32 v47, v46
	s_nop 0
	v_fma_f32 v49, -v46, v47, 1.0
	v_fmac_f32_e32 v47, v49, v47
	v_div_scale_f32 v49, vcc, 1.0, v44, 1.0
	v_mul_f32_e32 v50, v49, v47
	v_fma_f32 v51, -v46, v50, v49
	v_fmac_f32_e32 v50, v51, v47
	v_fma_f32 v46, -v46, v50, v49
	v_div_fmas_f32 v46, v46, v47, v50
	v_div_fixup_f32 v44, v46, v44, 1.0
	v_div_scale_f32 v46, s[6:7], v45, v45, 1.0
	v_rcp_f32_e32 v47, v46
	s_nop 0
	v_fma_f32 v49, -v46, v47, 1.0
	v_fmac_f32_e32 v47, v49, v47
	v_div_scale_f32 v49, vcc, 1.0, v45, 1.0
	v_mul_f32_e32 v50, v49, v47
	v_fma_f32 v51, -v46, v50, v49
	v_fmac_f32_e32 v50, v51, v47
	v_fma_f32 v46, -v46, v50, v49
	v_div_fmas_f32 v46, v46, v47, v50
	v_div_fixup_f32 v45, v46, v45, 1.0
	v_and_b32_sdwa v46, v48, v154 dst_sel:DWORD dst_unused:UNUSED_PAD src0_sel:WORD_1 src1_sel:DWORD
	v_and_b32_sdwa v47, v43, v154 dst_sel:DWORD dst_unused:UNUSED_PAD src0_sel:WORD_1 src1_sel:DWORD
	v_add3_u32 v43, v43, v47, s33
	v_add3_u32 v46, v48, v46, s33
	v_and_b32_sdwa v47, v45, v154 dst_sel:DWORD dst_unused:UNUSED_PAD src0_sel:WORD_1 src1_sel:DWORD
	v_and_b32_sdwa v48, v44, v154 dst_sel:DWORD dst_unused:UNUSED_PAD src0_sel:WORD_1 src1_sel:DWORD
	v_add3_u32 v45, v45, v47, s33
	v_add3_u32 v44, v44, v48, s33
	v_and_b32_e32 v45, 0xffff0000, v45
	v_and_b32_e32 v44, 0xffff0000, v44
	v_or_b32_sdwa v45, v45, v46 dst_sel:DWORD dst_unused:UNUSED_PAD src0_sel:DWORD src1_sel:WORD_1
	v_or_b32_sdwa v44, v44, v43 dst_sel:DWORD dst_unused:UNUSED_PAD src0_sel:DWORD src1_sel:WORD_1
	global_store_dwordx2 v[40:41], v[44:45], off
	v_exp_f32_e32 v44, v110
	v_exp_f32_e32 v45, v67
	v_exp_f32_e32 v46, v111
	v_exp_f32_e32 v47, v109
	v_pk_add_f32 v[44:45], v[44:45], 1.0 op_sel_hi:[1,0]
	s_nop 0
	v_div_scale_f32 v43, s[6:7], v44, v44, 1.0
	v_rcp_f32_e32 v48, v43
	s_nop 0
	v_fma_f32 v49, -v43, v48, 1.0
	v_fmac_f32_e32 v48, v49, v48
	v_div_scale_f32 v49, vcc, 1.0, v44, 1.0
	v_mul_f32_e32 v50, v49, v48
	v_fma_f32 v51, -v43, v50, v49
	v_fmac_f32_e32 v50, v51, v48
	v_fma_f32 v43, -v43, v50, v49
	v_div_fmas_f32 v43, v43, v48, v50
	v_div_fixup_f32 v43, v43, v44, 1.0
	v_div_scale_f32 v44, s[6:7], v45, v45, 1.0
	v_rcp_f32_e32 v48, v44
	s_nop 0
	v_fma_f32 v49, -v44, v48, 1.0
	v_fmac_f32_e32 v48, v49, v48
	v_div_scale_f32 v49, vcc, 1.0, v45, 1.0
	v_mul_f32_e32 v50, v49, v48
	v_fma_f32 v51, -v44, v50, v49
	v_fmac_f32_e32 v50, v51, v48
	v_fma_f32 v44, -v44, v50, v49
	v_div_fmas_f32 v44, v44, v48, v50
	v_div_fixup_f32 v48, v44, v45, 1.0
	v_pk_add_f32 v[44:45], v[46:47], 1.0 op_sel_hi:[1,0]
	s_nop 0
	v_div_scale_f32 v46, s[6:7], v44, v44, 1.0
	v_rcp_f32_e32 v47, v46
	s_nop 0
	v_fma_f32 v49, -v46, v47, 1.0
	v_fmac_f32_e32 v47, v49, v47
	v_div_scale_f32 v49, vcc, 1.0, v44, 1.0
	v_mul_f32_e32 v50, v49, v47
	v_fma_f32 v51, -v46, v50, v49
	v_fmac_f32_e32 v50, v51, v47
	v_fma_f32 v46, -v46, v50, v49
	v_div_fmas_f32 v46, v46, v47, v50
	v_div_fixup_f32 v44, v46, v44, 1.0
	v_div_scale_f32 v46, s[6:7], v45, v45, 1.0
	v_rcp_f32_e32 v47, v46
	s_nop 0
	v_fma_f32 v49, -v46, v47, 1.0
	v_fmac_f32_e32 v47, v49, v47
	v_div_scale_f32 v49, vcc, 1.0, v45, 1.0
	v_mul_f32_e32 v50, v49, v47
	v_fma_f32 v51, -v46, v50, v49
	v_fmac_f32_e32 v50, v51, v47
	v_fma_f32 v46, -v46, v50, v49
	v_div_fmas_f32 v46, v46, v47, v50
	v_div_fixup_f32 v45, v46, v45, 1.0
	v_and_b32_sdwa v46, v48, v154 dst_sel:DWORD dst_unused:UNUSED_PAD src0_sel:WORD_1 src1_sel:DWORD
	v_and_b32_sdwa v47, v43, v154 dst_sel:DWORD dst_unused:UNUSED_PAD src0_sel:WORD_1 src1_sel:DWORD
	v_add3_u32 v43, v43, v47, s33
	v_add3_u32 v46, v48, v46, s33
	v_and_b32_sdwa v47, v45, v154 dst_sel:DWORD dst_unused:UNUSED_PAD src0_sel:WORD_1 src1_sel:DWORD
	v_and_b32_sdwa v48, v44, v154 dst_sel:DWORD dst_unused:UNUSED_PAD src0_sel:WORD_1 src1_sel:DWORD
	v_add3_u32 v45, v45, v47, s33
	v_add3_u32 v44, v44, v48, s33
	v_and_b32_e32 v45, 0xffff0000, v45
	v_and_b32_e32 v44, 0xffff0000, v44
	v_or_b32_sdwa v45, v45, v46 dst_sel:DWORD dst_unused:UNUSED_PAD src0_sel:DWORD src1_sel:WORD_1
	v_or_b32_sdwa v44, v44, v43 dst_sel:DWORD dst_unused:UNUSED_PAD src0_sel:DWORD src1_sel:WORD_1
	global_store_dwordx2 v[40:41], v[44:45], off offset:32
	v_exp_f32_e32 v44, v37
	v_mul_f32_e32 v37, 0xbfb8aa3b, v38
	v_exp_f32_e32 v37, v37
	v_mul_f32_e32 v38, 0xbfb8aa3b, v39
	v_exp_f32_e32 v45, v38
	v_pk_add_f32 v[36:37], v[36:37], 1.0 op_sel_hi:[1,0]
	s_nop 0
	v_div_scale_f32 v38, s[6:7], v36, v36, 1.0
	v_rcp_f32_e32 v39, v38
	s_nop 0
	v_fma_f32 v43, -v38, v39, 1.0
	v_fmac_f32_e32 v39, v43, v39
	v_div_scale_f32 v43, vcc, 1.0, v36, 1.0
	v_mul_f32_e32 v46, v43, v39
	v_fma_f32 v47, -v38, v46, v43
	v_fmac_f32_e32 v46, v47, v39
	v_fma_f32 v38, -v38, v46, v43
	v_div_fmas_f32 v38, v38, v39, v46
	v_div_fixup_f32 v38, v38, v36, 1.0
	v_div_scale_f32 v36, s[6:7], v37, v37, 1.0
	v_rcp_f32_e32 v39, v36
	s_nop 0
	v_fma_f32 v43, -v36, v39, 1.0
	v_fmac_f32_e32 v39, v43, v39
	v_div_scale_f32 v43, vcc, 1.0, v37, 1.0
	v_mul_f32_e32 v46, v43, v39
	v_fma_f32 v47, -v36, v46, v43
	v_fmac_f32_e32 v46, v47, v39
	v_fma_f32 v36, -v36, v46, v43
	v_div_fmas_f32 v36, v36, v39, v46
	v_div_fixup_f32 v39, v36, v37, 1.0
	v_pk_add_f32 v[36:37], v[44:45], 1.0 op_sel_hi:[1,0]
	s_nop 0
	v_div_scale_f32 v43, s[6:7], v36, v36, 1.0
	v_rcp_f32_e32 v44, v43
	s_nop 0
	v_fma_f32 v45, -v43, v44, 1.0
	v_fmac_f32_e32 v44, v45, v44
	v_div_scale_f32 v45, vcc, 1.0, v36, 1.0
	v_mul_f32_e32 v46, v45, v44
	v_fma_f32 v47, -v43, v46, v45
	v_fmac_f32_e32 v46, v47, v44
	v_fma_f32 v43, -v43, v46, v45
	v_div_fmas_f32 v43, v43, v44, v46
	v_div_fixup_f32 v36, v43, v36, 1.0
	v_div_scale_f32 v43, s[6:7], v37, v37, 1.0
	v_rcp_f32_e32 v44, v43
	s_nop 0
	v_fma_f32 v45, -v43, v44, 1.0
	v_fmac_f32_e32 v44, v45, v44
	v_div_scale_f32 v45, vcc, 1.0, v37, 1.0
	v_mul_f32_e32 v46, v45, v44
	v_fma_f32 v47, -v43, v46, v45
	v_fmac_f32_e32 v46, v47, v44
	v_fma_f32 v43, -v43, v46, v45
	v_div_fmas_f32 v43, v43, v44, v46
	v_div_fixup_f32 v37, v43, v37, 1.0
	v_and_b32_sdwa v43, v39, v154 dst_sel:DWORD dst_unused:UNUSED_PAD src0_sel:WORD_1 src1_sel:DWORD
	v_and_b32_sdwa v44, v38, v154 dst_sel:DWORD dst_unused:UNUSED_PAD src0_sel:WORD_1 src1_sel:DWORD
	v_add3_u32 v38, v38, v44, s33
	v_add3_u32 v39, v39, v43, s33
	v_and_b32_sdwa v43, v37, v154 dst_sel:DWORD dst_unused:UNUSED_PAD src0_sel:WORD_1 src1_sel:DWORD
	v_and_b32_sdwa v44, v36, v154 dst_sel:DWORD dst_unused:UNUSED_PAD src0_sel:WORD_1 src1_sel:DWORD
	v_add3_u32 v37, v37, v43, s33
	v_add3_u32 v36, v36, v44, s33
	v_and_b32_e32 v37, 0xffff0000, v37
	v_and_b32_e32 v36, 0xffff0000, v36
	v_or_b32_sdwa v37, v37, v39 dst_sel:DWORD dst_unused:UNUSED_PAD src0_sel:DWORD src1_sel:WORD_1
	v_or_b32_sdwa v36, v36, v38 dst_sel:DWORD dst_unused:UNUSED_PAD src0_sel:DWORD src1_sel:WORD_1
	global_store_dwordx2 v[40:41], v[36:37], off offset:64
	v_exp_f32_e32 v36, v33
	v_mul_f32_e32 v33, 0xbfb8aa3b, v34
	v_exp_f32_e32 v33, v33
	v_mul_f32_e32 v34, 0xbfb8aa3b, v35
	v_exp_f32_e32 v37, v34
	v_pk_add_f32 v[32:33], v[32:33], 1.0 op_sel_hi:[1,0]
	s_nop 0
	v_div_scale_f32 v34, s[6:7], v32, v32, 1.0
	v_rcp_f32_e32 v35, v34
	s_nop 0
	v_fma_f32 v38, -v34, v35, 1.0
	v_fmac_f32_e32 v35, v38, v35
	v_div_scale_f32 v38, vcc, 1.0, v32, 1.0
	v_mul_f32_e32 v39, v38, v35
	v_fma_f32 v43, -v34, v39, v38
	v_fmac_f32_e32 v39, v43, v35
	v_fma_f32 v34, -v34, v39, v38
	v_div_fmas_f32 v34, v34, v35, v39
	v_div_fixup_f32 v34, v34, v32, 1.0
	v_div_scale_f32 v32, s[6:7], v33, v33, 1.0
	v_rcp_f32_e32 v35, v32
	s_nop 0
	v_fma_f32 v38, -v32, v35, 1.0
	v_fmac_f32_e32 v35, v38, v35
	v_div_scale_f32 v38, vcc, 1.0, v33, 1.0
	v_mul_f32_e32 v39, v38, v35
	v_fma_f32 v43, -v32, v39, v38
	v_fmac_f32_e32 v39, v43, v35
	v_fma_f32 v32, -v32, v39, v38
	v_div_fmas_f32 v32, v32, v35, v39
	v_div_fixup_f32 v35, v32, v33, 1.0
	v_pk_add_f32 v[32:33], v[36:37], 1.0 op_sel_hi:[1,0]
	s_nop 0
	v_div_scale_f32 v36, s[6:7], v32, v32, 1.0
	v_rcp_f32_e32 v37, v36
	s_nop 0
	v_fma_f32 v38, -v36, v37, 1.0
	v_fmac_f32_e32 v37, v38, v37
	v_div_scale_f32 v38, vcc, 1.0, v32, 1.0
	v_mul_f32_e32 v39, v38, v37
	v_fma_f32 v43, -v36, v39, v38
	v_fmac_f32_e32 v39, v43, v37
	v_fma_f32 v36, -v36, v39, v38
	v_div_fmas_f32 v36, v36, v37, v39
	v_div_fixup_f32 v32, v36, v32, 1.0
	v_div_scale_f32 v36, s[6:7], v33, v33, 1.0
	v_rcp_f32_e32 v37, v36
	s_nop 0
	v_fma_f32 v38, -v36, v37, 1.0
	v_fmac_f32_e32 v37, v38, v37
	v_div_scale_f32 v38, vcc, 1.0, v33, 1.0
	v_mul_f32_e32 v39, v38, v37
	v_fma_f32 v43, -v36, v39, v38
	v_fmac_f32_e32 v39, v43, v37
	v_fma_f32 v36, -v36, v39, v38
	v_div_fmas_f32 v36, v36, v37, v39
	v_div_fixup_f32 v33, v36, v33, 1.0
	v_and_b32_sdwa v36, v35, v154 dst_sel:DWORD dst_unused:UNUSED_PAD src0_sel:WORD_1 src1_sel:DWORD
	v_and_b32_sdwa v37, v34, v154 dst_sel:DWORD dst_unused:UNUSED_PAD src0_sel:WORD_1 src1_sel:DWORD
	v_add3_u32 v34, v34, v37, s33
	v_add3_u32 v35, v35, v36, s33
	v_and_b32_sdwa v36, v33, v154 dst_sel:DWORD dst_unused:UNUSED_PAD src0_sel:WORD_1 src1_sel:DWORD
	v_and_b32_sdwa v37, v32, v154 dst_sel:DWORD dst_unused:UNUSED_PAD src0_sel:WORD_1 src1_sel:DWORD
	v_add3_u32 v33, v33, v36, s33
	v_add3_u32 v32, v32, v37, s33
	v_and_b32_e32 v33, 0xffff0000, v33
	v_and_b32_e32 v32, 0xffff0000, v32
	v_or_b32_sdwa v33, v33, v35 dst_sel:DWORD dst_unused:UNUSED_PAD src0_sel:DWORD src1_sel:WORD_1
	v_or_b32_sdwa v32, v32, v34 dst_sel:DWORD dst_unused:UNUSED_PAD src0_sel:DWORD src1_sel:WORD_1
	global_store_dwordx2 v[40:41], v[32:33], off offset:96
	v_mul_f32_e32 v28, 0xbfb8aa3b, v28
	v_exp_f32_e32 v34, v28
	v_mul_f32_e32 v28, 0xbfb8aa3b, v29
	v_exp_f32_e32 v36, v28
	v_mul_f32_e32 v28, 0xbfb8aa3b, v30
	v_exp_f32_e32 v35, v28
	v_or_b32_e32 v32, 32, v42
	v_mad_i64_i32 v[32:33], s[6:7], v32, s67, v[74:75]
	v_mul_f32_e32 v28, 0xbfb8aa3b, v31
	v_pk_add_f32 v[30:31], v[34:35], 1.0 op_sel_hi:[1,0]
	v_exp_f32_e32 v37, v28
	v_lshl_add_u64 v[28:29], v[32:33], 0, v[96:97]
	v_div_scale_f32 v32, s[6:7], v30, v30, 1.0
	v_rcp_f32_e32 v33, v32
	v_mul_f32_e32 v25, 0xbfb8aa3b, v25
	v_mul_f32_e32 v24, 0xbfb8aa3b, v24
	v_exp_f32_e32 v24, v24
	v_fma_f32 v34, -v32, v33, 1.0
	v_fmac_f32_e32 v33, v34, v33
	v_div_scale_f32 v34, vcc, 1.0, v30, 1.0
	v_mul_f32_e32 v35, v34, v33
	v_fma_f32 v38, -v32, v35, v34
	v_fmac_f32_e32 v35, v38, v33
	v_fma_f32 v32, -v32, v35, v34
	v_div_fmas_f32 v32, v32, v33, v35
	v_div_fixup_f32 v32, v32, v30, 1.0
	v_div_scale_f32 v30, s[6:7], v31, v31, 1.0
	v_rcp_f32_e32 v33, v30
	v_mul_f32_e32 v21, 0xbfb8aa3b, v21
	v_mul_f32_e32 v20, 0xbfb8aa3b, v20
	v_exp_f32_e32 v20, v20
	v_fma_f32 v34, -v30, v33, 1.0
	v_fmac_f32_e32 v33, v34, v33
	v_div_scale_f32 v34, vcc, 1.0, v31, 1.0
	v_mul_f32_e32 v35, v34, v33
	v_fma_f32 v38, -v30, v35, v34
	v_fmac_f32_e32 v35, v38, v33
	v_fma_f32 v30, -v30, v35, v34
	v_div_fmas_f32 v30, v30, v33, v35
	v_div_fixup_f32 v33, v30, v31, 1.0
	v_pk_add_f32 v[30:31], v[36:37], 1.0 op_sel_hi:[1,0]
	v_mul_f32_e32 v17, 0xbfb8aa3b, v17
	v_div_scale_f32 v34, s[6:7], v30, v30, 1.0
	v_rcp_f32_e32 v35, v34
	v_mul_f32_e32 v16, 0xbfb8aa3b, v16
	v_exp_f32_e32 v16, v16
	v_fma_f32 v36, -v34, v35, 1.0
	v_fmac_f32_e32 v35, v36, v35
	v_div_scale_f32 v36, vcc, 1.0, v30, 1.0
	v_mul_f32_e32 v37, v36, v35
	v_fma_f32 v38, -v34, v37, v36
	v_fmac_f32_e32 v37, v38, v35
	v_fma_f32 v34, -v34, v37, v36
	v_div_fmas_f32 v34, v34, v35, v37
	v_div_fixup_f32 v30, v34, v30, 1.0
	v_div_scale_f32 v34, s[6:7], v31, v31, 1.0
	v_rcp_f32_e32 v35, v34
	s_nop 0
	v_fma_f32 v36, -v34, v35, 1.0
	v_fmac_f32_e32 v35, v36, v35
	v_div_scale_f32 v36, vcc, 1.0, v31, 1.0
	v_mul_f32_e32 v37, v36, v35
	v_fma_f32 v38, -v34, v37, v36
	v_fmac_f32_e32 v37, v38, v35
	v_fma_f32 v34, -v34, v37, v36
	v_div_fmas_f32 v34, v34, v35, v37
	v_div_fixup_f32 v31, v34, v31, 1.0
	v_and_b32_sdwa v34, v33, v154 dst_sel:DWORD dst_unused:UNUSED_PAD src0_sel:WORD_1 src1_sel:DWORD
	v_and_b32_sdwa v35, v32, v154 dst_sel:DWORD dst_unused:UNUSED_PAD src0_sel:WORD_1 src1_sel:DWORD
	v_add3_u32 v32, v32, v35, s33
	v_add3_u32 v33, v33, v34, s33
	v_and_b32_sdwa v34, v31, v154 dst_sel:DWORD dst_unused:UNUSED_PAD src0_sel:WORD_1 src1_sel:DWORD
	v_and_b32_sdwa v35, v30, v154 dst_sel:DWORD dst_unused:UNUSED_PAD src0_sel:WORD_1 src1_sel:DWORD
	v_add3_u32 v31, v31, v34, s33
	v_add3_u32 v30, v30, v35, s33
	v_and_b32_e32 v31, 0xffff0000, v31
	v_and_b32_e32 v30, 0xffff0000, v30
	v_or_b32_sdwa v31, v31, v33 dst_sel:DWORD dst_unused:UNUSED_PAD src0_sel:DWORD src1_sel:WORD_1
	v_or_b32_sdwa v30, v30, v32 dst_sel:DWORD dst_unused:UNUSED_PAD src0_sel:DWORD src1_sel:WORD_1
	global_store_dwordx2 v[28:29], v[30:31], off
	v_exp_f32_e32 v30, v25
	v_mul_f32_e32 v25, 0xbfb8aa3b, v26
	v_exp_f32_e32 v25, v25
	v_mul_f32_e32 v26, 0xbfb8aa3b, v27
	v_exp_f32_e32 v31, v26
	v_pk_add_f32 v[24:25], v[24:25], 1.0 op_sel_hi:[1,0]
	s_nop 0
	v_div_scale_f32 v26, s[6:7], v24, v24, 1.0
	v_rcp_f32_e32 v27, v26
	s_nop 0
	v_fma_f32 v32, -v26, v27, 1.0
	v_fmac_f32_e32 v27, v32, v27
	v_div_scale_f32 v32, vcc, 1.0, v24, 1.0
	v_mul_f32_e32 v33, v32, v27
	v_fma_f32 v34, -v26, v33, v32
	v_fmac_f32_e32 v33, v34, v27
	v_fma_f32 v26, -v26, v33, v32
	v_div_fmas_f32 v26, v26, v27, v33
	v_div_fixup_f32 v26, v26, v24, 1.0
	v_div_scale_f32 v24, s[6:7], v25, v25, 1.0
	v_rcp_f32_e32 v27, v24
	s_nop 0
	v_fma_f32 v32, -v24, v27, 1.0
	v_fmac_f32_e32 v27, v32, v27
	v_div_scale_f32 v32, vcc, 1.0, v25, 1.0
	v_mul_f32_e32 v33, v32, v27
	v_fma_f32 v34, -v24, v33, v32
	v_fmac_f32_e32 v33, v34, v27
	v_fma_f32 v24, -v24, v33, v32
	v_div_fmas_f32 v24, v24, v27, v33
	v_div_fixup_f32 v27, v24, v25, 1.0
	v_pk_add_f32 v[24:25], v[30:31], 1.0 op_sel_hi:[1,0]
	s_nop 0
	v_div_scale_f32 v30, s[6:7], v24, v24, 1.0
	v_rcp_f32_e32 v31, v30
	s_nop 0
	v_fma_f32 v32, -v30, v31, 1.0
	v_fmac_f32_e32 v31, v32, v31
	v_div_scale_f32 v32, vcc, 1.0, v24, 1.0
	v_mul_f32_e32 v33, v32, v31
	v_fma_f32 v34, -v30, v33, v32
	v_fmac_f32_e32 v33, v34, v31
	v_fma_f32 v30, -v30, v33, v32
	v_div_fmas_f32 v30, v30, v31, v33
	v_div_fixup_f32 v24, v30, v24, 1.0
	v_div_scale_f32 v30, s[6:7], v25, v25, 1.0
	v_rcp_f32_e32 v31, v30
	s_nop 0
	v_fma_f32 v32, -v30, v31, 1.0
	v_fmac_f32_e32 v31, v32, v31
	v_div_scale_f32 v32, vcc, 1.0, v25, 1.0
	v_mul_f32_e32 v33, v32, v31
	v_fma_f32 v34, -v30, v33, v32
	v_fmac_f32_e32 v33, v34, v31
	v_fma_f32 v30, -v30, v33, v32
	v_div_fmas_f32 v30, v30, v31, v33
	v_div_fixup_f32 v25, v30, v25, 1.0
	v_and_b32_sdwa v30, v27, v154 dst_sel:DWORD dst_unused:UNUSED_PAD src0_sel:WORD_1 src1_sel:DWORD
	v_and_b32_sdwa v31, v26, v154 dst_sel:DWORD dst_unused:UNUSED_PAD src0_sel:WORD_1 src1_sel:DWORD
	v_add3_u32 v26, v26, v31, s33
	v_add3_u32 v27, v27, v30, s33
	v_and_b32_sdwa v30, v25, v154 dst_sel:DWORD dst_unused:UNUSED_PAD src0_sel:WORD_1 src1_sel:DWORD
	v_and_b32_sdwa v31, v24, v154 dst_sel:DWORD dst_unused:UNUSED_PAD src0_sel:WORD_1 src1_sel:DWORD
	v_add3_u32 v25, v25, v30, s33
	v_add3_u32 v24, v24, v31, s33
	v_and_b32_e32 v25, 0xffff0000, v25
	v_and_b32_e32 v24, 0xffff0000, v24
	v_or_b32_sdwa v25, v25, v27 dst_sel:DWORD dst_unused:UNUSED_PAD src0_sel:DWORD src1_sel:WORD_1
	v_or_b32_sdwa v24, v24, v26 dst_sel:DWORD dst_unused:UNUSED_PAD src0_sel:DWORD src1_sel:WORD_1
	global_store_dwordx2 v[28:29], v[24:25], off offset:32
	v_exp_f32_e32 v24, v21
	v_mul_f32_e32 v21, 0xbfb8aa3b, v22
	v_exp_f32_e32 v21, v21
	v_mul_f32_e32 v22, 0xbfb8aa3b, v23
	v_exp_f32_e32 v25, v22
	v_pk_add_f32 v[20:21], v[20:21], 1.0 op_sel_hi:[1,0]
	s_nop 0
	v_div_scale_f32 v22, s[6:7], v20, v20, 1.0
	v_rcp_f32_e32 v23, v22
	s_nop 0
	v_fma_f32 v26, -v22, v23, 1.0
	v_fmac_f32_e32 v23, v26, v23
	v_div_scale_f32 v26, vcc, 1.0, v20, 1.0
	v_mul_f32_e32 v27, v26, v23
	v_fma_f32 v30, -v22, v27, v26
	v_fmac_f32_e32 v27, v30, v23
	v_fma_f32 v22, -v22, v27, v26
	v_div_fmas_f32 v22, v22, v23, v27
	v_div_fixup_f32 v22, v22, v20, 1.0
	v_div_scale_f32 v20, s[6:7], v21, v21, 1.0
	v_rcp_f32_e32 v23, v20
	s_nop 0
	v_fma_f32 v26, -v20, v23, 1.0
	v_fmac_f32_e32 v23, v26, v23
	v_div_scale_f32 v26, vcc, 1.0, v21, 1.0
	v_mul_f32_e32 v27, v26, v23
	v_fma_f32 v30, -v20, v27, v26
	v_fmac_f32_e32 v27, v30, v23
	v_fma_f32 v20, -v20, v27, v26
	v_div_fmas_f32 v20, v20, v23, v27
	v_div_fixup_f32 v23, v20, v21, 1.0
	v_pk_add_f32 v[20:21], v[24:25], 1.0 op_sel_hi:[1,0]
	s_nop 0
	v_div_scale_f32 v24, s[6:7], v20, v20, 1.0
	v_rcp_f32_e32 v25, v24
	s_nop 0
	v_fma_f32 v26, -v24, v25, 1.0
	v_fmac_f32_e32 v25, v26, v25
	v_div_scale_f32 v26, vcc, 1.0, v20, 1.0
	v_mul_f32_e32 v27, v26, v25
	v_fma_f32 v30, -v24, v27, v26
	v_fmac_f32_e32 v27, v30, v25
	v_fma_f32 v24, -v24, v27, v26
	v_div_fmas_f32 v24, v24, v25, v27
	v_div_fixup_f32 v20, v24, v20, 1.0
	v_div_scale_f32 v24, s[6:7], v21, v21, 1.0
	v_rcp_f32_e32 v25, v24
	s_nop 0
	v_fma_f32 v26, -v24, v25, 1.0
	v_fmac_f32_e32 v25, v26, v25
	v_div_scale_f32 v26, vcc, 1.0, v21, 1.0
	v_mul_f32_e32 v27, v26, v25
	v_fma_f32 v30, -v24, v27, v26
	v_fmac_f32_e32 v27, v30, v25
	v_fma_f32 v24, -v24, v27, v26
	v_div_fmas_f32 v24, v24, v25, v27
	v_div_fixup_f32 v21, v24, v21, 1.0
	v_and_b32_sdwa v24, v23, v154 dst_sel:DWORD dst_unused:UNUSED_PAD src0_sel:WORD_1 src1_sel:DWORD
	v_and_b32_sdwa v25, v22, v154 dst_sel:DWORD dst_unused:UNUSED_PAD src0_sel:WORD_1 src1_sel:DWORD
	v_add3_u32 v22, v22, v25, s33
	v_add3_u32 v23, v23, v24, s33
	v_and_b32_sdwa v24, v21, v154 dst_sel:DWORD dst_unused:UNUSED_PAD src0_sel:WORD_1 src1_sel:DWORD
	v_and_b32_sdwa v25, v20, v154 dst_sel:DWORD dst_unused:UNUSED_PAD src0_sel:WORD_1 src1_sel:DWORD
	v_add3_u32 v21, v21, v24, s33
	v_add3_u32 v20, v20, v25, s33
	v_and_b32_e32 v21, 0xffff0000, v21
	v_and_b32_e32 v20, 0xffff0000, v20
	v_or_b32_sdwa v21, v21, v23 dst_sel:DWORD dst_unused:UNUSED_PAD src0_sel:DWORD src1_sel:WORD_1
	v_or_b32_sdwa v20, v20, v22 dst_sel:DWORD dst_unused:UNUSED_PAD src0_sel:DWORD src1_sel:WORD_1
	global_store_dwordx2 v[28:29], v[20:21], off offset:64
	v_exp_f32_e32 v20, v17
	v_mul_f32_e32 v17, 0xbfb8aa3b, v18
	v_exp_f32_e32 v17, v17
	v_mul_f32_e32 v18, 0xbfb8aa3b, v19
	v_exp_f32_e32 v21, v18
	v_pk_add_f32 v[16:17], v[16:17], 1.0 op_sel_hi:[1,0]
	s_nop 0
	v_div_scale_f32 v18, s[6:7], v16, v16, 1.0
	v_rcp_f32_e32 v19, v18
	s_nop 0
	v_fma_f32 v22, -v18, v19, 1.0
	v_fmac_f32_e32 v19, v22, v19
	v_div_scale_f32 v22, vcc, 1.0, v16, 1.0
	v_mul_f32_e32 v23, v22, v19
	v_fma_f32 v24, -v18, v23, v22
	v_fmac_f32_e32 v23, v24, v19
	v_fma_f32 v18, -v18, v23, v22
	v_div_fmas_f32 v18, v18, v19, v23
	v_div_fixup_f32 v18, v18, v16, 1.0
	v_div_scale_f32 v16, s[6:7], v17, v17, 1.0
	v_rcp_f32_e32 v19, v16
	s_nop 0
	v_fma_f32 v22, -v16, v19, 1.0
	v_fmac_f32_e32 v19, v22, v19
	v_div_scale_f32 v22, vcc, 1.0, v17, 1.0
	v_mul_f32_e32 v23, v22, v19
	v_fma_f32 v24, -v16, v23, v22
	v_fmac_f32_e32 v23, v24, v19
	v_fma_f32 v16, -v16, v23, v22
	v_div_fmas_f32 v16, v16, v19, v23
	v_div_fixup_f32 v19, v16, v17, 1.0
	v_pk_add_f32 v[16:17], v[20:21], 1.0 op_sel_hi:[1,0]
	s_nop 0
	v_div_scale_f32 v20, s[6:7], v16, v16, 1.0
	v_rcp_f32_e32 v21, v20
	s_nop 0
	v_fma_f32 v22, -v20, v21, 1.0
	v_fmac_f32_e32 v21, v22, v21
	v_div_scale_f32 v22, vcc, 1.0, v16, 1.0
	v_mul_f32_e32 v23, v22, v21
	v_fma_f32 v24, -v20, v23, v22
	v_fmac_f32_e32 v23, v24, v21
	v_fma_f32 v20, -v20, v23, v22
	v_div_fmas_f32 v20, v20, v21, v23
	v_div_fixup_f32 v16, v20, v16, 1.0
	v_div_scale_f32 v20, s[6:7], v17, v17, 1.0
	v_rcp_f32_e32 v21, v20
	s_nop 0
	v_fma_f32 v22, -v20, v21, 1.0
	v_fmac_f32_e32 v21, v22, v21
	v_div_scale_f32 v22, vcc, 1.0, v17, 1.0
	v_mul_f32_e32 v23, v22, v21
	v_fma_f32 v24, -v20, v23, v22
	v_fmac_f32_e32 v23, v24, v21
	v_fma_f32 v20, -v20, v23, v22
	v_div_fmas_f32 v20, v20, v21, v23
	v_div_fixup_f32 v17, v20, v17, 1.0
	v_and_b32_sdwa v20, v19, v154 dst_sel:DWORD dst_unused:UNUSED_PAD src0_sel:WORD_1 src1_sel:DWORD
	v_and_b32_sdwa v21, v18, v154 dst_sel:DWORD dst_unused:UNUSED_PAD src0_sel:WORD_1 src1_sel:DWORD
	v_add3_u32 v18, v18, v21, s33
	v_add3_u32 v19, v19, v20, s33
	v_and_b32_sdwa v20, v17, v154 dst_sel:DWORD dst_unused:UNUSED_PAD src0_sel:WORD_1 src1_sel:DWORD
	v_and_b32_sdwa v21, v16, v154 dst_sel:DWORD dst_unused:UNUSED_PAD src0_sel:WORD_1 src1_sel:DWORD
	v_add3_u32 v17, v17, v20, s33
	v_add3_u32 v16, v16, v21, s33
	v_and_b32_e32 v17, 0xffff0000, v17
	v_and_b32_e32 v16, 0xffff0000, v16
	v_or_b32_sdwa v17, v17, v19 dst_sel:DWORD dst_unused:UNUSED_PAD src0_sel:DWORD src1_sel:WORD_1
	v_or_b32_sdwa v16, v16, v18 dst_sel:DWORD dst_unused:UNUSED_PAD src0_sel:DWORD src1_sel:WORD_1
	global_store_dwordx2 v[28:29], v[16:17], off offset:96
	v_mul_f32_e32 v12, 0xbfb8aa3b, v12
	v_exp_f32_e32 v18, v12
	v_mul_f32_e32 v12, 0xbfb8aa3b, v13
	v_exp_f32_e32 v20, v12
	v_mul_f32_e32 v12, 0xbfb8aa3b, v14
	v_exp_f32_e32 v19, v12
	v_or_b32_e32 v16, 48, v42
	v_mad_i64_i32 v[16:17], s[6:7], v16, s67, v[74:75]
	v_mul_f32_e32 v12, 0xbfb8aa3b, v15
	v_pk_add_f32 v[14:15], v[18:19], 1.0 op_sel_hi:[1,0]
	v_exp_f32_e32 v21, v12
	v_lshl_add_u64 v[12:13], v[16:17], 0, v[96:97]
	v_div_scale_f32 v16, s[6:7], v14, v14, 1.0
	v_rcp_f32_e32 v17, v16
	v_mul_f32_e32 v9, 0xbfb8aa3b, v9
	v_mul_f32_e32 v8, 0xbfb8aa3b, v8
	v_exp_f32_e32 v8, v8
	v_fma_f32 v18, -v16, v17, 1.0
	v_fmac_f32_e32 v17, v18, v17
	v_div_scale_f32 v18, vcc, 1.0, v14, 1.0
	v_mul_f32_e32 v19, v18, v17
	v_fma_f32 v22, -v16, v19, v18
	v_fmac_f32_e32 v19, v22, v17
	v_fma_f32 v16, -v16, v19, v18
	v_div_fmas_f32 v16, v16, v17, v19
	v_div_fixup_f32 v16, v16, v14, 1.0
	v_div_scale_f32 v14, s[6:7], v15, v15, 1.0
	v_rcp_f32_e32 v17, v14
	v_mul_f32_e32 v5, 0xbfb8aa3b, v5
	v_mul_f32_e32 v4, 0xbfb8aa3b, v4
	v_exp_f32_e32 v4, v4
	v_fma_f32 v18, -v14, v17, 1.0
	v_fmac_f32_e32 v17, v18, v17
	v_div_scale_f32 v18, vcc, 1.0, v15, 1.0
	v_mul_f32_e32 v19, v18, v17
	v_fma_f32 v22, -v14, v19, v18
	v_fmac_f32_e32 v19, v22, v17
	v_fma_f32 v14, -v14, v19, v18
	v_div_fmas_f32 v14, v14, v17, v19
	v_div_fixup_f32 v17, v14, v15, 1.0
	v_pk_add_f32 v[14:15], v[20:21], 1.0 op_sel_hi:[1,0]
	v_mul_f32_e32 v0, 0xbfb8aa3b, v0
	v_div_scale_f32 v18, s[6:7], v14, v14, 1.0
	v_rcp_f32_e32 v19, v18
	v_exp_f32_e32 v0, v0
	v_fma_f32 v20, -v18, v19, 1.0
	v_fmac_f32_e32 v19, v20, v19
	v_div_scale_f32 v20, vcc, 1.0, v14, 1.0
	v_mul_f32_e32 v21, v20, v19
	v_fma_f32 v22, -v18, v21, v20
	v_fmac_f32_e32 v21, v22, v19
	v_fma_f32 v18, -v18, v21, v20
	v_div_fmas_f32 v18, v18, v19, v21
	v_div_fixup_f32 v14, v18, v14, 1.0
	v_div_scale_f32 v18, s[6:7], v15, v15, 1.0
	v_rcp_f32_e32 v19, v18
	v_add_f32_e32 v0, 1.0, v0
	v_fma_f32 v20, -v18, v19, 1.0
	v_fmac_f32_e32 v19, v20, v19
	v_div_scale_f32 v20, vcc, 1.0, v15, 1.0
	v_mul_f32_e32 v21, v20, v19
	v_fma_f32 v22, -v18, v21, v20
	v_fmac_f32_e32 v21, v22, v19
	v_fma_f32 v18, -v18, v21, v20
	v_div_fmas_f32 v18, v18, v19, v21
	v_div_fixup_f32 v15, v18, v15, 1.0
	v_and_b32_sdwa v18, v17, v154 dst_sel:DWORD dst_unused:UNUSED_PAD src0_sel:WORD_1 src1_sel:DWORD
	v_and_b32_sdwa v19, v16, v154 dst_sel:DWORD dst_unused:UNUSED_PAD src0_sel:WORD_1 src1_sel:DWORD
	v_add3_u32 v16, v16, v19, s33
	v_add3_u32 v17, v17, v18, s33
	v_and_b32_sdwa v18, v15, v154 dst_sel:DWORD dst_unused:UNUSED_PAD src0_sel:WORD_1 src1_sel:DWORD
	v_and_b32_sdwa v19, v14, v154 dst_sel:DWORD dst_unused:UNUSED_PAD src0_sel:WORD_1 src1_sel:DWORD
	v_add3_u32 v15, v15, v18, s33
	v_add3_u32 v14, v14, v19, s33
	v_and_b32_e32 v15, 0xffff0000, v15
	v_and_b32_e32 v14, 0xffff0000, v14
	v_or_b32_sdwa v15, v15, v17 dst_sel:DWORD dst_unused:UNUSED_PAD src0_sel:DWORD src1_sel:WORD_1
	v_or_b32_sdwa v14, v14, v16 dst_sel:DWORD dst_unused:UNUSED_PAD src0_sel:DWORD src1_sel:WORD_1
	global_store_dwordx2 v[12:13], v[14:15], off
	v_exp_f32_e32 v14, v9
	v_mul_f32_e32 v9, 0xbfb8aa3b, v10
	v_exp_f32_e32 v9, v9
	v_mul_f32_e32 v10, 0xbfb8aa3b, v11
	v_exp_f32_e32 v15, v10
	v_pk_add_f32 v[8:9], v[8:9], 1.0 op_sel_hi:[1,0]
	s_nop 0
	v_div_scale_f32 v10, s[6:7], v8, v8, 1.0
	v_rcp_f32_e32 v11, v10
	s_nop 0
	v_fma_f32 v16, -v10, v11, 1.0
	v_fmac_f32_e32 v11, v16, v11
	v_div_scale_f32 v16, vcc, 1.0, v8, 1.0
	v_mul_f32_e32 v17, v16, v11
	v_fma_f32 v18, -v10, v17, v16
	v_fmac_f32_e32 v17, v18, v11
	v_fma_f32 v10, -v10, v17, v16
	v_div_fmas_f32 v10, v10, v11, v17
	v_div_fixup_f32 v10, v10, v8, 1.0
	v_div_scale_f32 v8, s[6:7], v9, v9, 1.0
	v_rcp_f32_e32 v11, v8
	s_nop 0
	v_fma_f32 v16, -v8, v11, 1.0
	v_fmac_f32_e32 v11, v16, v11
	v_div_scale_f32 v16, vcc, 1.0, v9, 1.0
	v_mul_f32_e32 v17, v16, v11
	v_fma_f32 v18, -v8, v17, v16
	v_fmac_f32_e32 v17, v18, v11
	v_fma_f32 v8, -v8, v17, v16
	v_div_fmas_f32 v8, v8, v11, v17
	v_div_fixup_f32 v11, v8, v9, 1.0
	v_pk_add_f32 v[8:9], v[14:15], 1.0 op_sel_hi:[1,0]
	s_nop 0
	v_div_scale_f32 v14, s[6:7], v8, v8, 1.0
	v_rcp_f32_e32 v15, v14
	s_nop 0
	v_fma_f32 v16, -v14, v15, 1.0
	v_fmac_f32_e32 v15, v16, v15
	v_div_scale_f32 v16, vcc, 1.0, v8, 1.0
	v_mul_f32_e32 v17, v16, v15
	v_fma_f32 v18, -v14, v17, v16
	v_fmac_f32_e32 v17, v18, v15
	v_fma_f32 v14, -v14, v17, v16
	v_div_fmas_f32 v14, v14, v15, v17
	v_div_fixup_f32 v8, v14, v8, 1.0
	v_div_scale_f32 v14, s[6:7], v9, v9, 1.0
	v_rcp_f32_e32 v15, v14
	s_nop 0
	v_fma_f32 v16, -v14, v15, 1.0
	v_fmac_f32_e32 v15, v16, v15
	v_div_scale_f32 v16, vcc, 1.0, v9, 1.0
	v_mul_f32_e32 v17, v16, v15
	v_fma_f32 v18, -v14, v17, v16
	v_fmac_f32_e32 v17, v18, v15
	v_fma_f32 v14, -v14, v17, v16
	v_div_fmas_f32 v14, v14, v15, v17
	v_div_fixup_f32 v9, v14, v9, 1.0
	v_and_b32_sdwa v14, v11, v154 dst_sel:DWORD dst_unused:UNUSED_PAD src0_sel:WORD_1 src1_sel:DWORD
	v_and_b32_sdwa v15, v10, v154 dst_sel:DWORD dst_unused:UNUSED_PAD src0_sel:WORD_1 src1_sel:DWORD
	v_add3_u32 v10, v10, v15, s33
	v_add3_u32 v11, v11, v14, s33
	v_and_b32_sdwa v14, v9, v154 dst_sel:DWORD dst_unused:UNUSED_PAD src0_sel:WORD_1 src1_sel:DWORD
	v_and_b32_sdwa v15, v8, v154 dst_sel:DWORD dst_unused:UNUSED_PAD src0_sel:WORD_1 src1_sel:DWORD
	v_add3_u32 v9, v9, v14, s33
	v_add3_u32 v8, v8, v15, s33
	v_and_b32_e32 v9, 0xffff0000, v9
	v_and_b32_e32 v8, 0xffff0000, v8
	v_or_b32_sdwa v9, v9, v11 dst_sel:DWORD dst_unused:UNUSED_PAD src0_sel:DWORD src1_sel:WORD_1
	v_or_b32_sdwa v8, v8, v10 dst_sel:DWORD dst_unused:UNUSED_PAD src0_sel:DWORD src1_sel:WORD_1
	global_store_dwordx2 v[12:13], v[8:9], off offset:32
	v_exp_f32_e32 v8, v5
	v_mul_f32_e32 v5, 0xbfb8aa3b, v6
	v_exp_f32_e32 v5, v5
	v_mul_f32_e32 v6, 0xbfb8aa3b, v7
	v_exp_f32_e32 v9, v6
	v_pk_add_f32 v[4:5], v[4:5], 1.0 op_sel_hi:[1,0]
	s_nop 0
	v_div_scale_f32 v6, s[6:7], v4, v4, 1.0
	v_rcp_f32_e32 v7, v6
	s_nop 0
	v_fma_f32 v10, -v6, v7, 1.0
	v_fmac_f32_e32 v7, v10, v7
	v_div_scale_f32 v10, vcc, 1.0, v4, 1.0
	v_mul_f32_e32 v11, v10, v7
	v_fma_f32 v14, -v6, v11, v10
	v_fmac_f32_e32 v11, v14, v7
	v_fma_f32 v6, -v6, v11, v10
	v_div_fmas_f32 v6, v6, v7, v11
	v_div_fixup_f32 v6, v6, v4, 1.0
	v_div_scale_f32 v4, s[6:7], v5, v5, 1.0
	v_rcp_f32_e32 v7, v4
	s_nop 0
	v_fma_f32 v10, -v4, v7, 1.0
	v_fmac_f32_e32 v7, v10, v7
	v_div_scale_f32 v10, vcc, 1.0, v5, 1.0
	v_mul_f32_e32 v11, v10, v7
	v_fma_f32 v14, -v4, v11, v10
	v_fmac_f32_e32 v11, v14, v7
	v_fma_f32 v4, -v4, v11, v10
	v_div_fmas_f32 v4, v4, v7, v11
	v_div_fixup_f32 v7, v4, v5, 1.0
	v_pk_add_f32 v[4:5], v[8:9], 1.0 op_sel_hi:[1,0]
	s_nop 0
	v_div_scale_f32 v8, s[6:7], v4, v4, 1.0
	v_rcp_f32_e32 v9, v8
	s_nop 0
	v_fma_f32 v10, -v8, v9, 1.0
	v_fmac_f32_e32 v9, v10, v9
	v_div_scale_f32 v10, vcc, 1.0, v4, 1.0
	v_mul_f32_e32 v11, v10, v9
	v_fma_f32 v14, -v8, v11, v10
	v_fmac_f32_e32 v11, v14, v9
	v_fma_f32 v8, -v8, v11, v10
	v_div_fmas_f32 v8, v8, v9, v11
	v_div_fixup_f32 v4, v8, v4, 1.0
	v_div_scale_f32 v8, s[6:7], v5, v5, 1.0
	v_rcp_f32_e32 v9, v8
	s_nop 0
	v_fma_f32 v10, -v8, v9, 1.0
	v_fmac_f32_e32 v9, v10, v9
	v_div_scale_f32 v10, vcc, 1.0, v5, 1.0
	v_mul_f32_e32 v11, v10, v9
	v_fma_f32 v14, -v8, v11, v10
	v_fmac_f32_e32 v11, v14, v9
	v_fma_f32 v8, -v8, v11, v10
	v_div_fmas_f32 v8, v8, v9, v11
	v_div_fixup_f32 v5, v8, v5, 1.0
	v_and_b32_sdwa v8, v7, v154 dst_sel:DWORD dst_unused:UNUSED_PAD src0_sel:WORD_1 src1_sel:DWORD
	v_and_b32_sdwa v9, v6, v154 dst_sel:DWORD dst_unused:UNUSED_PAD src0_sel:WORD_1 src1_sel:DWORD
	v_add3_u32 v6, v6, v9, s33
	v_add3_u32 v7, v7, v8, s33
	v_and_b32_sdwa v8, v5, v154 dst_sel:DWORD dst_unused:UNUSED_PAD src0_sel:WORD_1 src1_sel:DWORD
	v_and_b32_sdwa v9, v4, v154 dst_sel:DWORD dst_unused:UNUSED_PAD src0_sel:WORD_1 src1_sel:DWORD
	v_add3_u32 v5, v5, v8, s33
	v_add3_u32 v4, v4, v9, s33
	v_and_b32_e32 v5, 0xffff0000, v5
	v_and_b32_e32 v4, 0xffff0000, v4
	v_or_b32_sdwa v5, v5, v7 dst_sel:DWORD dst_unused:UNUSED_PAD src0_sel:DWORD src1_sel:WORD_1
	v_or_b32_sdwa v4, v4, v6 dst_sel:DWORD dst_unused:UNUSED_PAD src0_sel:DWORD src1_sel:WORD_1
	global_store_dwordx2 v[12:13], v[4:5], off offset:64
	v_div_scale_f32 v4, s[6:7], v0, v0, 1.0
	v_rcp_f32_e32 v5, v4
	s_nop 0
	v_fma_f32 v6, -v4, v5, 1.0
	v_fmac_f32_e32 v5, v6, v5
	v_div_scale_f32 v6, vcc, 1.0, v0, 1.0
	v_mul_f32_e32 v7, v6, v5
	v_fma_f32 v8, -v4, v7, v6
	v_fmac_f32_e32 v7, v8, v5
	v_fma_f32 v4, -v4, v7, v6
	v_div_fmas_f32 v4, v4, v5, v7
	v_div_fixup_f32 v4, v4, v0, 1.0
	v_mul_f32_e32 v0, 0xbfb8aa3b, v1
	v_exp_f32_e32 v0, v0
	s_nop 0
	v_add_f32_e32 v0, 1.0, v0
	v_div_scale_f32 v1, s[6:7], v0, v0, 1.0
	v_rcp_f32_e32 v5, v1
	s_nop 0
	v_fma_f32 v6, -v1, v5, 1.0
	v_fmac_f32_e32 v5, v6, v5
	v_div_scale_f32 v6, vcc, 1.0, v0, 1.0
	v_mul_f32_e32 v7, v6, v5
	v_fma_f32 v8, -v1, v7, v6
	v_fmac_f32_e32 v7, v8, v5
	v_fma_f32 v1, -v1, v7, v6
	v_div_fmas_f32 v1, v1, v5, v7
	v_div_fixup_f32 v5, v1, v0, 1.0
	v_mul_f32_e32 v0, 0xbfb8aa3b, v2
	v_exp_f32_e32 v1, v0
	v_mul_f32_e32 v0, 0xbfb8aa3b, v3
	v_exp_f32_e32 v0, v0
	v_bfe_u32 v2, v4, 16, 1
	v_add3_u32 v2, v4, v2, s33
	v_bfe_u32 v3, v5, 16, 1
	v_pk_add_f32 v[0:1], v[0:1], 1.0 op_sel_hi:[1,0]
	v_add3_u32 v3, v5, v3, s33
	v_div_scale_f32 v4, s[6:7], v0, v0, 1.0
	v_rcp_f32_e32 v5, v4
	v_lshrrev_b32_e32 v2, 16, v2
	v_fma_f32 v6, -v4, v5, 1.0
	v_fmac_f32_e32 v5, v6, v5
	v_div_scale_f32 v6, vcc, 1.0, v0, 1.0
	v_mul_f32_e32 v7, v6, v5
	v_fma_f32 v8, -v4, v7, v6
	v_fmac_f32_e32 v7, v8, v5
	v_fma_f32 v4, -v4, v7, v6
	v_div_fmas_f32 v4, v4, v5, v7
	v_div_fixup_f32 v0, v4, v0, 1.0
	v_div_scale_f32 v4, s[6:7], v1, v1, 1.0
	v_rcp_f32_e32 v5, v4
	s_mov_b32 s6, 0xffff0000
	v_and_or_b32 v2, v3, s6, v2
	global_store_dword v[12:13], v2, off offset:96
	v_fma_f32 v6, -v4, v5, 1.0
	v_fmac_f32_e32 v5, v6, v5
	v_div_scale_f32 v6, vcc, 1.0, v1, 1.0
	v_mul_f32_e32 v7, v6, v5
	v_fma_f32 v8, -v4, v7, v6
	v_fmac_f32_e32 v7, v8, v5
	v_fma_f32 v4, -v4, v7, v6
	v_div_fmas_f32 v4, v4, v5, v7
	v_div_fixup_f32 v1, v4, v1, 1.0
	v_and_b32_sdwa v4, v1, v154 dst_sel:DWORD dst_unused:UNUSED_PAD src0_sel:WORD_1 src1_sel:DWORD
	v_and_b32_sdwa v5, v0, v154 dst_sel:DWORD dst_unused:UNUSED_PAD src0_sel:WORD_1 src1_sel:DWORD
	v_add3_u32 v1, v1, v4, s33
	v_add3_u32 v0, v0, v5, s33
	v_lshrrev_b32_e32 v1, 16, v1
	v_and_or_b32 v81, v0, s6, v1
	s_mov_b64 s[6:7], 0x60
	v_lshl_add_u64 v[76:77], v[12:13], 0, s[6:7]

.LBB0_569:
	s_add_i32 s5, s1, 0x8000
	s_and_b32 s13, s5, 0x8000
	v_add_u32_e32 v81, s13, v74
	v_lshl_add_u64 v[82:83], v[70:71], 0, s[6:7]
	v_add_u32_e32 v90, 0x4000, v81
	v_readfirstlane_b32 s13, v81
	v_lshl_add_u64 v[84:85], v[82:83], 0, s[34:35]
	v_lshl_add_u64 v[86:87], v[72:73], 0, s[6:7]
	s_mov_b64 s[14:15], 0x12cb1080
	s_mov_b32 m0, s13
	v_readfirstlane_b32 s13, v90
	v_lshl_add_u64 v[88:89], v[86:87], 0, s[14:15]
	global_load_lds_dwordx4 v[84:85], off
	s_mov_b32 m0, s13
	v_lshl_add_u64 v[84:85], v[82:83], 0, s[36:37]
	global_load_lds_dwordx4 v[88:89], off
	v_add_u32_e32 v88, 0x1000, v81
	s_mov_b64 s[14:15], 0x12cc1080
	v_readfirstlane_b32 s13, v88
	v_add_u32_e32 v88, 0x5000, v81
	s_mov_b32 m0, s13
	v_readfirstlane_b32 s13, v88
	v_add_u32_e32 v88, 0x2000, v81
	global_load_lds_dwordx4 v[84:85], off
	v_lshl_add_u64 v[84:85], v[86:87], 0, s[14:15]
	s_mov_b32 m0, s13
	v_readfirstlane_b32 s13, v88
	v_add_u32_e32 v88, 0x6000, v81
	global_load_lds_dwordx4 v[84:85], off
	v_lshl_add_u64 v[84:85], v[82:83], 0, s[38:39]
	s_mov_b32 m0, s13
	s_mov_b64 s[14:15], 0x12cd1080
	v_readfirstlane_b32 s13, v88
	global_load_lds_dwordx4 v[84:85], off
	v_lshl_add_u64 v[84:85], v[86:87], 0, s[14:15]
	s_mov_b32 m0, s13
	v_lshl_add_u64 v[82:83], v[82:83], 0, s[40:41]
	global_load_lds_dwordx4 v[84:85], off
	v_add_u32_e32 v84, 0x3000, v81
	v_add_u32_e32 v81, 0x7000, v81
	v_readfirstlane_b32 s13, v84
	s_mov_b32 m0, s13
	s_mov_b64 s[14:15], 0x12ce1080
	v_readfirstlane_b32 s13, v81
	global_load_lds_dwordx4 v[82:83], off
	v_lshl_add_u64 v[82:83], v[86:87], 0, s[14:15]
	s_mov_b32 m0, s13
	s_and_b32 s1, s1, 0x8000
	global_load_lds_dwordx4 v[82:83], off
	s_add_i32 s1, s1, 0
	v_add_u32_e32 v81, s1, v75
	v_add_u32_e32 v94, v81, v76
	v_add_u32_e32 v81, v81, v77
	ds_read_b128 v[82:85], v94
	ds_read_b128 v[86:89], v94 offset:2048
	ds_read_b128 v[90:93], v94 offset:4096
	ds_read_b128 v[100:103], v94 offset:6144
	ds_read_b128 v[104:107], v81 offset:16384
	ds_read_b128 v[108:111], v81 offset:18432
	ds_read_b128 v[112:115], v81 offset:20480
	ds_read_b128 v[116:119], v81 offset:22528
	v_add_u32_e32 v206, s1, v78
	v_add_u32_e32 v207, v206, v76
	v_add_u32_e32 v208, v206, v77
	ds_read_b128 v[210:213], v207
	ds_read_b128 v[214:217], v207 offset:2048
	ds_read_b128 v[218:221], v207 offset:4096
	ds_read_b128 v[222:225], v207 offset:6144
	ds_read_b128 v[226:229], v208 offset:16384
	ds_read_b128 v[230:233], v208 offset:18432
	ds_read_b128 v[234:237], v208 offset:20480
	ds_read_b128 v[238:241], v208 offset:22528
	s_setprio 1
	s_waitcnt lgkmcnt(8)
	v_mfma_f32_16x16x32_bf16 v[60:63], v[104:107], v[82:85], v[60:63]
	v_mfma_f32_16x16x32_bf16 v[56:59], v[108:111], v[82:85], v[56:59]
	v_mfma_f32_16x16x32_bf16 v[52:55], v[112:115], v[82:85], v[52:55]
	v_mfma_f32_16x16x32_bf16 v[48:51], v[116:119], v[82:85], v[48:51]
	v_mfma_f32_16x16x32_bf16 v[44:47], v[104:107], v[86:89], v[44:47]
	v_mfma_f32_16x16x32_bf16 v[40:43], v[108:111], v[86:89], v[40:43]
	v_mfma_f32_16x16x32_bf16 v[36:39], v[112:115], v[86:89], v[36:39]
	v_mfma_f32_16x16x32_bf16 v[32:35], v[116:119], v[86:89], v[32:35]
	v_mfma_f32_16x16x32_bf16 v[28:31], v[104:107], v[90:93], v[28:31]
	v_mfma_f32_16x16x32_bf16 v[24:27], v[108:111], v[90:93], v[24:27]
	v_mfma_f32_16x16x32_bf16 v[20:23], v[112:115], v[90:93], v[20:23]
	v_mfma_f32_16x16x32_bf16 v[16:19], v[116:119], v[90:93], v[16:19]
	v_mfma_f32_16x16x32_bf16 v[12:15], v[104:107], v[100:103], v[12:15]
	v_mfma_f32_16x16x32_bf16 v[8:11], v[108:111], v[100:103], v[8:11]
	v_mfma_f32_16x16x32_bf16 v[4:7], v[112:115], v[100:103], v[4:7]
	v_mfma_f32_16x16x32_bf16 v[0:3], v[116:119], v[100:103], v[0:3]
	s_setprio 0
	s_setprio 1
	s_waitcnt lgkmcnt(0)
	v_mfma_f32_16x16x32_bf16 v[60:63], v[226:229], v[210:213], v[60:63]
	v_mfma_f32_16x16x32_bf16 v[56:59], v[230:233], v[210:213], v[56:59]
	v_mfma_f32_16x16x32_bf16 v[52:55], v[234:237], v[210:213], v[52:55]
	v_mfma_f32_16x16x32_bf16 v[48:51], v[238:241], v[210:213], v[48:51]
	v_mfma_f32_16x16x32_bf16 v[44:47], v[226:229], v[214:217], v[44:47]
	v_mfma_f32_16x16x32_bf16 v[40:43], v[230:233], v[214:217], v[40:43]
	v_mfma_f32_16x16x32_bf16 v[36:39], v[234:237], v[214:217], v[36:39]
	v_mfma_f32_16x16x32_bf16 v[32:35], v[238:241], v[214:217], v[32:35]
	v_mfma_f32_16x16x32_bf16 v[28:31], v[226:229], v[218:221], v[28:31]
	v_mfma_f32_16x16x32_bf16 v[24:27], v[230:233], v[218:221], v[24:27]
	v_mfma_f32_16x16x32_bf16 v[20:23], v[234:237], v[218:221], v[20:23]
	v_mfma_f32_16x16x32_bf16 v[16:19], v[238:241], v[218:221], v[16:19]
	v_mfma_f32_16x16x32_bf16 v[12:15], v[226:229], v[222:225], v[12:15]
	v_mfma_f32_16x16x32_bf16 v[8:11], v[230:233], v[222:225], v[8:11]
	v_mfma_f32_16x16x32_bf16 v[4:7], v[234:237], v[222:225], v[4:7]
	v_mfma_f32_16x16x32_bf16 v[0:3], v[238:241], v[222:225], v[0:3]
	s_setprio 0
	s_waitcnt vmcnt(0)
	s_add_u32 s6, s6, 0x80
	s_addc_u32 s7, s7, 0
	s_cmpk_lg_i32 s6, 0x780
	s_mov_b32 s1, s5
	s_waitcnt vmcnt(0)
	s_barrier
	s_cbranch_scc1 .LBB0_569
	v_add_u32_e32 v81, v79, v77
	ds_read_b128 v[70:73], v81 offset:55296
	ds_read_b128 v[82:85], v81 offset:53248
	ds_read_b128 v[86:89], v81 offset:51200
	ds_read_b128 v[90:93], v81 offset:49152
	v_add_u32_e32 v81, v79, v76
	ds_read_b128 v[100:103], v81 offset:38912
	ds_read_b128 v[104:107], v81 offset:36864
	ds_read_b128 v[108:111], v81 offset:34816
	ds_read_b128 v[112:115], v81 offset:32768
	s_setprio 1
	s_waitcnt lgkmcnt(0)
	v_mfma_f32_16x16x32_bf16 v[60:63], v[90:93], v[112:115], v[60:63]
	v_mfma_f32_16x16x32_bf16 v[56:59], v[86:89], v[112:115], v[56:59]
	v_mfma_f32_16x16x32_bf16 v[52:55], v[82:85], v[112:115], v[52:55]
	v_mfma_f32_16x16x32_bf16 v[48:51], v[70:73], v[112:115], v[48:51]
	v_mfma_f32_16x16x32_bf16 v[44:47], v[90:93], v[108:111], v[44:47]
	v_mfma_f32_16x16x32_bf16 v[40:43], v[86:89], v[108:111], v[40:43]
	v_mfma_f32_16x16x32_bf16 v[36:39], v[82:85], v[108:111], v[36:39]
	v_mfma_f32_16x16x32_bf16 v[32:35], v[70:73], v[108:111], v[32:35]
	v_mfma_f32_16x16x32_bf16 v[28:31], v[90:93], v[104:107], v[28:31]
	v_mfma_f32_16x16x32_bf16 v[24:27], v[86:89], v[104:107], v[24:27]
	v_mfma_f32_16x16x32_bf16 v[20:23], v[82:85], v[104:107], v[20:23]
	v_mfma_f32_16x16x32_bf16 v[16:19], v[70:73], v[104:107], v[16:19]
	v_mfma_f32_16x16x32_bf16 v[12:15], v[90:93], v[100:103], v[12:15]
	v_mfma_f32_16x16x32_bf16 v[8:11], v[86:89], v[100:103], v[8:11]
	v_mfma_f32_16x16x32_bf16 v[4:7], v[82:85], v[100:103], v[4:7]
	v_mfma_f32_16x16x32_bf16 v[0:3], v[70:73], v[100:103], v[0:3]
	s_setprio 0
	v_add_u32_e32 v81, v80, v76
	ds_read_b128 v[70:73], v81 offset:32768
	ds_read_b128 v[82:85], v81 offset:34816
	ds_read_b128 v[86:89], v81 offset:36864
	ds_read_b128 v[90:93], v81 offset:38912
	v_add_u32_e32 v81, v80, v77
	ds_read_b128 v[100:103], v81 offset:49152
	ds_read_b128 v[104:107], v81 offset:51200
	ds_read_b128 v[108:111], v81 offset:53248
	ds_read_b128 v[112:115], v81 offset:55296
	s_setprio 1
	s_waitcnt lgkmcnt(3)
	v_mfma_f32_16x16x32_bf16 v[60:63], v[100:103], v[70:73], v[60:63]
	s_waitcnt lgkmcnt(2)
	v_mfma_f32_16x16x32_bf16 v[56:59], v[104:107], v[70:73], v[56:59]
	s_waitcnt lgkmcnt(1)
	v_mfma_f32_16x16x32_bf16 v[52:55], v[108:111], v[70:73], v[52:55]
	s_waitcnt lgkmcnt(0)
	v_mfma_f32_16x16x32_bf16 v[48:51], v[112:115], v[70:73], v[48:51]
	v_mfma_f32_16x16x32_bf16 v[44:47], v[100:103], v[82:85], v[44:47]
	v_mfma_f32_16x16x32_bf16 v[40:43], v[104:107], v[82:85], v[40:43]
	v_mfma_f32_16x16x32_bf16 v[36:39], v[108:111], v[82:85], v[36:39]
	v_mfma_f32_16x16x32_bf16 v[32:35], v[112:115], v[82:85], v[32:35]
	v_mfma_f32_16x16x32_bf16 v[28:31], v[100:103], v[86:89], v[28:31]
	v_mfma_f32_16x16x32_bf16 v[24:27], v[104:107], v[86:89], v[24:27]
	v_mfma_f32_16x16x32_bf16 v[20:23], v[108:111], v[86:89], v[20:23]
	v_mfma_f32_16x16x32_bf16 v[16:19], v[112:115], v[86:89], v[16:19]
	v_mfma_f32_16x16x32_bf16 v[12:15], v[100:103], v[90:93], v[12:15]
	v_mfma_f32_16x16x32_bf16 v[8:11], v[104:107], v[90:93], v[8:11]
	v_mfma_f32_16x16x32_bf16 v[4:7], v[108:111], v[90:93], v[4:7]
	v_mfma_f32_16x16x32_bf16 v[0:3], v[112:115], v[90:93], v[0:3]
	s_setprio 0
	v_mov_b32_e32 v70, v97
	s_waitcnt vmcnt(0)
	s_barrier
	s_lshl_b32 s0, s0, 7
	v_add_u32_e32 v70, v70, v176
	v_and_b32_e32 v71, 64, v70
	v_ashrrev_i32_e32 v72, 1, v70
	v_lshrrev_b32_e32 v73, 2, v70
	v_and_or_b32 v70, v70, 15, s0
	s_lshl_b32 s0, s4, 7
	s_ashr_i32 s1, s0, 31
	s_lshl_b64 s[0:1], s[0:1], 1
	s_mov_b32 s6, 0
	v_and_b32_e32 v72, 0xffffffc0, v72
	s_add_u32 s0, s2, s0
	v_and_or_b32 v81, v73, 12, v71
	v_add_u32_e32 v82, v70, v72
	s_addc_u32 s1, s8, s1
	v_lshlrev_b32_e32 v96, 1, v81
	v_and_b32_sdwa v81, v62, v154 dst_sel:DWORD dst_unused:UNUSED_PAD src0_sel:WORD_1 src1_sel:DWORD
	v_and_b32_sdwa v83, v60, v154 dst_sel:DWORD dst_unused:UNUSED_PAD src0_sel:WORD_1 src1_sel:DWORD
	v_add3_u32 v60, v60, v83, s33
	v_add3_u32 v62, v62, v81, s33
	v_and_b32_sdwa v81, v63, v154 dst_sel:DWORD dst_unused:UNUSED_PAD src0_sel:WORD_1 src1_sel:DWORD
	v_and_b32_sdwa v83, v61, v154 dst_sel:DWORD dst_unused:UNUSED_PAD src0_sel:WORD_1 src1_sel:DWORD
	v_mov_b64_e32 v[70:71], s[0:1]
	s_movk_i32 s4, 0x3200
	v_add3_u32 v63, v63, v81, s33
	v_add3_u32 v61, v61, v83, s33
	v_mad_i64_i32 v[72:73], s[0:1], v82, s4, v[70:71]
	v_and_b32_e32 v63, 0xffff0000, v63
	v_and_b32_e32 v81, 0xffff0000, v61
	v_lshl_add_u64 v[72:73], v[72:73], 0, v[96:97]
	v_or_b32_sdwa v61, v63, v62 dst_sel:DWORD dst_unused:UNUSED_PAD src0_sel:DWORD src1_sel:WORD_1
	v_or_b32_sdwa v60, v81, v60 dst_sel:DWORD dst_unused:UNUSED_PAD src0_sel:DWORD src1_sel:WORD_1
	global_store_dwordx2 v[72:73], v[60:61], off
	v_and_b32_sdwa v60, v58, v154 dst_sel:DWORD dst_unused:UNUSED_PAD src0_sel:WORD_1 src1_sel:DWORD
	v_and_b32_sdwa v61, v56, v154 dst_sel:DWORD dst_unused:UNUSED_PAD src0_sel:WORD_1 src1_sel:DWORD
	v_add3_u32 v56, v56, v61, s33
	v_add3_u32 v58, v58, v60, s33
	v_and_b32_sdwa v60, v59, v154 dst_sel:DWORD dst_unused:UNUSED_PAD src0_sel:WORD_1 src1_sel:DWORD
	v_and_b32_sdwa v61, v57, v154 dst_sel:DWORD dst_unused:UNUSED_PAD src0_sel:WORD_1 src1_sel:DWORD
	v_add3_u32 v59, v59, v60, s33
	v_add3_u32 v57, v57, v61, s33
	v_and_b32_e32 v59, 0xffff0000, v59
	v_and_b32_e32 v60, 0xffff0000, v57
	v_or_b32_sdwa v57, v59, v58 dst_sel:DWORD dst_unused:UNUSED_PAD src0_sel:DWORD src1_sel:WORD_1
	v_or_b32_sdwa v56, v60, v56 dst_sel:DWORD dst_unused:UNUSED_PAD src0_sel:DWORD src1_sel:WORD_1
	global_store_dwordx2 v[72:73], v[56:57], off offset:32
	v_and_b32_sdwa v56, v54, v154 dst_sel:DWORD dst_unused:UNUSED_PAD src0_sel:WORD_1 src1_sel:DWORD
	v_and_b32_sdwa v57, v52, v154 dst_sel:DWORD dst_unused:UNUSED_PAD src0_sel:WORD_1 src1_sel:DWORD
	v_add3_u32 v52, v52, v57, s33
	v_add3_u32 v54, v54, v56, s33
	v_and_b32_sdwa v56, v55, v154 dst_sel:DWORD dst_unused:UNUSED_PAD src0_sel:WORD_1 src1_sel:DWORD
	v_and_b32_sdwa v57, v53, v154 dst_sel:DWORD dst_unused:UNUSED_PAD src0_sel:WORD_1 src1_sel:DWORD
	v_add3_u32 v55, v55, v56, s33
	v_add3_u32 v53, v53, v57, s33
	v_and_b32_e32 v55, 0xffff0000, v55
	v_and_b32_e32 v56, 0xffff0000, v53
	v_or_b32_sdwa v53, v55, v54 dst_sel:DWORD dst_unused:UNUSED_PAD src0_sel:DWORD src1_sel:WORD_1
	v_or_b32_sdwa v52, v56, v52 dst_sel:DWORD dst_unused:UNUSED_PAD src0_sel:DWORD src1_sel:WORD_1
	global_store_dwordx2 v[72:73], v[52:53], off offset:64
	v_and_b32_sdwa v52, v50, v154 dst_sel:DWORD dst_unused:UNUSED_PAD src0_sel:WORD_1 src1_sel:DWORD
	v_and_b32_sdwa v53, v48, v154 dst_sel:DWORD dst_unused:UNUSED_PAD src0_sel:WORD_1 src1_sel:DWORD
	v_add3_u32 v48, v48, v53, s33
	v_add3_u32 v50, v50, v52, s33
	v_and_b32_sdwa v52, v51, v154 dst_sel:DWORD dst_unused:UNUSED_PAD src0_sel:WORD_1 src1_sel:DWORD
	v_and_b32_sdwa v53, v49, v154 dst_sel:DWORD dst_unused:UNUSED_PAD src0_sel:WORD_1 src1_sel:DWORD
	v_add3_u32 v51, v51, v52, s33
	v_add3_u32 v49, v49, v53, s33
	v_and_b32_e32 v51, 0xffff0000, v51
	v_and_b32_e32 v52, 0xffff0000, v49
	v_or_b32_sdwa v49, v51, v50 dst_sel:DWORD dst_unused:UNUSED_PAD src0_sel:DWORD src1_sel:WORD_1
	v_or_b32_sdwa v48, v52, v48 dst_sel:DWORD dst_unused:UNUSED_PAD src0_sel:DWORD src1_sel:WORD_1
	global_store_dwordx2 v[72:73], v[48:49], off offset:96
	v_and_b32_sdwa v50, v46, v154 dst_sel:DWORD dst_unused:UNUSED_PAD src0_sel:WORD_1 src1_sel:DWORD
	v_and_b32_sdwa v51, v44, v154 dst_sel:DWORD dst_unused:UNUSED_PAD src0_sel:WORD_1 src1_sel:DWORD
	v_add3_u32 v44, v44, v51, s33
	v_add3_u32 v46, v46, v50, s33
	v_and_b32_sdwa v50, v47, v154 dst_sel:DWORD dst_unused:UNUSED_PAD src0_sel:WORD_1 src1_sel:DWORD
	v_and_b32_sdwa v51, v45, v154 dst_sel:DWORD dst_unused:UNUSED_PAD src0_sel:WORD_1 src1_sel:DWORD
	v_or_b32_e32 v48, 16, v82
	v_add3_u32 v47, v47, v50, s33
	v_add3_u32 v45, v45, v51, s33
	v_mad_i64_i32 v[48:49], s[0:1], v48, s4, v[70:71]
	v_and_b32_e32 v47, 0xffff0000, v47
	v_and_b32_e32 v50, 0xffff0000, v45
	v_lshl_add_u64 v[48:49], v[48:49], 0, v[96:97]
	v_or_b32_sdwa v45, v47, v46 dst_sel:DWORD dst_unused:UNUSED_PAD src0_sel:DWORD src1_sel:WORD_1
	v_or_b32_sdwa v44, v50, v44 dst_sel:DWORD dst_unused:UNUSED_PAD src0_sel:DWORD src1_sel:WORD_1
	global_store_dwordx2 v[48:49], v[44:45], off
	v_and_b32_sdwa v44, v42, v154 dst_sel:DWORD dst_unused:UNUSED_PAD src0_sel:WORD_1 src1_sel:DWORD
	v_and_b32_sdwa v45, v40, v154 dst_sel:DWORD dst_unused:UNUSED_PAD src0_sel:WORD_1 src1_sel:DWORD
	v_add3_u32 v40, v40, v45, s33
	v_add3_u32 v42, v42, v44, s33
	v_and_b32_sdwa v44, v43, v154 dst_sel:DWORD dst_unused:UNUSED_PAD src0_sel:WORD_1 src1_sel:DWORD
	v_and_b32_sdwa v45, v41, v154 dst_sel:DWORD dst_unused:UNUSED_PAD src0_sel:WORD_1 src1_sel:DWORD
	v_add3_u32 v43, v43, v44, s33
	v_add3_u32 v41, v41, v45, s33
	v_and_b32_e32 v43, 0xffff0000, v43
	v_and_b32_e32 v44, 0xffff0000, v41
	v_or_b32_sdwa v41, v43, v42 dst_sel:DWORD dst_unused:UNUSED_PAD src0_sel:DWORD src1_sel:WORD_1
	v_or_b32_sdwa v40, v44, v40 dst_sel:DWORD dst_unused:UNUSED_PAD src0_sel:DWORD src1_sel:WORD_1
	global_store_dwordx2 v[48:49], v[40:41], off offset:32
	v_and_b32_sdwa v40, v38, v154 dst_sel:DWORD dst_unused:UNUSED_PAD src0_sel:WORD_1 src1_sel:DWORD
	v_and_b32_sdwa v41, v36, v154 dst_sel:DWORD dst_unused:UNUSED_PAD src0_sel:WORD_1 src1_sel:DWORD
	v_add3_u32 v36, v36, v41, s33
	v_add3_u32 v38, v38, v40, s33
	v_and_b32_sdwa v40, v39, v154 dst_sel:DWORD dst_unused:UNUSED_PAD src0_sel:WORD_1 src1_sel:DWORD
	v_and_b32_sdwa v41, v37, v154 dst_sel:DWORD dst_unused:UNUSED_PAD src0_sel:WORD_1 src1_sel:DWORD
	v_add3_u32 v39, v39, v40, s33
	v_add3_u32 v37, v37, v41, s33
	v_and_b32_e32 v39, 0xffff0000, v39
	v_and_b32_e32 v40, 0xffff0000, v37
	v_or_b32_sdwa v37, v39, v38 dst_sel:DWORD dst_unused:UNUSED_PAD src0_sel:DWORD src1_sel:WORD_1
	v_or_b32_sdwa v36, v40, v36 dst_sel:DWORD dst_unused:UNUSED_PAD src0_sel:DWORD src1_sel:WORD_1
	global_store_dwordx2 v[48:49], v[36:37], off offset:64
	v_and_b32_sdwa v36, v34, v154 dst_sel:DWORD dst_unused:UNUSED_PAD src0_sel:WORD_1 src1_sel:DWORD
	v_and_b32_sdwa v37, v32, v154 dst_sel:DWORD dst_unused:UNUSED_PAD src0_sel:WORD_1 src1_sel:DWORD
	v_add3_u32 v32, v32, v37, s33
	v_add3_u32 v34, v34, v36, s33
	v_and_b32_sdwa v36, v35, v154 dst_sel:DWORD dst_unused:UNUSED_PAD src0_sel:WORD_1 src1_sel:DWORD
	v_and_b32_sdwa v37, v33, v154 dst_sel:DWORD dst_unused:UNUSED_PAD src0_sel:WORD_1 src1_sel:DWORD
	v_add3_u32 v35, v35, v36, s33
	v_add3_u32 v33, v33, v37, s33
	v_and_b32_e32 v35, 0xffff0000, v35
	v_and_b32_e32 v36, 0xffff0000, v33
	v_or_b32_sdwa v33, v35, v34 dst_sel:DWORD dst_unused:UNUSED_PAD src0_sel:DWORD src1_sel:WORD_1
	v_or_b32_sdwa v32, v36, v32 dst_sel:DWORD dst_unused:UNUSED_PAD src0_sel:DWORD src1_sel:WORD_1
	global_store_dwordx2 v[48:49], v[32:33], off offset:96
	v_and_b32_sdwa v34, v30, v154 dst_sel:DWORD dst_unused:UNUSED_PAD src0_sel:WORD_1 src1_sel:DWORD
	v_and_b32_sdwa v35, v28, v154 dst_sel:DWORD dst_unused:UNUSED_PAD src0_sel:WORD_1 src1_sel:DWORD
	v_add3_u32 v28, v28, v35, s33
	v_add3_u32 v30, v30, v34, s33
	v_and_b32_sdwa v34, v31, v154 dst_sel:DWORD dst_unused:UNUSED_PAD src0_sel:WORD_1 src1_sel:DWORD
	v_and_b32_sdwa v35, v29, v154 dst_sel:DWORD dst_unused:UNUSED_PAD src0_sel:WORD_1 src1_sel:DWORD
	v_or_b32_e32 v32, 32, v82
	v_add3_u32 v31, v31, v34, s33
	v_add3_u32 v29, v29, v35, s33
	v_mad_i64_i32 v[32:33], s[0:1], v32, s4, v[70:71]
	v_and_b32_e32 v31, 0xffff0000, v31
	v_and_b32_e32 v34, 0xffff0000, v29
	v_lshl_add_u64 v[32:33], v[32:33], 0, v[96:97]
	v_or_b32_sdwa v29, v31, v30 dst_sel:DWORD dst_unused:UNUSED_PAD src0_sel:DWORD src1_sel:WORD_1
	v_or_b32_sdwa v28, v34, v28 dst_sel:DWORD dst_unused:UNUSED_PAD src0_sel:DWORD src1_sel:WORD_1
	global_store_dwordx2 v[32:33], v[28:29], off
	v_and_b32_sdwa v28, v26, v154 dst_sel:DWORD dst_unused:UNUSED_PAD src0_sel:WORD_1 src1_sel:DWORD
	v_and_b32_sdwa v29, v24, v154 dst_sel:DWORD dst_unused:UNUSED_PAD src0_sel:WORD_1 src1_sel:DWORD
	v_add3_u32 v24, v24, v29, s33
	v_add3_u32 v26, v26, v28, s33
	v_and_b32_sdwa v28, v27, v154 dst_sel:DWORD dst_unused:UNUSED_PAD src0_sel:WORD_1 src1_sel:DWORD
	v_and_b32_sdwa v29, v25, v154 dst_sel:DWORD dst_unused:UNUSED_PAD src0_sel:WORD_1 src1_sel:DWORD
	v_add3_u32 v27, v27, v28, s33
	v_add3_u32 v25, v25, v29, s33
	v_and_b32_e32 v27, 0xffff0000, v27
	v_and_b32_e32 v28, 0xffff0000, v25
	v_or_b32_sdwa v25, v27, v26 dst_sel:DWORD dst_unused:UNUSED_PAD src0_sel:DWORD src1_sel:WORD_1
	v_or_b32_sdwa v24, v28, v24 dst_sel:DWORD dst_unused:UNUSED_PAD src0_sel:DWORD src1_sel:WORD_1
	global_store_dwordx2 v[32:33], v[24:25], off offset:32
	v_and_b32_sdwa v24, v22, v154 dst_sel:DWORD dst_unused:UNUSED_PAD src0_sel:WORD_1 src1_sel:DWORD
	v_and_b32_sdwa v25, v20, v154 dst_sel:DWORD dst_unused:UNUSED_PAD src0_sel:WORD_1 src1_sel:DWORD
	v_add3_u32 v20, v20, v25, s33
	v_add3_u32 v22, v22, v24, s33
	v_and_b32_sdwa v24, v23, v154 dst_sel:DWORD dst_unused:UNUSED_PAD src0_sel:WORD_1 src1_sel:DWORD
	v_and_b32_sdwa v25, v21, v154 dst_sel:DWORD dst_unused:UNUSED_PAD src0_sel:WORD_1 src1_sel:DWORD
	v_add3_u32 v23, v23, v24, s33
	v_add3_u32 v21, v21, v25, s33
	v_and_b32_e32 v23, 0xffff0000, v23
	v_and_b32_e32 v24, 0xffff0000, v21
	v_or_b32_sdwa v21, v23, v22 dst_sel:DWORD dst_unused:UNUSED_PAD src0_sel:DWORD src1_sel:WORD_1
	v_or_b32_sdwa v20, v24, v20 dst_sel:DWORD dst_unused:UNUSED_PAD src0_sel:DWORD src1_sel:WORD_1
	global_store_dwordx2 v[32:33], v[20:21], off offset:64
	v_and_b32_sdwa v20, v18, v154 dst_sel:DWORD dst_unused:UNUSED_PAD src0_sel:WORD_1 src1_sel:DWORD
	v_and_b32_sdwa v21, v16, v154 dst_sel:DWORD dst_unused:UNUSED_PAD src0_sel:WORD_1 src1_sel:DWORD
	v_add3_u32 v16, v16, v21, s33
	v_add3_u32 v18, v18, v20, s33
	v_and_b32_sdwa v20, v19, v154 dst_sel:DWORD dst_unused:UNUSED_PAD src0_sel:WORD_1 src1_sel:DWORD
	v_and_b32_sdwa v21, v17, v154 dst_sel:DWORD dst_unused:UNUSED_PAD src0_sel:WORD_1 src1_sel:DWORD
	v_add3_u32 v19, v19, v20, s33
	v_add3_u32 v17, v17, v21, s33
	v_and_b32_e32 v19, 0xffff0000, v19
	v_and_b32_e32 v20, 0xffff0000, v17
	v_or_b32_sdwa v17, v19, v18 dst_sel:DWORD dst_unused:UNUSED_PAD src0_sel:DWORD src1_sel:WORD_1
	v_or_b32_sdwa v16, v20, v16 dst_sel:DWORD dst_unused:UNUSED_PAD src0_sel:DWORD src1_sel:WORD_1
	global_store_dwordx2 v[32:33], v[16:17], off offset:96
	v_and_b32_sdwa v18, v14, v154 dst_sel:DWORD dst_unused:UNUSED_PAD src0_sel:WORD_1 src1_sel:DWORD
	v_and_b32_sdwa v19, v12, v154 dst_sel:DWORD dst_unused:UNUSED_PAD src0_sel:WORD_1 src1_sel:DWORD
	v_add3_u32 v12, v12, v19, s33
	v_add3_u32 v14, v14, v18, s33
	v_and_b32_sdwa v18, v15, v154 dst_sel:DWORD dst_unused:UNUSED_PAD src0_sel:WORD_1 src1_sel:DWORD
	v_and_b32_sdwa v19, v13, v154 dst_sel:DWORD dst_unused:UNUSED_PAD src0_sel:WORD_1 src1_sel:DWORD
	v_or_b32_e32 v16, 48, v82
	v_add3_u32 v15, v15, v18, s33
	v_add3_u32 v13, v13, v19, s33
	v_mad_i64_i32 v[16:17], s[0:1], v16, s4, v[70:71]
	v_and_b32_e32 v15, 0xffff0000, v15
	v_and_b32_e32 v18, 0xffff0000, v13
	v_lshl_add_u64 v[16:17], v[16:17], 0, v[96:97]
	v_or_b32_sdwa v13, v15, v14 dst_sel:DWORD dst_unused:UNUSED_PAD src0_sel:DWORD src1_sel:WORD_1
	v_or_b32_sdwa v12, v18, v12 dst_sel:DWORD dst_unused:UNUSED_PAD src0_sel:DWORD src1_sel:WORD_1
	global_store_dwordx2 v[16:17], v[12:13], off
	v_and_b32_sdwa v12, v10, v154 dst_sel:DWORD dst_unused:UNUSED_PAD src0_sel:WORD_1 src1_sel:DWORD
	v_and_b32_sdwa v13, v8, v154 dst_sel:DWORD dst_unused:UNUSED_PAD src0_sel:WORD_1 src1_sel:DWORD
	v_add3_u32 v8, v8, v13, s33
	v_add3_u32 v10, v10, v12, s33
	v_and_b32_sdwa v12, v11, v154 dst_sel:DWORD dst_unused:UNUSED_PAD src0_sel:WORD_1 src1_sel:DWORD
	v_and_b32_sdwa v13, v9, v154 dst_sel:DWORD dst_unused:UNUSED_PAD src0_sel:WORD_1 src1_sel:DWORD
	v_add3_u32 v11, v11, v12, s33
	v_add3_u32 v9, v9, v13, s33
	v_and_b32_e32 v11, 0xffff0000, v11
	v_and_b32_e32 v12, 0xffff0000, v9
	v_or_b32_sdwa v9, v11, v10 dst_sel:DWORD dst_unused:UNUSED_PAD src0_sel:DWORD src1_sel:WORD_1
	v_or_b32_sdwa v8, v12, v8 dst_sel:DWORD dst_unused:UNUSED_PAD src0_sel:DWORD src1_sel:WORD_1
	global_store_dwordx2 v[16:17], v[8:9], off offset:32
	v_and_b32_sdwa v8, v6, v154 dst_sel:DWORD dst_unused:UNUSED_PAD src0_sel:WORD_1 src1_sel:DWORD
	v_and_b32_sdwa v9, v4, v154 dst_sel:DWORD dst_unused:UNUSED_PAD src0_sel:WORD_1 src1_sel:DWORD
	v_add3_u32 v4, v4, v9, s33
	v_add3_u32 v6, v6, v8, s33
	v_and_b32_sdwa v8, v7, v154 dst_sel:DWORD dst_unused:UNUSED_PAD src0_sel:WORD_1 src1_sel:DWORD
	v_and_b32_sdwa v9, v5, v154 dst_sel:DWORD dst_unused:UNUSED_PAD src0_sel:WORD_1 src1_sel:DWORD
	v_add3_u32 v7, v7, v8, s33
	v_add3_u32 v5, v5, v9, s33
	v_and_b32_e32 v7, 0xffff0000, v7
	v_and_b32_e32 v8, 0xffff0000, v5
	v_or_b32_sdwa v5, v7, v6 dst_sel:DWORD dst_unused:UNUSED_PAD src0_sel:DWORD src1_sel:WORD_1
	v_or_b32_sdwa v4, v8, v4 dst_sel:DWORD dst_unused:UNUSED_PAD src0_sel:DWORD src1_sel:WORD_1
	global_store_dwordx2 v[16:17], v[4:5], off offset:64
	v_and_b32_sdwa v4, v2, v154 dst_sel:DWORD dst_unused:UNUSED_PAD src0_sel:WORD_1 src1_sel:DWORD
	v_and_b32_sdwa v5, v0, v154 dst_sel:DWORD dst_unused:UNUSED_PAD src0_sel:WORD_1 src1_sel:DWORD
	v_add3_u32 v0, v0, v5, s33
	v_add3_u32 v2, v2, v4, s33
	v_and_b32_sdwa v4, v3, v154 dst_sel:DWORD dst_unused:UNUSED_PAD src0_sel:WORD_1 src1_sel:DWORD
	v_and_b32_sdwa v5, v1, v154 dst_sel:DWORD dst_unused:UNUSED_PAD src0_sel:WORD_1 src1_sel:DWORD
	v_add3_u32 v3, v3, v4, s33
	v_add3_u32 v1, v1, v5, s33
	v_and_b32_e32 v3, 0xffff0000, v3
	v_and_b32_e32 v4, 0xffff0000, v1
	v_or_b32_sdwa v1, v3, v2 dst_sel:DWORD dst_unused:UNUSED_PAD src0_sel:DWORD src1_sel:WORD_1
	v_or_b32_sdwa v0, v4, v0 dst_sel:DWORD dst_unused:UNUSED_PAD src0_sel:DWORD src1_sel:WORD_1
	global_store_dwordx2 v[16:17], v[0:1], off offset:96

.LBB0_582:
	s_add_i32 s7, s5, 1
	s_bitcmp1_b32 s7, 0
	s_cselect_b32 s13, 0x9000, 0
	v_add_u32_e32 v106, s13, v92
	v_lshl_add_u64 v[102:103], v[88:89], 0, s[8:9]
	s_mov_b64 s[14:15], 0x1c9b1080
	v_readfirstlane_b32 s13, v106
	v_add_u32_e32 v107, 0x1000, v106
	v_lshl_add_u64 v[104:105], v[102:103], 0, s[14:15]
	s_mov_b32 m0, s13
	s_mov_b64 s[14:15], 0x1c9c1080
	v_readfirstlane_b32 s13, v107
	v_add_u32_e32 v107, 0x2000, v106
	global_load_lds_dwordx4 v[104:105], off
	v_lshl_add_u64 v[104:105], v[102:103], 0, s[14:15]
	s_mov_b32 m0, s13
	s_mov_b64 s[14:15], 0x1c9d1080
	v_readfirstlane_b32 s13, v107
	v_add_u32_e32 v107, 0x3000, v106
	global_load_lds_dwordx4 v[104:105], off
	v_lshl_add_u64 v[104:105], v[102:103], 0, s[14:15]
	s_mov_b32 m0, s13
	s_mov_b64 s[14:15], 0x1c9e1080
	v_readfirstlane_b32 s13, v107
	global_load_lds_dwordx4 v[104:105], off
	v_lshl_add_u64 v[104:105], v[102:103], 0, s[14:15]
	s_mov_b32 m0, s13
	s_mov_b64 s[14:15], 0x1c9f1080
	global_load_lds_dwordx4 v[104:105], off
	v_add_u32_e32 v104, 0x4000, v106
	v_lshl_add_u64 v[102:103], v[102:103], 0, s[14:15]
	v_readfirstlane_b32 s13, v104
	s_mov_b32 m0, s13
	v_add_u32_e32 v107, 0x5000, v106
	global_load_lds_dwordx4 v[102:103], off
	v_lshl_add_u64 v[102:103], v[90:91], 0, s[8:9]
	s_mov_b64 s[14:15], 0x14b31080
	v_readfirstlane_b32 s13, v107
	v_add_u32_e32 v107, 0x6000, v106
	v_lshl_add_u64 v[104:105], v[102:103], 0, s[14:15]
	s_mov_b32 m0, s13
	s_mov_b64 s[14:15], 0x14b41080
	v_readfirstlane_b32 s13, v107
	v_add_u32_e32 v107, 0x7000, v106
	global_load_lds_dwordx4 v[104:105], off
	v_lshl_add_u64 v[104:105], v[102:103], 0, s[14:15]
	s_mov_b32 m0, s13
	s_mov_b64 s[14:15], 0x14b51080
	v_readfirstlane_b32 s13, v107
	global_load_lds_dwordx4 v[104:105], off
	v_lshl_add_u64 v[104:105], v[102:103], 0, s[14:15]
	s_mov_b32 m0, s13
	s_mov_b64 s[14:15], 0x14b61080
	global_load_lds_dwordx4 v[104:105], off
	v_add_u32_e32 v104, 0x8000, v106
	v_lshl_add_u64 v[102:103], v[102:103], 0, s[14:15]
	v_readfirstlane_b32 s13, v104
	s_mov_b32 m0, s13
	s_bitcmp1_b32 s5, 0
	global_load_lds_dwordx4 v[102:103], off
	s_cselect_b32 s5, 0x9000, 0
	s_add_i32 s5, s5, 0
	v_add_u32_e32 v118, s5, v93
	v_add_u32_e32 v119, v118, v94
	v_add_u32_e32 v156, v118, v95
	ds_read_b128 v[102:105], v119
	ds_read_b128 v[106:109], v119 offset:2048
	ds_read_b128 v[110:113], v119 offset:4096
	ds_read_b128 v[114:117], v119 offset:6144
	ds_read_b128 v[118:121], v119 offset:8192
	ds_read_b128 v[122:125], v156 offset:20480
	ds_read_b128 v[126:129], v156 offset:22528
	ds_read_b128 v[130:133], v156 offset:24576
	ds_read_b128 v[156:159], v156 offset:26624
	v_add_u32_e32 v206, s5, v96
	v_add_u32_e32 v207, v206, v94
	v_add_u32_e32 v208, v206, v95
	ds_read_b128 v[210:213], v207
	ds_read_b128 v[214:217], v207 offset:2048
	ds_read_b128 v[218:221], v207 offset:4096
	ds_read_b128 v[222:225], v207 offset:6144
	ds_read_b128 v[226:229], v207 offset:8192
	ds_read_b128 v[230:233], v208 offset:20480
	ds_read_b128 v[234:237], v208 offset:22528
	ds_read_b128 v[238:241], v208 offset:24576
	ds_read_b128 v[242:245], v208 offset:26624
	s_setprio 1
	s_waitcnt lgkmcnt(9)
	v_mfma_f32_16x16x32_bf16 v[76:79], v[122:125], v[102:105], v[76:79]
	v_mfma_f32_16x16x32_bf16 v[72:75], v[126:129], v[102:105], v[72:75]
	v_mfma_f32_16x16x32_bf16 v[68:71], v[130:133], v[102:105], v[68:71]
	v_mfma_f32_16x16x32_bf16 v[64:67], v[156:159], v[102:105], v[64:67]
	v_mfma_f32_16x16x32_bf16 v[60:63], v[122:125], v[106:109], v[60:63]
	v_mfma_f32_16x16x32_bf16 v[56:59], v[126:129], v[106:109], v[56:59]
	v_mfma_f32_16x16x32_bf16 v[52:55], v[130:133], v[106:109], v[52:55]
	v_mfma_f32_16x16x32_bf16 v[48:51], v[156:159], v[106:109], v[48:51]
	v_mfma_f32_16x16x32_bf16 v[44:47], v[122:125], v[110:113], v[44:47]
	v_mfma_f32_16x16x32_bf16 v[40:43], v[126:129], v[110:113], v[40:43]
	v_mfma_f32_16x16x32_bf16 v[36:39], v[130:133], v[110:113], v[36:39]
	v_mfma_f32_16x16x32_bf16 v[32:35], v[156:159], v[110:113], v[32:35]
	v_mfma_f32_16x16x32_bf16 v[28:31], v[122:125], v[114:117], v[28:31]
	v_mfma_f32_16x16x32_bf16 v[24:27], v[126:129], v[114:117], v[24:27]
	v_mfma_f32_16x16x32_bf16 v[20:23], v[130:133], v[114:117], v[20:23]
	v_mfma_f32_16x16x32_bf16 v[16:19], v[156:159], v[114:117], v[16:19]
	v_mfma_f32_16x16x32_bf16 v[12:15], v[122:125], v[118:121], v[12:15]
	v_mfma_f32_16x16x32_bf16 v[8:11], v[126:129], v[118:121], v[8:11]
	v_mfma_f32_16x16x32_bf16 v[4:7], v[130:133], v[118:121], v[4:7]
	v_mfma_f32_16x16x32_bf16 v[0:3], v[156:159], v[118:121], v[0:3]
	s_setprio 0
	s_setprio 1
	s_waitcnt lgkmcnt(0)
	v_mfma_f32_16x16x32_bf16 v[76:79], v[230:233], v[210:213], v[76:79]
	v_mfma_f32_16x16x32_bf16 v[72:75], v[234:237], v[210:213], v[72:75]
	v_mfma_f32_16x16x32_bf16 v[68:71], v[238:241], v[210:213], v[68:71]
	v_mfma_f32_16x16x32_bf16 v[64:67], v[242:245], v[210:213], v[64:67]
	v_mfma_f32_16x16x32_bf16 v[60:63], v[230:233], v[214:217], v[60:63]
	v_mfma_f32_16x16x32_bf16 v[56:59], v[234:237], v[214:217], v[56:59]
	v_mfma_f32_16x16x32_bf16 v[52:55], v[238:241], v[214:217], v[52:55]
	v_mfma_f32_16x16x32_bf16 v[48:51], v[242:245], v[214:217], v[48:51]
	v_mfma_f32_16x16x32_bf16 v[44:47], v[230:233], v[218:221], v[44:47]
	v_mfma_f32_16x16x32_bf16 v[40:43], v[234:237], v[218:221], v[40:43]
	v_mfma_f32_16x16x32_bf16 v[36:39], v[238:241], v[218:221], v[36:39]
	v_mfma_f32_16x16x32_bf16 v[32:35], v[242:245], v[218:221], v[32:35]
	v_mfma_f32_16x16x32_bf16 v[28:31], v[230:233], v[222:225], v[28:31]
	v_mfma_f32_16x16x32_bf16 v[24:27], v[234:237], v[222:225], v[24:27]
	v_mfma_f32_16x16x32_bf16 v[20:23], v[238:241], v[222:225], v[20:23]
	v_mfma_f32_16x16x32_bf16 v[16:19], v[242:245], v[222:225], v[16:19]
	v_mfma_f32_16x16x32_bf16 v[12:15], v[230:233], v[226:229], v[12:15]
	v_mfma_f32_16x16x32_bf16 v[8:11], v[234:237], v[226:229], v[8:11]
	v_mfma_f32_16x16x32_bf16 v[4:7], v[238:241], v[226:229], v[4:7]
	v_mfma_f32_16x16x32_bf16 v[0:3], v[242:245], v[226:229], v[0:3]
	s_setprio 0
	s_waitcnt vmcnt(0)
	s_add_u32 s8, s8, 0x80
	s_addc_u32 s9, s9, 0
	s_cmpk_lg_i32 s8, 0x780
	s_mov_b32 s5, s7
	s_waitcnt vmcnt(0)
	s_barrier
	s_cbranch_scc1 .LBB0_582
	v_add_u32_e32 v110, v100, v95
	v_add_u32_e32 v130, v100, v94
	ds_read_b128 v[88:91], v110 offset:63488
	ds_read_b128 v[102:105], v110 offset:61440
	ds_read_b128 v[106:109], v110 offset:59392
	ds_read_b128 v[110:113], v110 offset:57344
	ds_read_b128 v[114:117], v130 offset:45056
	ds_read_b128 v[118:121], v130 offset:43008
	ds_read_b128 v[122:125], v130 offset:40960
	ds_read_b128 v[126:129], v130 offset:38912
	ds_read_b128 v[130:133], v130 offset:36864
	s_setprio 1
	s_waitcnt lgkmcnt(0)
	v_mfma_f32_16x16x32_bf16 v[76:79], v[110:113], v[130:133], v[76:79]
	v_mfma_f32_16x16x32_bf16 v[72:75], v[106:109], v[130:133], v[72:75]
	v_mfma_f32_16x16x32_bf16 v[68:71], v[102:105], v[130:133], v[68:71]
	v_mfma_f32_16x16x32_bf16 v[64:67], v[88:91], v[130:133], v[64:67]
	v_mfma_f32_16x16x32_bf16 v[60:63], v[110:113], v[126:129], v[60:63]
	v_mfma_f32_16x16x32_bf16 v[56:59], v[106:109], v[126:129], v[56:59]
	v_mfma_f32_16x16x32_bf16 v[52:55], v[102:105], v[126:129], v[52:55]
	v_mfma_f32_16x16x32_bf16 v[48:51], v[88:91], v[126:129], v[48:51]
	v_mfma_f32_16x16x32_bf16 v[44:47], v[110:113], v[122:125], v[44:47]
	v_mfma_f32_16x16x32_bf16 v[40:43], v[106:109], v[122:125], v[40:43]
	v_mfma_f32_16x16x32_bf16 v[36:39], v[102:105], v[122:125], v[36:39]
	v_mfma_f32_16x16x32_bf16 v[32:35], v[88:91], v[122:125], v[32:35]
	v_mfma_f32_16x16x32_bf16 v[28:31], v[110:113], v[118:121], v[28:31]
	v_mfma_f32_16x16x32_bf16 v[24:27], v[106:109], v[118:121], v[24:27]
	v_mfma_f32_16x16x32_bf16 v[20:23], v[102:105], v[118:121], v[20:23]
	v_mfma_f32_16x16x32_bf16 v[16:19], v[88:91], v[118:121], v[16:19]
	v_mfma_f32_16x16x32_bf16 v[12:15], v[110:113], v[114:117], v[12:15]
	v_mfma_f32_16x16x32_bf16 v[8:11], v[106:109], v[114:117], v[8:11]
	v_mfma_f32_16x16x32_bf16 v[4:7], v[102:105], v[114:117], v[4:7]
	v_mfma_f32_16x16x32_bf16 v[0:3], v[88:91], v[114:117], v[0:3]
	s_setprio 0
	v_add_u32_e32 v114, v101, v94
	v_add_u32_e32 v130, v101, v95
	ds_read_b128 v[88:91], v114 offset:36864
	ds_read_b128 v[102:105], v114 offset:38912
	ds_read_b128 v[106:109], v114 offset:40960
	ds_read_b128 v[110:113], v114 offset:43008
	ds_read_b128 v[114:117], v114 offset:45056
	ds_read_b128 v[118:121], v130 offset:57344
	ds_read_b128 v[122:125], v130 offset:59392
	ds_read_b128 v[126:129], v130 offset:61440
	ds_read_b128 v[130:133], v130 offset:63488
	s_setprio 1
	s_waitcnt lgkmcnt(3)
	v_mfma_f32_16x16x32_bf16 v[76:79], v[118:121], v[88:91], v[76:79]
	s_waitcnt lgkmcnt(2)
	v_mfma_f32_16x16x32_bf16 v[72:75], v[122:125], v[88:91], v[72:75]
	s_waitcnt lgkmcnt(1)
	v_mfma_f32_16x16x32_bf16 v[68:71], v[126:129], v[88:91], v[68:71]
	s_waitcnt lgkmcnt(0)
	v_mfma_f32_16x16x32_bf16 v[64:67], v[130:133], v[88:91], v[64:67]
	v_mfma_f32_16x16x32_bf16 v[60:63], v[118:121], v[102:105], v[60:63]
	v_mfma_f32_16x16x32_bf16 v[56:59], v[122:125], v[102:105], v[56:59]
	v_mfma_f32_16x16x32_bf16 v[88:91], v[126:129], v[102:105], v[52:55]
	v_mfma_f32_16x16x32_bf16 v[48:51], v[130:133], v[102:105], v[48:51]
	v_mfma_f32_16x16x32_bf16 v[44:47], v[118:121], v[106:109], v[44:47]
	v_mfma_f32_16x16x32_bf16 v[40:43], v[122:125], v[106:109], v[40:43]
	v_mfma_f32_16x16x32_bf16 v[36:39], v[126:129], v[106:109], v[36:39]
	v_mfma_f32_16x16x32_bf16 v[32:35], v[130:133], v[106:109], v[32:35]
	v_mfma_f32_16x16x32_bf16 v[28:31], v[118:121], v[110:113], v[28:31]
	v_mfma_f32_16x16x32_bf16 v[24:27], v[122:125], v[110:113], v[24:27]
	v_mfma_f32_16x16x32_bf16 v[20:23], v[126:129], v[110:113], v[20:23]
	v_mfma_f32_16x16x32_bf16 v[16:19], v[130:133], v[110:113], v[16:19]
	v_mfma_f32_16x16x32_bf16 v[12:15], v[118:121], v[114:117], v[12:15]
	v_mfma_f32_16x16x32_bf16 v[8:11], v[122:125], v[114:117], v[8:11]
	v_mfma_f32_16x16x32_bf16 v[4:7], v[126:129], v[114:117], v[4:7]
	v_mfma_f32_16x16x32_bf16 v[0:3], v[130:133], v[114:117], v[0:3]
	s_setprio 0
	v_mov_b32_e32 v52, v97
	s_waitcnt vmcnt(0)
	s_barrier
	s_mov_b32 s8, 0
	v_add_u32_e32 v52, v52, v176
	v_lshrrev_b32_e32 v55, 2, v52
	v_ashrrev_i32_e32 v53, 7, v52
	v_and_b32_e32 v54, 64, v52
	v_and_b32_e32 v55, 12, v55
	v_and_or_b32 v52, v52, 15, s6
	s_movk_i32 s5, 0x50
	s_lshl_b32 s4, s4, 7
	v_mad_u64_u32 v[52:53], s[6:7], v53, s5, v[52:53]
	v_or3_b32 v54, v54, v55, s4
	v_ashrrev_i32_e32 v53, 31, v52
	v_lshlrev_b64 v[52:53], 12, v[52:53]
	v_lshl_add_u64 v[52:53], s[0:1], 0, v[52:53]
	v_ashrrev_i32_e32 v55, 31, v54
	v_lshl_add_u64 v[52:53], v[54:55], 2, v[52:53]
	global_load_dwordx4 v[102:105], v[52:53], off
	s_waitcnt vmcnt(0)
	v_pk_add_f32 v[76:77], v[76:77], v[102:103]
	v_pk_add_f32 v[78:79], v[78:79], v[104:105]
	global_store_dwordx4 v[52:53], v[76:79], off
	global_load_dwordx4 v[76:79], v[52:53], off offset:64
	s_waitcnt vmcnt(0)
	v_pk_add_f32 v[72:73], v[72:73], v[76:77]
	v_pk_add_f32 v[74:75], v[74:75], v[78:79]
	global_store_dwordx4 v[52:53], v[72:75], off offset:64
	global_load_dwordx4 v[72:75], v[52:53], off offset:128
	s_waitcnt vmcnt(0)
	v_pk_add_f32 v[68:69], v[68:69], v[72:73]
	v_pk_add_f32 v[70:71], v[70:71], v[74:75]
	global_store_dwordx4 v[52:53], v[68:71], off offset:128
	global_load_dwordx4 v[68:71], v[52:53], off offset:192
	s_waitcnt vmcnt(0)
	v_pk_add_f32 v[64:65], v[64:65], v[68:69]
	v_pk_add_f32 v[66:67], v[66:67], v[70:71]
	global_store_dwordx4 v[52:53], v[64:67], off offset:192
	s_mov_b32 s4, 0x10000
	v_add_co_u32_e32 v54, vcc, s4, v52
	v_lshl_add_u64 v[68:69], v[52:53], 0, s[34:35]
	s_nop 0
	v_addc_co_u32_e32 v55, vcc, 0, v53, vcc
	global_load_dwordx4 v[64:67], v[54:55], off
	s_waitcnt vmcnt(0)
	v_pk_add_f32 v[60:61], v[60:61], v[64:65]
	v_pk_add_f32 v[62:63], v[62:63], v[66:67]
	global_store_dwordx4 v[54:55], v[60:63], off
	global_load_dwordx4 v[60:63], v[68:69], off offset:64
	s_waitcnt vmcnt(0)
	v_pk_add_f32 v[54:55], v[56:57], v[60:61]
	v_pk_add_f32 v[56:57], v[58:59], v[62:63]
	global_store_dwordx4 v[68:69], v[54:57], off offset:64
	global_load_dwordx4 v[54:57], v[68:69], off offset:128
	s_waitcnt vmcnt(0)
	v_pk_add_f32 v[54:55], v[88:89], v[54:55]
	v_pk_add_f32 v[56:57], v[90:91], v[56:57]
	global_store_dwordx4 v[68:69], v[54:57], off offset:128
	global_load_dwordx4 v[54:57], v[68:69], off offset:192
	s_waitcnt vmcnt(0)
	v_pk_add_f32 v[48:49], v[48:49], v[54:55]
	v_pk_add_f32 v[50:51], v[50:51], v[56:57]
	global_store_dwordx4 v[68:69], v[48:51], off offset:192
	s_mov_b64 s[4:5], 0x20000
	v_lshl_add_u64 v[54:55], v[52:53], 0, s[4:5]
	s_mov_b32 s4, 0x20000
	v_add_co_u32_e32 v56, vcc, s4, v52
	s_nop 1
	v_addc_co_u32_e32 v57, vcc, 0, v53, vcc
	global_load_dwordx4 v[48:51], v[56:57], off
	s_waitcnt vmcnt(0)
	v_pk_add_f32 v[44:45], v[44:45], v[48:49]
	v_pk_add_f32 v[46:47], v[46:47], v[50:51]
	global_store_dwordx4 v[56:57], v[44:47], off
	global_load_dwordx4 v[44:47], v[54:55], off offset:64
	s_waitcnt vmcnt(0)
	v_pk_add_f32 v[40:41], v[40:41], v[44:45]
	v_pk_add_f32 v[42:43], v[42:43], v[46:47]
	global_store_dwordx4 v[54:55], v[40:43], off offset:64
	global_load_dwordx4 v[40:43], v[54:55], off offset:128
	s_waitcnt vmcnt(0)
	v_pk_add_f32 v[36:37], v[36:37], v[40:41]
	v_pk_add_f32 v[38:39], v[38:39], v[42:43]
	global_store_dwordx4 v[54:55], v[36:39], off offset:128
	global_load_dwordx4 v[36:39], v[54:55], off offset:192
	s_waitcnt vmcnt(0)
	v_pk_add_f32 v[32:33], v[32:33], v[36:37]
	v_pk_add_f32 v[34:35], v[34:35], v[38:39]
	global_store_dwordx4 v[54:55], v[32:35], off offset:192
	s_mov_b64 s[4:5], 0x30000
	v_lshl_add_u64 v[36:37], v[52:53], 0, s[4:5]
	s_mov_b32 s4, 0x30000
	v_add_co_u32_e32 v38, vcc, s4, v52
	s_nop 1
	v_addc_co_u32_e32 v39, vcc, 0, v53, vcc
	global_load_dwordx4 v[32:35], v[38:39], off
	s_waitcnt vmcnt(0)
	v_pk_add_f32 v[28:29], v[28:29], v[32:33]
	v_pk_add_f32 v[30:31], v[30:31], v[34:35]
	global_store_dwordx4 v[38:39], v[28:31], off
	global_load_dwordx4 v[28:31], v[36:37], off offset:64
	s_waitcnt vmcnt(0)
	v_pk_add_f32 v[24:25], v[24:25], v[28:29]
	v_pk_add_f32 v[26:27], v[26:27], v[30:31]
	global_store_dwordx4 v[36:37], v[24:27], off offset:64
	global_load_dwordx4 v[24:27], v[36:37], off offset:128
	s_waitcnt vmcnt(0)
	v_pk_add_f32 v[20:21], v[20:21], v[24:25]
	v_pk_add_f32 v[22:23], v[22:23], v[26:27]
	global_store_dwordx4 v[36:37], v[20:23], off offset:128
	global_load_dwordx4 v[20:23], v[36:37], off offset:192
	s_waitcnt vmcnt(0)
	v_pk_add_f32 v[16:17], v[16:17], v[20:21]
	v_pk_add_f32 v[18:19], v[18:19], v[22:23]
	global_store_dwordx4 v[36:37], v[16:19], off offset:192
	s_mov_b64 s[4:5], 0x40000
	v_lshl_add_u64 v[20:21], v[52:53], 0, s[4:5]
	s_mov_b32 s4, 0x40000
	v_add_co_u32_e32 v22, vcc, s4, v52
	s_nop 1
	v_addc_co_u32_e32 v23, vcc, 0, v53, vcc
	global_load_dwordx4 v[16:19], v[22:23], off
	s_waitcnt vmcnt(0)
	v_pk_add_f32 v[12:13], v[12:13], v[16:17]
	v_pk_add_f32 v[14:15], v[14:15], v[18:19]
	global_store_dwordx4 v[22:23], v[12:15], off
	global_load_dwordx4 v[12:15], v[20:21], off offset:64
	s_waitcnt vmcnt(0)
	v_pk_add_f32 v[8:9], v[8:9], v[12:13]
	v_pk_add_f32 v[10:11], v[10:11], v[14:15]
	global_store_dwordx4 v[20:21], v[8:11], off offset:64
	global_load_dwordx4 v[8:11], v[20:21], off offset:128
	s_waitcnt vmcnt(0)
	v_pk_add_f32 v[4:5], v[4:5], v[8:9]
	v_pk_add_f32 v[6:7], v[6:7], v[10:11]
	global_store_dwordx4 v[20:21], v[4:7], off offset:128
	global_load_dwordx4 v[4:7], v[20:21], off offset:192
	s_waitcnt vmcnt(0)
	v_pk_add_f32 v[0:1], v[0:1], v[4:5]
	v_pk_add_f32 v[2:3], v[2:3], v[6:7]
	global_store_dwordx4 v[20:21], v[0:3], off offset:192
